# GEMM K-loops restructured: phase pairs merged (32 MFMA per barrier interval, 8 barriers per trip instead of 16), stage loads re-timed, vmcnt(8)/lgkmcnt(0) before each barrier
# speedup vs baseline: 1.0127x; 1.0077x over previous
; #define PG8_STAGE(bufoff, gbase, voff) do { _Pragma("unroll") for (int _i = 0; _i < 2; ++_i) \
;         __builtin_amdgcn_global_load_lds((const unsigned*)((const char*)(gbase) + (voff)[_i]), (PG8_LAS unsigned*)(lds + (bufoff) + ldsw + _i * 8192), 16, 0, 0); } while (0)
; #define PG8_WAIT_V(n) asm volatile("s_waitcnt vmcnt(" #n ")" ::: "memory")
; #define PG8_BAR __builtin_amdgcn_s_barrier()
; template <class Epi, class Sched>
; __device__ __forceinline__ void gemm_phase(PG8_LAS unsigned char* lds, const Gemm g, const Sched& S, const Epi& E) {
;     ...
;     for (int i = 0; i < 2; ++i) { int R, C; stage_rc(tid * 16 + i * 8192, R, C); const int Rb = Epi::PERM ? ((R & ~31) + perm32(R & 31)) : R;
;         voffA[i] = (unsigned)(R * K + C) * 2u; voffB[i] = (unsigned)(Rb * K + C) * 2u; }
;     const size_t kstep = (size_t)(BK * 2);
;     const size_t hstep = (size_t)HALF * K * 2;
;     const size_t tstep = 2 * hstep;
;     const unsigned ldsw = (unsigned)wid * 1024u;
;     const int aoff = lds_byte(wr * 64 + fr, fq * 8), boff = lds_byte(wc * 32 + fr, fq * 8);
;     ...
;     PG8_STAGE(PG8_SB(0, 0), cB, voffB); PG8_STAGE(PG8_SA(0, 0), cA, voffA); PG8_STAGE(PG8_SB(0, 1), cB + hstep, voffB); PG8_STAGE(PG8_SA(0, 1), cA + hstep, voffA);
;     if (wr == 1) PG8_BAR;
;     PG8_WAIT_V(4); PG8_BAR;
;     PG8_STAGE(PG8_SB(1, 0), cB + kstep, voffB); PG8_STAGE(PG8_SA(1, 0), cA + kstep, voffA); PG8_STAGE(PG8_SB(1, 1), cB + hstep + kstep, voffB);
;     PG8_WAIT_V(6); PG8_BAR;
.LBB0_191:
	s_lshl_b32 s4, s4, 27
	v_readlane_b32 s5, v245, 18
	s_add_u32 s4, s5, s4
	v_readlane_b32 s5, v245, 19
	s_addc_u32 s5, s5, 0
	s_lshl_b32 s10, s10, 5
	s_and_b32 s17, s10, 0x60
	s_mov_b64 s[10:11], 0x80
	s_add_i32 m0, s27, 0x18000
	v_lshl_add_u64 v[6:7], v[6:7], 0, s[10:11]
	s_lshl_b32 s16, s3, 13
	s_lshl_b32 s18, s17, 7
	s_waitcnt vmcnt(0)
	s_barrier
	global_load_lds_dwordx4 v[6:7], off
	v_lshl_add_u64 v[4:5], v[4:5], 0, s[10:11]
	s_add_i32 m0, s27, 0x1a000
	s_add_i32 s47, s27, 0x8000
	s_add_i32 s48, s27, 0xa000
	global_load_lds_dwordx4 v[4:5], off
	v_lshl_add_u64 v[2:3], v[2:3], 0, s[10:11]
	s_mov_b32 m0, s47
	s_add_u32 s14, s30, 0x40080
	global_load_lds_dwordx4 v[2:3], off
	v_lshl_add_u64 v[0:1], v[0:1], 0, s[10:11]
	s_mov_b32 m0, s48
	s_addc_u32 s15, s31, 0
	global_load_lds_dwordx4 v[0:1], off
	s_add_i32 m0, s27, 0x1c000
	v_lshl_add_u64 v[0:1], s[14:15], 0, v[132:133]
	global_load_lds_dwordx4 v[0:1], off
	v_lshl_add_u64 v[0:1], s[14:15], 0, v[128:129]
	s_add_i32 m0, s27, 0x1e000
	s_add_i32 s50, 0, 0x10000
	global_load_lds_dwordx4 v[0:1], off
	v_lshrrev_b32_e32 v1, 1, v8
	v_and_b32_e32 v1, 24, v1
	v_and_b32_e32 v0, 15, v8
	v_lshlrev_b32_e32 v2, 1, v1
	v_lshl_or_b32 v148, s3, 6, v0
	v_lshl_or_b32 v0, v0, 6, v2
	v_lshlrev_b32_e32 v2, 2, v8
	v_and_b32_e32 v2, 32, v2
	v_bitop3_b32 v3, v0, s16, v2 bitop3:0xde
	v_bitop3_b32 v149, v0, s18, v2 bitop3:0xde
	v_lshlrev_b32_e32 v0, 14, v13
	v_and_b32_e32 v0, 0xffff8000, v0
	v_or_b32_e32 v150, s17, v1
	v_lshl_add_u32 v0, v12, 11, v0
	v_and_b32_e32 v1, 1, v13
	v_lshl_or_b32 v0, v1, 6, v0
	v_lshl_add_u32 v136, v14, 1, v0
	v_lshlrev_b32_e32 v0, 14, v9
	v_and_b32_e32 v0, 0xffff8000, v0
	s_waitcnt vmcnt(6)
	v_lshl_add_u32 v0, v10, 11, v0
	v_and_b32_e32 v1, 1, v9
	v_lshl_or_b32 v0, v1, 6, v0
	s_add_i32 s51, 0, 0x14000
	s_sext_i32_i16 s53, s2
	s_ashr_i32 s49, s33, 31
	v_mov_b32_e32 v137, v133
	v_lshl_add_u32 v138, v11, 1, v0
	v_mov_b32_e32 v139, v133
	v_mov_b64_e32 v[140:141], 0x580
	v_mov_b64_e32 v[142:143], 0x57f
	v_add_u32_e32 v151, s50, v149
	v_add_u32_e32 v153, 0, v3
	v_add_u32_e32 v154, s51, v149
	s_movk_i32 s52, 0x1600
	s_barrier
	s_waitcnt vmcnt(0)

; #define PG8_STAGE(bufoff, gbase, voff) do { _Pragma("unroll") for (int _i = 0; _i < 2; ++_i) \
;         __builtin_amdgcn_global_load_lds((const unsigned*)((const char*)(gbase) + (voff)[_i]), (PG8_LAS unsigned*)(lds + (bufoff) + ldsw + _i * 8192), 16, 0, 0); } while (0)
; #define PG8_LDA(dst, b, h) do { _Pragma("unroll") for (int m = 0; m < 4; ++m) _Pragma("unroll") for (int k = 0; k < 2; ++k) dst[m][k] = *(const PG8_LAS bf16x8*)(lds + PG8_SA(b, h) + aoff + m * 2048 + k * 1024); } while (0)
; #define PG8_LDB(dst, b, h) do { _Pragma("unroll") for (int n = 0; n < 2; ++n) _Pragma("unroll") for (int k = 0; k < 2; ++k) dst[n][k] = *(const PG8_LAS bf16x8*)(lds + PG8_SB(b, h) + boff + n * 2048 + k * 1024); } while (0)
; #define PG8_MMA(ai, bj, At, Bt) do { __builtin_amdgcn_s_setprio(1); _Pragma("unroll") for (int m = 0; m < 4; ++m) _Pragma("unroll") for (int n = 0; n < 2; ++n) _Pragma("unroll") for (int k = 0; k < 2; ++k) \
;         acc[ai][bj][m][n] = __builtin_amdgcn_mfma_f32_16x16x32_bf16(Bt[n][k], At[m][k], acc[ai][bj][m][n], 0, 0, 0); __builtin_amdgcn_s_setprio(0); } while (0)
; #define PG8_WAIT_L(n) asm volatile("s_waitcnt lgkmcnt(" #n ")" ::: "memory")
; #define PG8_BAR __builtin_amdgcn_s_barrier()
; #define PG8_SCHED __builtin_amdgcn_sched_barrier(0)
; template <class Epi, class Sched>
; __device__ __forceinline__ void gemm_phase(PG8_LAS unsigned char* lds, const Gemm g, const Sched& S, const Epi& E) {
;     ...
;             PG8_LDB(B0, 0, 0); PG8_SCHED; PG8_LDA(At, 0, 0); PG8_STAGE(PG8_SA(1, 1), a1 + hstep, voffA);
;             PG8_WAIT_L(8); PG8_BAR; PG8_WAIT_L(0); PG8_MMA(0, 0, At, B0); PG8_BAR; PG8_SCHED;
;             PG8_LDB(B1, 0, 1); PG8_STAGE(PG8_SB(0, 0), b2, voffB);
;             PG8_BAR; PG8_WAIT_L(0); PG8_MMA(0, 1, At, B1); PG8_BAR;
;             PG8_LDA(At, 0, 1); PG8_STAGE(PG8_SA(0, 0), a2, voffA);
;             PG8_BAR; PG8_WAIT_L(0); PG8_MMA(1, 0, At, B0); PG8_BAR; PG8_SCHED;
.LBB0_195:
	ds_read_b128 v[144:147], v151
	ds_read_b128 v[156:159], v151 offset:1024
	ds_read_b128 v[160:163], v151 offset:2048
	ds_read_b128 v[166:169], v151 offset:3072
	s_add_u32 s30, s28, 0xfffc0080
	s_addc_u32 s31, s29, -1
	s_cmp_eq_u32 s58, 12
	s_cselect_b32 s35, s17, s31
	s_cselect_b32 s34, s54, s30
	s_cselect_b32 s31, s15, s57
	s_cselect_b32 s30, s55, s56
	v_lshl_add_u64 v[174:175], s[28:29], 0, v[136:137]
	s_add_i32 m0, s27, 0xc000
	ds_read_b128 v[170:173], v153
	ds_read_b128 v[182:185], v153 offset:1024
	ds_read_b128 v[190:193], v153 offset:2048
	ds_read_b128 v[194:197], v153 offset:3072
	ds_read_b128 v[198:201], v153 offset:4096
	ds_read_b128 v[202:205], v153 offset:5120
	ds_read_b128 v[206:209], v153 offset:6144
	ds_read_b128 v[210:213], v153 offset:7168
	global_load_lds_dwordx4 v[174:175], off
	v_lshl_add_u64 v[174:175], s[28:29], 0, v[138:139]
	s_add_i32 m0, s27, 0xe000
	s_nop 0
	global_load_lds_dwordx4 v[174:175], off
	s_waitcnt lgkmcnt(8)
	ds_read_b128 v[214:217], v154
	ds_read_b128 v[218:221], v154 offset:1024
	ds_read_b128 v[222:225], v154 offset:2048
	ds_read_b128 v[226:229], v154 offset:3072
	s_waitcnt vmcnt(8) lgkmcnt(0)
	s_barrier
	v_mfma_f32_16x16x32_bf16 v[124:127], v[144:147], v[170:173], v[124:127]
	v_mfma_f32_16x16x32_bf16 v[120:123], v[160:163], v[170:173], v[120:123]
	v_mfma_f32_16x16x32_bf16 v[108:111], v[144:147], v[190:193], v[108:111]
	v_mfma_f32_16x16x32_bf16 v[104:107], v[160:163], v[190:193], v[104:107]
	v_mfma_f32_16x16x32_bf16 v[92:95], v[144:147], v[198:201], v[92:95]
	v_mfma_f32_16x16x32_bf16 v[88:91], v[160:163], v[198:201], v[88:91]
	v_mfma_f32_16x16x32_bf16 v[76:79], v[144:147], v[206:209], v[76:79]
	v_mfma_f32_16x16x32_bf16 v[72:75], v[160:163], v[206:209], v[72:75]
	v_mfma_f32_16x16x32_bf16 v[124:127], v[156:159], v[182:185], v[124:127]
	v_mfma_f32_16x16x32_bf16 v[120:123], v[166:169], v[182:185], v[120:123]
	v_mfma_f32_16x16x32_bf16 v[108:111], v[156:159], v[194:197], v[108:111]
	v_mfma_f32_16x16x32_bf16 v[104:107], v[166:169], v[194:197], v[104:107]
	v_mfma_f32_16x16x32_bf16 v[92:95], v[156:159], v[202:205], v[92:95]
	v_mfma_f32_16x16x32_bf16 v[88:91], v[166:169], v[202:205], v[88:91]
	v_mfma_f32_16x16x32_bf16 v[76:79], v[156:159], v[210:213], v[76:79]
	v_mfma_f32_16x16x32_bf16 v[72:75], v[166:169], v[210:213], v[72:75]
	v_mfma_f32_16x16x32_bf16 v[116:119], v[214:217], v[170:173], v[116:119]
	v_mfma_f32_16x16x32_bf16 v[112:115], v[222:225], v[170:173], v[112:115]
	v_mfma_f32_16x16x32_bf16 v[100:103], v[214:217], v[190:193], v[100:103]
	v_mfma_f32_16x16x32_bf16 v[96:99], v[222:225], v[190:193], v[96:99]
	v_mfma_f32_16x16x32_bf16 v[84:87], v[214:217], v[198:201], v[84:87]
	v_mfma_f32_16x16x32_bf16 v[80:83], v[222:225], v[198:201], v[80:83]
	v_mfma_f32_16x16x32_bf16 v[68:71], v[214:217], v[206:209], v[68:71]
	v_mfma_f32_16x16x32_bf16 v[64:67], v[222:225], v[206:209], v[64:67]
	v_mfma_f32_16x16x32_bf16 v[116:119], v[218:221], v[182:185], v[116:119]
	v_mfma_f32_16x16x32_bf16 v[112:115], v[226:229], v[182:185], v[112:115]
	v_mfma_f32_16x16x32_bf16 v[100:103], v[218:221], v[194:197], v[100:103]
	v_mfma_f32_16x16x32_bf16 v[96:99], v[226:229], v[194:197], v[96:99]
	v_mfma_f32_16x16x32_bf16 v[84:87], v[218:221], v[202:205], v[84:87]
	v_mfma_f32_16x16x32_bf16 v[80:83], v[226:229], v[202:205], v[80:83]
	v_mfma_f32_16x16x32_bf16 v[68:71], v[218:221], v[210:213], v[68:71]
	v_mfma_f32_16x16x32_bf16 v[64:67], v[226:229], v[210:213], v[64:67]
	s_barrier
	ds_read_b128 v[170:173], v153 offset:16384
	ds_read_b128 v[182:185], v153 offset:17408
	ds_read_b128 v[190:193], v153 offset:18432
	ds_read_b128 v[194:197], v153 offset:19456
	ds_read_b128 v[198:201], v153 offset:20480
	ds_read_b128 v[202:205], v153 offset:21504
	ds_read_b128 v[206:209], v153 offset:22528
	ds_read_b128 v[210:213], v153 offset:23552
	s_add_i32 s59, s50, s40
	v_lshl_add_u64 v[174:175], s[30:31], 0, v[132:133]
	s_mov_b32 m0, s59
	s_nop 0
	global_load_lds_dwordx4 v[174:175], off
	v_lshl_add_u64 v[178:179], s[30:31], 0, v[128:129]
	s_add_i32 m0, s59, 0x2000
	s_nop 0
	global_load_lds_dwordx4 v[178:179], off
	s_nop 1
	s_mov_b32 m0, s27
	v_lshl_add_u64 v[186:187], s[34:35], 0, v[134:135]
	global_load_lds_dwordx4 v[186:187], off
	v_lshl_add_u64 v[230:231], s[34:35], 0, v[130:131]
	s_mov_b32 m0, s43
	s_nop 0
	global_load_lds_dwordx4 v[230:231], off
	s_add_u32 s60, s30, 0x40000
	s_addc_u32 s61, s31, 0
	s_add_i32 s59, s51, s40
	v_lshl_add_u64 v[246:247], s[60:61], 0, v[132:133]
	s_mov_b32 m0, s59
	s_nop 0
	global_load_lds_dwordx4 v[246:247], off
	v_lshl_add_u64 v[246:247], s[60:61], 0, v[128:129]
	s_add_i32 m0, s59, 0x2000
	s_nop 0
	global_load_lds_dwordx4 v[246:247], off
	s_waitcnt vmcnt(8) lgkmcnt(0)
	s_barrier
; #define PG8_STAGE(bufoff, gbase, voff) do { _Pragma("unroll") for (int _i = 0; _i < 2; ++_i) \
;         __builtin_amdgcn_global_load_lds((const unsigned*)((const char*)(gbase) + (voff)[_i]), (PG8_LAS unsigned*)(lds + (bufoff) + ldsw + _i * 8192), 16, 0, 0); } while (0)
; #define PG8_LDA(dst, b, h) do { _Pragma("unroll") for (int m = 0; m < 4; ++m) _Pragma("unroll") for (int k = 0; k < 2; ++k) dst[m][k] = *(const PG8_LAS bf16x8*)(lds + PG8_SA(b, h) + aoff + m * 2048 + k * 1024); } while (0)
; #define PG8_LDB(dst, b, h) do { _Pragma("unroll") for (int n = 0; n < 2; ++n) _Pragma("unroll") for (int k = 0; k < 2; ++k) dst[n][k] = *(const PG8_LAS bf16x8*)(lds + PG8_SB(b, h) + boff + n * 2048 + k * 1024); } while (0)
; #define PG8_MMA(ai, bj, At, Bt) do { __builtin_amdgcn_s_setprio(1); _Pragma("unroll") for (int m = 0; m < 4; ++m) _Pragma("unroll") for (int n = 0; n < 2; ++n) _Pragma("unroll") for (int k = 0; k < 2; ++k) \
;         acc[ai][bj][m][n] = __builtin_amdgcn_mfma_f32_16x16x32_bf16(Bt[n][k], At[m][k], acc[ai][bj][m][n], 0, 0, 0); __builtin_amdgcn_s_setprio(0); } while (0)
; #define PG8_WAIT_V(n) asm volatile("s_waitcnt vmcnt(" #n ")" ::: "memory")
; #define PG8_WAIT_L(n) asm volatile("s_waitcnt lgkmcnt(" #n ")" ::: "memory")
; #define PG8_BAR __builtin_amdgcn_s_barrier()
; #define PG8_SCHED __builtin_amdgcn_sched_barrier(0)
; template <class Epi, class Sched>
; __device__ __forceinline__ void gemm_phase(PG8_LAS unsigned char* lds, const Gemm g, const Sched& S, const Epi& E) {
;     ...
;             PG8_BAR; PG8_WAIT_L(0); PG8_MMA(1, 0, At, B0); PG8_BAR; PG8_SCHED;
;             PG8_STAGE(PG8_SB(0, 1), b2 + hstep, voffB);
;             PG8_WAIT_V(6); PG8_BAR; PG8_MMA(1, 1, At, B1); PG8_BAR;
;             PG8_LDB(B0, 1, 0); PG8_SCHED; PG8_LDA(At, 1, 0); PG8_STAGE(PG8_SA(0, 1), a2 + hstep, voffA);
;             PG8_WAIT_L(8); PG8_BAR; PG8_WAIT_L(0); PG8_MMA(0, 0, At, B0); PG8_BAR; PG8_SCHED;
;             PG8_LDB(B1, 1, 1); PG8_STAGE(PG8_SB(1, 0), b3, voffB);
;             PG8_BAR; PG8_WAIT_L(0); PG8_MMA(0, 1, At, B1); PG8_BAR;
	v_mfma_f32_16x16x32_bf16 v[60:63], v[144:147], v[170:173], v[60:63]
	v_mfma_f32_16x16x32_bf16 v[56:59], v[160:163], v[170:173], v[56:59]
	v_mfma_f32_16x16x32_bf16 v[44:47], v[144:147], v[190:193], v[44:47]
	v_mfma_f32_16x16x32_bf16 v[40:43], v[160:163], v[190:193], v[40:43]
	v_mfma_f32_16x16x32_bf16 v[28:31], v[144:147], v[198:201], v[28:31]
	v_mfma_f32_16x16x32_bf16 v[24:27], v[160:163], v[198:201], v[24:27]
	v_mfma_f32_16x16x32_bf16 v[12:15], v[144:147], v[206:209], v[12:15]
	v_mfma_f32_16x16x32_bf16 v[8:11], v[160:163], v[206:209], v[8:11]
	v_mfma_f32_16x16x32_bf16 v[60:63], v[156:159], v[182:185], v[60:63]
	v_mfma_f32_16x16x32_bf16 v[56:59], v[166:169], v[182:185], v[56:59]
	v_mfma_f32_16x16x32_bf16 v[44:47], v[156:159], v[194:197], v[44:47]
	v_mfma_f32_16x16x32_bf16 v[40:43], v[166:169], v[194:197], v[40:43]
	v_mfma_f32_16x16x32_bf16 v[28:31], v[156:159], v[202:205], v[28:31]
	v_mfma_f32_16x16x32_bf16 v[24:27], v[166:169], v[202:205], v[24:27]
	v_mfma_f32_16x16x32_bf16 v[12:15], v[156:159], v[210:213], v[12:15]
	v_mfma_f32_16x16x32_bf16 v[8:11], v[166:169], v[210:213], v[8:11]
	v_mfma_f32_16x16x32_bf16 v[52:55], v[214:217], v[170:173], v[52:55]
	v_mfma_f32_16x16x32_bf16 v[48:51], v[222:225], v[170:173], v[48:51]
	v_mfma_f32_16x16x32_bf16 v[36:39], v[214:217], v[190:193], v[36:39]
	v_mfma_f32_16x16x32_bf16 v[32:35], v[222:225], v[190:193], v[32:35]
	v_mfma_f32_16x16x32_bf16 v[20:23], v[214:217], v[198:201], v[20:23]
	v_mfma_f32_16x16x32_bf16 v[16:19], v[222:225], v[198:201], v[16:19]
	v_mfma_f32_16x16x32_bf16 v[4:7], v[214:217], v[206:209], v[4:7]
	v_mfma_f32_16x16x32_bf16 v[0:3], v[222:225], v[206:209], v[0:3]
	v_mfma_f32_16x16x32_bf16 v[52:55], v[218:221], v[182:185], v[52:55]
	v_mfma_f32_16x16x32_bf16 v[48:51], v[226:229], v[182:185], v[48:51]
	v_mfma_f32_16x16x32_bf16 v[36:39], v[218:221], v[194:197], v[36:39]
	v_mfma_f32_16x16x32_bf16 v[32:35], v[226:229], v[194:197], v[32:35]
	v_mfma_f32_16x16x32_bf16 v[20:23], v[218:221], v[202:205], v[20:23]
	v_mfma_f32_16x16x32_bf16 v[16:19], v[226:229], v[202:205], v[16:19]
	v_mfma_f32_16x16x32_bf16 v[4:7], v[218:221], v[210:213], v[4:7]
	v_mfma_f32_16x16x32_bf16 v[0:3], v[226:229], v[210:213], v[0:3]
	s_barrier
	s_add_i32 s59, 0, 0x18000
	v_add_u32_e32 v155, s59, v149
	ds_read_b128 v[144:147], v155
	ds_read_b128 v[156:159], v155 offset:1024
	ds_read_b128 v[160:163], v155 offset:2048
	ds_read_b128 v[166:169], v155 offset:3072
	s_add_u32 s34, s34, 0x40000
	s_addc_u32 s35, s35, 0
	s_mov_b32 m0, s44
	v_lshl_add_u64 v[214:215], s[34:35], 0, v[134:135]
	ds_read_b128 v[170:173], v153 offset:32768
	ds_read_b128 v[182:185], v153 offset:33792
	ds_read_b128 v[190:193], v153 offset:34816
	ds_read_b128 v[194:197], v153 offset:35840
	ds_read_b128 v[198:201], v153 offset:36864
	ds_read_b128 v[202:205], v153 offset:37888
	ds_read_b128 v[206:209], v153 offset:38912
	ds_read_b128 v[210:213], v153 offset:39936
	global_load_lds_dwordx4 v[214:215], off
	v_lshl_add_u64 v[214:215], s[34:35], 0, v[130:131]
	s_mov_b32 m0, s45
	s_nop 0
	global_load_lds_dwordx4 v[214:215], off
	s_add_i32 s34, 0, 0x1c000
	v_add_u32_e32 v155, s34, v149
	s_waitcnt lgkmcnt(8)
	ds_read_b128 v[214:217], v155
	ds_read_b128 v[218:221], v155 offset:1024
	ds_read_b128 v[222:225], v155 offset:2048
	ds_read_b128 v[226:229], v155 offset:3072
	s_waitcnt vmcnt(8) lgkmcnt(0)
	s_barrier
	v_mfma_f32_16x16x32_bf16 v[124:127], v[144:147], v[170:173], v[124:127]
	v_mfma_f32_16x16x32_bf16 v[120:123], v[160:163], v[170:173], v[120:123]
	v_mfma_f32_16x16x32_bf16 v[108:111], v[144:147], v[190:193], v[108:111]
	v_mfma_f32_16x16x32_bf16 v[104:107], v[160:163], v[190:193], v[104:107]
	v_mfma_f32_16x16x32_bf16 v[92:95], v[144:147], v[198:201], v[92:95]
	v_mfma_f32_16x16x32_bf16 v[88:91], v[160:163], v[198:201], v[88:91]
	v_mfma_f32_16x16x32_bf16 v[76:79], v[144:147], v[206:209], v[76:79]
	v_mfma_f32_16x16x32_bf16 v[72:75], v[160:163], v[206:209], v[72:75]
	v_mfma_f32_16x16x32_bf16 v[124:127], v[156:159], v[182:185], v[124:127]
	v_mfma_f32_16x16x32_bf16 v[120:123], v[166:169], v[182:185], v[120:123]
	v_mfma_f32_16x16x32_bf16 v[108:111], v[156:159], v[194:197], v[108:111]
	v_mfma_f32_16x16x32_bf16 v[104:107], v[166:169], v[194:197], v[104:107]
	v_mfma_f32_16x16x32_bf16 v[92:95], v[156:159], v[202:205], v[92:95]
	v_mfma_f32_16x16x32_bf16 v[88:91], v[166:169], v[202:205], v[88:91]
	v_mfma_f32_16x16x32_bf16 v[76:79], v[156:159], v[210:213], v[76:79]
	v_mfma_f32_16x16x32_bf16 v[72:75], v[166:169], v[210:213], v[72:75]
	v_mfma_f32_16x16x32_bf16 v[116:119], v[214:217], v[170:173], v[116:119]
	v_mfma_f32_16x16x32_bf16 v[112:115], v[222:225], v[170:173], v[112:115]
	v_mfma_f32_16x16x32_bf16 v[100:103], v[214:217], v[190:193], v[100:103]
	v_mfma_f32_16x16x32_bf16 v[96:99], v[222:225], v[190:193], v[96:99]
	v_mfma_f32_16x16x32_bf16 v[84:87], v[214:217], v[198:201], v[84:87]
	v_mfma_f32_16x16x32_bf16 v[80:83], v[222:225], v[198:201], v[80:83]
	v_mfma_f32_16x16x32_bf16 v[68:71], v[214:217], v[206:209], v[68:71]
	v_mfma_f32_16x16x32_bf16 v[64:67], v[222:225], v[206:209], v[64:67]
	v_mfma_f32_16x16x32_bf16 v[116:119], v[218:221], v[182:185], v[116:119]
	v_mfma_f32_16x16x32_bf16 v[112:115], v[226:229], v[182:185], v[112:115]
	v_mfma_f32_16x16x32_bf16 v[100:103], v[218:221], v[194:197], v[100:103]
	v_mfma_f32_16x16x32_bf16 v[96:99], v[226:229], v[194:197], v[96:99]
	v_mfma_f32_16x16x32_bf16 v[84:87], v[218:221], v[202:205], v[84:87]
	v_mfma_f32_16x16x32_bf16 v[80:83], v[226:229], v[202:205], v[80:83]
	v_mfma_f32_16x16x32_bf16 v[68:71], v[218:221], v[210:213], v[68:71]
	v_mfma_f32_16x16x32_bf16 v[64:67], v[226:229], v[210:213], v[64:67]
	s_barrier
; __device__ __forceinline__ unsigned cvt_pk_bf16(float lo, float hi) { unsigned r; asm volatile("v_cvt_pk_bf16_f32 %0, %1, %2" : "=v"(r) : "v"(lo), "v"(hi)); return r; }
; #define PG8_STAGE(bufoff, gbase, voff) do { _Pragma("unroll") for (int _i = 0; _i < 2; ++_i) \
;         __builtin_amdgcn_global_load_lds((const unsigned*)((const char*)(gbase) + (voff)[_i]), (PG8_LAS unsigned*)(lds + (bufoff) + ldsw + _i * 8192), 16, 0, 0); } while (0)
; #define PG8_LDA(dst, b, h) do { _Pragma("unroll") for (int m = 0; m < 4; ++m) _Pragma("unroll") for (int k = 0; k < 2; ++k) dst[m][k] = *(const PG8_LAS bf16x8*)(lds + PG8_SA(b, h) + aoff + m * 2048 + k * 1024); } while (0)
; #define PG8_MMA(ai, bj, At, Bt) do { __builtin_amdgcn_s_setprio(1); _Pragma("unroll") for (int m = 0; m < 4; ++m) _Pragma("unroll") for (int n = 0; n < 2; ++n) _Pragma("unroll") for (int k = 0; k < 2; ++k) \
;         acc[ai][bj][m][n] = __builtin_amdgcn_mfma_f32_16x16x32_bf16(Bt[n][k], At[m][k], acc[ai][bj][m][n], 0, 0, 0); __builtin_amdgcn_s_setprio(0); } while (0)
; #define PG8_BAR __builtin_amdgcn_s_barrier()
;     __device__ __forceinline__ void operator()(const f32x4 (&acc)[2][2][4][2], const Unit& u, int wr, int wc, int fr, int fq) const {
;         const int row0 = u.pm * BM + wr * 64 + fr, col0 = u.pn * HALF + wc * 32 + 8 * fq;
; #pragma unroll
;         for (int ai = 0; ai < 2; ++ai)
; #pragma unroll
;             for (int m = 0; m < 4; ++m) { bf16_t* rowp = O + (size_t)(row0 + ai * HALF + m * 16) * ldc + col0;
;                 f32x4 v0, v1;
; #pragma unroll
;                 for (int j = 0; j < 1; ++j) { v0 = acc[ai][0][m][0] * sigmoid4(acc[ai][0][m][0]) * acc[ai][1][m][0]; v1 = acc[ai][0][m][1] * sigmoid4(acc[ai][0][m][1]) * acc[ai][1][m][1]; }
;                 u32x4 w; w.x = cvt_pk_bf16(v0[0], v0[1]); w.y = cvt_pk_bf16(v0[2], v0[3]); w.z = cvt_pk_bf16(v1[0], v1[1]); w.w = cvt_pk_bf16(v1[2], v1[3]);
;                 *(u32x4*)rowp = w; }
; template <class Epi, class Sched>
; __device__ __forceinline__ void gemm_phase(PG8_LAS unsigned char* lds, const Gemm g, const Sched& S, const Epi& E) {
;     ...
;             PG8_LDA(At, 1, 1); PG8_STAGE(PG8_SA(1, 0), a3, voffA);
;             PG8_BAR; PG8_WAIT_L(0); PG8_MMA(1, 0, At, B0); PG8_BAR; PG8_SCHED;
;             PG8_STAGE(PG8_SB(1, 1), b3 + hstep, voffB);
;             PG8_WAIT_V(6); PG8_BAR; PG8_MMA(1, 1, At, B1); PG8_BAR;
	ds_read_b128 v[170:173], v153 offset:49152
	ds_read_b128 v[182:185], v153 offset:50176
	ds_read_b128 v[190:193], v153 offset:51200
	ds_read_b128 v[194:197], v153 offset:52224
	ds_read_b128 v[198:201], v153 offset:53248
	ds_read_b128 v[202:205], v153 offset:54272
	ds_read_b128 v[206:209], v153 offset:55296
	ds_read_b128 v[210:213], v153 offset:56320
	s_add_i32 s35, s59, s40
	v_lshl_add_u64 v[174:175], v[174:175], 0, s[10:11]
	s_mov_b32 m0, s35
	s_nop 0
	global_load_lds_dwordx4 v[174:175], off
	v_lshl_add_u64 v[174:175], v[178:179], 0, s[10:11]
	s_add_i32 m0, s35, 0x2000
	s_nop 0
	global_load_lds_dwordx4 v[174:175], off
	s_nop 1
	s_mov_b32 m0, s47
	v_lshl_add_u64 v[174:175], v[186:187], 0, s[10:11]
	global_load_lds_dwordx4 v[174:175], off
	v_lshl_add_u64 v[174:175], v[230:231], 0, s[10:11]
	s_mov_b32 m0, s48
	s_nop 0
	global_load_lds_dwordx4 v[174:175], off
	s_add_u32 s30, s30, 0x40080
	s_addc_u32 s31, s31, 0
	s_add_i32 s34, s34, s40
	v_lshl_add_u64 v[246:247], s[30:31], 0, v[132:133]
	s_mov_b32 m0, s34
	s_nop 0
	global_load_lds_dwordx4 v[246:247], off
	v_lshl_add_u64 v[246:247], s[30:31], 0, v[128:129]
	s_add_i32 m0, s34, 0x2000
	s_nop 0
	global_load_lds_dwordx4 v[246:247], off
	s_waitcnt vmcnt(8) lgkmcnt(0)
	s_barrier
	v_mfma_f32_16x16x32_bf16 v[60:63], v[144:147], v[170:173], v[60:63]
	v_mfma_f32_16x16x32_bf16 v[56:59], v[160:163], v[170:173], v[56:59]
	v_mfma_f32_16x16x32_bf16 v[44:47], v[144:147], v[190:193], v[44:47]
	v_mfma_f32_16x16x32_bf16 v[40:43], v[160:163], v[190:193], v[40:43]
	v_mfma_f32_16x16x32_bf16 v[28:31], v[144:147], v[198:201], v[28:31]
	v_mfma_f32_16x16x32_bf16 v[24:27], v[160:163], v[198:201], v[24:27]
	v_mfma_f32_16x16x32_bf16 v[12:15], v[144:147], v[206:209], v[12:15]
	v_mfma_f32_16x16x32_bf16 v[8:11], v[160:163], v[206:209], v[8:11]
	v_mfma_f32_16x16x32_bf16 v[60:63], v[156:159], v[182:185], v[60:63]
	v_mfma_f32_16x16x32_bf16 v[56:59], v[166:169], v[182:185], v[56:59]
	v_mfma_f32_16x16x32_bf16 v[44:47], v[156:159], v[194:197], v[44:47]
	v_mfma_f32_16x16x32_bf16 v[40:43], v[166:169], v[194:197], v[40:43]
	v_mfma_f32_16x16x32_bf16 v[28:31], v[156:159], v[202:205], v[28:31]
	v_mfma_f32_16x16x32_bf16 v[24:27], v[166:169], v[202:205], v[24:27]
	v_mfma_f32_16x16x32_bf16 v[12:15], v[156:159], v[210:213], v[12:15]
	v_mfma_f32_16x16x32_bf16 v[8:11], v[166:169], v[210:213], v[8:11]
	v_mfma_f32_16x16x32_bf16 v[52:55], v[214:217], v[170:173], v[52:55]
	v_mfma_f32_16x16x32_bf16 v[48:51], v[222:225], v[170:173], v[48:51]
	v_mfma_f32_16x16x32_bf16 v[36:39], v[214:217], v[190:193], v[36:39]
	v_mfma_f32_16x16x32_bf16 v[32:35], v[222:225], v[190:193], v[32:35]
	v_mfma_f32_16x16x32_bf16 v[20:23], v[214:217], v[198:201], v[20:23]
	v_mfma_f32_16x16x32_bf16 v[16:19], v[222:225], v[198:201], v[16:19]
	v_mfma_f32_16x16x32_bf16 v[4:7], v[214:217], v[206:209], v[4:7]
	v_mfma_f32_16x16x32_bf16 v[0:3], v[222:225], v[206:209], v[0:3]
	v_mfma_f32_16x16x32_bf16 v[52:55], v[218:221], v[182:185], v[52:55]
	v_mfma_f32_16x16x32_bf16 v[48:51], v[226:229], v[182:185], v[48:51]
	v_mfma_f32_16x16x32_bf16 v[36:39], v[218:221], v[194:197], v[36:39]
	v_mfma_f32_16x16x32_bf16 v[32:35], v[226:229], v[194:197], v[32:35]
	v_mfma_f32_16x16x32_bf16 v[20:23], v[218:221], v[202:205], v[20:23]
	v_mfma_f32_16x16x32_bf16 v[16:19], v[226:229], v[202:205], v[16:19]
	v_mfma_f32_16x16x32_bf16 v[4:7], v[218:221], v[210:213], v[4:7]
	v_mfma_f32_16x16x32_bf16 v[0:3], v[226:229], v[210:213], v[0:3]
	s_barrier
	s_add_i32 s58, s58, 2
	s_add_u32 s28, s28, 0x100
	s_addc_u32 s29, s29, 0
	s_add_u32 s56, s56, 0x100
	s_addc_u32 s57, s57, 0
	s_cmp_gt_u32 s58, 13
	s_cbranch_scc0 .LBB0_195
	v_max_f32_e32 v144, v124, v124
	v_max_f32_e32 v144, 0xc1a00000, v144
	v_mul_f32_e32 v144, 0xbfb8aa3b, v144
	v_exp_f32_e32 v157, v144
	v_max_f32_e32 v144, v125, v125
	v_max_f32_e32 v144, 0xc1a00000, v144
	v_mul_f32_e32 v144, 0xbfb8aa3b, v144
	v_exp_f32_e32 v156, v144
	v_max_f32_e32 v144, v126, v126
	v_max_f32_e32 v144, 0xc1a00000, v144
	v_mul_f32_e32 v144, 0xbfb8aa3b, v144
	v_exp_f32_e32 v159, v144
	v_max_f32_e32 v144, v127, v127
	v_max_f32_e32 v144, 0xc1a00000, v144
	v_mul_f32_e32 v144, 0xbfb8aa3b, v144
	v_exp_f32_e32 v158, v144
	v_pk_add_f32 v[156:157], v[156:157], 1.0 op_sel_hi:[1,0]
	v_lshl_or_b32 v146, s53, 7, v150
	v_mov_b32_e32 v160, v157
	v_pk_add_f32 v[158:159], v[158:159], 1.0 op_sel_hi:[1,0]
	v_mov_b32_e32 v162, v156
	v_mov_b32_e32 v161, v159
	v_mov_b32_e32 v163, v158
	v_pk_mul_f32 v[160:161], v[160:161], v[162:163]
	v_lshl_add_u32 v155, s26, 8, v148
	v_mul_f32_e32 v162, v160, v161
	v_rcp_f32_e32 v166, v162
	v_ashrrev_i32_e32 v147, 31, v146
	v_mov_b64_e32 v[144:145], s[4:5]
	v_mad_i64_i32 v[162:163], s[28:29], v155, s52, v[144:145]
	v_mul_f32_e32 v160, v160, v166
	v_mul_f32_e32 v164, v161, v166
	v_pk_mul_f32 v[158:159], v[158:159], v[160:161] op_sel_hi:[1,0]
	v_max_f32_e32 v160, v120, v120
	v_max_f32_e32 v166, v122, v122
	v_max_f32_e32 v160, 0xc1a00000, v160
	v_max_f32_e32 v166, 0xc1a00000, v166
	v_mul_f32_e32 v160, 0xbfb8aa3b, v160
	v_mul_f32_e32 v166, 0xbfb8aa3b, v166
	v_exp_f32_e32 v161, v160
	v_max_f32_e32 v160, v121, v121
	v_exp_f32_e32 v167, v166
	v_max_f32_e32 v166, v123, v123
	v_max_f32_e32 v160, 0xc1a00000, v160
	v_max_f32_e32 v166, 0xc1a00000, v166
	v_mul_f32_e32 v160, 0xbfb8aa3b, v160
	v_mul_f32_e32 v166, 0xbfb8aa3b, v166
	v_exp_f32_e32 v160, v160
	v_exp_f32_e32 v166, v166
	v_pk_mul_f32 v[156:157], v[156:157], v[164:165] op_sel_hi:[1,0]
	v_pk_mul_f32 v[126:127], v[126:127], v[158:159]
	v_pk_mul_f32 v[124:125], v[124:125], v[156:157]
	v_pk_add_f32 v[156:157], v[160:161], 1.0 op_sel_hi:[1,0]
	v_pk_add_f32 v[160:161], v[166:167], 1.0 op_sel_hi:[1,0]
	v_mov_b32_e32 v166, v157
; __device__ __forceinline__ unsigned cvt_pk_bf16(float lo, float hi) { unsigned r; asm volatile("v_cvt_pk_bf16_f32 %0, %1, %2" : "=v"(r) : "v"(lo), "v"(hi)); return r; }
; __device__ __forceinline__ f32x4 sigmoid4(f32x4 x) {
;     f32x4 d;
; #pragma unroll
;     for (int j = 0; j < 4; ++j) d[j] = 1.0f + __expf(-fmaxf(x[j], -20.0f));
;     const float p01 = d[0] * d[1], p23 = d[2] * d[3], r = __builtin_amdgcn_rcpf(p01 * p23), r01 = r * p23, r23 = r * p01;
;     return (f32x4){r01 * d[1], r01 * d[0], r23 * d[3], r23 * d[2]};
; }
;     __device__ __forceinline__ void operator()(const f32x4 (&acc)[2][2][4][2], const Unit& u, int wr, int wc, int fr, int fq) const {
;         const int row0 = u.pm * BM + wr * 64 + fr, col0 = u.pn * HALF + wc * 32 + 8 * fq;
; #pragma unroll
;         for (int ai = 0; ai < 2; ++ai)
; #pragma unroll
;             for (int m = 0; m < 4; ++m) { bf16_t* rowp = O + (size_t)(row0 + ai * HALF + m * 16) * ldc + col0;
;                 f32x4 v0, v1;
; #pragma unroll
;                 for (int j = 0; j < 1; ++j) { v0 = acc[ai][0][m][0] * sigmoid4(acc[ai][0][m][0]) * acc[ai][1][m][0]; v1 = acc[ai][0][m][1] * sigmoid4(acc[ai][0][m][1]) * acc[ai][1][m][1]; }
;                 u32x4 w; w.x = cvt_pk_bf16(v0[0], v0[1]); w.y = cvt_pk_bf16(v0[2], v0[3]); w.z = cvt_pk_bf16(v1[0], v1[1]); w.w = cvt_pk_bf16(v1[2], v1[3]);
;                 *(u32x4*)rowp = w; }
	v_mov_b32_e32 v167, v161
	v_mov_b32_e32 v168, v156
	v_mov_b32_e32 v169, v160
	v_pk_mul_f32 v[166:167], v[166:167], v[168:169]
	v_pk_mul_f32 v[118:119], v[126:127], v[118:119]
	v_mul_f32_e32 v164, v166, v167
	v_rcp_f32_e32 v164, v164
	v_pk_mul_f32 v[116:117], v[124:125], v[116:117]
	v_lshlrev_b64 v[146:147], 1, v[146:147]
	v_lshl_add_u64 v[162:163], v[162:163], 0, v[146:147]
	v_mul_f32_e32 v124, v167, v164
	v_mul_f32_e32 v126, v166, v164
	v_pk_mul_f32 v[126:127], v[160:161], v[126:127] op_sel_hi:[1,0]
	v_pk_mul_f32 v[124:125], v[156:157], v[124:125] op_sel_hi:[1,0]
	v_pk_mul_f32 v[122:123], v[122:123], v[126:127]
	v_pk_mul_f32 v[120:121], v[120:121], v[124:125]
	v_pk_mul_f32 v[122:123], v[122:123], v[114:115]
	v_pk_mul_f32 v[114:115], v[120:121], v[112:113]
	v_cvt_pk_bf16_f32 v112, v116, v117
	v_cvt_pk_bf16_f32 v113, v118, v119
	v_max_f32_e32 v116, v108, v108
	v_max_f32_e32 v118, v110, v110
	v_max_f32_e32 v116, 0xc1a00000, v116
	v_max_f32_e32 v118, 0xc1a00000, v118
	v_mul_f32_e32 v116, 0xbfb8aa3b, v116
	v_mul_f32_e32 v118, 0xbfb8aa3b, v118
	v_exp_f32_e32 v117, v116
	v_max_f32_e32 v116, v109, v109
	v_exp_f32_e32 v119, v118
	v_max_f32_e32 v118, v111, v111
	v_max_f32_e32 v116, 0xc1a00000, v116
	v_max_f32_e32 v118, 0xc1a00000, v118
	v_mul_f32_e32 v116, 0xbfb8aa3b, v116
	v_mul_f32_e32 v118, 0xbfb8aa3b, v118
	v_exp_f32_e32 v116, v116
	v_exp_f32_e32 v118, v118
	v_cvt_pk_bf16_f32 v114, v114, v115
	v_cvt_pk_bf16_f32 v115, v122, v123
	global_store_dwordx4 v[162:163], v[112:115], off
	v_or_b32_e32 v120, 16, v155
	s_and_b64 vcc, exec, s[2:3]
	v_pk_add_f32 v[112:113], v[116:117], 1.0 op_sel_hi:[1,0]
	v_pk_add_f32 v[114:115], v[118:119], 1.0 op_sel_hi:[1,0]
	v_mov_b32_e32 v116, v113
	v_mov_b32_e32 v117, v115
	v_mov_b32_e32 v118, v112
	v_mov_b32_e32 v119, v114
	v_pk_mul_f32 v[116:117], v[116:117], v[118:119]
	s_mov_b32 s53, s14
	v_mul_f32_e32 v118, v116, v117
	v_rcp_f32_e32 v121, v118
	v_mad_i64_i32 v[118:119], s[28:29], v120, s52, v[144:145]
	v_lshl_add_u64 v[118:119], v[118:119], 0, v[146:147]
	v_mul_f32_e32 v116, v116, v121
	v_mul_f32_e32 v120, v117, v121
	v_pk_mul_f32 v[114:115], v[114:115], v[116:117] op_sel_hi:[1,0]
	v_max_f32_e32 v116, v104, v104
	v_max_f32_e32 v121, v106, v106
	v_max_f32_e32 v116, 0xc1a00000, v116
	v_max_f32_e32 v121, 0xc1a00000, v121
	v_mul_f32_e32 v116, 0xbfb8aa3b, v116
	v_mul_f32_e32 v121, 0xbfb8aa3b, v121
	v_exp_f32_e32 v117, v116
	v_max_f32_e32 v116, v105, v105
	v_exp_f32_e32 v123, v121
	v_max_f32_e32 v121, v107, v107
	v_max_f32_e32 v116, 0xc1a00000, v116
	v_max_f32_e32 v121, 0xc1a00000, v121
	v_mul_f32_e32 v116, 0xbfb8aa3b, v116
	v_mul_f32_e32 v121, 0xbfb8aa3b, v121
	v_exp_f32_e32 v116, v116
	v_exp_f32_e32 v122, v121
	v_pk_mul_f32 v[112:113], v[112:113], v[120:121] op_sel_hi:[1,0]
	v_pk_mul_f32 v[110:111], v[110:111], v[114:115]
	v_pk_mul_f32 v[108:109], v[108:109], v[112:113]
	v_pk_add_f32 v[112:113], v[116:117], 1.0 op_sel_hi:[1,0]
	v_pk_add_f32 v[116:117], v[122:123], 1.0 op_sel_hi:[1,0]
	v_mov_b32_e32 v120, v113
	v_mov_b32_e32 v121, v117
	v_mov_b32_e32 v122, v112
	v_mov_b32_e32 v123, v116
	v_pk_mul_f32 v[120:121], v[120:121], v[122:123]
	v_pk_mul_f32 v[102:103], v[110:111], v[102:103]
	v_mul_f32_e32 v122, v120, v121
	v_rcp_f32_e32 v122, v122
	v_pk_mul_f32 v[100:101], v[108:109], v[100:101]
	s_mov_b32 s26, s16
	s_mov_b64 s[30:31], s[24:25]
	v_mul_f32_e32 v108, v121, v122
	v_mul_f32_e32 v110, v120, v122
	v_pk_mul_f32 v[110:111], v[116:117], v[110:111] op_sel_hi:[1,0]
	v_pk_mul_f32 v[108:109], v[112:113], v[108:109] op_sel_hi:[1,0]
	v_pk_mul_f32 v[106:107], v[106:107], v[110:111]
	v_pk_mul_f32 v[104:105], v[104:105], v[108:109]
	v_pk_mul_f32 v[106:107], v[106:107], v[98:99]
	v_pk_mul_f32 v[98:99], v[104:105], v[96:97]
	v_cvt_pk_bf16_f32 v96, v100, v101
	v_cvt_pk_bf16_f32 v97, v102, v103
	v_max_f32_e32 v100, v92, v92
	v_max_f32_e32 v102, v94, v94
	v_max_f32_e32 v100, 0xc1a00000, v100
	v_max_f32_e32 v102, 0xc1a00000, v102
	v_mul_f32_e32 v100, 0xbfb8aa3b, v100
	v_mul_f32_e32 v102, 0xbfb8aa3b, v102
	v_exp_f32_e32 v101, v100
	v_max_f32_e32 v100, v93, v93
	v_exp_f32_e32 v103, v102
	v_max_f32_e32 v102, v95, v95
	v_max_f32_e32 v100, 0xc1a00000, v100
	v_max_f32_e32 v102, 0xc1a00000, v102
	v_mul_f32_e32 v100, 0xbfb8aa3b, v100
	v_mul_f32_e32 v102, 0xbfb8aa3b, v102
	v_exp_f32_e32 v100, v100
	v_exp_f32_e32 v102, v102
	v_cvt_pk_bf16_f32 v98, v98, v99
	v_cvt_pk_bf16_f32 v99, v106, v107
	global_store_dwordx4 v[118:119], v[96:99], off
	v_or_b32_e32 v104, 32, v155
	s_nop 0
	v_pk_add_f32 v[96:97], v[100:101], 1.0 op_sel_hi:[1,0]
	v_pk_add_f32 v[98:99], v[102:103], 1.0 op_sel_hi:[1,0]
	v_mov_b32_e32 v100, v97
	v_mov_b32_e32 v101, v99
	v_mov_b32_e32 v102, v96
	v_mov_b32_e32 v103, v98
	v_pk_mul_f32 v[100:101], v[100:101], v[102:103]
	s_nop 0
	v_mul_f32_e32 v102, v100, v101
	v_rcp_f32_e32 v105, v102
	v_mad_i64_i32 v[102:103], s[28:29], v104, s52, v[144:145]
	v_lshl_add_u64 v[102:103], v[102:103], 0, v[146:147]
	v_mul_f32_e32 v100, v100, v105
	v_mul_f32_e32 v104, v101, v105
	v_pk_mul_f32 v[98:99], v[98:99], v[100:101] op_sel_hi:[1,0]
	v_max_f32_e32 v100, v88, v88
	v_max_f32_e32 v105, v90, v90
	v_max_f32_e32 v100, 0xc1a00000, v100
	v_max_f32_e32 v105, 0xc1a00000, v105
	v_mul_f32_e32 v100, 0xbfb8aa3b, v100
	v_mul_f32_e32 v105, 0xbfb8aa3b, v105
	v_exp_f32_e32 v101, v100
	v_max_f32_e32 v100, v89, v89
	v_exp_f32_e32 v107, v105
	v_max_f32_e32 v105, v91, v91
	v_max_f32_e32 v100, 0xc1a00000, v100
	v_max_f32_e32 v105, 0xc1a00000, v105
	v_mul_f32_e32 v100, 0xbfb8aa3b, v100
	v_mul_f32_e32 v105, 0xbfb8aa3b, v105
	v_exp_f32_e32 v100, v100
	v_exp_f32_e32 v106, v105
	v_pk_mul_f32 v[96:97], v[96:97], v[104:105] op_sel_hi:[1,0]
	v_pk_mul_f32 v[94:95], v[94:95], v[98:99]
; __device__ __forceinline__ unsigned cvt_pk_bf16(float lo, float hi) { unsigned r; asm volatile("v_cvt_pk_bf16_f32 %0, %1, %2" : "=v"(r) : "v"(lo), "v"(hi)); return r; }
; __device__ __forceinline__ f32x4 sigmoid4(f32x4 x) {
;     f32x4 d;
; #pragma unroll
;     for (int j = 0; j < 4; ++j) d[j] = 1.0f + __expf(-fmaxf(x[j], -20.0f));
;     const float p01 = d[0] * d[1], p23 = d[2] * d[3], r = __builtin_amdgcn_rcpf(p01 * p23), r01 = r * p23, r23 = r * p01;
;     return (f32x4){r01 * d[1], r01 * d[0], r23 * d[3], r23 * d[2]};
; }
;     __device__ __forceinline__ void operator()(const f32x4 (&acc)[2][2][4][2], const Unit& u, int wr, int wc, int fr, int fq) const {
;         const int row0 = u.pm * BM + wr * 64 + fr, col0 = u.pn * HALF + wc * 32 + 8 * fq;
; #pragma unroll
;         for (int ai = 0; ai < 2; ++ai)
; #pragma unroll
;             for (int m = 0; m < 4; ++m) { bf16_t* rowp = O + (size_t)(row0 + ai * HALF + m * 16) * ldc + col0;
;                 f32x4 v0, v1;
; #pragma unroll
;                 for (int j = 0; j < 1; ++j) { v0 = acc[ai][0][m][0] * sigmoid4(acc[ai][0][m][0]) * acc[ai][1][m][0]; v1 = acc[ai][0][m][1] * sigmoid4(acc[ai][0][m][1]) * acc[ai][1][m][1]; }
;                 u32x4 w; w.x = cvt_pk_bf16(v0[0], v0[1]); w.y = cvt_pk_bf16(v0[2], v0[3]); w.z = cvt_pk_bf16(v1[0], v1[1]); w.w = cvt_pk_bf16(v1[2], v1[3]);
;                 *(u32x4*)rowp = w; }
	v_pk_mul_f32 v[92:93], v[92:93], v[96:97]
	v_pk_add_f32 v[96:97], v[100:101], 1.0 op_sel_hi:[1,0]
	v_pk_add_f32 v[100:101], v[106:107], 1.0 op_sel_hi:[1,0]
	v_mov_b32_e32 v104, v97
	v_mov_b32_e32 v105, v101
	v_mov_b32_e32 v106, v96
	v_mov_b32_e32 v107, v100
	v_pk_mul_f32 v[104:105], v[104:105], v[106:107]
	v_pk_mul_f32 v[86:87], v[94:95], v[86:87]
	v_mul_f32_e32 v106, v104, v105
	v_rcp_f32_e32 v106, v106
	v_pk_mul_f32 v[84:85], v[92:93], v[84:85]
	v_mul_f32_e32 v92, v105, v106
	v_mul_f32_e32 v94, v104, v106
	v_pk_mul_f32 v[94:95], v[100:101], v[94:95] op_sel_hi:[1,0]
	v_pk_mul_f32 v[92:93], v[96:97], v[92:93] op_sel_hi:[1,0]
	v_pk_mul_f32 v[90:91], v[90:91], v[94:95]
	v_pk_mul_f32 v[88:89], v[88:89], v[92:93]
	v_pk_mul_f32 v[90:91], v[90:91], v[82:83]
	v_pk_mul_f32 v[82:83], v[88:89], v[80:81]
	v_cvt_pk_bf16_f32 v80, v84, v85
	v_cvt_pk_bf16_f32 v81, v86, v87
	v_max_f32_e32 v84, v76, v76
	v_max_f32_e32 v86, v78, v78
	v_max_f32_e32 v84, 0xc1a00000, v84
	v_max_f32_e32 v86, 0xc1a00000, v86
	v_mul_f32_e32 v84, 0xbfb8aa3b, v84
	v_mul_f32_e32 v86, 0xbfb8aa3b, v86
	v_exp_f32_e32 v85, v84
	v_max_f32_e32 v84, v77, v77
	v_exp_f32_e32 v87, v86
	v_max_f32_e32 v86, v79, v79
	v_max_f32_e32 v84, 0xc1a00000, v84
	v_max_f32_e32 v86, 0xc1a00000, v86
	v_mul_f32_e32 v84, 0xbfb8aa3b, v84
	v_mul_f32_e32 v86, 0xbfb8aa3b, v86
	v_exp_f32_e32 v84, v84
	v_exp_f32_e32 v86, v86
	v_cvt_pk_bf16_f32 v82, v82, v83
	v_cvt_pk_bf16_f32 v83, v90, v91
	global_store_dwordx4 v[102:103], v[80:83], off
	v_or_b32_e32 v88, 48, v155
	s_nop 0
	v_pk_add_f32 v[80:81], v[84:85], 1.0 op_sel_hi:[1,0]
	v_pk_add_f32 v[82:83], v[86:87], 1.0 op_sel_hi:[1,0]
	v_mov_b32_e32 v84, v81
	v_mov_b32_e32 v85, v83
	v_mov_b32_e32 v86, v80
	v_mov_b32_e32 v87, v82
	v_pk_mul_f32 v[84:85], v[84:85], v[86:87]
	s_nop 0
	v_mul_f32_e32 v86, v84, v85
	v_rcp_f32_e32 v89, v86
	v_mad_i64_i32 v[86:87], s[28:29], v88, s52, v[144:145]
	v_lshl_add_u64 v[86:87], v[86:87], 0, v[146:147]
	v_mul_f32_e32 v84, v84, v89
	v_mul_f32_e32 v88, v85, v89
	v_pk_mul_f32 v[82:83], v[82:83], v[84:85] op_sel_hi:[1,0]
	v_max_f32_e32 v84, v72, v72
	v_max_f32_e32 v89, v74, v74
	v_max_f32_e32 v84, 0xc1a00000, v84
	v_max_f32_e32 v89, 0xc1a00000, v89
	v_mul_f32_e32 v84, 0xbfb8aa3b, v84
	v_mul_f32_e32 v89, 0xbfb8aa3b, v89
	v_exp_f32_e32 v85, v84
	v_max_f32_e32 v84, v73, v73
	v_exp_f32_e32 v91, v89
	v_max_f32_e32 v89, v75, v75
	v_max_f32_e32 v84, 0xc1a00000, v84
	v_max_f32_e32 v89, 0xc1a00000, v89
	v_mul_f32_e32 v84, 0xbfb8aa3b, v84
	v_mul_f32_e32 v89, 0xbfb8aa3b, v89
	v_exp_f32_e32 v84, v84
	v_exp_f32_e32 v90, v89
	v_pk_mul_f32 v[80:81], v[80:81], v[88:89] op_sel_hi:[1,0]
	v_pk_mul_f32 v[78:79], v[78:79], v[82:83]
	v_pk_mul_f32 v[76:77], v[76:77], v[80:81]
	v_pk_add_f32 v[80:81], v[84:85], 1.0 op_sel_hi:[1,0]
	v_pk_add_f32 v[84:85], v[90:91], 1.0 op_sel_hi:[1,0]
	v_mov_b32_e32 v88, v81
	v_mov_b32_e32 v89, v85
	v_mov_b32_e32 v90, v80
	v_mov_b32_e32 v91, v84
	v_pk_mul_f32 v[88:89], v[88:89], v[90:91]
	v_pk_mul_f32 v[70:71], v[78:79], v[70:71]
	v_mul_f32_e32 v90, v88, v89
	v_rcp_f32_e32 v90, v90
	v_pk_mul_f32 v[68:69], v[76:77], v[68:69]
	v_mul_f32_e32 v76, v89, v90
	v_mul_f32_e32 v78, v88, v90
	v_pk_mul_f32 v[78:79], v[84:85], v[78:79] op_sel_hi:[1,0]
	v_pk_mul_f32 v[76:77], v[80:81], v[76:77] op_sel_hi:[1,0]
	v_pk_mul_f32 v[74:75], v[74:75], v[78:79]
	v_pk_mul_f32 v[72:73], v[72:73], v[76:77]
	v_pk_mul_f32 v[74:75], v[74:75], v[66:67]
	v_pk_mul_f32 v[66:67], v[72:73], v[64:65]
	v_cvt_pk_bf16_f32 v64, v68, v69
	v_cvt_pk_bf16_f32 v65, v70, v71
	v_max_f32_e32 v68, v60, v60
	v_max_f32_e32 v70, v62, v62
	v_max_f32_e32 v68, 0xc1a00000, v68
	v_max_f32_e32 v70, 0xc1a00000, v70
	v_mul_f32_e32 v68, 0xbfb8aa3b, v68
	v_mul_f32_e32 v70, 0xbfb8aa3b, v70
	v_exp_f32_e32 v69, v68
	v_max_f32_e32 v68, v61, v61
	v_exp_f32_e32 v71, v70
	v_max_f32_e32 v70, v63, v63
	v_max_f32_e32 v68, 0xc1a00000, v68
	v_max_f32_e32 v70, 0xc1a00000, v70
	v_mul_f32_e32 v68, 0xbfb8aa3b, v68
	v_mul_f32_e32 v70, 0xbfb8aa3b, v70
	v_exp_f32_e32 v68, v68
	v_exp_f32_e32 v70, v70
	v_cvt_pk_bf16_f32 v66, v66, v67
	v_cvt_pk_bf16_f32 v67, v74, v75
	global_store_dwordx4 v[86:87], v[64:67], off
	v_add_u32_e32 v72, 0x80, v155
	s_nop 0
	v_pk_add_f32 v[64:65], v[68:69], 1.0 op_sel_hi:[1,0]
	v_pk_add_f32 v[66:67], v[70:71], 1.0 op_sel_hi:[1,0]
	v_mov_b32_e32 v68, v65
	v_mov_b32_e32 v69, v67
	v_mov_b32_e32 v70, v64
	v_mov_b32_e32 v71, v66
	v_pk_mul_f32 v[68:69], v[68:69], v[70:71]
	s_nop 0
	v_mul_f32_e32 v70, v68, v69
	v_rcp_f32_e32 v73, v70
	v_mad_i64_i32 v[70:71], s[28:29], v72, s52, v[144:145]
	v_lshl_add_u64 v[70:71], v[70:71], 0, v[146:147]
	v_mul_f32_e32 v68, v68, v73
	v_mul_f32_e32 v72, v69, v73
	v_pk_mul_f32 v[66:67], v[66:67], v[68:69] op_sel_hi:[1,0]
	v_max_f32_e32 v68, v56, v56
	v_max_f32_e32 v73, v58, v58
	v_max_f32_e32 v68, 0xc1a00000, v68
	v_max_f32_e32 v73, 0xc1a00000, v73
	v_mul_f32_e32 v68, 0xbfb8aa3b, v68
	v_mul_f32_e32 v73, 0xbfb8aa3b, v73
	v_exp_f32_e32 v69, v68
	v_max_f32_e32 v68, v57, v57
	v_exp_f32_e32 v75, v73
	v_max_f32_e32 v73, v59, v59
	v_max_f32_e32 v68, 0xc1a00000, v68
	v_max_f32_e32 v73, 0xc1a00000, v73
	v_mul_f32_e32 v68, 0xbfb8aa3b, v68
	v_mul_f32_e32 v73, 0xbfb8aa3b, v73
	v_exp_f32_e32 v68, v68
	v_exp_f32_e32 v74, v73
	v_pk_mul_f32 v[64:65], v[64:65], v[72:73] op_sel_hi:[1,0]
	v_pk_mul_f32 v[62:63], v[62:63], v[66:67]
	v_pk_mul_f32 v[60:61], v[60:61], v[64:65]
	v_pk_add_f32 v[64:65], v[68:69], 1.0 op_sel_hi:[1,0]
	v_pk_add_f32 v[68:69], v[74:75], 1.0 op_sel_hi:[1,0]
	v_mov_b32_e32 v72, v65
	v_mov_b32_e32 v73, v69
	v_mov_b32_e32 v74, v64
	v_mov_b32_e32 v75, v68
	v_pk_mul_f32 v[72:73], v[72:73], v[74:75]
	v_pk_mul_f32 v[54:55], v[62:63], v[54:55]
	v_mul_f32_e32 v74, v72, v73
; __device__ __forceinline__ unsigned cvt_pk_bf16(float lo, float hi) { unsigned r; asm volatile("v_cvt_pk_bf16_f32 %0, %1, %2" : "=v"(r) : "v"(lo), "v"(hi)); return r; }
; __device__ __forceinline__ f32x4 sigmoid4(f32x4 x) {
;     f32x4 d;
; #pragma unroll
;     for (int j = 0; j < 4; ++j) d[j] = 1.0f + __expf(-fmaxf(x[j], -20.0f));
;     const float p01 = d[0] * d[1], p23 = d[2] * d[3], r = __builtin_amdgcn_rcpf(p01 * p23), r01 = r * p23, r23 = r * p01;
;     return (f32x4){r01 * d[1], r01 * d[0], r23 * d[3], r23 * d[2]};
; }
;     __device__ __forceinline__ void operator()(const f32x4 (&acc)[2][2][4][2], const Unit& u, int wr, int wc, int fr, int fq) const {
;         const int row0 = u.pm * BM + wr * 64 + fr, col0 = u.pn * HALF + wc * 32 + 8 * fq;
; #pragma unroll
;         for (int ai = 0; ai < 2; ++ai)
; #pragma unroll
;             for (int m = 0; m < 4; ++m) { bf16_t* rowp = O + (size_t)(row0 + ai * HALF + m * 16) * ldc + col0;
;                 f32x4 v0, v1;
; #pragma unroll
;                 for (int j = 0; j < 1; ++j) { v0 = acc[ai][0][m][0] * sigmoid4(acc[ai][0][m][0]) * acc[ai][1][m][0]; v1 = acc[ai][0][m][1] * sigmoid4(acc[ai][0][m][1]) * acc[ai][1][m][1]; }
;                 u32x4 w; w.x = cvt_pk_bf16(v0[0], v0[1]); w.y = cvt_pk_bf16(v0[2], v0[3]); w.z = cvt_pk_bf16(v1[0], v1[1]); w.w = cvt_pk_bf16(v1[2], v1[3]);
;                 *(u32x4*)rowp = w; }
	v_rcp_f32_e32 v74, v74
	v_pk_mul_f32 v[52:53], v[60:61], v[52:53]
	v_mul_f32_e32 v60, v73, v74
	v_mul_f32_e32 v62, v72, v74
	v_pk_mul_f32 v[62:63], v[68:69], v[62:63] op_sel_hi:[1,0]
	v_pk_mul_f32 v[60:61], v[64:65], v[60:61] op_sel_hi:[1,0]
	v_pk_mul_f32 v[58:59], v[58:59], v[62:63]
	v_pk_mul_f32 v[56:57], v[56:57], v[60:61]
	v_pk_mul_f32 v[58:59], v[58:59], v[50:51]
	v_pk_mul_f32 v[50:51], v[56:57], v[48:49]
	v_cvt_pk_bf16_f32 v48, v52, v53
	v_cvt_pk_bf16_f32 v49, v54, v55
	v_max_f32_e32 v52, v44, v44
	v_max_f32_e32 v54, v46, v46
	v_max_f32_e32 v52, 0xc1a00000, v52
	v_max_f32_e32 v54, 0xc1a00000, v54
	v_mul_f32_e32 v52, 0xbfb8aa3b, v52
	v_mul_f32_e32 v54, 0xbfb8aa3b, v54
	v_exp_f32_e32 v53, v52
	v_max_f32_e32 v52, v45, v45
	v_exp_f32_e32 v55, v54
	v_max_f32_e32 v54, v47, v47
	v_max_f32_e32 v52, 0xc1a00000, v52
	v_max_f32_e32 v54, 0xc1a00000, v54
	v_mul_f32_e32 v52, 0xbfb8aa3b, v52
	v_mul_f32_e32 v54, 0xbfb8aa3b, v54
	v_exp_f32_e32 v52, v52
	v_exp_f32_e32 v54, v54
	v_cvt_pk_bf16_f32 v50, v50, v51
	v_cvt_pk_bf16_f32 v51, v58, v59
	global_store_dwordx4 v[70:71], v[48:51], off
	v_add_u32_e32 v56, 0x90, v155
	s_nop 0
	v_pk_add_f32 v[48:49], v[52:53], 1.0 op_sel_hi:[1,0]
	v_pk_add_f32 v[50:51], v[54:55], 1.0 op_sel_hi:[1,0]
	v_mov_b32_e32 v52, v49
	v_mov_b32_e32 v53, v51
	v_mov_b32_e32 v54, v48
	v_mov_b32_e32 v55, v50
	v_pk_mul_f32 v[52:53], v[52:53], v[54:55]
	s_nop 0
	v_mul_f32_e32 v54, v52, v53
	v_rcp_f32_e32 v57, v54
	v_mad_i64_i32 v[54:55], s[28:29], v56, s52, v[144:145]
	v_lshl_add_u64 v[54:55], v[54:55], 0, v[146:147]
	v_mul_f32_e32 v52, v52, v57
	v_mul_f32_e32 v56, v53, v57
	v_pk_mul_f32 v[50:51], v[50:51], v[52:53] op_sel_hi:[1,0]
	v_max_f32_e32 v52, v40, v40
	v_max_f32_e32 v57, v42, v42
	v_max_f32_e32 v52, 0xc1a00000, v52
	v_max_f32_e32 v57, 0xc1a00000, v57
	v_mul_f32_e32 v52, 0xbfb8aa3b, v52
	v_mul_f32_e32 v57, 0xbfb8aa3b, v57
	v_exp_f32_e32 v53, v52
	v_max_f32_e32 v52, v41, v41
	v_exp_f32_e32 v59, v57
	v_max_f32_e32 v57, v43, v43
	v_max_f32_e32 v52, 0xc1a00000, v52
	v_max_f32_e32 v57, 0xc1a00000, v57
	v_mul_f32_e32 v52, 0xbfb8aa3b, v52
	v_mul_f32_e32 v57, 0xbfb8aa3b, v57
	v_exp_f32_e32 v52, v52
	v_exp_f32_e32 v58, v57
	v_pk_mul_f32 v[48:49], v[48:49], v[56:57] op_sel_hi:[1,0]
	v_pk_mul_f32 v[46:47], v[46:47], v[50:51]
	v_pk_mul_f32 v[44:45], v[44:45], v[48:49]
	v_pk_add_f32 v[48:49], v[52:53], 1.0 op_sel_hi:[1,0]
	v_pk_add_f32 v[52:53], v[58:59], 1.0 op_sel_hi:[1,0]
	v_mov_b32_e32 v56, v49
	v_mov_b32_e32 v57, v53
	v_mov_b32_e32 v58, v48
	v_mov_b32_e32 v59, v52
	v_pk_mul_f32 v[56:57], v[56:57], v[58:59]
	v_pk_mul_f32 v[38:39], v[46:47], v[38:39]
	v_mul_f32_e32 v58, v56, v57
	v_rcp_f32_e32 v58, v58
	v_pk_mul_f32 v[36:37], v[44:45], v[36:37]
	v_mul_f32_e32 v44, v57, v58
	v_mul_f32_e32 v46, v56, v58
	v_pk_mul_f32 v[46:47], v[52:53], v[46:47] op_sel_hi:[1,0]
	v_pk_mul_f32 v[44:45], v[48:49], v[44:45] op_sel_hi:[1,0]
	v_pk_mul_f32 v[42:43], v[42:43], v[46:47]
	v_pk_mul_f32 v[40:41], v[40:41], v[44:45]
	v_pk_mul_f32 v[42:43], v[42:43], v[34:35]
	v_pk_mul_f32 v[34:35], v[40:41], v[32:33]
	v_cvt_pk_bf16_f32 v32, v36, v37
	v_cvt_pk_bf16_f32 v33, v38, v39
	v_max_f32_e32 v36, v28, v28
	v_max_f32_e32 v38, v30, v30
	v_max_f32_e32 v36, 0xc1a00000, v36
	v_max_f32_e32 v38, 0xc1a00000, v38
	v_mul_f32_e32 v36, 0xbfb8aa3b, v36
	v_mul_f32_e32 v38, 0xbfb8aa3b, v38
	v_exp_f32_e32 v37, v36
	v_max_f32_e32 v36, v29, v29
	v_exp_f32_e32 v39, v38
	v_max_f32_e32 v38, v31, v31
	v_max_f32_e32 v36, 0xc1a00000, v36
	v_max_f32_e32 v38, 0xc1a00000, v38
	v_mul_f32_e32 v36, 0xbfb8aa3b, v36
	v_mul_f32_e32 v38, 0xbfb8aa3b, v38
	v_exp_f32_e32 v36, v36
	v_exp_f32_e32 v38, v38
	v_cvt_pk_bf16_f32 v34, v34, v35
	v_cvt_pk_bf16_f32 v35, v42, v43
	global_store_dwordx4 v[54:55], v[32:35], off
	v_add_u32_e32 v40, 0xa0, v155
	s_nop 0
	v_pk_add_f32 v[32:33], v[36:37], 1.0 op_sel_hi:[1,0]
	v_pk_add_f32 v[34:35], v[38:39], 1.0 op_sel_hi:[1,0]
	v_mov_b32_e32 v36, v33
	v_mov_b32_e32 v37, v35
	v_mov_b32_e32 v38, v32
	v_mov_b32_e32 v39, v34
	v_pk_mul_f32 v[36:37], v[36:37], v[38:39]
	s_nop 0
	v_mul_f32_e32 v38, v36, v37
	v_rcp_f32_e32 v41, v38
	v_mad_i64_i32 v[38:39], s[28:29], v40, s52, v[144:145]
	v_lshl_add_u64 v[38:39], v[38:39], 0, v[146:147]
	v_mul_f32_e32 v36, v36, v41
	v_mul_f32_e32 v40, v37, v41
	v_pk_mul_f32 v[34:35], v[34:35], v[36:37] op_sel_hi:[1,0]
; __device__ __forceinline__ unsigned cvt_pk_bf16(float lo, float hi) { unsigned r; asm volatile("v_cvt_pk_bf16_f32 %0, %1, %2" : "=v"(r) : "v"(lo), "v"(hi)); return r; }
; __device__ __forceinline__ f32x4 sigmoid4(f32x4 x) {
;     f32x4 d;
; #pragma unroll
;     for (int j = 0; j < 4; ++j) d[j] = 1.0f + __expf(-fmaxf(x[j], -20.0f));
;     const float p01 = d[0] * d[1], p23 = d[2] * d[3], r = __builtin_amdgcn_rcpf(p01 * p23), r01 = r * p23, r23 = r * p01;
;     return (f32x4){r01 * d[1], r01 * d[0], r23 * d[3], r23 * d[2]};
; }
;     __device__ __forceinline__ void operator()(const f32x4 (&acc)[2][2][4][2], const Unit& u, int wr, int wc, int fr, int fq) const {
;         const int row0 = u.pm * BM + wr * 64 + fr, col0 = u.pn * HALF + wc * 32 + 8 * fq;
; #pragma unroll
;         for (int ai = 0; ai < 2; ++ai)
; #pragma unroll
;             for (int m = 0; m < 4; ++m) { bf16_t* rowp = O + (size_t)(row0 + ai * HALF + m * 16) * ldc + col0;
;                 f32x4 v0, v1;
; #pragma unroll
;                 for (int j = 0; j < 1; ++j) { v0 = acc[ai][0][m][0] * sigmoid4(acc[ai][0][m][0]) * acc[ai][1][m][0]; v1 = acc[ai][0][m][1] * sigmoid4(acc[ai][0][m][1]) * acc[ai][1][m][1]; }
;                 u32x4 w; w.x = cvt_pk_bf16(v0[0], v0[1]); w.y = cvt_pk_bf16(v0[2], v0[3]); w.z = cvt_pk_bf16(v1[0], v1[1]); w.w = cvt_pk_bf16(v1[2], v1[3]);
;                 *(u32x4*)rowp = w; }
	v_max_f32_e32 v36, v24, v24
	v_max_f32_e32 v41, v26, v26
	v_max_f32_e32 v36, 0xc1a00000, v36
	v_max_f32_e32 v41, 0xc1a00000, v41
	v_mul_f32_e32 v36, 0xbfb8aa3b, v36
	v_mul_f32_e32 v41, 0xbfb8aa3b, v41
	v_exp_f32_e32 v37, v36
	v_max_f32_e32 v36, v25, v25
	v_exp_f32_e32 v43, v41
	v_max_f32_e32 v41, v27, v27
	v_max_f32_e32 v36, 0xc1a00000, v36
	v_max_f32_e32 v41, 0xc1a00000, v41
	v_mul_f32_e32 v36, 0xbfb8aa3b, v36
	v_mul_f32_e32 v41, 0xbfb8aa3b, v41
	v_exp_f32_e32 v36, v36
	v_exp_f32_e32 v42, v41
	v_pk_mul_f32 v[32:33], v[32:33], v[40:41] op_sel_hi:[1,0]
	v_pk_mul_f32 v[30:31], v[30:31], v[34:35]
	v_pk_mul_f32 v[28:29], v[28:29], v[32:33]
	v_pk_add_f32 v[32:33], v[36:37], 1.0 op_sel_hi:[1,0]
	v_pk_add_f32 v[36:37], v[42:43], 1.0 op_sel_hi:[1,0]
	v_mov_b32_e32 v40, v33
	v_mov_b32_e32 v41, v37
	v_mov_b32_e32 v42, v32
	v_mov_b32_e32 v43, v36
	v_pk_mul_f32 v[40:41], v[40:41], v[42:43]
	v_pk_mul_f32 v[22:23], v[30:31], v[22:23]
	v_mul_f32_e32 v42, v40, v41
	v_rcp_f32_e32 v42, v42
	v_pk_mul_f32 v[20:21], v[28:29], v[20:21]
	v_mul_f32_e32 v28, v41, v42
	v_mul_f32_e32 v30, v40, v42
	v_pk_mul_f32 v[30:31], v[36:37], v[30:31] op_sel_hi:[1,0]
	v_pk_mul_f32 v[28:29], v[32:33], v[28:29] op_sel_hi:[1,0]
	v_pk_mul_f32 v[26:27], v[26:27], v[30:31]
	v_pk_mul_f32 v[24:25], v[24:25], v[28:29]
	v_pk_mul_f32 v[26:27], v[26:27], v[18:19]
	v_pk_mul_f32 v[18:19], v[24:25], v[16:17]
	v_cvt_pk_bf16_f32 v16, v20, v21
	v_cvt_pk_bf16_f32 v17, v22, v23
	v_max_f32_e32 v20, v12, v12
	v_max_f32_e32 v22, v14, v14
	v_max_f32_e32 v20, 0xc1a00000, v20
	v_max_f32_e32 v22, 0xc1a00000, v22
	v_mul_f32_e32 v20, 0xbfb8aa3b, v20
	v_mul_f32_e32 v22, 0xbfb8aa3b, v22
	v_exp_f32_e32 v21, v20
	v_max_f32_e32 v20, v13, v13
	v_exp_f32_e32 v23, v22
	v_max_f32_e32 v22, v15, v15
	v_max_f32_e32 v20, 0xc1a00000, v20
	v_max_f32_e32 v22, 0xc1a00000, v22
	v_mul_f32_e32 v20, 0xbfb8aa3b, v20
	v_mul_f32_e32 v22, 0xbfb8aa3b, v22
	v_exp_f32_e32 v20, v20
	v_exp_f32_e32 v22, v22
	v_cvt_pk_bf16_f32 v18, v18, v19
	v_cvt_pk_bf16_f32 v19, v26, v27
	global_store_dwordx4 v[38:39], v[16:19], off
	v_add_u32_e32 v24, 0xb0, v155
	s_nop 0
	v_pk_add_f32 v[16:17], v[20:21], 1.0 op_sel_hi:[1,0]
	v_pk_add_f32 v[18:19], v[22:23], 1.0 op_sel_hi:[1,0]
	v_mov_b32_e32 v20, v17
	v_mov_b32_e32 v21, v19
	v_mov_b32_e32 v22, v16
	v_mov_b32_e32 v23, v18
	v_pk_mul_f32 v[20:21], v[20:21], v[22:23]
	s_nop 0
	v_mul_f32_e32 v22, v20, v21
	v_rcp_f32_e32 v25, v22
	v_mad_i64_i32 v[22:23], s[28:29], v24, s52, v[144:145]
	v_lshl_add_u64 v[22:23], v[22:23], 0, v[146:147]
	v_mul_f32_e32 v20, v20, v25
	v_mul_f32_e32 v24, v21, v25
	v_pk_mul_f32 v[18:19], v[18:19], v[20:21] op_sel_hi:[1,0]
	v_max_f32_e32 v20, v8, v8
	v_max_f32_e32 v25, v10, v10
	v_max_f32_e32 v20, 0xc1a00000, v20
	v_max_f32_e32 v25, 0xc1a00000, v25
	v_mul_f32_e32 v20, 0xbfb8aa3b, v20
	v_mul_f32_e32 v25, 0xbfb8aa3b, v25
	v_exp_f32_e32 v21, v20
	v_max_f32_e32 v20, v9, v9
	v_exp_f32_e32 v27, v25
	v_max_f32_e32 v25, v11, v11
	v_max_f32_e32 v20, 0xc1a00000, v20
	v_max_f32_e32 v25, 0xc1a00000, v25
	v_mul_f32_e32 v20, 0xbfb8aa3b, v20
	v_mul_f32_e32 v25, 0xbfb8aa3b, v25
	v_exp_f32_e32 v20, v20
	v_exp_f32_e32 v26, v25
	v_pk_mul_f32 v[16:17], v[16:17], v[24:25] op_sel_hi:[1,0]
	v_pk_mul_f32 v[14:15], v[14:15], v[18:19]
	v_pk_mul_f32 v[12:13], v[12:13], v[16:17]
	v_pk_add_f32 v[16:17], v[20:21], 1.0 op_sel_hi:[1,0]
	v_pk_add_f32 v[20:21], v[26:27], 1.0 op_sel_hi:[1,0]
	v_mov_b32_e32 v24, v17
	v_mov_b32_e32 v25, v21
	v_mov_b32_e32 v26, v16
	v_mov_b32_e32 v27, v20
	v_pk_mul_f32 v[24:25], v[24:25], v[26:27]
	v_pk_mul_f32 v[6:7], v[14:15], v[6:7]
	v_mul_f32_e32 v26, v24, v25
	v_rcp_f32_e32 v26, v26
	v_pk_mul_f32 v[4:5], v[12:13], v[4:5]
	s_mov_b64 s[28:29], s[18:19]
	v_mul_f32_e32 v12, v25, v26
	v_mul_f32_e32 v14, v24, v26
	v_pk_mul_f32 v[14:15], v[20:21], v[14:15] op_sel_hi:[1,0]
	v_pk_mul_f32 v[12:13], v[16:17], v[12:13] op_sel_hi:[1,0]
	v_pk_mul_f32 v[10:11], v[10:11], v[14:15]
	v_pk_mul_f32 v[8:9], v[8:9], v[12:13]
	v_pk_mul_f32 v[10:11], v[10:11], v[2:3]
	v_pk_mul_f32 v[2:3], v[8:9], v[0:1]
	v_cvt_pk_bf16_f32 v0, v4, v5
	v_cvt_pk_bf16_f32 v1, v6, v7
	s_nop 0
	v_cvt_pk_bf16_f32 v2, v2, v3
	v_cvt_pk_bf16_f32 v3, v10, v11
	global_store_dwordx4 v[22:23], v[0:3], off
	s_cbranch_vccz .LBB0_192
	s_waitcnt vmcnt(0)
	s_cmpk_gt_u32 s37, 0xff
	s_cbranch_scc1 .LBB0_199
	s_barrier

; #define PG8_STAGE(bufoff, gbase, voff) do { _Pragma("unroll") for (int _i = 0; _i < 2; ++_i) \
;         __builtin_amdgcn_global_load_lds((const unsigned*)((const char*)(gbase) + (voff)[_i]), (PG8_LAS unsigned*)(lds + (bufoff) + ldsw + _i * 8192), 16, 0, 0); } while (0)
; #define PG8_WAIT_V(n) asm volatile("s_waitcnt vmcnt(" #n ")" ::: "memory")
; #define PG8_BAR __builtin_amdgcn_s_barrier()
; template <class Epi, class Sched>
; __device__ __forceinline__ void gemm_phase(PG8_LAS unsigned char* lds, const Gemm g, const Sched& S, const Epi& E) {
;     ...
;     for (int i = 0; i < 2; ++i) { int R, C; stage_rc(tid * 16 + i * 8192, R, C); const int Rb = Epi::PERM ? ((R & ~31) + perm32(R & 31)) : R;
;         voffA[i] = (unsigned)(R * K + C) * 2u; voffB[i] = (unsigned)(Rb * K + C) * 2u; }
;     const size_t kstep = (size_t)(BK * 2);
;     const size_t hstep = (size_t)HALF * K * 2;
;     const size_t tstep = 2 * hstep;
;     const unsigned ldsw = (unsigned)wid * 1024u;
;     const int aoff = lds_byte(wr * 64 + fr, fq * 8), boff = lds_byte(wc * 32 + fr, fq * 8);
;     ...
;     PG8_STAGE(PG8_SB(0, 0), cB, voffB); PG8_STAGE(PG8_SA(0, 0), cA, voffA); PG8_STAGE(PG8_SB(0, 1), cB + hstep, voffB); PG8_STAGE(PG8_SA(0, 1), cA + hstep, voffA);
;     if (wr == 1) PG8_BAR;
;     PG8_WAIT_V(4); PG8_BAR;
;     PG8_STAGE(PG8_SB(1, 0), cB + kstep, voffB); PG8_STAGE(PG8_SA(1, 0), cA + kstep, voffA); PG8_STAGE(PG8_SB(1, 1), cB + hstep + kstep, voffB);
;     PG8_WAIT_V(6); PG8_BAR;
.LBB0_274:
	s_lshl_b32 s2, s2, 25
	v_readlane_b32 s5, v245, 24
	s_add_u32 s10, s5, s2
	v_readlane_b32 s2, v245, 25
	s_addc_u32 s11, s2, 0
	s_lshl_b32 s1, s1, 5
	s_mov_b64 s[14:15], 0x80
	s_and_b32 s1, s1, 0x60
	s_add_i32 m0, s38, 0x18000
	v_lshl_add_u64 v[6:7], v[6:7], 0, s[14:15]
	s_lshl_b32 s2, s3, 13
	s_lshl_b32 s5, s1, 7
	s_waitcnt vmcnt(0)
	s_barrier
	global_load_lds_dwordx4 v[6:7], off
	v_lshl_add_u64 v[4:5], v[4:5], 0, s[14:15]
	s_add_i32 m0, s38, 0x1a000
	s_add_i32 s43, s38, 0x8000
	s_add_i32 s44, s38, 0xa000
	global_load_lds_dwordx4 v[4:5], off
	v_lshl_add_u64 v[2:3], v[2:3], 0, s[14:15]
	s_mov_b32 m0, s43
	s_add_u32 s16, s24, 0xb0080
	global_load_lds_dwordx4 v[2:3], off
	v_lshl_add_u64 v[0:1], v[0:1], 0, s[14:15]
	s_mov_b32 m0, s44
	s_addc_u32 s17, s25, 0
	global_load_lds_dwordx4 v[0:1], off
	s_add_i32 m0, s38, 0x1c000
	v_lshl_add_u64 v[0:1], s[16:17], 0, v[130:131]
	global_load_lds_dwordx4 v[0:1], off
	v_lshl_add_u64 v[0:1], s[16:17], 0, v[134:135]
	s_add_i32 m0, s38, 0x1e000
	s_sext_i32_i8 s54, s4
	global_load_lds_dwordx4 v[0:1], off
	v_lshrrev_b32_e32 v1, 1, v8
	v_and_b32_e32 v1, 24, v1
	v_and_b32_e32 v0, 15, v8
	v_lshlrev_b32_e32 v2, 1, v1
	v_lshl_or_b32 v146, s3, 6, v0
	v_lshl_or_b32 v0, v0, 6, v2
	v_lshlrev_b32_e32 v2, 2, v8
	v_and_b32_e32 v2, 32, v2
	v_bitop3_b32 v3, v0, s2, v2 bitop3:0xde
	v_bitop3_b32 v147, v0, s5, v2 bitop3:0xde
	v_or_b32_e32 v148, s1, v1
	v_lshrrev_b32_e32 v1, 1, v9
	v_mul_lo_u32 v0, v11, s0
	s_mov_b32 s1, 0xb000
	v_mad_u64_u32 v[0:1], s[4:5], v1, s1, v[0:1]
	v_or_b32_e32 v0, v0, v10
	s_mov_b64 s[2:3], 0xb0080
	v_add_lshl_u32 v0, v0, v12, 1
	v_mov_b32_e32 v1, v131
	v_lshl_add_u64 v[136:137], v[0:1], 0, s[2:3]
	v_lshrrev_b32_e32 v1, 1, v13
	v_mul_lo_u32 v0, v14, s0
	v_mad_u64_u32 v[0:1], s[0:1], v1, s1, v[0:1]
	s_waitcnt vmcnt(6)
	v_or_b32_e32 v0, v0, v15
	v_add_lshl_u32 v0, v0, v16, 1
	v_mov_b32_e32 v1, v131
	s_add_i32 s46, 0, 0x10000
	s_add_i32 s47, 0, 0x14000
	s_ashr_i32 s45, s33, 31
	v_lshl_add_u64 v[138:139], v[0:1], 0, s[2:3]
	v_mov_b64_e32 v[140:141], 0x100
	v_mov_b64_e32 v[142:143], 0xff
	v_add_u32_e32 v149, s46, v147
	v_add_u32_e32 v150, 0, v3
	v_add_u32_e32 v151, s47, v147
	s_mov_b32 s48, 0x48000
	s_mov_b64 s[16:17], 0x50000
	s_mov_b32 s49, 0x50000
	s_mov_b64 s[18:19], 0x58000
	s_mov_b32 s50, 0x58000
	s_barrier

; #define PG8_STAGE(bufoff, gbase, voff) do { _Pragma("unroll") for (int _i = 0; _i < 2; ++_i) \
;         __builtin_amdgcn_global_load_lds((const unsigned*)((const char*)(gbase) + (voff)[_i]), (PG8_LAS unsigned*)(lds + (bufoff) + ldsw + _i * 8192), 16, 0, 0); } while (0)
; #define PG8_LDA(dst, b, h) do { _Pragma("unroll") for (int m = 0; m < 4; ++m) _Pragma("unroll") for (int k = 0; k < 2; ++k) dst[m][k] = *(const PG8_LAS bf16x8*)(lds + PG8_SA(b, h) + aoff + m * 2048 + k * 1024); } while (0)
; #define PG8_LDB(dst, b, h) do { _Pragma("unroll") for (int n = 0; n < 2; ++n) _Pragma("unroll") for (int k = 0; k < 2; ++k) dst[n][k] = *(const PG8_LAS bf16x8*)(lds + PG8_SB(b, h) + boff + n * 2048 + k * 1024); } while (0)
; #define PG8_MMA(ai, bj, At, Bt) do { __builtin_amdgcn_s_setprio(1); _Pragma("unroll") for (int m = 0; m < 4; ++m) _Pragma("unroll") for (int n = 0; n < 2; ++n) _Pragma("unroll") for (int k = 0; k < 2; ++k) \
;         acc[ai][bj][m][n] = __builtin_amdgcn_mfma_f32_16x16x32_bf16(Bt[n][k], At[m][k], acc[ai][bj][m][n], 0, 0, 0); __builtin_amdgcn_s_setprio(0); } while (0)
; #define PG8_WAIT_V(n) asm volatile("s_waitcnt vmcnt(" #n ")" ::: "memory")
; template <class Epi, class Sched>
; __device__ __forceinline__ void gemm_phase(PG8_LAS unsigned char* lds, const Gemm g, const Sched& S, const Epi& E) {
;     ...
;         for (int t = 0; t < nt; t += 2) {
;             const bool last = (t == nt - 2);
;             const char* a1 = cA + (size_t)(t + 1) * kstep;
;             const char* a2 = last ? nA : cA + (size_t)(t + 2) * kstep; const char* b2 = last ? nB : cB + (size_t)(t + 2) * kstep;
;             const char* a3 = a2 + kstep; const char* b3 = b2 + kstep;
;             if (last && has_next) S.a_ready(nxt);
;             PG8_LDB(B0, 0, 0); PG8_SCHED; PG8_LDA(At, 0, 0); PG8_STAGE(PG8_SA(1, 1), a1 + hstep, voffA);
;             PG8_WAIT_L(8); PG8_BAR; PG8_WAIT_L(0); PG8_MMA(0, 0, At, B0); PG8_BAR; PG8_SCHED;
;             PG8_LDB(B1, 0, 1); PG8_STAGE(PG8_SB(0, 0), b2, voffB);
;             PG8_BAR; PG8_WAIT_L(0); PG8_MMA(0, 1, At, B1); PG8_BAR;
;             PG8_LDA(At, 0, 1); PG8_STAGE(PG8_SA(0, 0), a2, voffA);
;             PG8_BAR; PG8_WAIT_L(0); PG8_MMA(1, 0, At, B0); PG8_BAR; PG8_SCHED;
;             PG8_STAGE(PG8_SB(0, 1), b2 + hstep, voffB);
;             PG8_WAIT_V(6); PG8_BAR; PG8_MMA(1, 1, At, B1); PG8_BAR;
.LBB0_286:
	ds_read_b128 v[154:157], v149
	ds_read_b128 v[158:161], v149 offset:1024
	ds_read_b128 v[166:169], v149 offset:2048
	ds_read_b128 v[170:173], v149 offset:3072
	s_add_u32 s24, s22, 0x100
	s_addc_u32 s25, s23, 0
	s_cmp_eq_u32 s57, 40
	s_cselect_b32 s29, s1, s25
	s_cselect_b32 s28, s0, s24
	s_cselect_b32 s27, s5, s56
	s_cselect_b32 s26, s4, s55
	v_lshl_add_u64 v[144:145], s[22:23], 0, v[136:137]
	s_add_i32 m0, s38, 0xc000
	ds_read_b128 v[182:185], v150
	ds_read_b128 v[190:193], v150 offset:1024
	ds_read_b128 v[194:197], v150 offset:2048
	ds_read_b128 v[198:201], v150 offset:3072
	ds_read_b128 v[202:205], v150 offset:4096
	ds_read_b128 v[206:209], v150 offset:5120
	ds_read_b128 v[210:213], v150 offset:6144
	ds_read_b128 v[214:217], v150 offset:7168
	global_load_lds_dwordx4 v[144:145], off
	v_lshl_add_u64 v[144:145], s[22:23], 0, v[138:139]
	s_add_i32 m0, s38, 0xe000
	s_nop 0
	global_load_lds_dwordx4 v[144:145], off
	s_waitcnt lgkmcnt(8)
	ds_read_b128 v[218:221], v151
	ds_read_b128 v[222:225], v151 offset:1024
	ds_read_b128 v[226:229], v151 offset:2048
	ds_read_b128 v[230:233], v151 offset:3072
	s_waitcnt vmcnt(8) lgkmcnt(0)
	s_barrier
	v_mfma_f32_16x16x32_bf16 v[124:127], v[154:157], v[182:185], v[124:127]
	v_mfma_f32_16x16x32_bf16 v[120:123], v[166:169], v[182:185], v[120:123]
	v_mfma_f32_16x16x32_bf16 v[108:111], v[154:157], v[194:197], v[108:111]
	v_mfma_f32_16x16x32_bf16 v[104:107], v[166:169], v[194:197], v[104:107]
	v_mfma_f32_16x16x32_bf16 v[92:95], v[154:157], v[202:205], v[92:95]
	v_mfma_f32_16x16x32_bf16 v[88:91], v[166:169], v[202:205], v[88:91]
	v_mfma_f32_16x16x32_bf16 v[76:79], v[154:157], v[210:213], v[76:79]
	v_mfma_f32_16x16x32_bf16 v[72:75], v[166:169], v[210:213], v[72:75]
	v_mfma_f32_16x16x32_bf16 v[124:127], v[158:161], v[190:193], v[124:127]
	v_mfma_f32_16x16x32_bf16 v[120:123], v[170:173], v[190:193], v[120:123]
	v_mfma_f32_16x16x32_bf16 v[108:111], v[158:161], v[198:201], v[108:111]
	v_mfma_f32_16x16x32_bf16 v[104:107], v[170:173], v[198:201], v[104:107]
	v_mfma_f32_16x16x32_bf16 v[92:95], v[158:161], v[206:209], v[92:95]
	v_mfma_f32_16x16x32_bf16 v[88:91], v[170:173], v[206:209], v[88:91]
	v_mfma_f32_16x16x32_bf16 v[76:79], v[158:161], v[214:217], v[76:79]
	v_mfma_f32_16x16x32_bf16 v[72:75], v[170:173], v[214:217], v[72:75]
	v_mfma_f32_16x16x32_bf16 v[116:119], v[218:221], v[182:185], v[116:119]
	v_mfma_f32_16x16x32_bf16 v[112:115], v[226:229], v[182:185], v[112:115]
	v_mfma_f32_16x16x32_bf16 v[100:103], v[218:221], v[194:197], v[100:103]
	v_mfma_f32_16x16x32_bf16 v[96:99], v[226:229], v[194:197], v[96:99]
	v_mfma_f32_16x16x32_bf16 v[84:87], v[218:221], v[202:205], v[84:87]
	v_mfma_f32_16x16x32_bf16 v[80:83], v[226:229], v[202:205], v[80:83]
	v_mfma_f32_16x16x32_bf16 v[68:71], v[218:221], v[210:213], v[68:71]
	v_mfma_f32_16x16x32_bf16 v[64:67], v[226:229], v[210:213], v[64:67]
	v_mfma_f32_16x16x32_bf16 v[116:119], v[222:225], v[190:193], v[116:119]
	v_mfma_f32_16x16x32_bf16 v[112:115], v[230:233], v[190:193], v[112:115]
	v_mfma_f32_16x16x32_bf16 v[100:103], v[222:225], v[198:201], v[100:103]
	v_mfma_f32_16x16x32_bf16 v[96:99], v[230:233], v[198:201], v[96:99]
	v_mfma_f32_16x16x32_bf16 v[84:87], v[222:225], v[206:209], v[84:87]
	v_mfma_f32_16x16x32_bf16 v[80:83], v[230:233], v[206:209], v[80:83]
	v_mfma_f32_16x16x32_bf16 v[68:71], v[222:225], v[214:217], v[68:71]
	v_mfma_f32_16x16x32_bf16 v[64:67], v[230:233], v[214:217], v[64:67]
	s_barrier
	ds_read_b128 v[182:185], v150 offset:16384
	ds_read_b128 v[190:193], v150 offset:17408
	ds_read_b128 v[194:197], v150 offset:18432
	ds_read_b128 v[198:201], v150 offset:19456
	ds_read_b128 v[202:205], v150 offset:20480
	ds_read_b128 v[206:209], v150 offset:21504
	ds_read_b128 v[210:213], v150 offset:22528
	ds_read_b128 v[214:217], v150 offset:23552
	s_add_i32 s22, s46, s37
	v_lshl_add_u64 v[144:145], s[26:27], 0, v[130:131]
	s_mov_b32 m0, s22
	s_nop 0
	global_load_lds_dwordx4 v[144:145], off
	v_lshl_add_u64 v[162:163], s[26:27], 0, v[134:135]
	s_add_i32 m0, s22, 0x2000
	s_nop 0
	global_load_lds_dwordx4 v[162:163], off
	s_nop 1
	s_mov_b32 m0, s38
	v_lshl_add_u64 v[174:175], s[28:29], 0, v[128:129]
	global_load_lds_dwordx4 v[174:175], off
	v_lshl_add_u64 v[178:179], s[28:29], 0, v[132:133]
	s_mov_b32 m0, s39
	s_nop 0
	global_load_lds_dwordx4 v[178:179], off
	s_add_u32 s22, s26, 0xb0000
	s_addc_u32 s23, s27, 0
	s_add_i32 s58, s47, s37
	v_lshl_add_u64 v[246:247], s[22:23], 0, v[130:131]
	s_mov_b32 m0, s58
	s_nop 0
	global_load_lds_dwordx4 v[246:247], off
	v_lshl_add_u64 v[246:247], s[22:23], 0, v[134:135]
	s_add_i32 m0, s58, 0x2000
	s_nop 0
	global_load_lds_dwordx4 v[246:247], off
	s_waitcnt vmcnt(8) lgkmcnt(0)
	s_barrier
; #define PG8_STAGE(bufoff, gbase, voff) do { _Pragma("unroll") for (int _i = 0; _i < 2; ++_i) \
;         __builtin_amdgcn_global_load_lds((const unsigned*)((const char*)(gbase) + (voff)[_i]), (PG8_LAS unsigned*)(lds + (bufoff) + ldsw + _i * 8192), 16, 0, 0); } while (0)
; #define PG8_LDA(dst, b, h) do { _Pragma("unroll") for (int m = 0; m < 4; ++m) _Pragma("unroll") for (int k = 0; k < 2; ++k) dst[m][k] = *(const PG8_LAS bf16x8*)(lds + PG8_SA(b, h) + aoff + m * 2048 + k * 1024); } while (0)
; #define PG8_LDB(dst, b, h) do { _Pragma("unroll") for (int n = 0; n < 2; ++n) _Pragma("unroll") for (int k = 0; k < 2; ++k) dst[n][k] = *(const PG8_LAS bf16x8*)(lds + PG8_SB(b, h) + boff + n * 2048 + k * 1024); } while (0)
; #define PG8_MMA(ai, bj, At, Bt) do { __builtin_amdgcn_s_setprio(1); _Pragma("unroll") for (int m = 0; m < 4; ++m) _Pragma("unroll") for (int n = 0; n < 2; ++n) _Pragma("unroll") for (int k = 0; k < 2; ++k) \
;         acc[ai][bj][m][n] = __builtin_amdgcn_mfma_f32_16x16x32_bf16(Bt[n][k], At[m][k], acc[ai][bj][m][n], 0, 0, 0); __builtin_amdgcn_s_setprio(0); } while (0)
; #define PG8_WAIT_V(n) asm volatile("s_waitcnt vmcnt(" #n ")" ::: "memory")
; #define PG8_WAIT_L(n) asm volatile("s_waitcnt lgkmcnt(" #n ")" ::: "memory")
; #define PG8_BAR __builtin_amdgcn_s_barrier()
; #define PG8_SCHED __builtin_amdgcn_sched_barrier(0)
; template <class Epi, class Sched>
; __device__ __forceinline__ void gemm_phase(PG8_LAS unsigned char* lds, const Gemm g, const Sched& S, const Epi& E) {
;     ...
;             PG8_BAR; PG8_WAIT_L(0); PG8_MMA(1, 0, At, B0); PG8_BAR; PG8_SCHED;
;             PG8_STAGE(PG8_SB(0, 1), b2 + hstep, voffB);
;             PG8_WAIT_V(6); PG8_BAR; PG8_MMA(1, 1, At, B1); PG8_BAR;
;             PG8_LDB(B0, 1, 0); PG8_SCHED; PG8_LDA(At, 1, 0); PG8_STAGE(PG8_SA(0, 1), a2 + hstep, voffA);
;             PG8_WAIT_L(8); PG8_BAR; PG8_WAIT_L(0); PG8_MMA(0, 0, At, B0); PG8_BAR; PG8_SCHED;
;             PG8_LDB(B1, 1, 1); PG8_STAGE(PG8_SB(1, 0), b3, voffB);
;             PG8_BAR; PG8_WAIT_L(0); PG8_MMA(0, 1, At, B1); PG8_BAR;
	v_mfma_f32_16x16x32_bf16 v[60:63], v[154:157], v[182:185], v[60:63]
	v_mfma_f32_16x16x32_bf16 v[56:59], v[166:169], v[182:185], v[56:59]
	v_mfma_f32_16x16x32_bf16 v[48:51], v[154:157], v[194:197], v[48:51]
	v_mfma_f32_16x16x32_bf16 v[40:43], v[166:169], v[194:197], v[40:43]
	v_mfma_f32_16x16x32_bf16 v[32:35], v[154:157], v[202:205], v[32:35]
	v_mfma_f32_16x16x32_bf16 v[24:27], v[166:169], v[202:205], v[24:27]
	v_mfma_f32_16x16x32_bf16 v[16:19], v[154:157], v[210:213], v[16:19]
	v_mfma_f32_16x16x32_bf16 v[8:11], v[166:169], v[210:213], v[8:11]
	v_mfma_f32_16x16x32_bf16 v[60:63], v[158:161], v[190:193], v[60:63]
	v_mfma_f32_16x16x32_bf16 v[56:59], v[170:173], v[190:193], v[56:59]
	v_mfma_f32_16x16x32_bf16 v[48:51], v[158:161], v[198:201], v[48:51]
	v_mfma_f32_16x16x32_bf16 v[40:43], v[170:173], v[198:201], v[40:43]
	v_mfma_f32_16x16x32_bf16 v[32:35], v[158:161], v[206:209], v[32:35]
	v_mfma_f32_16x16x32_bf16 v[24:27], v[170:173], v[206:209], v[24:27]
	v_mfma_f32_16x16x32_bf16 v[16:19], v[158:161], v[214:217], v[16:19]
	v_mfma_f32_16x16x32_bf16 v[8:11], v[170:173], v[214:217], v[8:11]
	v_mfma_f32_16x16x32_bf16 v[52:55], v[218:221], v[182:185], v[52:55]
	v_mfma_f32_16x16x32_bf16 v[44:47], v[226:229], v[182:185], v[44:47]
	v_mfma_f32_16x16x32_bf16 v[36:39], v[218:221], v[194:197], v[36:39]
	v_mfma_f32_16x16x32_bf16 v[28:31], v[226:229], v[194:197], v[28:31]
	v_mfma_f32_16x16x32_bf16 v[20:23], v[218:221], v[202:205], v[20:23]
	v_mfma_f32_16x16x32_bf16 v[12:15], v[226:229], v[202:205], v[12:15]
	v_mfma_f32_16x16x32_bf16 v[4:7], v[218:221], v[210:213], v[4:7]
	v_mfma_f32_16x16x32_bf16 v[0:3], v[226:229], v[210:213], v[0:3]
	v_mfma_f32_16x16x32_bf16 v[52:55], v[222:225], v[190:193], v[52:55]
	v_mfma_f32_16x16x32_bf16 v[44:47], v[230:233], v[190:193], v[44:47]
	v_mfma_f32_16x16x32_bf16 v[36:39], v[222:225], v[198:201], v[36:39]
	v_mfma_f32_16x16x32_bf16 v[28:31], v[230:233], v[198:201], v[28:31]
	v_mfma_f32_16x16x32_bf16 v[20:23], v[222:225], v[206:209], v[20:23]
	v_mfma_f32_16x16x32_bf16 v[12:15], v[230:233], v[206:209], v[12:15]
	v_mfma_f32_16x16x32_bf16 v[4:7], v[222:225], v[214:217], v[4:7]
	v_mfma_f32_16x16x32_bf16 v[0:3], v[230:233], v[214:217], v[0:3]
	s_barrier
	s_add_i32 s58, 0, 0x18000
	v_add_u32_e32 v153, s58, v147
	ds_read_b128 v[154:157], v153
	ds_read_b128 v[158:161], v153 offset:1024
	ds_read_b128 v[166:169], v153 offset:2048
	ds_read_b128 v[170:173], v153 offset:3072
	s_add_u32 s22, s28, 0xb0000
	s_addc_u32 s23, s29, 0
	s_mov_b32 m0, s40
	v_lshl_add_u64 v[186:187], s[22:23], 0, v[128:129]
	ds_read_b128 v[182:185], v150 offset:32768
	ds_read_b128 v[190:193], v150 offset:33792
	ds_read_b128 v[194:197], v150 offset:34816
	ds_read_b128 v[198:201], v150 offset:35840
	ds_read_b128 v[202:205], v150 offset:36864
	ds_read_b128 v[206:209], v150 offset:37888
	ds_read_b128 v[210:213], v150 offset:38912
	ds_read_b128 v[214:217], v150 offset:39936
	global_load_lds_dwordx4 v[186:187], off
	v_lshl_add_u64 v[186:187], s[22:23], 0, v[132:133]
	s_mov_b32 m0, s41
	s_nop 0
	global_load_lds_dwordx4 v[186:187], off
	s_add_i32 s28, 0, 0x1c000
	v_add_u32_e32 v153, s28, v147
	s_waitcnt lgkmcnt(8)
	ds_read_b128 v[218:221], v153
	ds_read_b128 v[222:225], v153 offset:1024
	ds_read_b128 v[226:229], v153 offset:2048
	ds_read_b128 v[230:233], v153 offset:3072
	s_waitcnt vmcnt(8) lgkmcnt(0)
	s_barrier
	v_mfma_f32_16x16x32_bf16 v[124:127], v[154:157], v[182:185], v[124:127]
	v_mfma_f32_16x16x32_bf16 v[120:123], v[166:169], v[182:185], v[120:123]
	v_mfma_f32_16x16x32_bf16 v[108:111], v[154:157], v[194:197], v[108:111]
	v_mfma_f32_16x16x32_bf16 v[104:107], v[166:169], v[194:197], v[104:107]
	v_mfma_f32_16x16x32_bf16 v[92:95], v[154:157], v[202:205], v[92:95]
	v_mfma_f32_16x16x32_bf16 v[88:91], v[166:169], v[202:205], v[88:91]
	v_mfma_f32_16x16x32_bf16 v[76:79], v[154:157], v[210:213], v[76:79]
	v_mfma_f32_16x16x32_bf16 v[72:75], v[166:169], v[210:213], v[72:75]
	v_mfma_f32_16x16x32_bf16 v[124:127], v[158:161], v[190:193], v[124:127]
	v_mfma_f32_16x16x32_bf16 v[120:123], v[170:173], v[190:193], v[120:123]
	v_mfma_f32_16x16x32_bf16 v[108:111], v[158:161], v[198:201], v[108:111]
	v_mfma_f32_16x16x32_bf16 v[104:107], v[170:173], v[198:201], v[104:107]
	v_mfma_f32_16x16x32_bf16 v[92:95], v[158:161], v[206:209], v[92:95]
	v_mfma_f32_16x16x32_bf16 v[88:91], v[170:173], v[206:209], v[88:91]
	v_mfma_f32_16x16x32_bf16 v[76:79], v[158:161], v[214:217], v[76:79]
	v_mfma_f32_16x16x32_bf16 v[72:75], v[170:173], v[214:217], v[72:75]
	v_mfma_f32_16x16x32_bf16 v[116:119], v[218:221], v[182:185], v[116:119]
	v_mfma_f32_16x16x32_bf16 v[112:115], v[226:229], v[182:185], v[112:115]
	v_mfma_f32_16x16x32_bf16 v[100:103], v[218:221], v[194:197], v[100:103]
	v_mfma_f32_16x16x32_bf16 v[96:99], v[226:229], v[194:197], v[96:99]
	v_mfma_f32_16x16x32_bf16 v[84:87], v[218:221], v[202:205], v[84:87]
	v_mfma_f32_16x16x32_bf16 v[80:83], v[226:229], v[202:205], v[80:83]
	v_mfma_f32_16x16x32_bf16 v[68:71], v[218:221], v[210:213], v[68:71]
	v_mfma_f32_16x16x32_bf16 v[64:67], v[226:229], v[210:213], v[64:67]
	v_mfma_f32_16x16x32_bf16 v[116:119], v[222:225], v[190:193], v[116:119]
	v_mfma_f32_16x16x32_bf16 v[112:115], v[230:233], v[190:193], v[112:115]
	v_mfma_f32_16x16x32_bf16 v[100:103], v[222:225], v[198:201], v[100:103]
	v_mfma_f32_16x16x32_bf16 v[96:99], v[230:233], v[198:201], v[96:99]
	v_mfma_f32_16x16x32_bf16 v[84:87], v[222:225], v[206:209], v[84:87]
	v_mfma_f32_16x16x32_bf16 v[80:83], v[230:233], v[206:209], v[80:83]
	v_mfma_f32_16x16x32_bf16 v[68:71], v[222:225], v[214:217], v[68:71]
	v_mfma_f32_16x16x32_bf16 v[64:67], v[230:233], v[214:217], v[64:67]
	s_barrier
; __device__ __forceinline__ unsigned cvt_pk_bf16(float lo, float hi) { unsigned r; asm volatile("v_cvt_pk_bf16_f32 %0, %1, %2" : "=v"(r) : "v"(lo), "v"(hi)); return r; }
; __device__ __forceinline__ float flogsig16(float x) { return (fminf(x, 0.f) - __logf(1.0f + __expf(-fabsf(x)))) * 0.0625f; }
; #define PG8_STAGE(bufoff, gbase, voff) do { _Pragma("unroll") for (int _i = 0; _i < 2; ++_i) \
;         __builtin_amdgcn_global_load_lds((const unsigned*)((const char*)(gbase) + (voff)[_i]), (PG8_LAS unsigned*)(lds + (bufoff) + ldsw + _i * 8192), 16, 0, 0); } while (0)
; #define PG8_LDA(dst, b, h) do { _Pragma("unroll") for (int m = 0; m < 4; ++m) _Pragma("unroll") for (int k = 0; k < 2; ++k) dst[m][k] = *(const PG8_LAS bf16x8*)(lds + PG8_SA(b, h) + aoff + m * 2048 + k * 1024); } while (0)
;     __device__ __forceinline__ void operator()(const f32x4 (&acc)[2][2][4][2], const Unit& u, int wr, int wc, int fr, int fq) const {
;     ...
;         for (int ai = 0; ai < 2; ++ai)
; #pragma unroll
;             for (int m = 0; m < 4; ++m) { bf16_t* rowp = O + (size_t)(row0 + ai * HALF + m * 16) * ldc + col0;
; #pragma unroll
;                 for (int bj = 0; bj < 2; ++bj) { f32x4 v0 = acc[ai][bj][m][0] + bv[bj][0], v1 = acc[ai][bj][m][1] + bv[bj][1];
;                     if (act == 1) {
; #pragma unroll
;                         for (int j = 0; j < 1; ++j) { v0 = v0 * sigmoid4(v0); v1 = v1 * sigmoid4(v1); } }
;                     else if (act == 2) {
; #pragma unroll
;                         for (int j = 0; j < 1; ++j) { v0 = sigmoid4(v0); v1 = sigmoid4(v1); } }
;                     else if (act == 3) {
; #pragma unroll
;                         for (int j = 0; j < 4; ++j) { v0[j] = flogsig16(v0[j]); v1[j] = flogsig16(v1[j]); } }
;                     u32x4 w; w.x = cvt_pk_bf16(v0[0], v0[1]); w.y = cvt_pk_bf16(v0[2], v0[3]); w.z = cvt_pk_bf16(v1[0], v1[1]); w.w = cvt_pk_bf16(v1[2], v1[3]);
;                     *(u32x4*)(rowp + bj * HALF) = w; } }
; template <class Epi, class Sched>
; __device__ __forceinline__ void gemm_phase(PG8_LAS unsigned char* lds, const Gemm g, const Sched& S, const Epi& E) {
;     ...
;             PG8_LDA(At, 1, 1); PG8_STAGE(PG8_SA(1, 0), a3, voffA);
;             PG8_BAR; PG8_WAIT_L(0); PG8_MMA(1, 0, At, B0); PG8_BAR; PG8_SCHED;
;             PG8_STAGE(PG8_SB(1, 1), b3 + hstep, voffB);
;             PG8_WAIT_V(6); PG8_BAR; PG8_MMA(1, 1, At, B1); PG8_BAR;
	ds_read_b128 v[182:185], v150 offset:49152
	ds_read_b128 v[190:193], v150 offset:50176
	ds_read_b128 v[194:197], v150 offset:51200
	ds_read_b128 v[198:201], v150 offset:52224
	ds_read_b128 v[202:205], v150 offset:53248
	ds_read_b128 v[206:209], v150 offset:54272
	ds_read_b128 v[210:213], v150 offset:55296
	ds_read_b128 v[214:217], v150 offset:56320
	s_add_i32 s22, s58, s37
	v_lshl_add_u64 v[144:145], v[144:145], 0, s[14:15]
	s_mov_b32 m0, s22
	s_nop 0
	global_load_lds_dwordx4 v[144:145], off
	v_lshl_add_u64 v[144:145], v[162:163], 0, s[14:15]
	s_add_i32 m0, s22, 0x2000
	s_nop 0
	global_load_lds_dwordx4 v[144:145], off
	s_nop 1
	s_mov_b32 m0, s43
	v_lshl_add_u64 v[144:145], v[174:175], 0, s[14:15]
	global_load_lds_dwordx4 v[144:145], off
	v_lshl_add_u64 v[144:145], v[178:179], 0, s[14:15]
	s_mov_b32 m0, s44
	s_nop 0
	global_load_lds_dwordx4 v[144:145], off
	s_add_u32 s22, s26, 0xb0080
	s_addc_u32 s23, s27, 0
	s_add_i32 s26, s28, s37
	v_lshl_add_u64 v[144:145], s[22:23], 0, v[130:131]
	s_mov_b32 m0, s26
	s_nop 0
	global_load_lds_dwordx4 v[144:145], off
	v_lshl_add_u64 v[144:145], s[22:23], 0, v[134:135]
	s_add_i32 m0, s26, 0x2000
	s_nop 0
	global_load_lds_dwordx4 v[144:145], off
	s_waitcnt vmcnt(8) lgkmcnt(0)
	s_barrier
	v_mfma_f32_16x16x32_bf16 v[60:63], v[154:157], v[182:185], v[60:63]
	v_mfma_f32_16x16x32_bf16 v[56:59], v[166:169], v[182:185], v[56:59]
	v_mfma_f32_16x16x32_bf16 v[48:51], v[154:157], v[194:197], v[48:51]
	v_mfma_f32_16x16x32_bf16 v[40:43], v[166:169], v[194:197], v[40:43]
	v_mfma_f32_16x16x32_bf16 v[32:35], v[154:157], v[202:205], v[32:35]
	v_mfma_f32_16x16x32_bf16 v[24:27], v[166:169], v[202:205], v[24:27]
	v_mfma_f32_16x16x32_bf16 v[16:19], v[154:157], v[210:213], v[16:19]
	v_mfma_f32_16x16x32_bf16 v[8:11], v[166:169], v[210:213], v[8:11]
	v_mfma_f32_16x16x32_bf16 v[60:63], v[158:161], v[190:193], v[60:63]
	v_mfma_f32_16x16x32_bf16 v[56:59], v[170:173], v[190:193], v[56:59]
	v_mfma_f32_16x16x32_bf16 v[48:51], v[158:161], v[198:201], v[48:51]
	v_mfma_f32_16x16x32_bf16 v[40:43], v[170:173], v[198:201], v[40:43]
	v_mfma_f32_16x16x32_bf16 v[32:35], v[158:161], v[206:209], v[32:35]
	v_mfma_f32_16x16x32_bf16 v[24:27], v[170:173], v[206:209], v[24:27]
	v_mfma_f32_16x16x32_bf16 v[16:19], v[158:161], v[214:217], v[16:19]
	v_mfma_f32_16x16x32_bf16 v[8:11], v[170:173], v[214:217], v[8:11]
	v_mfma_f32_16x16x32_bf16 v[52:55], v[218:221], v[182:185], v[52:55]
	v_mfma_f32_16x16x32_bf16 v[44:47], v[226:229], v[182:185], v[44:47]
	v_mfma_f32_16x16x32_bf16 v[36:39], v[218:221], v[194:197], v[36:39]
	v_mfma_f32_16x16x32_bf16 v[28:31], v[226:229], v[194:197], v[28:31]
	v_mfma_f32_16x16x32_bf16 v[20:23], v[218:221], v[202:205], v[20:23]
	v_mfma_f32_16x16x32_bf16 v[12:15], v[226:229], v[202:205], v[12:15]
	v_mfma_f32_16x16x32_bf16 v[4:7], v[218:221], v[210:213], v[4:7]
	v_mfma_f32_16x16x32_bf16 v[0:3], v[226:229], v[210:213], v[0:3]
	v_mfma_f32_16x16x32_bf16 v[52:55], v[222:225], v[190:193], v[52:55]
	v_mfma_f32_16x16x32_bf16 v[44:47], v[230:233], v[190:193], v[44:47]
	v_mfma_f32_16x16x32_bf16 v[36:39], v[222:225], v[198:201], v[36:39]
	v_mfma_f32_16x16x32_bf16 v[28:31], v[230:233], v[198:201], v[28:31]
	v_mfma_f32_16x16x32_bf16 v[20:23], v[222:225], v[206:209], v[20:23]
	v_mfma_f32_16x16x32_bf16 v[12:15], v[230:233], v[206:209], v[12:15]
	v_mfma_f32_16x16x32_bf16 v[4:7], v[222:225], v[214:217], v[4:7]
	v_mfma_f32_16x16x32_bf16 v[0:3], v[230:233], v[214:217], v[0:3]
	s_barrier
	s_add_i32 s57, s57, 2
	s_add_u32 s55, s55, 0x100
	s_addc_u32 s56, s56, 0
	s_cmp_gt_u32 s57, 41
	s_mov_b64 s[22:23], s[24:25]
	s_cbranch_scc0 .LBB0_286
	v_lshl_add_u32 v154, s53, 8, v146
	v_lshl_or_b32 v144, s54, 8, v148
	v_ashrrev_i32_e32 v155, 31, v154
	v_ashrrev_i32_e32 v145, 31, v144
	v_lshlrev_b64 v[156:157], 11, v[154:155]
	v_lshl_add_u64 v[156:157], s[10:11], 0, v[156:157]
	v_lshlrev_b64 v[158:159], 1, v[144:145]
	v_lshl_add_u64 v[144:145], v[156:157], 0, v[158:159]
	v_pk_add_f32 v[126:127], v[126:127], 0 op_sel_hi:[1,0]
	v_pk_add_f32 v[124:125], v[124:125], 0 op_sel_hi:[1,0]
	v_pk_add_f32 v[156:157], v[122:123], 0 op_sel_hi:[1,0]
	v_pk_add_f32 v[122:123], v[120:121], 0 op_sel_hi:[1,0]
	v_cvt_pk_bf16_f32 v120, v124, v125
	v_cvt_pk_bf16_f32 v121, v126, v127
	v_pk_add_f32 v[116:117], v[116:117], 0 op_sel_hi:[1,0]
	v_cvt_pk_bf16_f32 v122, v122, v123
	v_cvt_pk_bf16_f32 v123, v156, v157
	global_store_dwordx4 v[144:145], v[120:123], off
	v_pk_add_f32 v[118:119], v[118:119], 0 op_sel_hi:[1,0]
	v_pk_add_f32 v[110:111], v[110:111], 0 op_sel_hi:[1,0]
	v_pk_add_f32 v[120:121], v[114:115], 0 op_sel_hi:[1,0]
	v_pk_add_f32 v[114:115], v[112:113], 0 op_sel_hi:[1,0]
	v_cvt_pk_bf16_f32 v112, v116, v117
	v_cvt_pk_bf16_f32 v113, v118, v119
	v_pk_add_f32 v[108:109], v[108:109], 0 op_sel_hi:[1,0]
	v_cvt_pk_bf16_f32 v114, v114, v115
	v_cvt_pk_bf16_f32 v115, v120, v121
	global_store_dwordx4 v[144:145], v[112:115], off offset:256
	v_pk_add_f32 v[100:101], v[100:101], 0 op_sel_hi:[1,0]
	v_pk_add_f32 v[102:103], v[102:103], 0 op_sel_hi:[1,0]
	v_or_b32_e32 v112, 16, v154
	v_ashrrev_i32_e32 v113, 31, v112
	v_lshlrev_b64 v[112:113], 11, v[112:113]
	v_lshl_add_u64 v[112:113], s[10:11], 0, v[112:113]
	v_lshl_add_u64 v[112:113], v[112:113], 0, v[158:159]
	v_pk_add_f32 v[114:115], v[106:107], 0 op_sel_hi:[1,0]
	v_pk_add_f32 v[106:107], v[104:105], 0 op_sel_hi:[1,0]
	v_cvt_pk_bf16_f32 v104, v108, v109
	v_cvt_pk_bf16_f32 v105, v110, v111
	v_pk_add_f32 v[94:95], v[94:95], 0 op_sel_hi:[1,0]
	v_cvt_pk_bf16_f32 v106, v106, v107
	v_cvt_pk_bf16_f32 v107, v114, v115
	global_store_dwordx4 v[112:113], v[104:107], off
	v_pk_add_f32 v[92:93], v[92:93], 0 op_sel_hi:[1,0]
	v_pk_add_f32 v[84:85], v[84:85], 0 op_sel_hi:[1,0]
; __device__ __forceinline__ unsigned cvt_pk_bf16(float lo, float hi) { unsigned r; asm volatile("v_cvt_pk_bf16_f32 %0, %1, %2" : "=v"(r) : "v"(lo), "v"(hi)); return r; }
; __device__ __forceinline__ float flogsig16(float x) { return (fminf(x, 0.f) - __logf(1.0f + __expf(-fabsf(x)))) * 0.0625f; }
; #define PG8_WAIT_V(n) asm volatile("s_waitcnt vmcnt(" #n ")" ::: "memory")
; #define PG8_BAR __builtin_amdgcn_s_barrier()
;     __device__ __forceinline__ void operator()(const f32x4 (&acc)[2][2][4][2], const Unit& u, int wr, int wc, int fr, int fq) const {
;     ...
;         for (int ai = 0; ai < 2; ++ai)
; #pragma unroll
;             for (int m = 0; m < 4; ++m) { bf16_t* rowp = O + (size_t)(row0 + ai * HALF + m * 16) * ldc + col0;
; #pragma unroll
;                 for (int bj = 0; bj < 2; ++bj) { f32x4 v0 = acc[ai][bj][m][0] + bv[bj][0], v1 = acc[ai][bj][m][1] + bv[bj][1];
;                     if (act == 1) {
; #pragma unroll
;                         for (int j = 0; j < 1; ++j) { v0 = v0 * sigmoid4(v0); v1 = v1 * sigmoid4(v1); } }
;                     else if (act == 2) {
; #pragma unroll
;                         for (int j = 0; j < 1; ++j) { v0 = sigmoid4(v0); v1 = sigmoid4(v1); } }
;                     else if (act == 3) {
; #pragma unroll
;                         for (int j = 0; j < 4; ++j) { v0[j] = flogsig16(v0[j]); v1[j] = flogsig16(v1[j]); } }
;                     u32x4 w; w.x = cvt_pk_bf16(v0[0], v0[1]); w.y = cvt_pk_bf16(v0[2], v0[3]); w.z = cvt_pk_bf16(v1[0], v1[1]); w.w = cvt_pk_bf16(v1[2], v1[3]);
;                     *(u32x4*)(rowp + bj * HALF) = w; } }
; template <class Epi, class Sched>
; __device__ __forceinline__ void gemm_phase(PG8_LAS unsigned char* lds, const Gemm g, const Sched& S, const Epi& E) {
;     ...
;         if constexpr (!Epi::AFTER_DRAIN) { E(acc, cur, wr, wc, fr, fq); S.done(cur); }
;         if (!has_next) break;
; #pragma unroll
;         for (int a = 0; a < 2; ++a)
; #pragma unroll
;             for (int b = 0; b < 2; ++b)
; #pragma unroll
;                 for (int m = 0; m < 4; ++m)
; #pragma unroll
;                     for (int n = 0; n < 2; ++n) acc[a][b][m][n] = (f32x4){0.f, 0.f, 0.f, 0.f};
;         cur = nxt; cA = nA; cB = nB; ++ui;
;     }
;     PG8_WAIT_V(0);
;     if (wr == 0) PG8_BAR;
;     PG8_BAR;
	v_pk_add_f32 v[104:105], v[98:99], 0 op_sel_hi:[1,0]
	v_pk_add_f32 v[98:99], v[96:97], 0 op_sel_hi:[1,0]
	v_cvt_pk_bf16_f32 v96, v100, v101
	v_cvt_pk_bf16_f32 v97, v102, v103
	v_pk_add_f32 v[86:87], v[86:87], 0 op_sel_hi:[1,0]
	v_cvt_pk_bf16_f32 v98, v98, v99
	v_cvt_pk_bf16_f32 v99, v104, v105
	global_store_dwordx4 v[112:113], v[96:99], off offset:256
	v_pk_add_f32 v[78:79], v[78:79], 0 op_sel_hi:[1,0]
	v_pk_add_f32 v[76:77], v[76:77], 0 op_sel_hi:[1,0]
	v_or_b32_e32 v96, 32, v154
	v_ashrrev_i32_e32 v97, 31, v96
	v_lshlrev_b64 v[96:97], 11, v[96:97]
	v_lshl_add_u64 v[96:97], s[10:11], 0, v[96:97]
	v_lshl_add_u64 v[96:97], v[96:97], 0, v[158:159]
	v_pk_add_f32 v[98:99], v[90:91], 0 op_sel_hi:[1,0]
	v_pk_add_f32 v[90:91], v[88:89], 0 op_sel_hi:[1,0]
	v_cvt_pk_bf16_f32 v88, v92, v93
	v_cvt_pk_bf16_f32 v89, v94, v95
	v_pk_add_f32 v[70:71], v[70:71], 0 op_sel_hi:[1,0]
	v_cvt_pk_bf16_f32 v90, v90, v91
	v_cvt_pk_bf16_f32 v91, v98, v99
	global_store_dwordx4 v[96:97], v[88:91], off
	v_pk_add_f32 v[68:69], v[68:69], 0 op_sel_hi:[1,0]
	s_mov_b64 s[22:23], 0x40000
	v_pk_add_f32 v[88:89], v[82:83], 0 op_sel_hi:[1,0]
	v_pk_add_f32 v[82:83], v[80:81], 0 op_sel_hi:[1,0]
	v_cvt_pk_bf16_f32 v80, v84, v85
	v_cvt_pk_bf16_f32 v81, v86, v87
	v_pk_add_f32 v[60:61], v[60:61], 0 op_sel_hi:[1,0]
	v_cvt_pk_bf16_f32 v82, v82, v83
	v_cvt_pk_bf16_f32 v83, v88, v89
	global_store_dwordx4 v[96:97], v[80:83], off offset:256
	v_pk_add_f32 v[62:63], v[62:63], 0 op_sel_hi:[1,0]
	v_pk_add_f32 v[54:55], v[54:55], 0 op_sel_hi:[1,0]
	v_or_b32_e32 v80, 48, v154
	v_ashrrev_i32_e32 v81, 31, v80
	v_lshlrev_b64 v[80:81], 11, v[80:81]
	v_lshl_add_u64 v[80:81], s[10:11], 0, v[80:81]
	v_lshl_add_u64 v[80:81], v[80:81], 0, v[158:159]
	v_pk_add_f32 v[82:83], v[74:75], 0 op_sel_hi:[1,0]
	v_pk_add_f32 v[74:75], v[72:73], 0 op_sel_hi:[1,0]
	v_cvt_pk_bf16_f32 v72, v76, v77
	v_cvt_pk_bf16_f32 v73, v78, v79
	v_pk_add_f32 v[52:53], v[52:53], 0 op_sel_hi:[1,0]
	v_cvt_pk_bf16_f32 v74, v74, v75
	v_cvt_pk_bf16_f32 v75, v82, v83
	global_store_dwordx4 v[80:81], v[72:75], off
	v_pk_add_f32 v[48:49], v[48:49], 0 op_sel_hi:[1,0]
	v_pk_add_f32 v[38:39], v[38:39], 0 op_sel_hi:[1,0]
	v_pk_add_f32 v[72:73], v[66:67], 0 op_sel_hi:[1,0]
	v_pk_add_f32 v[66:67], v[64:65], 0 op_sel_hi:[1,0]
	v_cvt_pk_bf16_f32 v64, v68, v69
	v_cvt_pk_bf16_f32 v65, v70, v71
	v_pk_add_f32 v[36:37], v[36:37], 0 op_sel_hi:[1,0]
	v_cvt_pk_bf16_f32 v66, v66, v67
	v_cvt_pk_bf16_f32 v67, v72, v73
	global_store_dwordx4 v[80:81], v[64:67], off offset:256
	v_pk_add_f32 v[32:33], v[32:33], 0 op_sel_hi:[1,0]
	v_pk_add_f32 v[22:23], v[22:23], 0 op_sel_hi:[1,0]
	v_lshl_add_u64 v[64:65], v[144:145], 0, s[22:23]
	s_mov_b32 s22, 0x40000
	v_pk_add_f32 v[66:67], v[58:59], 0 op_sel_hi:[1,0]
	v_pk_add_f32 v[58:59], v[56:57], 0 op_sel_hi:[1,0]
	v_cvt_pk_bf16_f32 v56, v60, v61
	v_add_co_u32_e32 v60, vcc, s22, v144
	v_cvt_pk_bf16_f32 v57, v62, v63
	v_cvt_pk_bf16_f32 v58, v58, v59
	v_cvt_pk_bf16_f32 v59, v66, v67
	s_mov_b64 s[22:23], 0x48000
	s_nop 0
	v_addc_co_u32_e32 v61, vcc, 0, v145, vcc
	global_store_dwordx4 v[60:61], v[56:59], off
	v_pk_add_f32 v[20:21], v[20:21], 0 op_sel_hi:[1,0]
	v_pk_add_f32 v[16:17], v[16:17], 0 op_sel_hi:[1,0]
	v_pk_add_f32 v[56:57], v[46:47], 0 op_sel_hi:[1,0]
	v_pk_add_f32 v[46:47], v[44:45], 0 op_sel_hi:[1,0]
	v_cvt_pk_bf16_f32 v44, v52, v53
	v_cvt_pk_bf16_f32 v45, v54, v55
	s_mov_b32 s54, s51
	v_cvt_pk_bf16_f32 v46, v46, v47
	v_cvt_pk_bf16_f32 v47, v56, v57
	global_store_dwordx4 v[64:65], v[44:47], off offset:256
	s_mov_b32 s53, s52
	s_mov_b64 s[24:25], s[4:5]
	v_pk_add_f32 v[46:47], v[50:51], 0 op_sel_hi:[1,0]
	v_pk_add_f32 v[50:51], v[42:43], 0 op_sel_hi:[1,0]
	v_pk_add_f32 v[42:43], v[40:41], 0 op_sel_hi:[1,0]
	v_cvt_pk_bf16_f32 v40, v48, v49
	v_cvt_pk_bf16_f32 v41, v46, v47
	v_add_co_u32_e32 v46, vcc, s48, v144
	v_cvt_pk_bf16_f32 v42, v42, v43
	v_cvt_pk_bf16_f32 v43, v50, v51
	v_lshl_add_u64 v[44:45], v[144:145], 0, s[22:23]
	s_nop 0
	v_addc_co_u32_e32 v47, vcc, 0, v145, vcc
	global_store_dwordx4 v[46:47], v[40:43], off
	s_mov_b64 s[22:23], s[0:1]
	v_pk_add_f32 v[6:7], v[6:7], 0 op_sel_hi:[1,0]
	v_pk_add_f32 v[40:41], v[30:31], 0 op_sel_hi:[1,0]
	v_pk_add_f32 v[30:31], v[28:29], 0 op_sel_hi:[1,0]
	v_cvt_pk_bf16_f32 v28, v36, v37
	v_cvt_pk_bf16_f32 v29, v38, v39
	v_pk_add_f32 v[4:5], v[4:5], 0 op_sel_hi:[1,0]
	v_cvt_pk_bf16_f32 v30, v30, v31
	v_cvt_pk_bf16_f32 v31, v40, v41
	global_store_dwordx4 v[44:45], v[28:31], off offset:256
	s_nop 1
	v_pk_add_f32 v[30:31], v[34:35], 0 op_sel_hi:[1,0]
	v_pk_add_f32 v[34:35], v[26:27], 0 op_sel_hi:[1,0]
	v_pk_add_f32 v[26:27], v[24:25], 0 op_sel_hi:[1,0]
	v_cvt_pk_bf16_f32 v24, v32, v33
	v_cvt_pk_bf16_f32 v25, v30, v31
	v_add_co_u32_e32 v30, vcc, s49, v144
	v_cvt_pk_bf16_f32 v26, v26, v27
	v_cvt_pk_bf16_f32 v27, v34, v35
	v_lshl_add_u64 v[28:29], v[144:145], 0, s[16:17]
	s_nop 0
	v_addc_co_u32_e32 v31, vcc, 0, v145, vcc
	global_store_dwordx4 v[30:31], v[24:27], off
	s_nop 1
	v_pk_add_f32 v[24:25], v[14:15], 0 op_sel_hi:[1,0]
	v_pk_add_f32 v[14:15], v[12:13], 0 op_sel_hi:[1,0]
	v_cvt_pk_bf16_f32 v12, v20, v21
	v_cvt_pk_bf16_f32 v13, v22, v23
	s_nop 0
	v_cvt_pk_bf16_f32 v14, v14, v15
	v_cvt_pk_bf16_f32 v15, v24, v25
	global_store_dwordx4 v[28:29], v[12:15], off offset:256
	s_nop 1
	v_pk_add_f32 v[14:15], v[18:19], 0 op_sel_hi:[1,0]
	v_pk_add_f32 v[18:19], v[10:11], 0 op_sel_hi:[1,0]
	v_pk_add_f32 v[10:11], v[8:9], 0 op_sel_hi:[1,0]
	v_cvt_pk_bf16_f32 v8, v16, v17
	v_cvt_pk_bf16_f32 v9, v14, v15
	v_add_co_u32_e32 v14, vcc, s50, v144
	v_lshl_add_u64 v[12:13], v[144:145], 0, s[18:19]
	s_nop 0
	v_addc_co_u32_e32 v15, vcc, 0, v145, vcc
	v_cvt_pk_bf16_f32 v10, v10, v11
	v_cvt_pk_bf16_f32 v11, v18, v19
	global_store_dwordx4 v[14:15], v[8:11], off
	s_and_b64 vcc, exec, s[2:3]
	s_nop 0
	v_pk_add_f32 v[8:9], v[2:3], 0 op_sel_hi:[1,0]
	v_pk_add_f32 v[2:3], v[0:1], 0 op_sel_hi:[1,0]
	v_cvt_pk_bf16_f32 v0, v4, v5
	v_cvt_pk_bf16_f32 v1, v6, v7
	s_nop 0
	v_cvt_pk_bf16_f32 v2, v2, v3
	v_cvt_pk_bf16_f32 v3, v8, v9
	global_store_dwordx4 v[12:13], v[0:3], off offset:256
	s_cbranch_vccz .LBB0_275
	s_waitcnt vmcnt(0)
	s_cmpk_gt_u32 s31, 0xff
	s_cbranch_scc1 .LBB0_290
	s_barrier

; #define PG8_STAGE(bufoff, gbase, voff) do { _Pragma("unroll") for (int _i = 0; _i < 2; ++_i) \
;         __builtin_amdgcn_global_load_lds((const unsigned*)((const char*)(gbase) + (voff)[_i]), (PG8_LAS unsigned*)(lds + (bufoff) + ldsw + _i * 8192), 16, 0, 0); } while (0)
; #define PG8_WAIT_V(n) asm volatile("s_waitcnt vmcnt(" #n ")" ::: "memory")
; #define PG8_BAR __builtin_amdgcn_s_barrier()
; template <class Epi, class Sched>
; __device__ __forceinline__ void gemm_phase(PG8_LAS unsigned char* lds, const Gemm g, const Sched& S, const Epi& E) {
;     ...
;     for (int i = 0; i < 2; ++i) { int R, C; stage_rc(tid * 16 + i * 8192, R, C); const int Rb = Epi::PERM ? ((R & ~31) + perm32(R & 31)) : R;
;         voffA[i] = (unsigned)(R * K + C) * 2u; voffB[i] = (unsigned)(Rb * K + C) * 2u; }
;     const size_t kstep = (size_t)(BK * 2);
;     const size_t hstep = (size_t)HALF * K * 2;
;     const size_t tstep = 2 * hstep;
;     const unsigned ldsw = (unsigned)wid * 1024u;
;     const int aoff = lds_byte(wr * 64 + fr, fq * 8), boff = lds_byte(wc * 32 + fr, fq * 8);
;     ...
;     PG8_STAGE(PG8_SB(0, 0), cB, voffB); PG8_STAGE(PG8_SA(0, 0), cA, voffA); PG8_STAGE(PG8_SB(0, 1), cB + hstep, voffB); PG8_STAGE(PG8_SA(0, 1), cA + hstep, voffA);
;     if (wr == 1) PG8_BAR;
;     PG8_WAIT_V(4); PG8_BAR;
;     PG8_STAGE(PG8_SB(1, 0), cB + kstep, voffB); PG8_STAGE(PG8_SA(1, 0), cA + kstep, voffA); PG8_STAGE(PG8_SB(1, 1), cB + hstep + kstep, voffB);
;     PG8_WAIT_V(6); PG8_BAR;
.LBB0_407:
	s_lshl_b32 s3, s3, 27
	v_readlane_b32 s7, v245, 18
	s_add_u32 s12, s7, s3
	v_readlane_b32 s3, v245, 19
	s_addc_u32 s13, s3, 0
	s_lshl_b32 s2, s2, 5
	s_mov_b64 s[14:15], 0x80
	s_and_b32 s16, s2, 0x60
	s_add_i32 m0, s27, 0x18000
	v_lshl_add_u64 v[6:7], v[6:7], 0, s[14:15]
	s_lshl_b32 s7, s10, 13
	s_lshl_b32 s18, s16, 7
	s_waitcnt vmcnt(0)
	s_barrier
	global_load_lds_dwordx4 v[6:7], off
	v_lshl_add_u64 v[4:5], v[4:5], 0, s[14:15]
	s_add_i32 m0, s27, 0x1a000
	s_add_i32 s39, s27, 0x8000
	s_add_i32 s40, s27, 0xa000
	global_load_lds_dwordx4 v[4:5], off
	v_lshl_add_u64 v[2:3], v[2:3], 0, s[14:15]
	s_mov_b32 m0, s39
	s_add_u32 s2, s4, 0x40080
	global_load_lds_dwordx4 v[2:3], off
	v_lshl_add_u64 v[0:1], v[0:1], 0, s[14:15]
	s_mov_b32 m0, s40
	s_addc_u32 s3, s5, 0
	global_load_lds_dwordx4 v[0:1], off
	s_add_i32 m0, s27, 0x1c000
	v_lshl_add_u64 v[0:1], s[2:3], 0, v[156:157]
	global_load_lds_dwordx4 v[0:1], off
	v_lshl_add_u64 v[0:1], s[2:3], 0, v[160:161]
	s_add_i32 m0, s27, 0x1e000
	s_add_i32 s43, 0, 0x10000
	global_load_lds_dwordx4 v[0:1], off
	v_lshrrev_b32_e32 v1, 1, v8
	v_and_b32_e32 v1, 24, v1
	v_and_b32_e32 v0, 15, v8
	v_lshlrev_b32_e32 v2, 1, v1
	v_lshl_or_b32 v153, s10, 6, v0
	v_lshl_or_b32 v0, v0, 6, v2
	v_lshlrev_b32_e32 v2, 2, v8
	v_and_b32_e32 v2, 32, v2
	v_bitop3_b32 v3, v0, s7, v2 bitop3:0xde
	v_bitop3_b32 v179, v0, s18, v2 bitop3:0xde
	v_lshlrev_b32_e32 v0, 14, v9
	v_and_b32_e32 v0, 0xffff8000, v0
	v_or_b32_e32 v164, s16, v1
	v_lshl_add_u32 v0, v10, 11, v0
	v_and_b32_e32 v1, 1, v9
	v_lshl_or_b32 v0, v1, 6, v0
	v_lshl_add_u32 v166, v11, 1, v0
	v_lshlrev_b32_e32 v0, 14, v12
	v_and_b32_e32 v0, 0xffff8000, v0
	s_waitcnt vmcnt(6)
	v_lshl_add_u32 v0, v13, 11, v0
	v_and_b32_e32 v1, 1, v12
	v_lshl_or_b32 v0, v1, 6, v0
	s_add_i32 s44, 0, 0x14000
	s_ashr_i32 s41, s33, 31
	s_ashr_i32 s42, s17, 31
	v_mov_b32_e32 v167, v163
	v_lshl_add_u32 v168, v14, 1, v0
	v_mov_b32_e32 v169, v163
	v_mov_b64_e32 v[170:171], 0x400
	v_mov_b64_e32 v[172:173], 0x3ff
	v_add_u32_e32 v186, s43, v179
	v_add_u32_e32 v187, 0, v3
	v_add_u32_e32 v189, s44, v179
	s_mov_b32 s45, 0xbfb8aa3b
	s_mov_b32 s46, 0x800000
	s_mov_b32 s47, 0x3f317217
	s_mov_b32 s48, 0x7f800000
	s_mov_b32 s16, 0x3d800000
	s_mov_b32 s49, 0x160000
	v_mov_b32_e32 v190, 0x41b17218
	s_mov_b32 s50, 0
	s_barrier
	s_branch .LBB0_409

; #define PG8_STAGE(bufoff, gbase, voff) do { _Pragma("unroll") for (int _i = 0; _i < 2; ++_i) \
;         __builtin_amdgcn_global_load_lds((const unsigned*)((const char*)(gbase) + (voff)[_i]), (PG8_LAS unsigned*)(lds + (bufoff) + ldsw + _i * 8192), 16, 0, 0); } while (0)
; #define PG8_LDA(dst, b, h) do { _Pragma("unroll") for (int m = 0; m < 4; ++m) _Pragma("unroll") for (int k = 0; k < 2; ++k) dst[m][k] = *(const PG8_LAS bf16x8*)(lds + PG8_SA(b, h) + aoff + m * 2048 + k * 1024); } while (0)
; #define PG8_LDB(dst, b, h) do { _Pragma("unroll") for (int n = 0; n < 2; ++n) _Pragma("unroll") for (int k = 0; k < 2; ++k) dst[n][k] = *(const PG8_LAS bf16x8*)(lds + PG8_SB(b, h) + boff + n * 2048 + k * 1024); } while (0)
; #define PG8_MMA(ai, bj, At, Bt) do { __builtin_amdgcn_s_setprio(1); _Pragma("unroll") for (int m = 0; m < 4; ++m) _Pragma("unroll") for (int n = 0; n < 2; ++n) _Pragma("unroll") for (int k = 0; k < 2; ++k) \
;         acc[ai][bj][m][n] = __builtin_amdgcn_mfma_f32_16x16x32_bf16(Bt[n][k], At[m][k], acc[ai][bj][m][n], 0, 0, 0); __builtin_amdgcn_s_setprio(0); } while (0)
; #define PG8_WAIT_V(n) asm volatile("s_waitcnt vmcnt(" #n ")" ::: "memory")
; template <class Epi, class Sched>
; __device__ __forceinline__ void gemm_phase(PG8_LAS unsigned char* lds, const Gemm g, const Sched& S, const Epi& E) {
;     ...
;         for (int t = 0; t < nt; t += 2) {
;             const bool last = (t == nt - 2);
;             const char* a1 = cA + (size_t)(t + 1) * kstep;
;             const char* a2 = last ? nA : cA + (size_t)(t + 2) * kstep; const char* b2 = last ? nB : cB + (size_t)(t + 2) * kstep;
;             const char* a3 = a2 + kstep; const char* b3 = b2 + kstep;
;             if (last && has_next) S.a_ready(nxt);
;             PG8_LDB(B0, 0, 0); PG8_SCHED; PG8_LDA(At, 0, 0); PG8_STAGE(PG8_SA(1, 1), a1 + hstep, voffA);
;             PG8_WAIT_L(8); PG8_BAR; PG8_WAIT_L(0); PG8_MMA(0, 0, At, B0); PG8_BAR; PG8_SCHED;
;             PG8_LDB(B1, 0, 1); PG8_STAGE(PG8_SB(0, 0), b2, voffB);
;             PG8_BAR; PG8_WAIT_L(0); PG8_MMA(0, 1, At, B1); PG8_BAR;
;             PG8_LDA(At, 0, 1); PG8_STAGE(PG8_SA(0, 0), a2, voffA);
;             PG8_BAR; PG8_WAIT_L(0); PG8_MMA(1, 0, At, B0); PG8_BAR; PG8_SCHED;
;             PG8_STAGE(PG8_SB(0, 1), b2 + hstep, voffB);
;             PG8_WAIT_V(6); PG8_BAR; PG8_MMA(1, 1, At, B1); PG8_BAR;
.LBB0_416:
	ds_read_b128 v[24:27], v186
	ds_read_b128 v[28:31], v186 offset:1024
	ds_read_b128 v[40:43], v186 offset:2048
	ds_read_b128 v[44:47], v186 offset:3072
	s_add_u32 s4, s0, 0xfffc0080
	s_addc_u32 s5, s1, -1
	s_cmp_eq_u32 s53, 12
	s_cselect_b32 s29, s7, s5
	s_cselect_b32 s28, s10, s4
	s_cselect_b32 s5, s19, s52
	s_cselect_b32 s4, s21, s51
	v_lshl_add_u64 v[174:175], s[0:1], 0, v[166:167]
	s_add_i32 m0, s27, 0xc000
	ds_read_b128 v[144:147], v187
	ds_read_b128 v[148:151], v187 offset:1024
	ds_read_b128 v[182:185], v187 offset:2048
	ds_read_b128 v[192:195], v187 offset:3072
	ds_read_b128 v[196:199], v187 offset:4096
	ds_read_b128 v[200:203], v187 offset:5120
	ds_read_b128 v[204:207], v187 offset:6144
	ds_read_b128 v[208:211], v187 offset:7168
	global_load_lds_dwordx4 v[174:175], off
	v_lshl_add_u64 v[174:175], s[0:1], 0, v[168:169]
	s_add_i32 m0, s27, 0xe000
	s_nop 0
	global_load_lds_dwordx4 v[174:175], off
	s_waitcnt lgkmcnt(8)
	ds_read_b128 v[212:215], v189
	ds_read_b128 v[216:219], v189 offset:1024
	ds_read_b128 v[220:223], v189 offset:2048
	ds_read_b128 v[224:227], v189 offset:3072
	s_waitcnt vmcnt(8) lgkmcnt(0)
	s_barrier
	v_mfma_f32_16x16x32_bf16 v[140:143], v[24:27], v[144:147], v[140:143]
	v_mfma_f32_16x16x32_bf16 v[136:139], v[40:43], v[144:147], v[136:139]
	v_mfma_f32_16x16x32_bf16 v[124:127], v[24:27], v[182:185], v[124:127]
	v_mfma_f32_16x16x32_bf16 v[120:123], v[40:43], v[182:185], v[120:123]
	v_mfma_f32_16x16x32_bf16 v[108:111], v[24:27], v[196:199], v[108:111]
	v_mfma_f32_16x16x32_bf16 v[104:107], v[40:43], v[196:199], v[104:107]
	v_mfma_f32_16x16x32_bf16 v[92:95], v[24:27], v[204:207], v[92:95]
	v_mfma_f32_16x16x32_bf16 v[88:91], v[40:43], v[204:207], v[88:91]
	v_mfma_f32_16x16x32_bf16 v[140:143], v[28:31], v[148:151], v[140:143]
	v_mfma_f32_16x16x32_bf16 v[136:139], v[44:47], v[148:151], v[136:139]
	v_mfma_f32_16x16x32_bf16 v[124:127], v[28:31], v[192:195], v[124:127]
	v_mfma_f32_16x16x32_bf16 v[120:123], v[44:47], v[192:195], v[120:123]
	v_mfma_f32_16x16x32_bf16 v[108:111], v[28:31], v[200:203], v[108:111]
	v_mfma_f32_16x16x32_bf16 v[104:107], v[44:47], v[200:203], v[104:107]
	v_mfma_f32_16x16x32_bf16 v[92:95], v[28:31], v[208:211], v[92:95]
	v_mfma_f32_16x16x32_bf16 v[88:91], v[44:47], v[208:211], v[88:91]
	v_mfma_f32_16x16x32_bf16 v[132:135], v[212:215], v[144:147], v[132:135]
	v_mfma_f32_16x16x32_bf16 v[128:131], v[220:223], v[144:147], v[128:131]
	v_mfma_f32_16x16x32_bf16 v[116:119], v[212:215], v[182:185], v[116:119]
	v_mfma_f32_16x16x32_bf16 v[112:115], v[220:223], v[182:185], v[112:115]
	v_mfma_f32_16x16x32_bf16 v[100:103], v[212:215], v[196:199], v[100:103]
	v_mfma_f32_16x16x32_bf16 v[96:99], v[220:223], v[196:199], v[96:99]
	v_mfma_f32_16x16x32_bf16 v[84:87], v[212:215], v[204:207], v[84:87]
	v_mfma_f32_16x16x32_bf16 v[80:83], v[220:223], v[204:207], v[80:83]
	v_mfma_f32_16x16x32_bf16 v[132:135], v[216:219], v[148:151], v[132:135]
	v_mfma_f32_16x16x32_bf16 v[128:131], v[224:227], v[148:151], v[128:131]
	v_mfma_f32_16x16x32_bf16 v[116:119], v[216:219], v[192:195], v[116:119]
	v_mfma_f32_16x16x32_bf16 v[112:115], v[224:227], v[192:195], v[112:115]
	v_mfma_f32_16x16x32_bf16 v[100:103], v[216:219], v[200:203], v[100:103]
	v_mfma_f32_16x16x32_bf16 v[96:99], v[224:227], v[200:203], v[96:99]
	v_mfma_f32_16x16x32_bf16 v[84:87], v[216:219], v[208:211], v[84:87]
	v_mfma_f32_16x16x32_bf16 v[80:83], v[224:227], v[208:211], v[80:83]
	s_barrier
	ds_read_b128 v[144:147], v187 offset:16384
	ds_read_b128 v[148:151], v187 offset:17408
	ds_read_b128 v[182:185], v187 offset:18432
	ds_read_b128 v[192:195], v187 offset:19456
	ds_read_b128 v[196:199], v187 offset:20480
	ds_read_b128 v[200:203], v187 offset:21504
	ds_read_b128 v[204:207], v187 offset:22528
	ds_read_b128 v[208:211], v187 offset:23552
	s_add_i32 s54, s43, s35
	v_lshl_add_u64 v[174:175], s[4:5], 0, v[156:157]
	s_mov_b32 m0, s54
	s_nop 0
	global_load_lds_dwordx4 v[174:175], off
	v_lshl_add_u64 v[228:229], s[4:5], 0, v[160:161]
	s_add_i32 m0, s54, 0x2000
	s_nop 0
	global_load_lds_dwordx4 v[228:229], off
	s_nop 1
	s_mov_b32 m0, s27
	v_lshl_add_u64 v[230:231], s[28:29], 0, v[154:155]
	global_load_lds_dwordx4 v[230:231], off
	v_lshl_add_u64 v[232:233], s[28:29], 0, v[158:159]
	s_mov_b32 m0, s36
	s_nop 0
	global_load_lds_dwordx4 v[232:233], off
	s_add_u32 s54, s4, 0x40000
	s_addc_u32 s55, s5, 0
	s_add_i32 s56, s44, s35
	v_lshl_add_u64 v[246:247], s[54:55], 0, v[156:157]
	s_mov_b32 m0, s56
	s_nop 0
	global_load_lds_dwordx4 v[246:247], off
	v_lshl_add_u64 v[246:247], s[54:55], 0, v[160:161]
	s_add_i32 m0, s56, 0x2000
	s_nop 0
	global_load_lds_dwordx4 v[246:247], off
	s_waitcnt vmcnt(8) lgkmcnt(0)
	s_barrier
; #define PG8_STAGE(bufoff, gbase, voff) do { _Pragma("unroll") for (int _i = 0; _i < 2; ++_i) \
;         __builtin_amdgcn_global_load_lds((const unsigned*)((const char*)(gbase) + (voff)[_i]), (PG8_LAS unsigned*)(lds + (bufoff) + ldsw + _i * 8192), 16, 0, 0); } while (0)
; #define PG8_LDA(dst, b, h) do { _Pragma("unroll") for (int m = 0; m < 4; ++m) _Pragma("unroll") for (int k = 0; k < 2; ++k) dst[m][k] = *(const PG8_LAS bf16x8*)(lds + PG8_SA(b, h) + aoff + m * 2048 + k * 1024); } while (0)
; #define PG8_LDB(dst, b, h) do { _Pragma("unroll") for (int n = 0; n < 2; ++n) _Pragma("unroll") for (int k = 0; k < 2; ++k) dst[n][k] = *(const PG8_LAS bf16x8*)(lds + PG8_SB(b, h) + boff + n * 2048 + k * 1024); } while (0)
; #define PG8_MMA(ai, bj, At, Bt) do { __builtin_amdgcn_s_setprio(1); _Pragma("unroll") for (int m = 0; m < 4; ++m) _Pragma("unroll") for (int n = 0; n < 2; ++n) _Pragma("unroll") for (int k = 0; k < 2; ++k) \
;         acc[ai][bj][m][n] = __builtin_amdgcn_mfma_f32_16x16x32_bf16(Bt[n][k], At[m][k], acc[ai][bj][m][n], 0, 0, 0); __builtin_amdgcn_s_setprio(0); } while (0)
; #define PG8_WAIT_V(n) asm volatile("s_waitcnt vmcnt(" #n ")" ::: "memory")
; #define PG8_WAIT_L(n) asm volatile("s_waitcnt lgkmcnt(" #n ")" ::: "memory")
; #define PG8_BAR __builtin_amdgcn_s_barrier()
; #define PG8_SCHED __builtin_amdgcn_sched_barrier(0)
; template <class Epi, class Sched>
; __device__ __forceinline__ void gemm_phase(PG8_LAS unsigned char* lds, const Gemm g, const Sched& S, const Epi& E) {
;     ...
;             PG8_BAR; PG8_WAIT_L(0); PG8_MMA(1, 0, At, B0); PG8_BAR; PG8_SCHED;
;             PG8_STAGE(PG8_SB(0, 1), b2 + hstep, voffB);
;             PG8_WAIT_V(6); PG8_BAR; PG8_MMA(1, 1, At, B1); PG8_BAR;
;             PG8_LDB(B0, 1, 0); PG8_SCHED; PG8_LDA(At, 1, 0); PG8_STAGE(PG8_SA(0, 1), a2 + hstep, voffA);
;             PG8_WAIT_L(8); PG8_BAR; PG8_WAIT_L(0); PG8_MMA(0, 0, At, B0); PG8_BAR; PG8_SCHED;
;             PG8_LDB(B1, 1, 1); PG8_STAGE(PG8_SB(1, 0), b3, voffB);
;             PG8_BAR; PG8_WAIT_L(0); PG8_MMA(0, 1, At, B1); PG8_BAR;
	v_mfma_f32_16x16x32_bf16 v[76:79], v[24:27], v[144:147], v[76:79]
	v_mfma_f32_16x16x32_bf16 v[72:75], v[40:43], v[144:147], v[72:75]
	v_mfma_f32_16x16x32_bf16 v[60:63], v[24:27], v[182:185], v[60:63]
	v_mfma_f32_16x16x32_bf16 v[56:59], v[40:43], v[182:185], v[56:59]
	v_mfma_f32_16x16x32_bf16 v[36:39], v[24:27], v[196:199], v[36:39]
	v_mfma_f32_16x16x32_bf16 v[32:35], v[40:43], v[196:199], v[32:35]
	v_mfma_f32_16x16x32_bf16 v[12:15], v[24:27], v[204:207], v[12:15]
	v_mfma_f32_16x16x32_bf16 v[8:11], v[40:43], v[204:207], v[8:11]
	v_mfma_f32_16x16x32_bf16 v[76:79], v[28:31], v[148:151], v[76:79]
	v_mfma_f32_16x16x32_bf16 v[72:75], v[44:47], v[148:151], v[72:75]
	v_mfma_f32_16x16x32_bf16 v[60:63], v[28:31], v[192:195], v[60:63]
	v_mfma_f32_16x16x32_bf16 v[56:59], v[44:47], v[192:195], v[56:59]
	v_mfma_f32_16x16x32_bf16 v[36:39], v[28:31], v[200:203], v[36:39]
	v_mfma_f32_16x16x32_bf16 v[32:35], v[44:47], v[200:203], v[32:35]
	v_mfma_f32_16x16x32_bf16 v[12:15], v[28:31], v[208:211], v[12:15]
	v_mfma_f32_16x16x32_bf16 v[8:11], v[44:47], v[208:211], v[8:11]
	v_mfma_f32_16x16x32_bf16 v[20:23], v[212:215], v[196:199], v[20:23]
	v_mfma_f32_16x16x32_bf16 v[16:19], v[220:223], v[196:199], v[16:19]
	v_mfma_f32_16x16x32_bf16 v[4:7], v[212:215], v[204:207], v[4:7]
	v_mfma_f32_16x16x32_bf16 v[0:3], v[220:223], v[204:207], v[0:3]
	v_mfma_f32_16x16x32_bf16 v[24:27], v[212:215], v[144:147], v[68:71]
	v_mfma_f32_16x16x32_bf16 v[28:31], v[220:223], v[144:147], v[64:67]
	v_mfma_f32_16x16x32_bf16 v[40:43], v[212:215], v[182:185], v[52:55]
	v_mfma_f32_16x16x32_bf16 v[44:47], v[220:223], v[182:185], v[48:51]
	v_mfma_f32_16x16x32_bf16 v[20:23], v[216:219], v[200:203], v[20:23]
	v_mfma_f32_16x16x32_bf16 v[16:19], v[224:227], v[200:203], v[16:19]
	v_mfma_f32_16x16x32_bf16 v[4:7], v[216:219], v[208:211], v[4:7]
	v_mfma_f32_16x16x32_bf16 v[0:3], v[224:227], v[208:211], v[0:3]
	v_mfma_f32_16x16x32_bf16 v[24:27], v[216:219], v[148:151], v[24:27]
	v_mfma_f32_16x16x32_bf16 v[28:31], v[224:227], v[148:151], v[28:31]
	v_mfma_f32_16x16x32_bf16 v[40:43], v[216:219], v[192:195], v[40:43]
	v_mfma_f32_16x16x32_bf16 v[44:47], v[224:227], v[192:195], v[44:47]
	s_barrier
	s_add_i32 s54, 0, 0x18000
	v_add_u32_e32 v68, s54, v179
	ds_read_b128 v[48:51], v68
	ds_read_b128 v[52:55], v68 offset:1024
	ds_read_b128 v[64:67], v68 offset:2048
	ds_read_b128 v[68:71], v68 offset:3072
	s_add_u32 s28, s28, 0x40000
	s_addc_u32 s29, s29, 0
	s_mov_b32 m0, s37
	v_lshl_add_u64 v[212:213], s[28:29], 0, v[154:155]
	ds_read_b128 v[144:147], v187 offset:32768
	ds_read_b128 v[148:151], v187 offset:33792
	ds_read_b128 v[182:185], v187 offset:34816
	ds_read_b128 v[192:195], v187 offset:35840
	ds_read_b128 v[196:199], v187 offset:36864
	ds_read_b128 v[200:203], v187 offset:37888
	ds_read_b128 v[204:207], v187 offset:38912
	ds_read_b128 v[208:211], v187 offset:39936
	global_load_lds_dwordx4 v[212:213], off
	v_lshl_add_u64 v[212:213], s[28:29], 0, v[158:159]
	s_mov_b32 m0, s38
	s_nop 0
	global_load_lds_dwordx4 v[212:213], off
	s_add_i32 s28, 0, 0x1c000
	v_add_u32_e32 v162, s28, v179
	s_waitcnt lgkmcnt(8)
	ds_read_b128 v[212:215], v162
	ds_read_b128 v[216:219], v162 offset:1024
	ds_read_b128 v[220:223], v162 offset:2048
	ds_read_b128 v[224:227], v162 offset:3072
	s_waitcnt vmcnt(8) lgkmcnt(0)
	s_barrier
	v_mfma_f32_16x16x32_bf16 v[140:143], v[48:51], v[144:147], v[140:143]
	v_mfma_f32_16x16x32_bf16 v[136:139], v[64:67], v[144:147], v[136:139]
	v_mfma_f32_16x16x32_bf16 v[124:127], v[48:51], v[182:185], v[124:127]
	v_mfma_f32_16x16x32_bf16 v[120:123], v[64:67], v[182:185], v[120:123]
	v_mfma_f32_16x16x32_bf16 v[108:111], v[48:51], v[196:199], v[108:111]
	v_mfma_f32_16x16x32_bf16 v[104:107], v[64:67], v[196:199], v[104:107]
	v_mfma_f32_16x16x32_bf16 v[92:95], v[48:51], v[204:207], v[92:95]
	v_mfma_f32_16x16x32_bf16 v[88:91], v[64:67], v[204:207], v[88:91]
	v_mfma_f32_16x16x32_bf16 v[140:143], v[52:55], v[148:151], v[140:143]
	v_mfma_f32_16x16x32_bf16 v[136:139], v[68:71], v[148:151], v[136:139]
	v_mfma_f32_16x16x32_bf16 v[124:127], v[52:55], v[192:195], v[124:127]
	v_mfma_f32_16x16x32_bf16 v[120:123], v[68:71], v[192:195], v[120:123]
	v_mfma_f32_16x16x32_bf16 v[108:111], v[52:55], v[200:203], v[108:111]
	v_mfma_f32_16x16x32_bf16 v[104:107], v[68:71], v[200:203], v[104:107]
	v_mfma_f32_16x16x32_bf16 v[92:95], v[52:55], v[208:211], v[92:95]
	v_mfma_f32_16x16x32_bf16 v[88:91], v[68:71], v[208:211], v[88:91]
	v_mfma_f32_16x16x32_bf16 v[132:135], v[212:215], v[144:147], v[132:135]
	v_mfma_f32_16x16x32_bf16 v[128:131], v[220:223], v[144:147], v[128:131]
	v_mfma_f32_16x16x32_bf16 v[116:119], v[212:215], v[182:185], v[116:119]
	v_mfma_f32_16x16x32_bf16 v[112:115], v[220:223], v[182:185], v[112:115]
	v_mfma_f32_16x16x32_bf16 v[100:103], v[212:215], v[196:199], v[100:103]
	v_mfma_f32_16x16x32_bf16 v[96:99], v[220:223], v[196:199], v[96:99]
	v_mfma_f32_16x16x32_bf16 v[84:87], v[212:215], v[204:207], v[84:87]
	v_mfma_f32_16x16x32_bf16 v[80:83], v[220:223], v[204:207], v[80:83]
	v_mfma_f32_16x16x32_bf16 v[132:135], v[216:219], v[148:151], v[132:135]
	v_mfma_f32_16x16x32_bf16 v[128:131], v[224:227], v[148:151], v[128:131]
	v_mfma_f32_16x16x32_bf16 v[116:119], v[216:219], v[192:195], v[116:119]
	v_mfma_f32_16x16x32_bf16 v[112:115], v[224:227], v[192:195], v[112:115]
	v_mfma_f32_16x16x32_bf16 v[100:103], v[216:219], v[200:203], v[100:103]
	v_mfma_f32_16x16x32_bf16 v[96:99], v[224:227], v[200:203], v[96:99]
	v_mfma_f32_16x16x32_bf16 v[84:87], v[216:219], v[208:211], v[84:87]
	v_mfma_f32_16x16x32_bf16 v[80:83], v[224:227], v[208:211], v[80:83]
	s_barrier
; #define PG8_STAGE(bufoff, gbase, voff) do { _Pragma("unroll") for (int _i = 0; _i < 2; ++_i) \
;         __builtin_amdgcn_global_load_lds((const unsigned*)((const char*)(gbase) + (voff)[_i]), (PG8_LAS unsigned*)(lds + (bufoff) + ldsw + _i * 8192), 16, 0, 0); } while (0)
; #define PG8_LDA(dst, b, h) do { _Pragma("unroll") for (int m = 0; m < 4; ++m) _Pragma("unroll") for (int k = 0; k < 2; ++k) dst[m][k] = *(const PG8_LAS bf16x8*)(lds + PG8_SA(b, h) + aoff + m * 2048 + k * 1024); } while (0)
; #define PG8_MMA(ai, bj, At, Bt) do { __builtin_amdgcn_s_setprio(1); _Pragma("unroll") for (int m = 0; m < 4; ++m) _Pragma("unroll") for (int n = 0; n < 2; ++n) _Pragma("unroll") for (int k = 0; k < 2; ++k) \
;         acc[ai][bj][m][n] = __builtin_amdgcn_mfma_f32_16x16x32_bf16(Bt[n][k], At[m][k], acc[ai][bj][m][n], 0, 0, 0); __builtin_amdgcn_s_setprio(0); } while (0)
; #define PG8_WAIT_V(n) asm volatile("s_waitcnt vmcnt(" #n ")" ::: "memory")
; #define PG8_WAIT_L(n) asm volatile("s_waitcnt lgkmcnt(" #n ")" ::: "memory")
; #define PG8_BAR __builtin_amdgcn_s_barrier()
; #define PG8_SCHED __builtin_amdgcn_sched_barrier(0)
;     __device__ __forceinline__ void operator()(const f32x4 (&acc)[2][2][4][2], const Unit& u, int wr, int wc, int fr, int fq) const {
;         int act = 0; const float* bias = nullptr;
;         if (mode == 1) { if (u.pn >= 8 && u.pn < 12) act = 1; else if (u.pn >= 12) { act = 3; bias = (u.pn >= 14) ? bias_b + (u.pn - 14) * 256 : bias_f + (u.pn - 12) * 256; } }
;         else if (mode == 2) { if (u.pn >= 6) act = 2; }
;         const int row0 = u.pm * BM + wr * 64 + fr, col0 = u.pn * BM + wc * 32 + 8 * fq, bcol0 = wc * 32 + 8 * fq;
; template <class Epi, class Sched>
; __device__ __forceinline__ void gemm_phase(PG8_LAS unsigned char* lds, const Gemm g, const Sched& S, const Epi& E) {
;     ...
;             PG8_LDA(At, 1, 1); PG8_STAGE(PG8_SA(1, 0), a3, voffA);
;             PG8_BAR; PG8_WAIT_L(0); PG8_MMA(1, 0, At, B0); PG8_BAR; PG8_SCHED;
;             PG8_STAGE(PG8_SB(1, 1), b3 + hstep, voffB);
;             PG8_WAIT_V(6); PG8_BAR; PG8_MMA(1, 1, At, B1); PG8_BAR;
	ds_read_b128 v[144:147], v187 offset:49152
	ds_read_b128 v[148:151], v187 offset:50176
	ds_read_b128 v[182:185], v187 offset:51200
	ds_read_b128 v[192:195], v187 offset:52224
	ds_read_b128 v[196:199], v187 offset:53248
	ds_read_b128 v[200:203], v187 offset:54272
	ds_read_b128 v[204:207], v187 offset:55296
	ds_read_b128 v[208:211], v187 offset:56320
	s_add_i32 s29, s54, s35
	v_lshl_add_u64 v[174:175], v[174:175], 0, s[14:15]
	s_mov_b32 m0, s29
	s_nop 0
	global_load_lds_dwordx4 v[174:175], off
	v_lshl_add_u64 v[174:175], v[228:229], 0, s[14:15]
	s_add_i32 m0, s29, 0x2000
	s_nop 0
	global_load_lds_dwordx4 v[174:175], off
	s_nop 1
	s_mov_b32 m0, s39
	v_lshl_add_u64 v[174:175], v[230:231], 0, s[14:15]
	global_load_lds_dwordx4 v[174:175], off
	v_lshl_add_u64 v[174:175], v[232:233], 0, s[14:15]
	s_mov_b32 m0, s40
	s_nop 0
	global_load_lds_dwordx4 v[174:175], off
	s_add_u32 s4, s4, 0x40080
	s_addc_u32 s5, s5, 0
	s_add_i32 s28, s28, s35
	v_lshl_add_u64 v[246:247], s[4:5], 0, v[156:157]
	s_mov_b32 m0, s28
	s_nop 0
	global_load_lds_dwordx4 v[246:247], off
	v_lshl_add_u64 v[246:247], s[4:5], 0, v[160:161]
	s_add_i32 m0, s28, 0x2000
	s_nop 0
	global_load_lds_dwordx4 v[246:247], off
	s_waitcnt vmcnt(8) lgkmcnt(0)
	s_barrier
	v_mfma_f32_16x16x32_bf16 v[76:79], v[48:51], v[144:147], v[76:79]
	v_mfma_f32_16x16x32_bf16 v[72:75], v[64:67], v[144:147], v[72:75]
	v_mfma_f32_16x16x32_bf16 v[60:63], v[48:51], v[182:185], v[60:63]
	v_mfma_f32_16x16x32_bf16 v[56:59], v[64:67], v[182:185], v[56:59]
	v_mfma_f32_16x16x32_bf16 v[36:39], v[48:51], v[196:199], v[36:39]
	v_mfma_f32_16x16x32_bf16 v[32:35], v[64:67], v[196:199], v[32:35]
	v_mfma_f32_16x16x32_bf16 v[12:15], v[48:51], v[204:207], v[12:15]
	v_mfma_f32_16x16x32_bf16 v[8:11], v[64:67], v[204:207], v[8:11]
	v_mfma_f32_16x16x32_bf16 v[76:79], v[52:55], v[148:151], v[76:79]
	v_mfma_f32_16x16x32_bf16 v[72:75], v[68:71], v[148:151], v[72:75]
	v_mfma_f32_16x16x32_bf16 v[60:63], v[52:55], v[192:195], v[60:63]
	v_mfma_f32_16x16x32_bf16 v[56:59], v[68:71], v[192:195], v[56:59]
	v_mfma_f32_16x16x32_bf16 v[36:39], v[52:55], v[200:203], v[36:39]
	v_mfma_f32_16x16x32_bf16 v[32:35], v[68:71], v[200:203], v[32:35]
	v_mfma_f32_16x16x32_bf16 v[12:15], v[52:55], v[208:211], v[12:15]
	v_mfma_f32_16x16x32_bf16 v[8:11], v[68:71], v[208:211], v[8:11]
	v_mfma_f32_16x16x32_bf16 v[24:27], v[212:215], v[144:147], v[24:27]
	v_mfma_f32_16x16x32_bf16 v[68:71], v[216:219], v[148:151], v[24:27]
	v_mfma_f32_16x16x32_bf16 v[24:27], v[220:223], v[144:147], v[28:31]
	v_mfma_f32_16x16x32_bf16 v[64:67], v[224:227], v[148:151], v[24:27]
	v_mfma_f32_16x16x32_bf16 v[24:27], v[212:215], v[182:185], v[40:43]
	v_mfma_f32_16x16x32_bf16 v[52:55], v[216:219], v[192:195], v[24:27]
	v_mfma_f32_16x16x32_bf16 v[24:27], v[220:223], v[182:185], v[44:47]
	v_mfma_f32_16x16x32_bf16 v[20:23], v[212:215], v[196:199], v[20:23]
	v_mfma_f32_16x16x32_bf16 v[16:19], v[220:223], v[196:199], v[16:19]
	v_mfma_f32_16x16x32_bf16 v[4:7], v[212:215], v[204:207], v[4:7]
	v_mfma_f32_16x16x32_bf16 v[0:3], v[220:223], v[204:207], v[0:3]
	v_mfma_f32_16x16x32_bf16 v[48:51], v[224:227], v[192:195], v[24:27]
	v_mfma_f32_16x16x32_bf16 v[20:23], v[216:219], v[200:203], v[20:23]
	v_mfma_f32_16x16x32_bf16 v[16:19], v[224:227], v[200:203], v[16:19]
	v_mfma_f32_16x16x32_bf16 v[4:7], v[216:219], v[208:211], v[4:7]
	v_mfma_f32_16x16x32_bf16 v[0:3], v[224:227], v[208:211], v[0:3]
	s_barrier
	s_add_i32 s53, s53, 2
	s_add_u32 s0, s0, 0x100
	s_addc_u32 s1, s1, 0
	s_add_u32 s51, s51, 0x100
	s_addc_u32 s52, s52, 0
	s_cmp_gt_u32 s53, 13
	s_cbranch_scc0 .LBB0_416
	s_cmp_gt_i32 s26, 11
	s_cselect_b64 s[4:5], -1, 0
	s_cmp_lt_i32 s26, 12
	s_mov_b64 s[0:1], 0
	s_cbranch_scc1 .LBB0_422
	s_lshl_b32 s10, s26, 8
	s_cmp_lt_u32 s26, 14
	s_mov_b64 s[28:29], -1
	s_cbranch_scc0 .LBB0_420
	s_lshl_b64 s[0:1], s[10:11], 2
	v_readlane_b32 s52, v245, 0
	v_readlane_b32 s53, v245, 1
	s_add_u32 s0, s52, s0
	s_addc_u32 s1, s53, s1
	s_add_u32 s0, s0, 0xffffd000
	v_readlane_b32 s54, v245, 2
	v_readlane_b32 s55, v245, 3
	v_readlane_b32 s56, v245, 4
	v_readlane_b32 s57, v245, 5
	v_readlane_b32 s58, v245, 6
	v_readlane_b32 s59, v245, 7
	v_readlane_b32 s60, v245, 8
	v_readlane_b32 s61, v245, 9
	v_readlane_b32 s62, v245, 10
	v_readlane_b32 s63, v245, 11
	v_readlane_b32 s64, v245, 12
	v_readlane_b32 s65, v245, 13
	v_readlane_b32 s66, v245, 14
	v_readlane_b32 s67, v245, 15
	s_addc_u32 s1, s1, -1
	s_mov_b64 s[28:29], 0

; #define PG8_STAGE(bufoff, gbase, voff) do { _Pragma("unroll") for (int _i = 0; _i < 2; ++_i) \
;         __builtin_amdgcn_global_load_lds((const unsigned*)((const char*)(gbase) + (voff)[_i]), (PG8_LAS unsigned*)(lds + (bufoff) + ldsw + _i * 8192), 16, 0, 0); } while (0)
; #define PG8_WAIT_V(n) asm volatile("s_waitcnt vmcnt(" #n ")" ::: "memory")
; #define PG8_BAR __builtin_amdgcn_s_barrier()
; template <class Epi, class Sched>
; __device__ __forceinline__ void gemm_phase(PG8_LAS unsigned char* lds, const Gemm g, const Sched& S, const Epi& E) {
;     ...
;     for (int i = 0; i < 2; ++i) { int R, C; stage_rc(tid * 16 + i * 8192, R, C); const int Rb = Epi::PERM ? ((R & ~31) + perm32(R & 31)) : R;
;         voffA[i] = (unsigned)(R * K + C) * 2u; voffB[i] = (unsigned)(Rb * K + C) * 2u; }
;     const size_t kstep = (size_t)(BK * 2);
;     const size_t hstep = (size_t)HALF * K * 2;
;     const size_t tstep = 2 * hstep;
;     const unsigned ldsw = (unsigned)wid * 1024u;
;     const int aoff = lds_byte(wr * 64 + fr, fq * 8), boff = lds_byte(wc * 32 + fr, fq * 8);
;     ...
;     PG8_STAGE(PG8_SB(0, 0), cB, voffB); PG8_STAGE(PG8_SA(0, 0), cA, voffA); PG8_STAGE(PG8_SB(0, 1), cB + hstep, voffB); PG8_STAGE(PG8_SA(0, 1), cA + hstep, voffA);
;     if (wr == 1) PG8_BAR;
;     PG8_WAIT_V(4); PG8_BAR;
;     PG8_STAGE(PG8_SB(1, 0), cB + kstep, voffB); PG8_STAGE(PG8_SA(1, 0), cA + kstep, voffA); PG8_STAGE(PG8_SB(1, 1), cB + hstep + kstep, voffB);
;     PG8_WAIT_V(6); PG8_BAR;
.LBB0_719:
	s_lshl_b32 s0, s0, 27
	v_readlane_b32 s1, v245, 18
	s_add_u32 s0, s1, s0
	v_readlane_b32 s1, v245, 19
	s_addc_u32 s1, s1, 0
	s_lshl_b32 s2, s2, 5
	s_mov_b64 s[6:7], 0x80
	s_and_b32 s2, s2, 0x60
	s_add_i32 m0, s17, 0x18000
	v_lshl_add_u64 v[6:7], v[6:7], 0, s[6:7]
	s_lshl_b32 s5, s3, 13
	s_lshl_b32 s10, s2, 7
	s_waitcnt vmcnt(0)
	s_barrier
	global_load_lds_dwordx4 v[6:7], off
	v_lshl_add_u64 v[4:5], v[4:5], 0, s[6:7]
	s_add_i32 m0, s17, 0x1a000
	s_add_i32 s37, s17, 0x8000
	s_add_i32 s38, s17, 0xa000
	global_load_lds_dwordx4 v[4:5], off
	v_lshl_add_u64 v[2:3], v[2:3], 0, s[6:7]
	s_mov_b32 m0, s37
	s_add_u32 s8, s20, 0x40080
	global_load_lds_dwordx4 v[2:3], off
	v_lshl_add_u64 v[0:1], v[0:1], 0, s[6:7]
	s_mov_b32 m0, s38
	s_addc_u32 s9, s21, 0
	global_load_lds_dwordx4 v[0:1], off
	s_add_i32 m0, s17, 0x1c000
	v_lshl_add_u64 v[0:1], s[8:9], 0, v[130:131]
	global_load_lds_dwordx4 v[0:1], off
	v_lshl_add_u64 v[0:1], s[8:9], 0, v[134:135]
	s_add_i32 m0, s17, 0x1e000
	s_add_i32 s42, 0, 0x10000
	global_load_lds_dwordx4 v[0:1], off
	v_lshrrev_b32_e32 v1, 1, v8
	v_and_b32_e32 v1, 24, v1
	v_and_b32_e32 v0, 15, v8
	v_lshlrev_b32_e32 v2, 1, v1
	v_lshl_or_b32 v148, s3, 6, v0
	v_lshl_or_b32 v0, v0, 6, v2
	v_lshlrev_b32_e32 v2, 2, v8
	v_and_b32_e32 v2, 32, v2
	v_bitop3_b32 v3, v0, s5, v2 bitop3:0xde
	v_bitop3_b32 v149, v0, s10, v2 bitop3:0xde
	v_lshlrev_b32_e32 v0, 14, v9
	v_and_b32_e32 v0, 0xffff8000, v0
	v_or_b32_e32 v150, s2, v1
	v_lshl_add_u32 v0, v10, 11, v0
	v_and_b32_e32 v1, 1, v9
	v_lshl_or_b32 v0, v1, 6, v0
	v_lshl_add_u32 v136, v11, 1, v0
	v_lshlrev_b32_e32 v0, 14, v12
	v_and_b32_e32 v0, 0xffff8000, v0
	s_waitcnt vmcnt(6)
	v_lshl_add_u32 v0, v13, 11, v0
	v_and_b32_e32 v1, 1, v12
	v_lshl_or_b32 v0, v1, 6, v0
	s_add_i32 s43, 0, 0x14000
	s_ashr_i32 s39, s33, 31
	s_ashr_i32 s40, s24, 31
	v_mov_b32_e32 v137, v131
	v_lshl_add_u32 v138, v14, 1, v0
	v_mov_b32_e32 v139, v131
	v_mov_b64_e32 v[140:141], 0x380
	v_mov_b64_e32 v[142:143], 0x37f
	s_movk_i32 s41, 0xe1
	v_add_u32_e32 v151, s42, v149
	v_add_u32_e32 v153, 0, v3
	v_add_u32_e32 v154, s43, v149
	s_movk_i32 s44, 0x1c00
	s_barrier
	s_branch .LBB0_721

; #define PG8_STAGE(bufoff, gbase, voff) do { _Pragma("unroll") for (int _i = 0; _i < 2; ++_i) \
;         __builtin_amdgcn_global_load_lds((const unsigned*)((const char*)(gbase) + (voff)[_i]), (PG8_LAS unsigned*)(lds + (bufoff) + ldsw + _i * 8192), 16, 0, 0); } while (0)
; #define PG8_LDA(dst, b, h) do { _Pragma("unroll") for (int m = 0; m < 4; ++m) _Pragma("unroll") for (int k = 0; k < 2; ++k) dst[m][k] = *(const PG8_LAS bf16x8*)(lds + PG8_SA(b, h) + aoff + m * 2048 + k * 1024); } while (0)
; #define PG8_LDB(dst, b, h) do { _Pragma("unroll") for (int n = 0; n < 2; ++n) _Pragma("unroll") for (int k = 0; k < 2; ++k) dst[n][k] = *(const PG8_LAS bf16x8*)(lds + PG8_SB(b, h) + boff + n * 2048 + k * 1024); } while (0)
; #define PG8_MMA(ai, bj, At, Bt) do { __builtin_amdgcn_s_setprio(1); _Pragma("unroll") for (int m = 0; m < 4; ++m) _Pragma("unroll") for (int n = 0; n < 2; ++n) _Pragma("unroll") for (int k = 0; k < 2; ++k) \
;         acc[ai][bj][m][n] = __builtin_amdgcn_mfma_f32_16x16x32_bf16(Bt[n][k], At[m][k], acc[ai][bj][m][n], 0, 0, 0); __builtin_amdgcn_s_setprio(0); } while (0)
; #define PG8_WAIT_V(n) asm volatile("s_waitcnt vmcnt(" #n ")" ::: "memory")
; template <class Epi, class Sched>
; __device__ __forceinline__ void gemm_phase(PG8_LAS unsigned char* lds, const Gemm g, const Sched& S, const Epi& E) {
;     ...
;         for (int t = 0; t < nt; t += 2) {
;             const bool last = (t == nt - 2);
;             const char* a1 = cA + (size_t)(t + 1) * kstep;
;             const char* a2 = last ? nA : cA + (size_t)(t + 2) * kstep; const char* b2 = last ? nB : cB + (size_t)(t + 2) * kstep;
;             const char* a3 = a2 + kstep; const char* b3 = b2 + kstep;
;             if (last && has_next) S.a_ready(nxt);
;             PG8_LDB(B0, 0, 0); PG8_SCHED; PG8_LDA(At, 0, 0); PG8_STAGE(PG8_SA(1, 1), a1 + hstep, voffA);
;             PG8_WAIT_L(8); PG8_BAR; PG8_WAIT_L(0); PG8_MMA(0, 0, At, B0); PG8_BAR; PG8_SCHED;
;             PG8_LDB(B1, 0, 1); PG8_STAGE(PG8_SB(0, 0), b2, voffB);
;             PG8_BAR; PG8_WAIT_L(0); PG8_MMA(0, 1, At, B1); PG8_BAR;
;             PG8_LDA(At, 0, 1); PG8_STAGE(PG8_SA(0, 0), a2, voffA);
;             PG8_BAR; PG8_WAIT_L(0); PG8_MMA(1, 0, At, B0); PG8_BAR; PG8_SCHED;
;             PG8_STAGE(PG8_SB(0, 1), b2 + hstep, voffB);
;             PG8_WAIT_V(6); PG8_BAR; PG8_MMA(1, 1, At, B1); PG8_BAR;
.LBB0_724:
	ds_read_b128 v[144:147], v151
	ds_read_b128 v[156:159], v151 offset:1024
	ds_read_b128 v[160:163], v151 offset:2048
	ds_read_b128 v[166:169], v151 offset:3072
	s_add_u32 s20, s18, 0xfffc0080
	s_addc_u32 s21, s19, -1
	s_cmp_eq_u32 s48, 12
	s_cselect_b32 s23, s5, s21
	s_cselect_b32 s22, s11, s20
	s_cselect_b32 s21, s9, s47
	s_cselect_b32 s20, s45, s46
	v_lshl_add_u64 v[174:175], s[18:19], 0, v[136:137]
	s_add_i32 m0, s17, 0xc000
	ds_read_b128 v[170:173], v153
	ds_read_b128 v[182:185], v153 offset:1024
	ds_read_b128 v[190:193], v153 offset:2048
	ds_read_b128 v[194:197], v153 offset:3072
	ds_read_b128 v[198:201], v153 offset:4096
	ds_read_b128 v[202:205], v153 offset:5120
	ds_read_b128 v[206:209], v153 offset:6144
	ds_read_b128 v[210:213], v153 offset:7168
	global_load_lds_dwordx4 v[174:175], off
	v_lshl_add_u64 v[174:175], s[18:19], 0, v[138:139]
	s_add_i32 m0, s17, 0xe000
	s_nop 0
	global_load_lds_dwordx4 v[174:175], off
	s_waitcnt lgkmcnt(8)
	ds_read_b128 v[214:217], v154
	ds_read_b128 v[218:221], v154 offset:1024
	ds_read_b128 v[222:225], v154 offset:2048
	ds_read_b128 v[226:229], v154 offset:3072
	s_waitcnt vmcnt(8) lgkmcnt(0)
	s_barrier
	v_mfma_f32_16x16x32_bf16 v[124:127], v[144:147], v[170:173], v[124:127]
	v_mfma_f32_16x16x32_bf16 v[120:123], v[160:163], v[170:173], v[120:123]
	v_mfma_f32_16x16x32_bf16 v[108:111], v[144:147], v[190:193], v[108:111]
	v_mfma_f32_16x16x32_bf16 v[104:107], v[160:163], v[190:193], v[104:107]
	v_mfma_f32_16x16x32_bf16 v[92:95], v[144:147], v[198:201], v[92:95]
	v_mfma_f32_16x16x32_bf16 v[88:91], v[160:163], v[198:201], v[88:91]
	v_mfma_f32_16x16x32_bf16 v[76:79], v[144:147], v[206:209], v[76:79]
	v_mfma_f32_16x16x32_bf16 v[72:75], v[160:163], v[206:209], v[72:75]
	v_mfma_f32_16x16x32_bf16 v[124:127], v[156:159], v[182:185], v[124:127]
	v_mfma_f32_16x16x32_bf16 v[120:123], v[166:169], v[182:185], v[120:123]
	v_mfma_f32_16x16x32_bf16 v[108:111], v[156:159], v[194:197], v[108:111]
	v_mfma_f32_16x16x32_bf16 v[104:107], v[166:169], v[194:197], v[104:107]
	v_mfma_f32_16x16x32_bf16 v[92:95], v[156:159], v[202:205], v[92:95]
	v_mfma_f32_16x16x32_bf16 v[88:91], v[166:169], v[202:205], v[88:91]
	v_mfma_f32_16x16x32_bf16 v[76:79], v[156:159], v[210:213], v[76:79]
	v_mfma_f32_16x16x32_bf16 v[72:75], v[166:169], v[210:213], v[72:75]
	v_mfma_f32_16x16x32_bf16 v[116:119], v[214:217], v[170:173], v[116:119]
	v_mfma_f32_16x16x32_bf16 v[112:115], v[222:225], v[170:173], v[112:115]
	v_mfma_f32_16x16x32_bf16 v[100:103], v[214:217], v[190:193], v[100:103]
	v_mfma_f32_16x16x32_bf16 v[96:99], v[222:225], v[190:193], v[96:99]
	v_mfma_f32_16x16x32_bf16 v[84:87], v[214:217], v[198:201], v[84:87]
	v_mfma_f32_16x16x32_bf16 v[80:83], v[222:225], v[198:201], v[80:83]
	v_mfma_f32_16x16x32_bf16 v[68:71], v[214:217], v[206:209], v[68:71]
	v_mfma_f32_16x16x32_bf16 v[64:67], v[222:225], v[206:209], v[64:67]
	v_mfma_f32_16x16x32_bf16 v[116:119], v[218:221], v[182:185], v[116:119]
	v_mfma_f32_16x16x32_bf16 v[112:115], v[226:229], v[182:185], v[112:115]
	v_mfma_f32_16x16x32_bf16 v[100:103], v[218:221], v[194:197], v[100:103]
	v_mfma_f32_16x16x32_bf16 v[96:99], v[226:229], v[194:197], v[96:99]
	v_mfma_f32_16x16x32_bf16 v[84:87], v[218:221], v[202:205], v[84:87]
	v_mfma_f32_16x16x32_bf16 v[80:83], v[226:229], v[202:205], v[80:83]
	v_mfma_f32_16x16x32_bf16 v[68:71], v[218:221], v[210:213], v[68:71]
	v_mfma_f32_16x16x32_bf16 v[64:67], v[226:229], v[210:213], v[64:67]
	s_barrier
	ds_read_b128 v[170:173], v153 offset:16384
	ds_read_b128 v[182:185], v153 offset:17408
	ds_read_b128 v[190:193], v153 offset:18432
	ds_read_b128 v[194:197], v153 offset:19456
	ds_read_b128 v[198:201], v153 offset:20480
	ds_read_b128 v[202:205], v153 offset:21504
	ds_read_b128 v[206:209], v153 offset:22528
	ds_read_b128 v[210:213], v153 offset:23552
	s_add_i32 s49, s42, s30
	v_lshl_add_u64 v[174:175], s[20:21], 0, v[130:131]
	s_mov_b32 m0, s49
	s_nop 0
	global_load_lds_dwordx4 v[174:175], off
	v_lshl_add_u64 v[186:187], s[20:21], 0, v[134:135]
	s_add_i32 m0, s49, 0x2000
	s_nop 0
	global_load_lds_dwordx4 v[186:187], off
	s_nop 1
	s_mov_b32 m0, s17
	v_lshl_add_u64 v[230:231], s[22:23], 0, v[128:129]
	global_load_lds_dwordx4 v[230:231], off
	v_lshl_add_u64 v[232:233], s[22:23], 0, v[132:133]
	s_mov_b32 m0, s31
	s_nop 0
	global_load_lds_dwordx4 v[232:233], off
	s_add_u32 s50, s20, 0x40000
	s_addc_u32 s51, s21, 0
	s_add_i32 s49, s43, s30
	v_lshl_add_u64 v[246:247], s[50:51], 0, v[130:131]
	s_mov_b32 m0, s49
	s_nop 0
	global_load_lds_dwordx4 v[246:247], off
	v_lshl_add_u64 v[246:247], s[50:51], 0, v[134:135]
	s_add_i32 m0, s49, 0x2000
	s_nop 0
	global_load_lds_dwordx4 v[246:247], off
	s_waitcnt vmcnt(8) lgkmcnt(0)
	s_barrier
; #define PG8_STAGE(bufoff, gbase, voff) do { _Pragma("unroll") for (int _i = 0; _i < 2; ++_i) \
;         __builtin_amdgcn_global_load_lds((const unsigned*)((const char*)(gbase) + (voff)[_i]), (PG8_LAS unsigned*)(lds + (bufoff) + ldsw + _i * 8192), 16, 0, 0); } while (0)
; #define PG8_LDA(dst, b, h) do { _Pragma("unroll") for (int m = 0; m < 4; ++m) _Pragma("unroll") for (int k = 0; k < 2; ++k) dst[m][k] = *(const PG8_LAS bf16x8*)(lds + PG8_SA(b, h) + aoff + m * 2048 + k * 1024); } while (0)
; #define PG8_LDB(dst, b, h) do { _Pragma("unroll") for (int n = 0; n < 2; ++n) _Pragma("unroll") for (int k = 0; k < 2; ++k) dst[n][k] = *(const PG8_LAS bf16x8*)(lds + PG8_SB(b, h) + boff + n * 2048 + k * 1024); } while (0)
; #define PG8_MMA(ai, bj, At, Bt) do { __builtin_amdgcn_s_setprio(1); _Pragma("unroll") for (int m = 0; m < 4; ++m) _Pragma("unroll") for (int n = 0; n < 2; ++n) _Pragma("unroll") for (int k = 0; k < 2; ++k) \
;         acc[ai][bj][m][n] = __builtin_amdgcn_mfma_f32_16x16x32_bf16(Bt[n][k], At[m][k], acc[ai][bj][m][n], 0, 0, 0); __builtin_amdgcn_s_setprio(0); } while (0)
; #define PG8_WAIT_V(n) asm volatile("s_waitcnt vmcnt(" #n ")" ::: "memory")
; #define PG8_WAIT_L(n) asm volatile("s_waitcnt lgkmcnt(" #n ")" ::: "memory")
; #define PG8_BAR __builtin_amdgcn_s_barrier()
; #define PG8_SCHED __builtin_amdgcn_sched_barrier(0)
; template <class Epi, class Sched>
; __device__ __forceinline__ void gemm_phase(PG8_LAS unsigned char* lds, const Gemm g, const Sched& S, const Epi& E) {
;     ...
;             PG8_BAR; PG8_WAIT_L(0); PG8_MMA(1, 0, At, B0); PG8_BAR; PG8_SCHED;
;             PG8_STAGE(PG8_SB(0, 1), b2 + hstep, voffB);
;             PG8_WAIT_V(6); PG8_BAR; PG8_MMA(1, 1, At, B1); PG8_BAR;
;             PG8_LDB(B0, 1, 0); PG8_SCHED; PG8_LDA(At, 1, 0); PG8_STAGE(PG8_SA(0, 1), a2 + hstep, voffA);
;             PG8_WAIT_L(8); PG8_BAR; PG8_WAIT_L(0); PG8_MMA(0, 0, At, B0); PG8_BAR; PG8_SCHED;
;             PG8_LDB(B1, 1, 1); PG8_STAGE(PG8_SB(1, 0), b3, voffB);
;             PG8_BAR; PG8_WAIT_L(0); PG8_MMA(0, 1, At, B1); PG8_BAR;
	v_mfma_f32_16x16x32_bf16 v[60:63], v[144:147], v[170:173], v[60:63]
	v_mfma_f32_16x16x32_bf16 v[56:59], v[160:163], v[170:173], v[56:59]
	v_mfma_f32_16x16x32_bf16 v[44:47], v[144:147], v[190:193], v[44:47]
	v_mfma_f32_16x16x32_bf16 v[40:43], v[160:163], v[190:193], v[40:43]
	v_mfma_f32_16x16x32_bf16 v[28:31], v[144:147], v[198:201], v[28:31]
	v_mfma_f32_16x16x32_bf16 v[24:27], v[160:163], v[198:201], v[24:27]
	v_mfma_f32_16x16x32_bf16 v[12:15], v[144:147], v[206:209], v[12:15]
	v_mfma_f32_16x16x32_bf16 v[8:11], v[160:163], v[206:209], v[8:11]
	v_mfma_f32_16x16x32_bf16 v[60:63], v[156:159], v[182:185], v[60:63]
	v_mfma_f32_16x16x32_bf16 v[56:59], v[166:169], v[182:185], v[56:59]
	v_mfma_f32_16x16x32_bf16 v[44:47], v[156:159], v[194:197], v[44:47]
	v_mfma_f32_16x16x32_bf16 v[40:43], v[166:169], v[194:197], v[40:43]
	v_mfma_f32_16x16x32_bf16 v[28:31], v[156:159], v[202:205], v[28:31]
	v_mfma_f32_16x16x32_bf16 v[24:27], v[166:169], v[202:205], v[24:27]
	v_mfma_f32_16x16x32_bf16 v[12:15], v[156:159], v[210:213], v[12:15]
	v_mfma_f32_16x16x32_bf16 v[8:11], v[166:169], v[210:213], v[8:11]
	v_mfma_f32_16x16x32_bf16 v[52:55], v[214:217], v[170:173], v[52:55]
	v_mfma_f32_16x16x32_bf16 v[48:51], v[222:225], v[170:173], v[48:51]
	v_mfma_f32_16x16x32_bf16 v[36:39], v[214:217], v[190:193], v[36:39]
	v_mfma_f32_16x16x32_bf16 v[32:35], v[222:225], v[190:193], v[32:35]
	v_mfma_f32_16x16x32_bf16 v[20:23], v[214:217], v[198:201], v[20:23]
	v_mfma_f32_16x16x32_bf16 v[16:19], v[222:225], v[198:201], v[16:19]
	v_mfma_f32_16x16x32_bf16 v[4:7], v[214:217], v[206:209], v[4:7]
	v_mfma_f32_16x16x32_bf16 v[0:3], v[222:225], v[206:209], v[0:3]
	v_mfma_f32_16x16x32_bf16 v[52:55], v[218:221], v[182:185], v[52:55]
	v_mfma_f32_16x16x32_bf16 v[48:51], v[226:229], v[182:185], v[48:51]
	v_mfma_f32_16x16x32_bf16 v[36:39], v[218:221], v[194:197], v[36:39]
	v_mfma_f32_16x16x32_bf16 v[32:35], v[226:229], v[194:197], v[32:35]
	v_mfma_f32_16x16x32_bf16 v[20:23], v[218:221], v[202:205], v[20:23]
	v_mfma_f32_16x16x32_bf16 v[16:19], v[226:229], v[202:205], v[16:19]
	v_mfma_f32_16x16x32_bf16 v[4:7], v[218:221], v[210:213], v[4:7]
	v_mfma_f32_16x16x32_bf16 v[0:3], v[226:229], v[210:213], v[0:3]
	s_barrier
	s_add_i32 s49, 0, 0x18000
	v_add_u32_e32 v155, s49, v149
	ds_read_b128 v[144:147], v155
	ds_read_b128 v[156:159], v155 offset:1024
	ds_read_b128 v[160:163], v155 offset:2048
	ds_read_b128 v[166:169], v155 offset:3072
	s_add_u32 s22, s22, 0x40000
	s_addc_u32 s23, s23, 0
	s_mov_b32 m0, s34
	v_lshl_add_u64 v[214:215], s[22:23], 0, v[128:129]
	ds_read_b128 v[170:173], v153 offset:32768
	ds_read_b128 v[182:185], v153 offset:33792
	ds_read_b128 v[190:193], v153 offset:34816
	ds_read_b128 v[194:197], v153 offset:35840
	ds_read_b128 v[198:201], v153 offset:36864
	ds_read_b128 v[202:205], v153 offset:37888
	ds_read_b128 v[206:209], v153 offset:38912
	ds_read_b128 v[210:213], v153 offset:39936
	global_load_lds_dwordx4 v[214:215], off
	v_lshl_add_u64 v[214:215], s[22:23], 0, v[132:133]
	s_mov_b32 m0, s35
	s_nop 0
	global_load_lds_dwordx4 v[214:215], off
	s_add_i32 s22, 0, 0x1c000
	v_add_u32_e32 v155, s22, v149
	s_waitcnt lgkmcnt(8)
	ds_read_b128 v[214:217], v155
	ds_read_b128 v[218:221], v155 offset:1024
	ds_read_b128 v[222:225], v155 offset:2048
	ds_read_b128 v[226:229], v155 offset:3072
	s_waitcnt vmcnt(8) lgkmcnt(0)
	s_barrier
	v_mfma_f32_16x16x32_bf16 v[124:127], v[144:147], v[170:173], v[124:127]
	v_mfma_f32_16x16x32_bf16 v[120:123], v[160:163], v[170:173], v[120:123]
	v_mfma_f32_16x16x32_bf16 v[108:111], v[144:147], v[190:193], v[108:111]
	v_mfma_f32_16x16x32_bf16 v[104:107], v[160:163], v[190:193], v[104:107]
	v_mfma_f32_16x16x32_bf16 v[92:95], v[144:147], v[198:201], v[92:95]
	v_mfma_f32_16x16x32_bf16 v[88:91], v[160:163], v[198:201], v[88:91]
	v_mfma_f32_16x16x32_bf16 v[76:79], v[144:147], v[206:209], v[76:79]
	v_mfma_f32_16x16x32_bf16 v[72:75], v[160:163], v[206:209], v[72:75]
	v_mfma_f32_16x16x32_bf16 v[124:127], v[156:159], v[182:185], v[124:127]
	v_mfma_f32_16x16x32_bf16 v[120:123], v[166:169], v[182:185], v[120:123]
	v_mfma_f32_16x16x32_bf16 v[108:111], v[156:159], v[194:197], v[108:111]
	v_mfma_f32_16x16x32_bf16 v[104:107], v[166:169], v[194:197], v[104:107]
	v_mfma_f32_16x16x32_bf16 v[92:95], v[156:159], v[202:205], v[92:95]
	v_mfma_f32_16x16x32_bf16 v[88:91], v[166:169], v[202:205], v[88:91]
	v_mfma_f32_16x16x32_bf16 v[76:79], v[156:159], v[210:213], v[76:79]
	v_mfma_f32_16x16x32_bf16 v[72:75], v[166:169], v[210:213], v[72:75]
	v_mfma_f32_16x16x32_bf16 v[116:119], v[214:217], v[170:173], v[116:119]
	v_mfma_f32_16x16x32_bf16 v[112:115], v[222:225], v[170:173], v[112:115]
	v_mfma_f32_16x16x32_bf16 v[100:103], v[214:217], v[190:193], v[100:103]
	v_mfma_f32_16x16x32_bf16 v[96:99], v[222:225], v[190:193], v[96:99]
	v_mfma_f32_16x16x32_bf16 v[84:87], v[214:217], v[198:201], v[84:87]
	v_mfma_f32_16x16x32_bf16 v[80:83], v[222:225], v[198:201], v[80:83]
	v_mfma_f32_16x16x32_bf16 v[68:71], v[214:217], v[206:209], v[68:71]
	v_mfma_f32_16x16x32_bf16 v[64:67], v[222:225], v[206:209], v[64:67]
	v_mfma_f32_16x16x32_bf16 v[116:119], v[218:221], v[182:185], v[116:119]
	v_mfma_f32_16x16x32_bf16 v[112:115], v[226:229], v[182:185], v[112:115]
	v_mfma_f32_16x16x32_bf16 v[100:103], v[218:221], v[194:197], v[100:103]
	v_mfma_f32_16x16x32_bf16 v[96:99], v[226:229], v[194:197], v[96:99]
	v_mfma_f32_16x16x32_bf16 v[84:87], v[218:221], v[202:205], v[84:87]
	v_mfma_f32_16x16x32_bf16 v[80:83], v[226:229], v[202:205], v[80:83]
	v_mfma_f32_16x16x32_bf16 v[68:71], v[218:221], v[210:213], v[68:71]
	v_mfma_f32_16x16x32_bf16 v[64:67], v[226:229], v[210:213], v[64:67]
	s_barrier
; #define PG8_STAGE(bufoff, gbase, voff) do { _Pragma("unroll") for (int _i = 0; _i < 2; ++_i) \
;         __builtin_amdgcn_global_load_lds((const unsigned*)((const char*)(gbase) + (voff)[_i]), (PG8_LAS unsigned*)(lds + (bufoff) + ldsw + _i * 8192), 16, 0, 0); } while (0)
; #define PG8_LDA(dst, b, h) do { _Pragma("unroll") for (int m = 0; m < 4; ++m) _Pragma("unroll") for (int k = 0; k < 2; ++k) dst[m][k] = *(const PG8_LAS bf16x8*)(lds + PG8_SA(b, h) + aoff + m * 2048 + k * 1024); } while (0)
; #define PG8_MMA(ai, bj, At, Bt) do { __builtin_amdgcn_s_setprio(1); _Pragma("unroll") for (int m = 0; m < 4; ++m) _Pragma("unroll") for (int n = 0; n < 2; ++n) _Pragma("unroll") for (int k = 0; k < 2; ++k) \
;         acc[ai][bj][m][n] = __builtin_amdgcn_mfma_f32_16x16x32_bf16(Bt[n][k], At[m][k], acc[ai][bj][m][n], 0, 0, 0); __builtin_amdgcn_s_setprio(0); } while (0)
; #define PG8_WAIT_V(n) asm volatile("s_waitcnt vmcnt(" #n ")" ::: "memory")
; #define PG8_BAR __builtin_amdgcn_s_barrier()
; __device__ __forceinline__ f32x4 sigmoid4(f32x4 x) {
;     f32x4 d;
; #pragma unroll
;     for (int j = 0; j < 4; ++j) d[j] = 1.0f + __expf(-fmaxf(x[j], -20.0f));
;     const float p01 = d[0] * d[1], p23 = d[2] * d[3], r = __builtin_amdgcn_rcpf(p01 * p23), r01 = r * p23, r23 = r * p01;
;     return (f32x4){r01 * d[1], r01 * d[0], r23 * d[3], r23 * d[2]};
; }
;     __device__ __forceinline__ void operator()(const f32x4 (&acc)[2][2][4][2], const Unit& u, int wr, int wc, int fr, int fq) const {
;     ...
;                 for (int bj = 0; bj < 2; ++bj) { f32x4 v0 = acc[ai][bj][m][0] + bv[bj][0], v1 = acc[ai][bj][m][1] + bv[bj][1];
;                     if (act == 1) {
; #pragma unroll
;                         for (int j = 0; j < 1; ++j) { v0 = v0 * sigmoid4(v0); v1 = v1 * sigmoid4(v1); } }
;                     else if (act == 2) {
; #pragma unroll
;                         for (int j = 0; j < 1; ++j) { v0 = sigmoid4(v0); v1 = sigmoid4(v1); } }
; template <class Epi, class Sched>
; __device__ __forceinline__ void gemm_phase(PG8_LAS unsigned char* lds, const Gemm g, const Sched& S, const Epi& E) {
;     ...
;             PG8_LDA(At, 1, 1); PG8_STAGE(PG8_SA(1, 0), a3, voffA);
;             PG8_BAR; PG8_WAIT_L(0); PG8_MMA(1, 0, At, B0); PG8_BAR; PG8_SCHED;
;             PG8_STAGE(PG8_SB(1, 1), b3 + hstep, voffB);
;             PG8_WAIT_V(6); PG8_BAR; PG8_MMA(1, 1, At, B1); PG8_BAR;
	ds_read_b128 v[170:173], v153 offset:49152
	ds_read_b128 v[182:185], v153 offset:50176
	ds_read_b128 v[190:193], v153 offset:51200
	ds_read_b128 v[194:197], v153 offset:52224
	ds_read_b128 v[198:201], v153 offset:53248
	ds_read_b128 v[202:205], v153 offset:54272
	ds_read_b128 v[206:209], v153 offset:55296
	ds_read_b128 v[210:213], v153 offset:56320
	s_add_i32 s23, s49, s30
	v_lshl_add_u64 v[174:175], v[174:175], 0, s[6:7]
	s_mov_b32 m0, s23
	s_nop 0
	global_load_lds_dwordx4 v[174:175], off
	v_lshl_add_u64 v[174:175], v[186:187], 0, s[6:7]
	s_add_i32 m0, s23, 0x2000
	s_nop 0
	global_load_lds_dwordx4 v[174:175], off
	s_nop 1
	s_mov_b32 m0, s37
	v_lshl_add_u64 v[174:175], v[230:231], 0, s[6:7]
	global_load_lds_dwordx4 v[174:175], off
	v_lshl_add_u64 v[174:175], v[232:233], 0, s[6:7]
	s_mov_b32 m0, s38
	s_nop 0
	global_load_lds_dwordx4 v[174:175], off
	s_add_u32 s20, s20, 0x40080
	s_addc_u32 s21, s21, 0
	s_add_i32 s22, s22, s30
	v_lshl_add_u64 v[246:247], s[20:21], 0, v[130:131]
	s_mov_b32 m0, s22
	s_nop 0
	global_load_lds_dwordx4 v[246:247], off
	v_lshl_add_u64 v[246:247], s[20:21], 0, v[134:135]
	s_add_i32 m0, s22, 0x2000
	s_nop 0
	global_load_lds_dwordx4 v[246:247], off
	s_waitcnt vmcnt(8) lgkmcnt(0)
	s_barrier
	v_mfma_f32_16x16x32_bf16 v[60:63], v[144:147], v[170:173], v[60:63]
	v_mfma_f32_16x16x32_bf16 v[56:59], v[160:163], v[170:173], v[56:59]
	v_mfma_f32_16x16x32_bf16 v[44:47], v[144:147], v[190:193], v[44:47]
	v_mfma_f32_16x16x32_bf16 v[40:43], v[160:163], v[190:193], v[40:43]
	v_mfma_f32_16x16x32_bf16 v[28:31], v[144:147], v[198:201], v[28:31]
	v_mfma_f32_16x16x32_bf16 v[24:27], v[160:163], v[198:201], v[24:27]
	v_mfma_f32_16x16x32_bf16 v[12:15], v[144:147], v[206:209], v[12:15]
	v_mfma_f32_16x16x32_bf16 v[8:11], v[160:163], v[206:209], v[8:11]
	v_mfma_f32_16x16x32_bf16 v[60:63], v[156:159], v[182:185], v[60:63]
	v_mfma_f32_16x16x32_bf16 v[56:59], v[166:169], v[182:185], v[56:59]
	v_mfma_f32_16x16x32_bf16 v[44:47], v[156:159], v[194:197], v[44:47]
	v_mfma_f32_16x16x32_bf16 v[40:43], v[166:169], v[194:197], v[40:43]
	v_mfma_f32_16x16x32_bf16 v[28:31], v[156:159], v[202:205], v[28:31]
	v_mfma_f32_16x16x32_bf16 v[24:27], v[166:169], v[202:205], v[24:27]
	v_mfma_f32_16x16x32_bf16 v[12:15], v[156:159], v[210:213], v[12:15]
	v_mfma_f32_16x16x32_bf16 v[8:11], v[166:169], v[210:213], v[8:11]
	v_mfma_f32_16x16x32_bf16 v[52:55], v[214:217], v[170:173], v[52:55]
	v_mfma_f32_16x16x32_bf16 v[48:51], v[222:225], v[170:173], v[48:51]
	v_mfma_f32_16x16x32_bf16 v[36:39], v[214:217], v[190:193], v[36:39]
	v_mfma_f32_16x16x32_bf16 v[32:35], v[222:225], v[190:193], v[32:35]
	v_mfma_f32_16x16x32_bf16 v[20:23], v[214:217], v[198:201], v[20:23]
	v_mfma_f32_16x16x32_bf16 v[16:19], v[222:225], v[198:201], v[16:19]
	v_mfma_f32_16x16x32_bf16 v[4:7], v[214:217], v[206:209], v[4:7]
	v_mfma_f32_16x16x32_bf16 v[0:3], v[222:225], v[206:209], v[0:3]
	v_mfma_f32_16x16x32_bf16 v[52:55], v[218:221], v[182:185], v[52:55]
	v_mfma_f32_16x16x32_bf16 v[48:51], v[226:229], v[182:185], v[48:51]
	v_mfma_f32_16x16x32_bf16 v[36:39], v[218:221], v[194:197], v[36:39]
	v_mfma_f32_16x16x32_bf16 v[32:35], v[226:229], v[194:197], v[32:35]
	v_mfma_f32_16x16x32_bf16 v[20:23], v[218:221], v[202:205], v[20:23]
	v_mfma_f32_16x16x32_bf16 v[16:19], v[226:229], v[202:205], v[16:19]
	v_mfma_f32_16x16x32_bf16 v[4:7], v[218:221], v[210:213], v[4:7]
	v_mfma_f32_16x16x32_bf16 v[0:3], v[226:229], v[210:213], v[0:3]
	s_barrier
	s_add_i32 s48, s48, 2
	s_add_u32 s18, s18, 0x100
	s_addc_u32 s19, s19, 0
	s_add_u32 s46, s46, 0x100
	s_addc_u32 s47, s47, 0
	s_cmp_gt_u32 s48, 13
	s_cbranch_scc0 .LBB0_724
	s_cmp_gt_i32 s4, 5
	s_cselect_b64 s[18:19], -1, 0
	s_cmp_lt_i32 s4, 6
	v_pk_add_f32 v[144:145], v[126:127], 0 op_sel_hi:[1,0]
	v_pk_add_f32 v[146:147], v[124:125], 0 op_sel_hi:[1,0]
	v_pk_add_f32 v[124:125], v[122:123], 0 op_sel_hi:[1,0]
	v_pk_add_f32 v[126:127], v[120:121], 0 op_sel_hi:[1,0]
	s_cbranch_scc1 .LBB0_727
	v_max_f32_e32 v122, v144, v144
	v_max_f32_e32 v122, 0xc1a00000, v122
	v_mul_f32_e32 v122, 0xbfb8aa3b, v122
	v_max_f32_e32 v120, v146, v146
	v_max_f32_e32 v121, v147, v147
	v_exp_f32_e32 v123, v122
	v_max_f32_e32 v122, v145, v145
	v_max_f32_e32 v120, 0xc1a00000, v120
	v_max_f32_e32 v121, 0xc1a00000, v121
	v_max_f32_e32 v122, 0xc1a00000, v122
	v_mul_f32_e32 v120, 0xbfb8aa3b, v120
	v_mul_f32_e32 v121, 0xbfb8aa3b, v121
	v_mul_f32_e32 v122, 0xbfb8aa3b, v122
	v_exp_f32_e32 v120, v120
	v_exp_f32_e32 v121, v121
	v_exp_f32_e32 v122, v122
	v_max_f32_e32 v124, v124, v124
	v_max_f32_e32 v124, 0xc1a00000, v124
	v_pk_add_f32 v[120:121], v[120:121], 1.0 op_sel_hi:[1,0]
	v_pk_add_f32 v[122:123], v[122:123], 1.0 op_sel_hi:[1,0]
	v_mov_b32_e32 v144, v120
	v_mov_b32_e32 v145, v123
	v_pk_mov_b32 v[146:147], v[120:121], v[122:123] op_sel:[1,0]
	v_mul_f32_e32 v124, 0xbfb8aa3b, v124
	v_pk_mul_f32 v[144:145], v[144:145], v[146:147]
	v_max_f32_e32 v126, v126, v126
	v_max_f32_e32 v127, v127, v127
	v_exp_f32_e32 v147, v124
	v_max_f32_e32 v124, v125, v125
	v_max_f32_e32 v126, 0xc1a00000, v126
	v_max_f32_e32 v127, 0xc1a00000, v127
	v_max_f32_e32 v124, 0xc1a00000, v124
	v_mul_f32_e32 v146, v144, v145
	v_mul_f32_e32 v126, 0xbfb8aa3b, v126
	v_mul_f32_e32 v127, 0xbfb8aa3b, v127
	v_mul_f32_e32 v124, 0xbfb8aa3b, v124
	v_rcp_f32_e32 v155, v146
	v_exp_f32_e32 v126, v126
	v_exp_f32_e32 v127, v127
	v_exp_f32_e32 v146, v124
	v_mul_f32_e32 v124, v145, v155
	v_mul_f32_e32 v144, v144, v155
	v_pk_add_f32 v[126:127], v[126:127], 1.0 op_sel_hi:[1,0]
	v_pk_add_f32 v[156:157], v[146:147], 1.0 op_sel_hi:[1,0]
	v_mov_b32_e32 v146, v126
	v_mov_b32_e32 v147, v157
	v_pk_mov_b32 v[158:159], v[126:127], v[156:157] op_sel:[1,0]
	v_pk_mul_f32 v[144:145], v[122:123], v[144:145] op_sel_hi:[1,0]
	v_pk_mul_f32 v[158:159], v[146:147], v[158:159]
	s_nop 0
	v_mul_f32_e32 v125, v158, v159
	v_rcp_f32_e32 v125, v125
	s_nop 0
	v_pk_mul_f32 v[146:147], v[120:121], v[124:125] op_sel:[1,0] op_sel_hi:[0,0]
	v_mul_f32_e32 v120, v159, v125
	v_mul_f32_e32 v122, v158, v125
	v_pk_mul_f32 v[124:125], v[156:157], v[122:123] op_sel_hi:[1,0]
	v_pk_mul_f32 v[126:127], v[126:127], v[120:121] op_sel:[1,0] op_sel_hi:[0,0]

; #define PG8_STAGE(bufoff, gbase, voff) do { _Pragma("unroll") for (int _i = 0; _i < 2; ++_i) \
;         __builtin_amdgcn_global_load_lds((const unsigned*)((const char*)(gbase) + (voff)[_i]), (PG8_LAS unsigned*)(lds + (bufoff) + ldsw + _i * 8192), 16, 0, 0); } while (0)
; #define PG8_WAIT_V(n) asm volatile("s_waitcnt vmcnt(" #n ")" ::: "memory")
; #define PG8_BAR __builtin_amdgcn_s_barrier()
; template <class Epi, class Sched>
; __device__ __forceinline__ void gemm_phase(PG8_LAS unsigned char* lds, const Gemm g, const Sched& S, const Epi& E) {
;     ...
;     for (int i = 0; i < 2; ++i) { int R, C; stage_rc(tid * 16 + i * 8192, R, C); const int Rb = Epi::PERM ? ((R & ~31) + perm32(R & 31)) : R;
;         voffA[i] = (unsigned)(R * K + C) * 2u; voffB[i] = (unsigned)(Rb * K + C) * 2u; }
;     const size_t kstep = (size_t)(BK * 2);
;     const size_t hstep = (size_t)HALF * K * 2;
;     const size_t tstep = 2 * hstep;
;     const unsigned ldsw = (unsigned)wid * 1024u;
;     const int aoff = lds_byte(wr * 64 + fr, fq * 8), boff = lds_byte(wc * 32 + fr, fq * 8);
;     ...
;     const char* cA = (const char*)g.A + (size_t)cur.pm * tstep; const char* cB = (const char*)g.Bt + (size_t)cur.pn * tstep;
;     S.a_ready(cur);
;     PG8_STAGE(PG8_SB(0, 0), cB, voffB); PG8_STAGE(PG8_SA(0, 0), cA, voffA); PG8_STAGE(PG8_SB(0, 1), cB + hstep, voffB); PG8_STAGE(PG8_SA(0, 1), cA + hstep, voffA);
;     if (wr == 1) PG8_BAR;
;     PG8_WAIT_V(4); PG8_BAR;
;     PG8_STAGE(PG8_SB(1, 0), cB + kstep, voffB); PG8_STAGE(PG8_SA(1, 0), cA + kstep, voffA); PG8_STAGE(PG8_SB(1, 1), cB + hstep + kstep, voffB);
;     PG8_WAIT_V(6); PG8_BAR;
.LBB0_983:
	s_lshl_b32 s0, s0, 1
	v_readlane_b32 s1, v245, 24
	s_add_u32 s0, s1, s0
	v_readlane_b32 s1, v245, 25
	s_addc_u32 s1, s1, 0
	s_lshl_b32 s4, s4, 27
	v_readlane_b32 s5, v245, 18
	s_add_u32 s4, s5, s4
	v_readlane_b32 s5, v245, 19
	s_addc_u32 s5, s5, 0
	s_lshl_b32 s6, s6, 5
	s_and_b32 s11, s6, 0x60
	s_mov_b64 s[6:7], 0x80
	s_add_i32 m0, s17, 0x18000
	v_lshl_add_u64 v[6:7], v[6:7], 0, s[6:7]
	s_lshl_b32 s10, s3, 13
	s_lshl_b32 s12, s11, 7
	s_waitcnt vmcnt(0)
	s_barrier
	global_load_lds_dwordx4 v[6:7], off
	v_lshl_add_u64 v[4:5], v[4:5], 0, s[6:7]
	s_add_i32 m0, s17, 0x1a000
	s_add_i32 s36, s17, 0x8000
	s_add_i32 s37, s17, 0xa000
	global_load_lds_dwordx4 v[4:5], off
	v_lshl_add_u64 v[2:3], v[2:3], 0, s[6:7]
	s_mov_b32 m0, s36
	s_add_u32 s8, s20, 0x40080
	global_load_lds_dwordx4 v[2:3], off
	v_lshl_add_u64 v[0:1], v[0:1], 0, s[6:7]
	s_mov_b32 m0, s37
	s_addc_u32 s9, s21, 0
	global_load_lds_dwordx4 v[0:1], off
	s_add_i32 m0, s17, 0x1c000
	v_lshl_add_u64 v[0:1], s[8:9], 0, v[130:131]
	global_load_lds_dwordx4 v[0:1], off
	v_lshl_add_u64 v[0:1], s[8:9], 0, v[134:135]
	s_add_i32 m0, s17, 0x1e000
	s_add_i32 s39, 0, 0x10000
	global_load_lds_dwordx4 v[0:1], off
	v_lshrrev_b32_e32 v1, 1, v8
	v_and_b32_e32 v1, 24, v1
	v_and_b32_e32 v0, 15, v8
	v_lshlrev_b32_e32 v2, 1, v1
	v_lshl_or_b32 v150, s3, 6, v0
	v_lshl_or_b32 v0, v0, 6, v2
	v_lshlrev_b32_e32 v2, 2, v8
	v_and_b32_e32 v2, 32, v2
	v_bitop3_b32 v3, v0, s10, v2 bitop3:0xde
	v_bitop3_b32 v151, v0, s12, v2 bitop3:0xde
	v_lshlrev_b32_e32 v0, 14, v9
	v_and_b32_e32 v0, 0xffff8000, v0
	v_or_b32_e32 v152, s11, v1
	v_lshl_add_u32 v0, v10, 11, v0
	v_and_b32_e32 v1, 1, v9
	v_lshl_or_b32 v0, v1, 6, v0
	v_lshl_add_u32 v136, v11, 1, v0
	v_lshlrev_b32_e32 v0, 14, v12
	v_and_b32_e32 v0, 0xffff8000, v0
	s_waitcnt vmcnt(6)
	v_lshl_add_u32 v0, v13, 11, v0
	v_and_b32_e32 v1, 1, v12
	v_lshl_or_b32 v0, v1, 6, v0
	s_add_i32 s40, 0, 0x14000
	s_sext_i32_i8 s42, s2
	s_ashr_i32 s38, s33, 31
	v_mov_b32_e32 v137, v131
	v_lshl_add_u32 v138, v14, 1, v0
	v_mov_b32_e32 v139, v131
	v_mov_b64_e32 v[140:141], 0x100
	v_mov_b64_e32 v[142:143], 0xff
	v_add_u32_e32 v153, s39, v151
	v_add_u32_e32 v154, 0, v3
	v_add_u32_e32 v155, s40, v151
	s_movk_i32 s41, 0x1c00
	s_barrier

; #define PG8_STAGE(bufoff, gbase, voff) do { _Pragma("unroll") for (int _i = 0; _i < 2; ++_i) \
;         __builtin_amdgcn_global_load_lds((const unsigned*)((const char*)(gbase) + (voff)[_i]), (PG8_LAS unsigned*)(lds + (bufoff) + ldsw + _i * 8192), 16, 0, 0); } while (0)
; #define PG8_LDA(dst, b, h) do { _Pragma("unroll") for (int m = 0; m < 4; ++m) _Pragma("unroll") for (int k = 0; k < 2; ++k) dst[m][k] = *(const PG8_LAS bf16x8*)(lds + PG8_SA(b, h) + aoff + m * 2048 + k * 1024); } while (0)
; #define PG8_LDB(dst, b, h) do { _Pragma("unroll") for (int n = 0; n < 2; ++n) _Pragma("unroll") for (int k = 0; k < 2; ++k) dst[n][k] = *(const PG8_LAS bf16x8*)(lds + PG8_SB(b, h) + boff + n * 2048 + k * 1024); } while (0)
; #define PG8_MMA(ai, bj, At, Bt) do { __builtin_amdgcn_s_setprio(1); _Pragma("unroll") for (int m = 0; m < 4; ++m) _Pragma("unroll") for (int n = 0; n < 2; ++n) _Pragma("unroll") for (int k = 0; k < 2; ++k) \
;         acc[ai][bj][m][n] = __builtin_amdgcn_mfma_f32_16x16x32_bf16(Bt[n][k], At[m][k], acc[ai][bj][m][n], 0, 0, 0); __builtin_amdgcn_s_setprio(0); } while (0)
; #define PG8_WAIT_V(n) asm volatile("s_waitcnt vmcnt(" #n ")" ::: "memory")
; template <class Epi, class Sched>
; __device__ __forceinline__ void gemm_phase(PG8_LAS unsigned char* lds, const Gemm g, const Sched& S, const Epi& E) {
;     ...
;         for (int t = 0; t < nt; t += 2) {
;             const bool last = (t == nt - 2);
;             const char* a1 = cA + (size_t)(t + 1) * kstep;
;             const char* a2 = last ? nA : cA + (size_t)(t + 2) * kstep; const char* b2 = last ? nB : cB + (size_t)(t + 2) * kstep;
;             const char* a3 = a2 + kstep; const char* b3 = b2 + kstep;
;             if (last && has_next) S.a_ready(nxt);
;             PG8_LDB(B0, 0, 0); PG8_SCHED; PG8_LDA(At, 0, 0); PG8_STAGE(PG8_SA(1, 1), a1 + hstep, voffA);
;             PG8_WAIT_L(8); PG8_BAR; PG8_WAIT_L(0); PG8_MMA(0, 0, At, B0); PG8_BAR; PG8_SCHED;
;             PG8_LDB(B1, 0, 1); PG8_STAGE(PG8_SB(0, 0), b2, voffB);
;             PG8_BAR; PG8_WAIT_L(0); PG8_MMA(0, 1, At, B1); PG8_BAR;
;             PG8_LDA(At, 0, 1); PG8_STAGE(PG8_SA(0, 0), a2, voffA);
;             PG8_BAR; PG8_WAIT_L(0); PG8_MMA(1, 0, At, B0); PG8_BAR; PG8_SCHED;
;             PG8_STAGE(PG8_SB(0, 1), b2 + hstep, voffB);
;             PG8_WAIT_V(6); PG8_BAR; PG8_MMA(1, 1, At, B1); PG8_BAR;
.LBB0_991:
	ds_read_b128 v[144:147], v153
	ds_read_b128 v[156:159], v153 offset:1024
	ds_read_b128 v[160:163], v153 offset:2048
	ds_read_b128 v[164:167], v153 offset:3072
	s_add_u32 s20, s18, 0xfffc0080
	s_addc_u32 s21, s19, -1
	s_cmp_eq_u32 s47, 12
	s_cselect_b32 s23, s11, s21
	s_cselect_b32 s22, s43, s20
	s_cselect_b32 s21, s9, s46
	s_cselect_b32 s20, s44, s45
	v_lshl_add_u64 v[148:149], s[18:19], 0, v[136:137]
	s_add_i32 m0, s17, 0xc000
	ds_read_b128 v[168:171], v154
	ds_read_b128 v[172:175], v154 offset:1024
	ds_read_b128 v[182:185], v154 offset:2048
	ds_read_b128 v[190:193], v154 offset:3072
	ds_read_b128 v[194:197], v154 offset:4096
	ds_read_b128 v[198:201], v154 offset:5120
	ds_read_b128 v[202:205], v154 offset:6144
	ds_read_b128 v[206:209], v154 offset:7168
	global_load_lds_dwordx4 v[148:149], off
	v_lshl_add_u64 v[148:149], s[18:19], 0, v[138:139]
	s_add_i32 m0, s17, 0xe000
	s_nop 0
	global_load_lds_dwordx4 v[148:149], off
	s_waitcnt lgkmcnt(8)
	ds_read_b128 v[210:213], v155
	ds_read_b128 v[214:217], v155 offset:1024
	ds_read_b128 v[218:221], v155 offset:2048
	ds_read_b128 v[222:225], v155 offset:3072
	s_waitcnt vmcnt(8) lgkmcnt(0)
	s_barrier
	v_mfma_f32_16x16x32_bf16 v[124:127], v[144:147], v[168:171], v[124:127]
	v_mfma_f32_16x16x32_bf16 v[120:123], v[160:163], v[168:171], v[120:123]
	v_mfma_f32_16x16x32_bf16 v[112:115], v[144:147], v[182:185], v[112:115]
	v_mfma_f32_16x16x32_bf16 v[104:107], v[160:163], v[182:185], v[104:107]
	v_mfma_f32_16x16x32_bf16 v[96:99], v[144:147], v[194:197], v[96:99]
	v_mfma_f32_16x16x32_bf16 v[88:91], v[160:163], v[194:197], v[88:91]
	v_mfma_f32_16x16x32_bf16 v[80:83], v[144:147], v[202:205], v[80:83]
	v_mfma_f32_16x16x32_bf16 v[72:75], v[160:163], v[202:205], v[72:75]
	v_mfma_f32_16x16x32_bf16 v[124:127], v[156:159], v[172:175], v[124:127]
	v_mfma_f32_16x16x32_bf16 v[120:123], v[164:167], v[172:175], v[120:123]
	v_mfma_f32_16x16x32_bf16 v[112:115], v[156:159], v[190:193], v[112:115]
	v_mfma_f32_16x16x32_bf16 v[104:107], v[164:167], v[190:193], v[104:107]
	v_mfma_f32_16x16x32_bf16 v[96:99], v[156:159], v[198:201], v[96:99]
	v_mfma_f32_16x16x32_bf16 v[88:91], v[164:167], v[198:201], v[88:91]
	v_mfma_f32_16x16x32_bf16 v[80:83], v[156:159], v[206:209], v[80:83]
	v_mfma_f32_16x16x32_bf16 v[72:75], v[164:167], v[206:209], v[72:75]
	v_mfma_f32_16x16x32_bf16 v[116:119], v[210:213], v[168:171], v[116:119]
	v_mfma_f32_16x16x32_bf16 v[108:111], v[218:221], v[168:171], v[108:111]
	v_mfma_f32_16x16x32_bf16 v[100:103], v[210:213], v[182:185], v[100:103]
	v_mfma_f32_16x16x32_bf16 v[92:95], v[218:221], v[182:185], v[92:95]
	v_mfma_f32_16x16x32_bf16 v[84:87], v[210:213], v[194:197], v[84:87]
	v_mfma_f32_16x16x32_bf16 v[76:79], v[218:221], v[194:197], v[76:79]
	v_mfma_f32_16x16x32_bf16 v[68:71], v[210:213], v[202:205], v[68:71]
	v_mfma_f32_16x16x32_bf16 v[64:67], v[218:221], v[202:205], v[64:67]
	v_mfma_f32_16x16x32_bf16 v[116:119], v[214:217], v[172:175], v[116:119]
	v_mfma_f32_16x16x32_bf16 v[108:111], v[222:225], v[172:175], v[108:111]
	v_mfma_f32_16x16x32_bf16 v[100:103], v[214:217], v[190:193], v[100:103]
	v_mfma_f32_16x16x32_bf16 v[92:95], v[222:225], v[190:193], v[92:95]
	v_mfma_f32_16x16x32_bf16 v[84:87], v[214:217], v[198:201], v[84:87]
	v_mfma_f32_16x16x32_bf16 v[76:79], v[222:225], v[198:201], v[76:79]
	v_mfma_f32_16x16x32_bf16 v[68:71], v[214:217], v[206:209], v[68:71]
	v_mfma_f32_16x16x32_bf16 v[64:67], v[222:225], v[206:209], v[64:67]
	s_barrier
	ds_read_b128 v[168:171], v154 offset:16384
	ds_read_b128 v[172:175], v154 offset:17408
	ds_read_b128 v[182:185], v154 offset:18432
	ds_read_b128 v[190:193], v154 offset:19456
	ds_read_b128 v[194:197], v154 offset:20480
	ds_read_b128 v[198:201], v154 offset:21504
	ds_read_b128 v[202:205], v154 offset:22528
	ds_read_b128 v[206:209], v154 offset:23552
	s_add_i32 s48, s39, s29
	v_lshl_add_u64 v[148:149], s[20:21], 0, v[130:131]
	s_mov_b32 m0, s48
	s_nop 0
	global_load_lds_dwordx4 v[148:149], off
	v_lshl_add_u64 v[186:187], s[20:21], 0, v[134:135]
	s_add_i32 m0, s48, 0x2000
	s_nop 0
	global_load_lds_dwordx4 v[186:187], off
	s_nop 1
	s_mov_b32 m0, s17
	v_lshl_add_u64 v[226:227], s[22:23], 0, v[128:129]
	global_load_lds_dwordx4 v[226:227], off
	v_lshl_add_u64 v[228:229], s[22:23], 0, v[132:133]
	s_mov_b32 m0, s30
	s_nop 0
	global_load_lds_dwordx4 v[228:229], off
	s_add_u32 s48, s20, 0x40000
	s_addc_u32 s49, s21, 0
	s_add_i32 s50, s40, s29
	v_lshl_add_u64 v[246:247], s[48:49], 0, v[130:131]
	s_mov_b32 m0, s50
	s_nop 0
	global_load_lds_dwordx4 v[246:247], off
	v_lshl_add_u64 v[246:247], s[48:49], 0, v[134:135]
	s_add_i32 m0, s50, 0x2000
	s_nop 0
	global_load_lds_dwordx4 v[246:247], off
	s_waitcnt vmcnt(8) lgkmcnt(0)
	s_barrier
; #define PG8_STAGE(bufoff, gbase, voff) do { _Pragma("unroll") for (int _i = 0; _i < 2; ++_i) \
;         __builtin_amdgcn_global_load_lds((const unsigned*)((const char*)(gbase) + (voff)[_i]), (PG8_LAS unsigned*)(lds + (bufoff) + ldsw + _i * 8192), 16, 0, 0); } while (0)
; #define PG8_LDA(dst, b, h) do { _Pragma("unroll") for (int m = 0; m < 4; ++m) _Pragma("unroll") for (int k = 0; k < 2; ++k) dst[m][k] = *(const PG8_LAS bf16x8*)(lds + PG8_SA(b, h) + aoff + m * 2048 + k * 1024); } while (0)
; #define PG8_LDB(dst, b, h) do { _Pragma("unroll") for (int n = 0; n < 2; ++n) _Pragma("unroll") for (int k = 0; k < 2; ++k) dst[n][k] = *(const PG8_LAS bf16x8*)(lds + PG8_SB(b, h) + boff + n * 2048 + k * 1024); } while (0)
; #define PG8_MMA(ai, bj, At, Bt) do { __builtin_amdgcn_s_setprio(1); _Pragma("unroll") for (int m = 0; m < 4; ++m) _Pragma("unroll") for (int n = 0; n < 2; ++n) _Pragma("unroll") for (int k = 0; k < 2; ++k) \
;         acc[ai][bj][m][n] = __builtin_amdgcn_mfma_f32_16x16x32_bf16(Bt[n][k], At[m][k], acc[ai][bj][m][n], 0, 0, 0); __builtin_amdgcn_s_setprio(0); } while (0)
; #define PG8_WAIT_V(n) asm volatile("s_waitcnt vmcnt(" #n ")" ::: "memory")
; #define PG8_WAIT_L(n) asm volatile("s_waitcnt lgkmcnt(" #n ")" ::: "memory")
; #define PG8_BAR __builtin_amdgcn_s_barrier()
; #define PG8_SCHED __builtin_amdgcn_sched_barrier(0)
; template <class Epi, class Sched>
; __device__ __forceinline__ void gemm_phase(PG8_LAS unsigned char* lds, const Gemm g, const Sched& S, const Epi& E) {
;     ...
;             PG8_BAR; PG8_WAIT_L(0); PG8_MMA(1, 0, At, B0); PG8_BAR; PG8_SCHED;
;             PG8_STAGE(PG8_SB(0, 1), b2 + hstep, voffB);
;             PG8_WAIT_V(6); PG8_BAR; PG8_MMA(1, 1, At, B1); PG8_BAR;
;             PG8_LDB(B0, 1, 0); PG8_SCHED; PG8_LDA(At, 1, 0); PG8_STAGE(PG8_SA(0, 1), a2 + hstep, voffA);
;             PG8_WAIT_L(8); PG8_BAR; PG8_WAIT_L(0); PG8_MMA(0, 0, At, B0); PG8_BAR; PG8_SCHED;
;             PG8_LDB(B1, 1, 1); PG8_STAGE(PG8_SB(1, 0), b3, voffB);
;             PG8_BAR; PG8_WAIT_L(0); PG8_MMA(0, 1, At, B1); PG8_BAR;
	v_mfma_f32_16x16x32_bf16 v[60:63], v[144:147], v[168:171], v[60:63]
	v_mfma_f32_16x16x32_bf16 v[56:59], v[160:163], v[168:171], v[56:59]
	v_mfma_f32_16x16x32_bf16 v[48:51], v[144:147], v[182:185], v[48:51]
	v_mfma_f32_16x16x32_bf16 v[40:43], v[160:163], v[182:185], v[40:43]
	v_mfma_f32_16x16x32_bf16 v[32:35], v[144:147], v[194:197], v[32:35]
	v_mfma_f32_16x16x32_bf16 v[24:27], v[160:163], v[194:197], v[24:27]
	v_mfma_f32_16x16x32_bf16 v[16:19], v[144:147], v[202:205], v[16:19]
	v_mfma_f32_16x16x32_bf16 v[8:11], v[160:163], v[202:205], v[8:11]
	v_mfma_f32_16x16x32_bf16 v[60:63], v[156:159], v[172:175], v[60:63]
	v_mfma_f32_16x16x32_bf16 v[56:59], v[164:167], v[172:175], v[56:59]
	v_mfma_f32_16x16x32_bf16 v[48:51], v[156:159], v[190:193], v[48:51]
	v_mfma_f32_16x16x32_bf16 v[40:43], v[164:167], v[190:193], v[40:43]
	v_mfma_f32_16x16x32_bf16 v[32:35], v[156:159], v[198:201], v[32:35]
	v_mfma_f32_16x16x32_bf16 v[24:27], v[164:167], v[198:201], v[24:27]
	v_mfma_f32_16x16x32_bf16 v[16:19], v[156:159], v[206:209], v[16:19]
	v_mfma_f32_16x16x32_bf16 v[8:11], v[164:167], v[206:209], v[8:11]
	v_mfma_f32_16x16x32_bf16 v[52:55], v[210:213], v[168:171], v[52:55]
	v_mfma_f32_16x16x32_bf16 v[44:47], v[218:221], v[168:171], v[44:47]
	v_mfma_f32_16x16x32_bf16 v[36:39], v[210:213], v[182:185], v[36:39]
	v_mfma_f32_16x16x32_bf16 v[28:31], v[218:221], v[182:185], v[28:31]
	v_mfma_f32_16x16x32_bf16 v[20:23], v[210:213], v[194:197], v[20:23]
	v_mfma_f32_16x16x32_bf16 v[12:15], v[218:221], v[194:197], v[12:15]
	v_mfma_f32_16x16x32_bf16 v[4:7], v[210:213], v[202:205], v[4:7]
	v_mfma_f32_16x16x32_bf16 v[0:3], v[218:221], v[202:205], v[0:3]
	v_mfma_f32_16x16x32_bf16 v[52:55], v[214:217], v[172:175], v[52:55]
	v_mfma_f32_16x16x32_bf16 v[44:47], v[222:225], v[172:175], v[44:47]
	v_mfma_f32_16x16x32_bf16 v[36:39], v[214:217], v[190:193], v[36:39]
	v_mfma_f32_16x16x32_bf16 v[28:31], v[222:225], v[190:193], v[28:31]
	v_mfma_f32_16x16x32_bf16 v[20:23], v[214:217], v[198:201], v[20:23]
	v_mfma_f32_16x16x32_bf16 v[12:15], v[222:225], v[198:201], v[12:15]
	v_mfma_f32_16x16x32_bf16 v[4:7], v[214:217], v[206:209], v[4:7]
	v_mfma_f32_16x16x32_bf16 v[0:3], v[222:225], v[206:209], v[0:3]
	s_barrier
	s_add_i32 s48, 0, 0x18000
	v_add_u32_e32 v164, s48, v151
	ds_read_b128 v[144:147], v164
	ds_read_b128 v[156:159], v164 offset:1024
	ds_read_b128 v[160:163], v164 offset:2048
	ds_read_b128 v[164:167], v164 offset:3072
	s_add_u32 s22, s22, 0x40000
	s_addc_u32 s23, s23, 0
	s_mov_b32 m0, s31
	v_lshl_add_u64 v[210:211], s[22:23], 0, v[128:129]
	ds_read_b128 v[168:171], v154 offset:32768
	ds_read_b128 v[172:175], v154 offset:33792
	ds_read_b128 v[182:185], v154 offset:34816
	ds_read_b128 v[190:193], v154 offset:35840
	ds_read_b128 v[194:197], v154 offset:36864
	ds_read_b128 v[198:201], v154 offset:37888
	ds_read_b128 v[202:205], v154 offset:38912
	ds_read_b128 v[206:209], v154 offset:39936
	global_load_lds_dwordx4 v[210:211], off
	v_lshl_add_u64 v[210:211], s[22:23], 0, v[132:133]
	s_mov_b32 m0, s34
	s_nop 0
	global_load_lds_dwordx4 v[210:211], off
	s_add_i32 s22, 0, 0x1c000
	v_add_u32_e32 v179, s22, v151
	s_waitcnt lgkmcnt(8)
	ds_read_b128 v[210:213], v179
	ds_read_b128 v[214:217], v179 offset:1024
	ds_read_b128 v[218:221], v179 offset:2048
	ds_read_b128 v[222:225], v179 offset:3072
	s_waitcnt vmcnt(8) lgkmcnt(0)
	s_barrier
	v_mfma_f32_16x16x32_bf16 v[124:127], v[144:147], v[168:171], v[124:127]
	v_mfma_f32_16x16x32_bf16 v[120:123], v[160:163], v[168:171], v[120:123]
	v_mfma_f32_16x16x32_bf16 v[112:115], v[144:147], v[182:185], v[112:115]
	v_mfma_f32_16x16x32_bf16 v[104:107], v[160:163], v[182:185], v[104:107]
	v_mfma_f32_16x16x32_bf16 v[96:99], v[144:147], v[194:197], v[96:99]
	v_mfma_f32_16x16x32_bf16 v[88:91], v[160:163], v[194:197], v[88:91]
	v_mfma_f32_16x16x32_bf16 v[80:83], v[144:147], v[202:205], v[80:83]
	v_mfma_f32_16x16x32_bf16 v[72:75], v[160:163], v[202:205], v[72:75]
	v_mfma_f32_16x16x32_bf16 v[124:127], v[156:159], v[172:175], v[124:127]
	v_mfma_f32_16x16x32_bf16 v[120:123], v[164:167], v[172:175], v[120:123]
	v_mfma_f32_16x16x32_bf16 v[112:115], v[156:159], v[190:193], v[112:115]
	v_mfma_f32_16x16x32_bf16 v[104:107], v[164:167], v[190:193], v[104:107]
	v_mfma_f32_16x16x32_bf16 v[96:99], v[156:159], v[198:201], v[96:99]
	v_mfma_f32_16x16x32_bf16 v[88:91], v[164:167], v[198:201], v[88:91]
	v_mfma_f32_16x16x32_bf16 v[80:83], v[156:159], v[206:209], v[80:83]
	v_mfma_f32_16x16x32_bf16 v[72:75], v[164:167], v[206:209], v[72:75]
	v_mfma_f32_16x16x32_bf16 v[116:119], v[210:213], v[168:171], v[116:119]
	v_mfma_f32_16x16x32_bf16 v[108:111], v[218:221], v[168:171], v[108:111]
	v_mfma_f32_16x16x32_bf16 v[100:103], v[210:213], v[182:185], v[100:103]
	v_mfma_f32_16x16x32_bf16 v[92:95], v[218:221], v[182:185], v[92:95]
	v_mfma_f32_16x16x32_bf16 v[84:87], v[210:213], v[194:197], v[84:87]
	v_mfma_f32_16x16x32_bf16 v[76:79], v[218:221], v[194:197], v[76:79]
	v_mfma_f32_16x16x32_bf16 v[68:71], v[210:213], v[202:205], v[68:71]
	v_mfma_f32_16x16x32_bf16 v[64:67], v[218:221], v[202:205], v[64:67]
	v_mfma_f32_16x16x32_bf16 v[116:119], v[214:217], v[172:175], v[116:119]
	v_mfma_f32_16x16x32_bf16 v[108:111], v[222:225], v[172:175], v[108:111]
	v_mfma_f32_16x16x32_bf16 v[100:103], v[214:217], v[190:193], v[100:103]
	v_mfma_f32_16x16x32_bf16 v[92:95], v[222:225], v[190:193], v[92:95]
	v_mfma_f32_16x16x32_bf16 v[84:87], v[214:217], v[198:201], v[84:87]
	v_mfma_f32_16x16x32_bf16 v[76:79], v[222:225], v[198:201], v[76:79]
	v_mfma_f32_16x16x32_bf16 v[68:71], v[214:217], v[206:209], v[68:71]
	v_mfma_f32_16x16x32_bf16 v[64:67], v[222:225], v[206:209], v[64:67]
	s_barrier
; __device__ __forceinline__ float bf_lo(unsigned u) { return __uint_as_float(u << 16); }
; __device__ __forceinline__ float bf_hi(unsigned u) { return __uint_as_float(u & 0xffff0000u); }
; #define PG8_STAGE(bufoff, gbase, voff) do { _Pragma("unroll") for (int _i = 0; _i < 2; ++_i) \
;         __builtin_amdgcn_global_load_lds((const unsigned*)((const char*)(gbase) + (voff)[_i]), (PG8_LAS unsigned*)(lds + (bufoff) + ldsw + _i * 8192), 16, 0, 0); } while (0)
; #define PG8_LDA(dst, b, h) do { _Pragma("unroll") for (int m = 0; m < 4; ++m) _Pragma("unroll") for (int k = 0; k < 2; ++k) dst[m][k] = *(const PG8_LAS bf16x8*)(lds + PG8_SA(b, h) + aoff + m * 2048 + k * 1024); } while (0)
; #define PG8_MMA(ai, bj, At, Bt) do { __builtin_amdgcn_s_setprio(1); _Pragma("unroll") for (int m = 0; m < 4; ++m) _Pragma("unroll") for (int n = 0; n < 2; ++n) _Pragma("unroll") for (int k = 0; k < 2; ++k) \
;         acc[ai][bj][m][n] = __builtin_amdgcn_mfma_f32_16x16x32_bf16(Bt[n][k], At[m][k], acc[ai][bj][m][n], 0, 0, 0); __builtin_amdgcn_s_setprio(0); } while (0)
; #define PG8_WAIT_V(n) asm volatile("s_waitcnt vmcnt(" #n ")" ::: "memory")
; #define PG8_WAIT_L(n) asm volatile("s_waitcnt lgkmcnt(" #n ")" ::: "memory")
;     __device__ __forceinline__ void operator()(const f32x4 (&acc)[2][2][4][2], const Unit& u, int wr, int wc, int fr, int fq) const {
;     ...
;             for (int m = 0; m < 4; ++m) { const size_t r = (size_t)(row0 + ai * HALF + m * 16); bf16_t* rowp = O + r * ldc + col0; const bf16_t* gp = G + r * ldg + col0;
; #pragma unroll
;                 for (int bj = 0; bj < 2; ++bj) { const u32x4 gw = *(const u32x4*)(gp + bj * HALF);
;                     f32x4 v0 = acc[ai][bj][m][0], v1 = acc[ai][bj][m][1];
;                     v0[0] *= bf_lo(gw.x); v0[1] *= bf_hi(gw.x); v0[2] *= bf_lo(gw.y); v0[3] *= bf_hi(gw.y);
;                     v1[0] *= bf_lo(gw.z); v1[1] *= bf_hi(gw.z); v1[2] *= bf_lo(gw.w); v1[3] *= bf_hi(gw.w);
; template <class Epi, class Sched>
; __device__ __forceinline__ void gemm_phase(PG8_LAS unsigned char* lds, const Gemm g, const Sched& S, const Epi& E) {
;     ...
;             PG8_LDA(At, 1, 1); PG8_STAGE(PG8_SA(1, 0), a3, voffA);
;             PG8_BAR; PG8_WAIT_L(0); PG8_MMA(1, 0, At, B0); PG8_BAR; PG8_SCHED;
;             PG8_STAGE(PG8_SB(1, 1), b3 + hstep, voffB);
;             PG8_WAIT_V(6); PG8_BAR; PG8_MMA(1, 1, At, B1); PG8_BAR;
	ds_read_b128 v[168:171], v154 offset:49152
	ds_read_b128 v[172:175], v154 offset:50176
	ds_read_b128 v[182:185], v154 offset:51200
	ds_read_b128 v[190:193], v154 offset:52224
	ds_read_b128 v[194:197], v154 offset:53248
	ds_read_b128 v[198:201], v154 offset:54272
	ds_read_b128 v[202:205], v154 offset:55296
	ds_read_b128 v[206:209], v154 offset:56320
	s_add_i32 s23, s48, s29
	v_lshl_add_u64 v[148:149], v[148:149], 0, s[6:7]
	s_mov_b32 m0, s23
	s_nop 0
	global_load_lds_dwordx4 v[148:149], off
	v_lshl_add_u64 v[148:149], v[186:187], 0, s[6:7]
	s_add_i32 m0, s23, 0x2000
	s_nop 0
	global_load_lds_dwordx4 v[148:149], off
	s_nop 1
	s_mov_b32 m0, s36
	v_lshl_add_u64 v[148:149], v[226:227], 0, s[6:7]
	global_load_lds_dwordx4 v[148:149], off
	v_lshl_add_u64 v[148:149], v[228:229], 0, s[6:7]
	s_mov_b32 m0, s37
	s_nop 0
	global_load_lds_dwordx4 v[148:149], off
	s_add_u32 s20, s20, 0x40080
	s_addc_u32 s21, s21, 0
	s_add_i32 s22, s22, s29
	v_lshl_add_u64 v[246:247], s[20:21], 0, v[130:131]
	s_mov_b32 m0, s22
	s_nop 0
	global_load_lds_dwordx4 v[246:247], off
	v_lshl_add_u64 v[246:247], s[20:21], 0, v[134:135]
	s_add_i32 m0, s22, 0x2000
	s_nop 0
	global_load_lds_dwordx4 v[246:247], off
	s_waitcnt vmcnt(8) lgkmcnt(0)
	s_barrier
	v_mfma_f32_16x16x32_bf16 v[60:63], v[144:147], v[168:171], v[60:63]
	v_mfma_f32_16x16x32_bf16 v[56:59], v[160:163], v[168:171], v[56:59]
	v_mfma_f32_16x16x32_bf16 v[48:51], v[144:147], v[182:185], v[48:51]
	v_mfma_f32_16x16x32_bf16 v[40:43], v[160:163], v[182:185], v[40:43]
	v_mfma_f32_16x16x32_bf16 v[32:35], v[144:147], v[194:197], v[32:35]
	v_mfma_f32_16x16x32_bf16 v[24:27], v[160:163], v[194:197], v[24:27]
	v_mfma_f32_16x16x32_bf16 v[16:19], v[144:147], v[202:205], v[16:19]
	v_mfma_f32_16x16x32_bf16 v[8:11], v[160:163], v[202:205], v[8:11]
	v_mfma_f32_16x16x32_bf16 v[60:63], v[156:159], v[172:175], v[60:63]
	v_mfma_f32_16x16x32_bf16 v[56:59], v[164:167], v[172:175], v[56:59]
	v_mfma_f32_16x16x32_bf16 v[48:51], v[156:159], v[190:193], v[48:51]
	v_mfma_f32_16x16x32_bf16 v[40:43], v[164:167], v[190:193], v[40:43]
	v_mfma_f32_16x16x32_bf16 v[32:35], v[156:159], v[198:201], v[32:35]
	v_mfma_f32_16x16x32_bf16 v[24:27], v[164:167], v[198:201], v[24:27]
	v_mfma_f32_16x16x32_bf16 v[16:19], v[156:159], v[206:209], v[16:19]
	v_mfma_f32_16x16x32_bf16 v[8:11], v[164:167], v[206:209], v[8:11]
	v_mfma_f32_16x16x32_bf16 v[52:55], v[210:213], v[168:171], v[52:55]
	v_mfma_f32_16x16x32_bf16 v[44:47], v[218:221], v[168:171], v[44:47]
	v_mfma_f32_16x16x32_bf16 v[36:39], v[210:213], v[182:185], v[36:39]
	v_mfma_f32_16x16x32_bf16 v[28:31], v[218:221], v[182:185], v[28:31]
	v_mfma_f32_16x16x32_bf16 v[20:23], v[210:213], v[194:197], v[20:23]
	v_mfma_f32_16x16x32_bf16 v[12:15], v[218:221], v[194:197], v[12:15]
	v_mfma_f32_16x16x32_bf16 v[4:7], v[210:213], v[202:205], v[4:7]
	v_mfma_f32_16x16x32_bf16 v[0:3], v[218:221], v[202:205], v[0:3]
	v_mfma_f32_16x16x32_bf16 v[52:55], v[214:217], v[172:175], v[52:55]
	v_mfma_f32_16x16x32_bf16 v[44:47], v[222:225], v[172:175], v[44:47]
	v_mfma_f32_16x16x32_bf16 v[36:39], v[214:217], v[190:193], v[36:39]
	v_mfma_f32_16x16x32_bf16 v[28:31], v[222:225], v[190:193], v[28:31]
	v_mfma_f32_16x16x32_bf16 v[20:23], v[214:217], v[198:201], v[20:23]
	v_mfma_f32_16x16x32_bf16 v[12:15], v[222:225], v[198:201], v[12:15]
	v_mfma_f32_16x16x32_bf16 v[4:7], v[214:217], v[206:209], v[4:7]
	v_mfma_f32_16x16x32_bf16 v[0:3], v[222:225], v[206:209], v[0:3]
	s_barrier
	s_add_i32 s47, s47, 2
	s_add_u32 s18, s18, 0x100
	s_addc_u32 s19, s19, 0
	s_add_u32 s45, s45, 0x100
	s_addc_u32 s46, s46, 0
	s_cmp_gt_u32 s47, 13
	s_cbranch_scc0 .LBB0_991
	v_lshl_or_b32 v144, s42, 8, v152
	v_lshl_add_u32 v146, s16, 8, v150
	v_ashrrev_i32_e32 v145, 31, v144
	v_mov_b64_e32 v[148:149], s[4:5]
	v_lshlrev_b64 v[144:145], 1, v[144:145]
	v_mad_i64_i32 v[156:157], s[18:19], v146, s41, v[148:149]
	v_lshl_add_u64 v[160:161], v[156:157], 0, v[144:145]
	global_load_dwordx4 v[156:159], v[160:161], off offset:3072
	s_and_b64 vcc, exec, s[2:3]
	s_mov_b32 s42, s8
	s_mov_b32 s16, s10
	s_mov_b64 s[20:21], s[14:15]
	s_waitcnt vmcnt(0)
	v_lshlrev_b32_e32 v147, 16, v156
	v_and_b32_e32 v156, 0xffff0000, v156
	v_lshlrev_b32_e32 v162, 16, v157
	v_and_b32_e32 v157, 0xffff0000, v157
	v_lshlrev_b32_e32 v164, 16, v159
	v_and_b32_e32 v159, 0xffff0000, v159
	v_lshlrev_b32_e32 v163, 16, v158
	v_and_b32_e32 v158, 0xffff0000, v158
	v_mul_f32_e32 v124, v124, v147
	v_mul_f32_e32 v125, v125, v156
	v_mul_f32_e32 v126, v126, v162
	v_mul_f32_e32 v127, v127, v157
	v_mul_f32_e32 v123, v123, v159
	v_mul_f32_e32 v147, v120, v163
	v_mul_f32_e32 v156, v121, v158
	v_mul_f32_e32 v157, v122, v164
	v_cvt_pk_bf16_f32 v120, v124, v125
	v_cvt_pk_bf16_f32 v121, v126, v127
	v_cvt_pk_bf16_f32 v122, v147, v156
	v_cvt_pk_bf16_f32 v123, v157, v123
	global_load_dwordx4 v[124:127], v[160:161], off offset:3328
	v_ashrrev_i32_e32 v147, 31, v146
	v_lshlrev_b64 v[158:159], 11, v[146:147]
	v_lshl_add_u64 v[158:159], s[0:1], 0, v[158:159]
	v_or_b32_e32 v156, 16, v146
	v_lshl_add_u64 v[158:159], v[158:159], 0, v[144:145]
	v_mad_i64_i32 v[160:161], s[18:19], v156, s41, v[148:149]
	global_store_dwordx4 v[158:159], v[120:123], off
	v_lshl_add_u64 v[160:161], v[160:161], 0, v[144:145]
	v_ashrrev_i32_e32 v157, 31, v156
	s_waitcnt vmcnt(0)
; __device__ __forceinline__ unsigned cvt_pk_bf16(float lo, float hi) { unsigned r; asm volatile("v_cvt_pk_bf16_f32 %0, %1, %2" : "=v"(r) : "v"(lo), "v"(hi)); return r; }
; __device__ __forceinline__ float bf_lo(unsigned u) { return __uint_as_float(u << 16); }
; __device__ __forceinline__ float bf_hi(unsigned u) { return __uint_as_float(u & 0xffff0000u); }
;     __device__ __forceinline__ void operator()(const f32x4 (&acc)[2][2][4][2], const Unit& u, int wr, int wc, int fr, int fq) const {
;     ...
;             for (int m = 0; m < 4; ++m) { const size_t r = (size_t)(row0 + ai * HALF + m * 16); bf16_t* rowp = O + r * ldc + col0; const bf16_t* gp = G + r * ldg + col0;
; #pragma unroll
;                 for (int bj = 0; bj < 2; ++bj) { const u32x4 gw = *(const u32x4*)(gp + bj * HALF);
;                     f32x4 v0 = acc[ai][bj][m][0], v1 = acc[ai][bj][m][1];
;                     v0[0] *= bf_lo(gw.x); v0[1] *= bf_hi(gw.x); v0[2] *= bf_lo(gw.y); v0[3] *= bf_hi(gw.y);
;                     v1[0] *= bf_lo(gw.z); v1[1] *= bf_hi(gw.z); v1[2] *= bf_lo(gw.w); v1[3] *= bf_hi(gw.w);
;                     if (ACCUM) { const u32x4 pw = *(const u32x4*)(rowp + bj * HALF);
;                         v0[0] += bf_lo(pw.x); v0[1] += bf_hi(pw.x); v0[2] += bf_lo(pw.y); v0[3] += bf_hi(pw.y);
;                         v1[0] += bf_lo(pw.z); v1[1] += bf_hi(pw.z); v1[2] += bf_lo(pw.w); v1[3] += bf_hi(pw.w); }
;                     u32x4 w; w.x = cvt_pk_bf16(v0[0], v0[1]); w.y = cvt_pk_bf16(v0[2], v0[3]); w.z = cvt_pk_bf16(v1[0], v1[1]); w.w = cvt_pk_bf16(v1[2], v1[3]);
;                     *(u32x4*)(rowp + bj * HALF) = w; } }
	v_lshlrev_b32_e32 v120, 16, v124
	v_and_b32_e32 v121, 0xffff0000, v124
	v_lshlrev_b32_e32 v122, 16, v125
	v_and_b32_e32 v123, 0xffff0000, v125
	v_lshlrev_b32_e32 v124, 16, v126
	v_and_b32_e32 v125, 0xffff0000, v126
	v_lshlrev_b32_e32 v126, 16, v127
	v_and_b32_e32 v127, 0xffff0000, v127
	v_mul_f32_e32 v116, v116, v120
	v_mul_f32_e32 v117, v117, v121
	v_mul_f32_e32 v118, v118, v122
	v_mul_f32_e32 v119, v119, v123
	v_mul_f32_e32 v111, v111, v127
	v_mul_f32_e32 v120, v108, v124
	v_mul_f32_e32 v121, v109, v125
	v_mul_f32_e32 v122, v110, v126
	v_cvt_pk_bf16_f32 v108, v116, v117
	v_cvt_pk_bf16_f32 v109, v118, v119
	v_cvt_pk_bf16_f32 v110, v120, v121
	v_cvt_pk_bf16_f32 v111, v122, v111
	global_load_dwordx4 v[116:119], v[160:161], off offset:3072
	s_nop 0
	global_store_dwordx4 v[158:159], v[108:111], off offset:256
	s_waitcnt vmcnt(0)
	s_nop 0
	v_lshlrev_b32_e32 v108, 16, v116
	v_and_b32_e32 v109, 0xffff0000, v116
	v_lshlrev_b32_e32 v110, 16, v117
	v_and_b32_e32 v111, 0xffff0000, v117
	v_lshlrev_b32_e32 v116, 16, v118
	v_and_b32_e32 v117, 0xffff0000, v118
	v_lshlrev_b32_e32 v118, 16, v119
	v_and_b32_e32 v119, 0xffff0000, v119
	v_mul_f32_e32 v108, v112, v108
	v_mul_f32_e32 v109, v113, v109
	v_mul_f32_e32 v110, v114, v110
	v_mul_f32_e32 v111, v115, v111
	v_mul_f32_e32 v107, v107, v119
	v_mul_f32_e32 v112, v104, v116
	v_mul_f32_e32 v113, v105, v117
	v_mul_f32_e32 v114, v106, v118
	v_cvt_pk_bf16_f32 v104, v108, v109
	v_cvt_pk_bf16_f32 v105, v110, v111
	v_cvt_pk_bf16_f32 v106, v112, v113
	v_cvt_pk_bf16_f32 v107, v114, v107
	global_load_dwordx4 v[108:111], v[160:161], off offset:3328
	v_lshlrev_b64 v[116:117], 11, v[156:157]
	v_lshl_add_u64 v[116:117], s[0:1], 0, v[116:117]
	v_or_b32_e32 v112, 32, v146
	v_lshl_add_u64 v[116:117], v[116:117], 0, v[144:145]
	v_mad_i64_i32 v[114:115], s[18:19], v112, s41, v[148:149]
	global_store_dwordx4 v[116:117], v[104:107], off
	v_lshl_add_u64 v[114:115], v[114:115], 0, v[144:145]
	v_ashrrev_i32_e32 v113, 31, v112
	s_waitcnt vmcnt(0)
	v_lshlrev_b32_e32 v104, 16, v108
	v_and_b32_e32 v105, 0xffff0000, v108
	v_lshlrev_b32_e32 v106, 16, v109
	v_and_b32_e32 v107, 0xffff0000, v109
	v_lshlrev_b32_e32 v108, 16, v110
	v_and_b32_e32 v109, 0xffff0000, v110
	v_lshlrev_b32_e32 v110, 16, v111
	v_and_b32_e32 v111, 0xffff0000, v111
	v_mul_f32_e32 v100, v100, v104
	v_mul_f32_e32 v101, v101, v105
	v_mul_f32_e32 v102, v102, v106
	v_mul_f32_e32 v103, v103, v107
	v_mul_f32_e32 v95, v95, v111
	v_mul_f32_e32 v104, v92, v108
	v_mul_f32_e32 v105, v93, v109
	v_mul_f32_e32 v106, v94, v110
	v_cvt_pk_bf16_f32 v92, v100, v101
	v_cvt_pk_bf16_f32 v93, v102, v103
	v_cvt_pk_bf16_f32 v94, v104, v105
	v_cvt_pk_bf16_f32 v95, v106, v95
	global_load_dwordx4 v[100:103], v[114:115], off offset:3072
	s_nop 0
	global_store_dwordx4 v[116:117], v[92:95], off offset:256
	s_waitcnt vmcnt(0)
	s_nop 0
	v_lshlrev_b32_e32 v92, 16, v100
	v_and_b32_e32 v93, 0xffff0000, v100
	v_lshlrev_b32_e32 v94, 16, v101
	v_and_b32_e32 v95, 0xffff0000, v101
	v_lshlrev_b32_e32 v100, 16, v102
	v_and_b32_e32 v101, 0xffff0000, v102
	v_lshlrev_b32_e32 v102, 16, v103
	v_and_b32_e32 v103, 0xffff0000, v103
	v_mul_f32_e32 v92, v96, v92
	v_mul_f32_e32 v93, v97, v93
	v_mul_f32_e32 v94, v98, v94
	v_mul_f32_e32 v95, v99, v95
	v_mul_f32_e32 v91, v91, v103
	v_mul_f32_e32 v96, v88, v100
	v_mul_f32_e32 v97, v89, v101
	v_mul_f32_e32 v98, v90, v102
	v_cvt_pk_bf16_f32 v88, v92, v93
	v_cvt_pk_bf16_f32 v89, v94, v95
	v_cvt_pk_bf16_f32 v90, v96, v97
	v_cvt_pk_bf16_f32 v91, v98, v91
	global_load_dwordx4 v[92:95], v[114:115], off offset:3328
	v_lshlrev_b64 v[100:101], 11, v[112:113]
	v_lshl_add_u64 v[100:101], s[0:1], 0, v[100:101]
	v_or_b32_e32 v96, 48, v146
	v_lshl_add_u64 v[100:101], v[100:101], 0, v[144:145]
	v_mad_i64_i32 v[98:99], s[18:19], v96, s41, v[148:149]
	global_store_dwordx4 v[100:101], v[88:91], off
	v_lshl_add_u64 v[98:99], v[98:99], 0, v[144:145]
	v_ashrrev_i32_e32 v97, 31, v96
	s_waitcnt vmcnt(0)
	v_lshlrev_b32_e32 v88, 16, v92
	v_and_b32_e32 v89, 0xffff0000, v92
	v_lshlrev_b32_e32 v90, 16, v93
	v_and_b32_e32 v91, 0xffff0000, v93
	v_lshlrev_b32_e32 v92, 16, v94
	v_and_b32_e32 v93, 0xffff0000, v94
	v_lshlrev_b32_e32 v94, 16, v95
	v_and_b32_e32 v95, 0xffff0000, v95
	v_mul_f32_e32 v84, v84, v88
	v_mul_f32_e32 v85, v85, v89
	v_mul_f32_e32 v86, v86, v90
	v_mul_f32_e32 v87, v87, v91
	v_mul_f32_e32 v79, v79, v95
	v_mul_f32_e32 v88, v76, v92
	v_mul_f32_e32 v89, v77, v93
	v_mul_f32_e32 v90, v78, v94
	v_cvt_pk_bf16_f32 v76, v84, v85
	v_cvt_pk_bf16_f32 v77, v86, v87
	v_cvt_pk_bf16_f32 v78, v88, v89
	v_cvt_pk_bf16_f32 v79, v90, v79
	global_load_dwordx4 v[84:87], v[98:99], off offset:3072
	s_nop 0
	global_store_dwordx4 v[100:101], v[76:79], off offset:256
	s_waitcnt vmcnt(0)
	s_nop 0
	v_lshlrev_b32_e32 v76, 16, v84
	v_and_b32_e32 v77, 0xffff0000, v84
	v_lshlrev_b32_e32 v78, 16, v85
	v_and_b32_e32 v79, 0xffff0000, v85
	v_lshlrev_b32_e32 v84, 16, v86
	v_and_b32_e32 v85, 0xffff0000, v86
	v_lshlrev_b32_e32 v86, 16, v87
	v_and_b32_e32 v87, 0xffff0000, v87
	v_mul_f32_e32 v76, v80, v76
	v_mul_f32_e32 v77, v81, v77
	v_mul_f32_e32 v78, v82, v78
	v_mul_f32_e32 v79, v83, v79
	v_mul_f32_e32 v75, v75, v87
	v_mul_f32_e32 v80, v72, v84
	v_mul_f32_e32 v81, v73, v85
	v_mul_f32_e32 v82, v74, v86
	v_cvt_pk_bf16_f32 v72, v76, v77
	v_cvt_pk_bf16_f32 v73, v78, v79
	v_cvt_pk_bf16_f32 v74, v80, v81
	v_cvt_pk_bf16_f32 v75, v82, v75
	global_load_dwordx4 v[76:79], v[98:99], off offset:3328
	v_lshlrev_b64 v[84:85], 11, v[96:97]
	v_lshl_add_u64 v[84:85], s[0:1], 0, v[84:85]
	v_add_u32_e32 v80, 0x80, v146
	v_lshl_add_u64 v[84:85], v[84:85], 0, v[144:145]
	v_mad_i64_i32 v[82:83], s[18:19], v80, s41, v[148:149]
	global_store_dwordx4 v[84:85], v[72:75], off
	v_lshl_add_u64 v[82:83], v[82:83], 0, v[144:145]
	v_ashrrev_i32_e32 v81, 31, v80
	s_waitcnt vmcnt(0)
; __device__ __forceinline__ unsigned cvt_pk_bf16(float lo, float hi) { unsigned r; asm volatile("v_cvt_pk_bf16_f32 %0, %1, %2" : "=v"(r) : "v"(lo), "v"(hi)); return r; }
; __device__ __forceinline__ float bf_lo(unsigned u) { return __uint_as_float(u << 16); }
; __device__ __forceinline__ float bf_hi(unsigned u) { return __uint_as_float(u & 0xffff0000u); }
;     __device__ __forceinline__ void operator()(const f32x4 (&acc)[2][2][4][2], const Unit& u, int wr, int wc, int fr, int fq) const {
;     ...
;             for (int m = 0; m < 4; ++m) { const size_t r = (size_t)(row0 + ai * HALF + m * 16); bf16_t* rowp = O + r * ldc + col0; const bf16_t* gp = G + r * ldg + col0;
; #pragma unroll
;                 for (int bj = 0; bj < 2; ++bj) { const u32x4 gw = *(const u32x4*)(gp + bj * HALF);
;                     f32x4 v0 = acc[ai][bj][m][0], v1 = acc[ai][bj][m][1];
;                     v0[0] *= bf_lo(gw.x); v0[1] *= bf_hi(gw.x); v0[2] *= bf_lo(gw.y); v0[3] *= bf_hi(gw.y);
;                     v1[0] *= bf_lo(gw.z); v1[1] *= bf_hi(gw.z); v1[2] *= bf_lo(gw.w); v1[3] *= bf_hi(gw.w);
;                     if (ACCUM) { const u32x4 pw = *(const u32x4*)(rowp + bj * HALF);
;                         v0[0] += bf_lo(pw.x); v0[1] += bf_hi(pw.x); v0[2] += bf_lo(pw.y); v0[3] += bf_hi(pw.y);
;                         v1[0] += bf_lo(pw.z); v1[1] += bf_hi(pw.z); v1[2] += bf_lo(pw.w); v1[3] += bf_hi(pw.w); }
;                     u32x4 w; w.x = cvt_pk_bf16(v0[0], v0[1]); w.y = cvt_pk_bf16(v0[2], v0[3]); w.z = cvt_pk_bf16(v1[0], v1[1]); w.w = cvt_pk_bf16(v1[2], v1[3]);
;                     *(u32x4*)(rowp + bj * HALF) = w; } }
	v_lshlrev_b32_e32 v72, 16, v76
	v_and_b32_e32 v73, 0xffff0000, v76
	v_lshlrev_b32_e32 v74, 16, v77
	v_and_b32_e32 v75, 0xffff0000, v77
	v_lshlrev_b32_e32 v76, 16, v78
	v_and_b32_e32 v77, 0xffff0000, v78
	v_lshlrev_b32_e32 v78, 16, v79
	v_and_b32_e32 v79, 0xffff0000, v79
	v_mul_f32_e32 v68, v68, v72
	v_mul_f32_e32 v69, v69, v73
	v_mul_f32_e32 v70, v70, v74
	v_mul_f32_e32 v71, v71, v75
	v_mul_f32_e32 v67, v67, v79
	v_mul_f32_e32 v72, v64, v76
	v_mul_f32_e32 v73, v65, v77
	v_mul_f32_e32 v74, v66, v78
	v_cvt_pk_bf16_f32 v64, v68, v69
	v_cvt_pk_bf16_f32 v65, v70, v71
	v_cvt_pk_bf16_f32 v66, v72, v73
	v_cvt_pk_bf16_f32 v67, v74, v67
	global_load_dwordx4 v[68:71], v[82:83], off offset:3072
	s_nop 0
	global_store_dwordx4 v[84:85], v[64:67], off offset:256
	s_waitcnt vmcnt(0)
	s_nop 0
	v_lshlrev_b32_e32 v64, 16, v68
	v_and_b32_e32 v65, 0xffff0000, v68
	v_lshlrev_b32_e32 v66, 16, v69
	v_and_b32_e32 v67, 0xffff0000, v69
	v_lshlrev_b32_e32 v68, 16, v70
	v_and_b32_e32 v69, 0xffff0000, v70
	v_lshlrev_b32_e32 v70, 16, v71
	v_and_b32_e32 v71, 0xffff0000, v71
	v_mul_f32_e32 v60, v60, v64
	v_mul_f32_e32 v61, v61, v65
	v_mul_f32_e32 v62, v62, v66
	v_mul_f32_e32 v63, v63, v67
	v_mul_f32_e32 v59, v59, v71
	v_mul_f32_e32 v64, v56, v68
	v_mul_f32_e32 v65, v57, v69
	v_mul_f32_e32 v66, v58, v70
	v_cvt_pk_bf16_f32 v56, v60, v61
	v_cvt_pk_bf16_f32 v57, v62, v63
	v_cvt_pk_bf16_f32 v58, v64, v65
	v_cvt_pk_bf16_f32 v59, v66, v59
	global_load_dwordx4 v[60:63], v[82:83], off offset:3328
	v_lshlrev_b64 v[68:69], 11, v[80:81]
	v_lshl_add_u64 v[68:69], s[0:1], 0, v[68:69]
	v_add_u32_e32 v64, 0x90, v146
	v_lshl_add_u64 v[68:69], v[68:69], 0, v[144:145]
	v_mad_i64_i32 v[66:67], s[18:19], v64, s41, v[148:149]
	global_store_dwordx4 v[68:69], v[56:59], off
	v_lshl_add_u64 v[66:67], v[66:67], 0, v[144:145]
	v_ashrrev_i32_e32 v65, 31, v64
	s_waitcnt vmcnt(0)
	v_lshlrev_b32_e32 v56, 16, v60
	v_and_b32_e32 v57, 0xffff0000, v60
	v_lshlrev_b32_e32 v58, 16, v61
	v_and_b32_e32 v59, 0xffff0000, v61
	v_lshlrev_b32_e32 v60, 16, v62
	v_and_b32_e32 v61, 0xffff0000, v62
	v_lshlrev_b32_e32 v62, 16, v63
	v_and_b32_e32 v63, 0xffff0000, v63
	v_mul_f32_e32 v52, v52, v56
	v_mul_f32_e32 v53, v53, v57
	v_mul_f32_e32 v54, v54, v58
	v_mul_f32_e32 v55, v55, v59
	v_mul_f32_e32 v47, v47, v63
	v_mul_f32_e32 v56, v44, v60
	v_mul_f32_e32 v57, v45, v61
	v_mul_f32_e32 v58, v46, v62
	v_cvt_pk_bf16_f32 v44, v52, v53
	v_cvt_pk_bf16_f32 v45, v54, v55
	v_cvt_pk_bf16_f32 v46, v56, v57
	v_cvt_pk_bf16_f32 v47, v58, v47
	global_load_dwordx4 v[52:55], v[66:67], off offset:3072
	s_nop 0
	global_store_dwordx4 v[68:69], v[44:47], off offset:256
	s_waitcnt vmcnt(0)
	s_nop 0
	v_lshlrev_b32_e32 v44, 16, v52
	v_and_b32_e32 v45, 0xffff0000, v52
	v_lshlrev_b32_e32 v46, 16, v53
	v_and_b32_e32 v47, 0xffff0000, v53
	v_lshlrev_b32_e32 v52, 16, v54
	v_and_b32_e32 v53, 0xffff0000, v54
	v_lshlrev_b32_e32 v54, 16, v55
	v_and_b32_e32 v55, 0xffff0000, v55
	v_mul_f32_e32 v44, v48, v44
	v_mul_f32_e32 v45, v49, v45
	v_mul_f32_e32 v46, v50, v46
	v_mul_f32_e32 v47, v51, v47
	v_mul_f32_e32 v43, v43, v55
	v_mul_f32_e32 v48, v40, v52
	v_mul_f32_e32 v49, v41, v53
	v_mul_f32_e32 v50, v42, v54
	v_cvt_pk_bf16_f32 v40, v44, v45
	v_cvt_pk_bf16_f32 v41, v46, v47
	v_cvt_pk_bf16_f32 v42, v48, v49
	v_cvt_pk_bf16_f32 v43, v50, v43
	global_load_dwordx4 v[44:47], v[66:67], off offset:3328
	v_lshlrev_b64 v[52:53], 11, v[64:65]
	v_lshl_add_u64 v[52:53], s[0:1], 0, v[52:53]
	v_add_u32_e32 v48, 0xa0, v146
	v_lshl_add_u64 v[52:53], v[52:53], 0, v[144:145]
	v_mad_i64_i32 v[50:51], s[18:19], v48, s41, v[148:149]
	global_store_dwordx4 v[52:53], v[40:43], off
	v_lshl_add_u64 v[50:51], v[50:51], 0, v[144:145]
	v_ashrrev_i32_e32 v49, 31, v48
	s_waitcnt vmcnt(0)
; __device__ __forceinline__ unsigned cvt_pk_bf16(float lo, float hi) { unsigned r; asm volatile("v_cvt_pk_bf16_f32 %0, %1, %2" : "=v"(r) : "v"(lo), "v"(hi)); return r; }
; __device__ __forceinline__ float bf_lo(unsigned u) { return __uint_as_float(u << 16); }
; __device__ __forceinline__ float bf_hi(unsigned u) { return __uint_as_float(u & 0xffff0000u); }
; #define PG8_WAIT_V(n) asm volatile("s_waitcnt vmcnt(" #n ")" ::: "memory")
;     __device__ __forceinline__ void operator()(const f32x4 (&acc)[2][2][4][2], const Unit& u, int wr, int wc, int fr, int fq) const {
;     ...
;             for (int m = 0; m < 4; ++m) { const size_t r = (size_t)(row0 + ai * HALF + m * 16); bf16_t* rowp = O + r * ldc + col0; const bf16_t* gp = G + r * ldg + col0;
; #pragma unroll
;                 for (int bj = 0; bj < 2; ++bj) { const u32x4 gw = *(const u32x4*)(gp + bj * HALF);
;                     f32x4 v0 = acc[ai][bj][m][0], v1 = acc[ai][bj][m][1];
;                     v0[0] *= bf_lo(gw.x); v0[1] *= bf_hi(gw.x); v0[2] *= bf_lo(gw.y); v0[3] *= bf_hi(gw.y);
;                     v1[0] *= bf_lo(gw.z); v1[1] *= bf_hi(gw.z); v1[2] *= bf_lo(gw.w); v1[3] *= bf_hi(gw.w);
;                     if (ACCUM) { const u32x4 pw = *(const u32x4*)(rowp + bj * HALF);
;                         v0[0] += bf_lo(pw.x); v0[1] += bf_hi(pw.x); v0[2] += bf_lo(pw.y); v0[3] += bf_hi(pw.y);
;                         v1[0] += bf_lo(pw.z); v1[1] += bf_hi(pw.z); v1[2] += bf_lo(pw.w); v1[3] += bf_hi(pw.w); }
;                     u32x4 w; w.x = cvt_pk_bf16(v0[0], v0[1]); w.y = cvt_pk_bf16(v0[2], v0[3]); w.z = cvt_pk_bf16(v1[0], v1[1]); w.w = cvt_pk_bf16(v1[2], v1[3]);
;                     *(u32x4*)(rowp + bj * HALF) = w; } }
; template <class Epi, class Sched>
; __device__ __forceinline__ void gemm_phase(PG8_LAS unsigned char* lds, const Gemm g, const Sched& S, const Epi& E) {
;     ...
;         if constexpr (!Epi::AFTER_DRAIN) { E(acc, cur, wr, wc, fr, fq); S.done(cur); }
;         if (!has_next) break;
; #pragma unroll
;         for (int a = 0; a < 2; ++a)
; #pragma unroll
;             for (int b = 0; b < 2; ++b)
; #pragma unroll
;                 for (int m = 0; m < 4; ++m)
; #pragma unroll
;                     for (int n = 0; n < 2; ++n) acc[a][b][m][n] = (f32x4){0.f, 0.f, 0.f, 0.f};
;         cur = nxt; cA = nA; cB = nB; ++ui;
;     }
;     PG8_WAIT_V(0);
;     if (wr == 0) PG8_BAR;
;     PG8_BAR;
	v_lshlrev_b32_e32 v40, 16, v44
	v_and_b32_e32 v41, 0xffff0000, v44
	v_lshlrev_b32_e32 v42, 16, v45
	v_and_b32_e32 v43, 0xffff0000, v45
	v_lshlrev_b32_e32 v44, 16, v46
	v_and_b32_e32 v45, 0xffff0000, v46
	v_lshlrev_b32_e32 v46, 16, v47
	v_and_b32_e32 v47, 0xffff0000, v47
	v_mul_f32_e32 v36, v36, v40
	v_mul_f32_e32 v37, v37, v41
	v_mul_f32_e32 v38, v38, v42
	v_mul_f32_e32 v39, v39, v43
	v_mul_f32_e32 v31, v31, v47
	v_mul_f32_e32 v40, v28, v44
	v_mul_f32_e32 v41, v29, v45
	v_mul_f32_e32 v42, v30, v46
	v_cvt_pk_bf16_f32 v28, v36, v37
	v_cvt_pk_bf16_f32 v29, v38, v39
	v_cvt_pk_bf16_f32 v30, v40, v41
	v_cvt_pk_bf16_f32 v31, v42, v31
	global_load_dwordx4 v[36:39], v[50:51], off offset:3072
	s_nop 0
	global_store_dwordx4 v[52:53], v[28:31], off offset:256
	s_waitcnt vmcnt(0)
	s_nop 0
	v_lshlrev_b32_e32 v28, 16, v36
	v_and_b32_e32 v29, 0xffff0000, v36
	v_lshlrev_b32_e32 v30, 16, v37
	v_and_b32_e32 v31, 0xffff0000, v37
	v_lshlrev_b32_e32 v36, 16, v38
	v_and_b32_e32 v37, 0xffff0000, v38
	v_lshlrev_b32_e32 v38, 16, v39
	v_and_b32_e32 v39, 0xffff0000, v39
	v_mul_f32_e32 v28, v32, v28
	v_mul_f32_e32 v29, v33, v29
	v_mul_f32_e32 v30, v34, v30
	v_mul_f32_e32 v31, v35, v31
	v_mul_f32_e32 v27, v27, v39
	v_mul_f32_e32 v32, v24, v36
	v_mul_f32_e32 v33, v25, v37
	v_mul_f32_e32 v34, v26, v38
	v_cvt_pk_bf16_f32 v24, v28, v29
	v_cvt_pk_bf16_f32 v25, v30, v31
	v_cvt_pk_bf16_f32 v26, v32, v33
	v_cvt_pk_bf16_f32 v27, v34, v27
	global_load_dwordx4 v[28:31], v[50:51], off offset:3328
	v_lshlrev_b64 v[36:37], 11, v[48:49]
	v_lshl_add_u64 v[36:37], s[0:1], 0, v[36:37]
	v_add_u32_e32 v32, 0xb0, v146
	v_lshl_add_u64 v[36:37], v[36:37], 0, v[144:145]
	v_mad_i64_i32 v[34:35], s[18:19], v32, s41, v[148:149]
	global_store_dwordx4 v[36:37], v[24:27], off
	v_lshl_add_u64 v[34:35], v[34:35], 0, v[144:145]
	v_ashrrev_i32_e32 v33, 31, v32
	s_mov_b64 s[18:19], s[12:13]
	s_waitcnt vmcnt(0)
	v_lshlrev_b32_e32 v24, 16, v28
	v_and_b32_e32 v25, 0xffff0000, v28
	v_lshlrev_b32_e32 v26, 16, v29
	v_and_b32_e32 v27, 0xffff0000, v29
	v_lshlrev_b32_e32 v28, 16, v30
	v_and_b32_e32 v29, 0xffff0000, v30
	v_lshlrev_b32_e32 v30, 16, v31
	v_and_b32_e32 v31, 0xffff0000, v31
	v_mul_f32_e32 v20, v20, v24
	v_mul_f32_e32 v21, v21, v25
	v_mul_f32_e32 v22, v22, v26
	v_mul_f32_e32 v23, v23, v27
	v_mul_f32_e32 v15, v15, v31
	v_mul_f32_e32 v24, v12, v28
	v_mul_f32_e32 v25, v13, v29
	v_mul_f32_e32 v26, v14, v30
	v_cvt_pk_bf16_f32 v12, v20, v21
	v_cvt_pk_bf16_f32 v13, v22, v23
	v_cvt_pk_bf16_f32 v14, v24, v25
	v_cvt_pk_bf16_f32 v15, v26, v15
	global_load_dwordx4 v[20:23], v[34:35], off offset:3072
	s_nop 0
	global_store_dwordx4 v[36:37], v[12:15], off offset:256
	s_waitcnt vmcnt(0)
	s_nop 0
	v_lshlrev_b32_e32 v12, 16, v20
	v_and_b32_e32 v13, 0xffff0000, v20
	v_lshlrev_b32_e32 v14, 16, v21
	v_and_b32_e32 v15, 0xffff0000, v21
	v_lshlrev_b32_e32 v20, 16, v22
	v_and_b32_e32 v21, 0xffff0000, v22
	v_lshlrev_b32_e32 v22, 16, v23
	v_and_b32_e32 v23, 0xffff0000, v23
	v_mul_f32_e32 v12, v16, v12
	v_mul_f32_e32 v13, v17, v13
	v_mul_f32_e32 v14, v18, v14
	v_mul_f32_e32 v15, v19, v15
	v_mul_f32_e32 v11, v11, v23
	v_mul_f32_e32 v16, v8, v20
	v_mul_f32_e32 v17, v9, v21
	v_mul_f32_e32 v18, v10, v22
	v_cvt_pk_bf16_f32 v8, v12, v13
	v_cvt_pk_bf16_f32 v9, v14, v15
	v_cvt_pk_bf16_f32 v10, v16, v17
	v_cvt_pk_bf16_f32 v11, v18, v11
	global_load_dwordx4 v[12:15], v[34:35], off offset:3328
	v_lshlrev_b64 v[16:17], 11, v[32:33]
	v_lshl_add_u64 v[16:17], s[0:1], 0, v[16:17]
	v_lshl_add_u64 v[16:17], v[16:17], 0, v[144:145]
	global_store_dwordx4 v[16:17], v[8:11], off
	s_waitcnt vmcnt(0)
	s_nop 0
	v_lshlrev_b32_e32 v8, 16, v12
	v_and_b32_e32 v9, 0xffff0000, v12
	v_lshlrev_b32_e32 v10, 16, v13
	v_and_b32_e32 v11, 0xffff0000, v13
	v_lshlrev_b32_e32 v12, 16, v14
	v_and_b32_e32 v13, 0xffff0000, v14
	v_lshlrev_b32_e32 v14, 16, v15
	v_and_b32_e32 v15, 0xffff0000, v15
	v_mul_f32_e32 v3, v3, v15
	v_mul_f32_e32 v4, v4, v8
	v_mul_f32_e32 v5, v5, v9
	v_mul_f32_e32 v6, v6, v10
	v_mul_f32_e32 v7, v7, v11
	v_mul_f32_e32 v8, v0, v12
	v_mul_f32_e32 v9, v1, v13
	v_mul_f32_e32 v10, v2, v14
	v_cvt_pk_bf16_f32 v0, v4, v5
	v_cvt_pk_bf16_f32 v1, v6, v7
	v_cvt_pk_bf16_f32 v2, v8, v9
	v_cvt_pk_bf16_f32 v3, v10, v3
	global_store_dwordx4 v[16:17], v[0:3], off offset:256
	s_cbranch_vccz .LBB0_984
	s_waitcnt vmcnt(0)
	s_cmpk_gt_u32 s25, 0xff
	s_cbranch_scc1 .LBB0_995
	s_barrier

; #define PG8_STAGE(bufoff, gbase, voff) do { _Pragma("unroll") for (int _i = 0; _i < 2; ++_i) \
;         __builtin_amdgcn_global_load_lds((const unsigned*)((const char*)(gbase) + (voff)[_i]), (PG8_LAS unsigned*)(lds + (bufoff) + ldsw + _i * 8192), 16, 0, 0); } while (0)
; #define PG8_WAIT_V(n) asm volatile("s_waitcnt vmcnt(" #n ")" ::: "memory")
; #define PG8_BAR __builtin_amdgcn_s_barrier()
; template <class Epi, class Sched>
; __device__ __forceinline__ void gemm_phase(PG8_LAS unsigned char* lds, const Gemm g, const Sched& S, const Epi& E) {
;     ...
;     for (int i = 0; i < 2; ++i) { int R, C; stage_rc(tid * 16 + i * 8192, R, C); const int Rb = Epi::PERM ? ((R & ~31) + perm32(R & 31)) : R;
;         voffA[i] = (unsigned)(R * K + C) * 2u; voffB[i] = (unsigned)(Rb * K + C) * 2u; }
;     const size_t kstep = (size_t)(BK * 2);
;     const size_t hstep = (size_t)HALF * K * 2;
;     const size_t tstep = 2 * hstep;
;     const unsigned ldsw = (unsigned)wid * 1024u;
;     const int aoff = lds_byte(wr * 64 + fr, fq * 8), boff = lds_byte(wc * 32 + fr, fq * 8);
;     ...
;     const char* cA = (const char*)g.A + (size_t)cur.pm * tstep; const char* cB = (const char*)g.Bt + (size_t)cur.pn * tstep;
;     S.a_ready(cur);
;     PG8_STAGE(PG8_SB(0, 0), cB, voffB); PG8_STAGE(PG8_SA(0, 0), cA, voffA); PG8_STAGE(PG8_SB(0, 1), cB + hstep, voffB); PG8_STAGE(PG8_SA(0, 1), cA + hstep, voffA);
;     if (wr == 1) PG8_BAR;
;     PG8_WAIT_V(4); PG8_BAR;
;     PG8_STAGE(PG8_SB(1, 0), cB + kstep, voffB); PG8_STAGE(PG8_SA(1, 0), cA + kstep, voffA); PG8_STAGE(PG8_SB(1, 1), cB + hstep + kstep, voffB);
;     PG8_WAIT_V(6); PG8_BAR;
.LBB0_1003:
	s_lshl_b32 s0, s0, 1
	v_readlane_b32 s1, v245, 24
	s_add_u32 s0, s1, s0
	v_readlane_b32 s1, v245, 25
	s_addc_u32 s1, s1, 0
	s_lshl_b32 s4, s4, 27
	v_readlane_b32 s5, v245, 18
	s_add_u32 s4, s5, s4
	v_readlane_b32 s5, v245, 19
	s_addc_u32 s5, s5, 0
	s_add_u32 s4, s4, 0x1400
	s_addc_u32 s5, s5, 0
	s_lshl_b32 s6, s6, 5
	s_and_b32 s11, s6, 0x60
	s_mov_b64 s[6:7], 0x80
	s_add_i32 m0, s17, 0x18000
	v_lshl_add_u64 v[6:7], v[6:7], 0, s[6:7]
	s_lshl_b32 s10, s3, 13
	s_lshl_b32 s12, s11, 7
	s_waitcnt vmcnt(0)
	s_barrier
	global_load_lds_dwordx4 v[6:7], off
	v_lshl_add_u64 v[4:5], v[4:5], 0, s[6:7]
	s_add_i32 m0, s17, 0x1a000
	s_add_i32 s36, s17, 0x8000
	s_add_i32 s37, s17, 0xa000
	global_load_lds_dwordx4 v[4:5], off
	v_lshl_add_u64 v[2:3], v[2:3], 0, s[6:7]
	s_mov_b32 m0, s36
	s_add_u32 s8, s20, 0x40080
	global_load_lds_dwordx4 v[2:3], off
	v_lshl_add_u64 v[0:1], v[0:1], 0, s[6:7]
	s_mov_b32 m0, s37
	s_addc_u32 s9, s21, 0
	global_load_lds_dwordx4 v[0:1], off
	s_add_i32 m0, s17, 0x1c000
	v_lshl_add_u64 v[0:1], s[8:9], 0, v[130:131]
	global_load_lds_dwordx4 v[0:1], off
	v_lshl_add_u64 v[0:1], s[8:9], 0, v[134:135]
	s_add_i32 m0, s17, 0x1e000
	s_add_i32 s39, 0, 0x10000
	global_load_lds_dwordx4 v[0:1], off
	v_lshrrev_b32_e32 v1, 1, v8
	v_and_b32_e32 v1, 24, v1
	v_and_b32_e32 v0, 15, v8
	v_lshlrev_b32_e32 v2, 1, v1
	v_lshl_or_b32 v150, s3, 6, v0
	v_lshl_or_b32 v0, v0, 6, v2
	v_lshlrev_b32_e32 v2, 2, v8
	v_and_b32_e32 v2, 32, v2
	v_bitop3_b32 v3, v0, s10, v2 bitop3:0xde
	v_bitop3_b32 v151, v0, s12, v2 bitop3:0xde
	v_lshlrev_b32_e32 v0, 14, v9
	v_and_b32_e32 v0, 0xffff8000, v0
	v_or_b32_e32 v152, s11, v1
	v_lshl_add_u32 v0, v10, 11, v0
	v_and_b32_e32 v1, 1, v9
	v_lshl_or_b32 v0, v1, 6, v0
	v_lshl_add_u32 v136, v11, 1, v0
	v_lshlrev_b32_e32 v0, 14, v12
	v_and_b32_e32 v0, 0xffff8000, v0
	s_waitcnt vmcnt(6)
	v_lshl_add_u32 v0, v13, 11, v0
	v_and_b32_e32 v1, 1, v12
	v_lshl_or_b32 v0, v1, 6, v0
	s_add_i32 s40, 0, 0x14000
	s_sext_i32_i8 s42, s2
	s_ashr_i32 s38, s33, 31
	v_mov_b32_e32 v137, v131
	v_lshl_add_u32 v138, v14, 1, v0
	v_mov_b32_e32 v139, v131
	v_mov_b64_e32 v[140:141], 0x100
	v_mov_b64_e32 v[142:143], 0xff
	v_add_u32_e32 v153, s39, v151
	v_add_u32_e32 v154, 0, v3
	v_add_u32_e32 v155, s40, v151
	s_movk_i32 s41, 0x1c00
	s_barrier

; #define PG8_STAGE(bufoff, gbase, voff) do { _Pragma("unroll") for (int _i = 0; _i < 2; ++_i) \
;         __builtin_amdgcn_global_load_lds((const unsigned*)((const char*)(gbase) + (voff)[_i]), (PG8_LAS unsigned*)(lds + (bufoff) + ldsw + _i * 8192), 16, 0, 0); } while (0)
; #define PG8_LDA(dst, b, h) do { _Pragma("unroll") for (int m = 0; m < 4; ++m) _Pragma("unroll") for (int k = 0; k < 2; ++k) dst[m][k] = *(const PG8_LAS bf16x8*)(lds + PG8_SA(b, h) + aoff + m * 2048 + k * 1024); } while (0)
; #define PG8_LDB(dst, b, h) do { _Pragma("unroll") for (int n = 0; n < 2; ++n) _Pragma("unroll") for (int k = 0; k < 2; ++k) dst[n][k] = *(const PG8_LAS bf16x8*)(lds + PG8_SB(b, h) + boff + n * 2048 + k * 1024); } while (0)
; #define PG8_MMA(ai, bj, At, Bt) do { __builtin_amdgcn_s_setprio(1); _Pragma("unroll") for (int m = 0; m < 4; ++m) _Pragma("unroll") for (int n = 0; n < 2; ++n) _Pragma("unroll") for (int k = 0; k < 2; ++k) \
;         acc[ai][bj][m][n] = __builtin_amdgcn_mfma_f32_16x16x32_bf16(Bt[n][k], At[m][k], acc[ai][bj][m][n], 0, 0, 0); __builtin_amdgcn_s_setprio(0); } while (0)
; #define PG8_WAIT_V(n) asm volatile("s_waitcnt vmcnt(" #n ")" ::: "memory")
; template <class Epi, class Sched>
; __device__ __forceinline__ void gemm_phase(PG8_LAS unsigned char* lds, const Gemm g, const Sched& S, const Epi& E) {
;     ...
;         for (int t = 0; t < nt; t += 2) {
;             const bool last = (t == nt - 2);
;             const char* a1 = cA + (size_t)(t + 1) * kstep;
;             const char* a2 = last ? nA : cA + (size_t)(t + 2) * kstep; const char* b2 = last ? nB : cB + (size_t)(t + 2) * kstep;
;             const char* a3 = a2 + kstep; const char* b3 = b2 + kstep;
;             if (last && has_next) S.a_ready(nxt);
;             PG8_LDB(B0, 0, 0); PG8_SCHED; PG8_LDA(At, 0, 0); PG8_STAGE(PG8_SA(1, 1), a1 + hstep, voffA);
;             PG8_WAIT_L(8); PG8_BAR; PG8_WAIT_L(0); PG8_MMA(0, 0, At, B0); PG8_BAR; PG8_SCHED;
;             PG8_LDB(B1, 0, 1); PG8_STAGE(PG8_SB(0, 0), b2, voffB);
;             PG8_BAR; PG8_WAIT_L(0); PG8_MMA(0, 1, At, B1); PG8_BAR;
;             PG8_LDA(At, 0, 1); PG8_STAGE(PG8_SA(0, 0), a2, voffA);
;             PG8_BAR; PG8_WAIT_L(0); PG8_MMA(1, 0, At, B0); PG8_BAR; PG8_SCHED;
;             PG8_STAGE(PG8_SB(0, 1), b2 + hstep, voffB);
;             PG8_WAIT_V(6); PG8_BAR; PG8_MMA(1, 1, At, B1); PG8_BAR;
.LBB0_1011:
	ds_read_b128 v[144:147], v153
	ds_read_b128 v[156:159], v153 offset:1024
	ds_read_b128 v[160:163], v153 offset:2048
	ds_read_b128 v[164:167], v153 offset:3072
	s_add_u32 s20, s18, 0xfffc0080
	s_addc_u32 s21, s19, -1
	s_cmp_eq_u32 s47, 12
	s_cselect_b32 s23, s11, s21
	s_cselect_b32 s22, s43, s20
	s_cselect_b32 s21, s9, s46
	s_cselect_b32 s20, s44, s45
	v_lshl_add_u64 v[148:149], s[18:19], 0, v[136:137]
	s_add_i32 m0, s17, 0xc000
	ds_read_b128 v[168:171], v154
	ds_read_b128 v[172:175], v154 offset:1024
	ds_read_b128 v[182:185], v154 offset:2048
	ds_read_b128 v[190:193], v154 offset:3072
	ds_read_b128 v[194:197], v154 offset:4096
	ds_read_b128 v[198:201], v154 offset:5120
	ds_read_b128 v[202:205], v154 offset:6144
	ds_read_b128 v[206:209], v154 offset:7168
	global_load_lds_dwordx4 v[148:149], off
	v_lshl_add_u64 v[148:149], s[18:19], 0, v[138:139]
	s_add_i32 m0, s17, 0xe000
	s_nop 0
	global_load_lds_dwordx4 v[148:149], off
	s_waitcnt lgkmcnt(8)
	ds_read_b128 v[210:213], v155
	ds_read_b128 v[214:217], v155 offset:1024
	ds_read_b128 v[218:221], v155 offset:2048
	ds_read_b128 v[222:225], v155 offset:3072
	s_waitcnt vmcnt(8) lgkmcnt(0)
	s_barrier
	v_mfma_f32_16x16x32_bf16 v[124:127], v[144:147], v[168:171], v[124:127]
	v_mfma_f32_16x16x32_bf16 v[120:123], v[160:163], v[168:171], v[120:123]
	v_mfma_f32_16x16x32_bf16 v[108:111], v[144:147], v[182:185], v[108:111]
	v_mfma_f32_16x16x32_bf16 v[104:107], v[160:163], v[182:185], v[104:107]
	v_mfma_f32_16x16x32_bf16 v[92:95], v[144:147], v[194:197], v[92:95]
	v_mfma_f32_16x16x32_bf16 v[88:91], v[160:163], v[194:197], v[88:91]
	v_mfma_f32_16x16x32_bf16 v[76:79], v[144:147], v[202:205], v[76:79]
	v_mfma_f32_16x16x32_bf16 v[72:75], v[160:163], v[202:205], v[72:75]
	v_mfma_f32_16x16x32_bf16 v[124:127], v[156:159], v[172:175], v[124:127]
	v_mfma_f32_16x16x32_bf16 v[120:123], v[164:167], v[172:175], v[120:123]
	v_mfma_f32_16x16x32_bf16 v[108:111], v[156:159], v[190:193], v[108:111]
	v_mfma_f32_16x16x32_bf16 v[104:107], v[164:167], v[190:193], v[104:107]
	v_mfma_f32_16x16x32_bf16 v[92:95], v[156:159], v[198:201], v[92:95]
	v_mfma_f32_16x16x32_bf16 v[88:91], v[164:167], v[198:201], v[88:91]
	v_mfma_f32_16x16x32_bf16 v[76:79], v[156:159], v[206:209], v[76:79]
	v_mfma_f32_16x16x32_bf16 v[72:75], v[164:167], v[206:209], v[72:75]
	v_mfma_f32_16x16x32_bf16 v[116:119], v[210:213], v[168:171], v[116:119]
	v_mfma_f32_16x16x32_bf16 v[112:115], v[218:221], v[168:171], v[112:115]
	v_mfma_f32_16x16x32_bf16 v[100:103], v[210:213], v[182:185], v[100:103]
	v_mfma_f32_16x16x32_bf16 v[96:99], v[218:221], v[182:185], v[96:99]
	v_mfma_f32_16x16x32_bf16 v[84:87], v[210:213], v[194:197], v[84:87]
	v_mfma_f32_16x16x32_bf16 v[80:83], v[218:221], v[194:197], v[80:83]
	v_mfma_f32_16x16x32_bf16 v[68:71], v[210:213], v[202:205], v[68:71]
	v_mfma_f32_16x16x32_bf16 v[64:67], v[218:221], v[202:205], v[64:67]
	v_mfma_f32_16x16x32_bf16 v[116:119], v[214:217], v[172:175], v[116:119]
	v_mfma_f32_16x16x32_bf16 v[112:115], v[222:225], v[172:175], v[112:115]
	v_mfma_f32_16x16x32_bf16 v[100:103], v[214:217], v[190:193], v[100:103]
	v_mfma_f32_16x16x32_bf16 v[96:99], v[222:225], v[190:193], v[96:99]
	v_mfma_f32_16x16x32_bf16 v[84:87], v[214:217], v[198:201], v[84:87]
	v_mfma_f32_16x16x32_bf16 v[80:83], v[222:225], v[198:201], v[80:83]
	v_mfma_f32_16x16x32_bf16 v[68:71], v[214:217], v[206:209], v[68:71]
	v_mfma_f32_16x16x32_bf16 v[64:67], v[222:225], v[206:209], v[64:67]
	s_barrier
	ds_read_b128 v[168:171], v154 offset:16384
	ds_read_b128 v[172:175], v154 offset:17408
	ds_read_b128 v[182:185], v154 offset:18432
	ds_read_b128 v[190:193], v154 offset:19456
	ds_read_b128 v[194:197], v154 offset:20480
	ds_read_b128 v[198:201], v154 offset:21504
	ds_read_b128 v[202:205], v154 offset:22528
	ds_read_b128 v[206:209], v154 offset:23552
	s_add_i32 s48, s39, s29
	v_lshl_add_u64 v[148:149], s[20:21], 0, v[130:131]
	s_mov_b32 m0, s48
	s_nop 0
	global_load_lds_dwordx4 v[148:149], off
	v_lshl_add_u64 v[186:187], s[20:21], 0, v[134:135]
	s_add_i32 m0, s48, 0x2000
	s_nop 0
	global_load_lds_dwordx4 v[186:187], off
	s_nop 1
	s_mov_b32 m0, s17
	v_lshl_add_u64 v[226:227], s[22:23], 0, v[128:129]
	global_load_lds_dwordx4 v[226:227], off
	v_lshl_add_u64 v[228:229], s[22:23], 0, v[132:133]
	s_mov_b32 m0, s30
	s_nop 0
	global_load_lds_dwordx4 v[228:229], off
	s_add_u32 s48, s20, 0x40000
	s_addc_u32 s49, s21, 0
	s_add_i32 s50, s40, s29
	v_lshl_add_u64 v[246:247], s[48:49], 0, v[130:131]
	s_mov_b32 m0, s50
	s_nop 0
	global_load_lds_dwordx4 v[246:247], off
	v_lshl_add_u64 v[246:247], s[48:49], 0, v[134:135]
	s_add_i32 m0, s50, 0x2000
	s_nop 0
	global_load_lds_dwordx4 v[246:247], off
	s_waitcnt vmcnt(8) lgkmcnt(0)
	s_barrier
; #define PG8_STAGE(bufoff, gbase, voff) do { _Pragma("unroll") for (int _i = 0; _i < 2; ++_i) \
;         __builtin_amdgcn_global_load_lds((const unsigned*)((const char*)(gbase) + (voff)[_i]), (PG8_LAS unsigned*)(lds + (bufoff) + ldsw + _i * 8192), 16, 0, 0); } while (0)
; #define PG8_LDA(dst, b, h) do { _Pragma("unroll") for (int m = 0; m < 4; ++m) _Pragma("unroll") for (int k = 0; k < 2; ++k) dst[m][k] = *(const PG8_LAS bf16x8*)(lds + PG8_SA(b, h) + aoff + m * 2048 + k * 1024); } while (0)
; #define PG8_LDB(dst, b, h) do { _Pragma("unroll") for (int n = 0; n < 2; ++n) _Pragma("unroll") for (int k = 0; k < 2; ++k) dst[n][k] = *(const PG8_LAS bf16x8*)(lds + PG8_SB(b, h) + boff + n * 2048 + k * 1024); } while (0)
; #define PG8_MMA(ai, bj, At, Bt) do { __builtin_amdgcn_s_setprio(1); _Pragma("unroll") for (int m = 0; m < 4; ++m) _Pragma("unroll") for (int n = 0; n < 2; ++n) _Pragma("unroll") for (int k = 0; k < 2; ++k) \
;         acc[ai][bj][m][n] = __builtin_amdgcn_mfma_f32_16x16x32_bf16(Bt[n][k], At[m][k], acc[ai][bj][m][n], 0, 0, 0); __builtin_amdgcn_s_setprio(0); } while (0)
; #define PG8_WAIT_V(n) asm volatile("s_waitcnt vmcnt(" #n ")" ::: "memory")
; #define PG8_WAIT_L(n) asm volatile("s_waitcnt lgkmcnt(" #n ")" ::: "memory")
; #define PG8_BAR __builtin_amdgcn_s_barrier()
; #define PG8_SCHED __builtin_amdgcn_sched_barrier(0)
; template <class Epi, class Sched>
; __device__ __forceinline__ void gemm_phase(PG8_LAS unsigned char* lds, const Gemm g, const Sched& S, const Epi& E) {
;     ...
;             PG8_BAR; PG8_WAIT_L(0); PG8_MMA(1, 0, At, B0); PG8_BAR; PG8_SCHED;
;             PG8_STAGE(PG8_SB(0, 1), b2 + hstep, voffB);
;             PG8_WAIT_V(6); PG8_BAR; PG8_MMA(1, 1, At, B1); PG8_BAR;
;             PG8_LDB(B0, 1, 0); PG8_SCHED; PG8_LDA(At, 1, 0); PG8_STAGE(PG8_SA(0, 1), a2 + hstep, voffA);
;             PG8_WAIT_L(8); PG8_BAR; PG8_WAIT_L(0); PG8_MMA(0, 0, At, B0); PG8_BAR; PG8_SCHED;
;             PG8_LDB(B1, 1, 1); PG8_STAGE(PG8_SB(1, 0), b3, voffB);
;             PG8_BAR; PG8_WAIT_L(0); PG8_MMA(0, 1, At, B1); PG8_BAR;
	v_mfma_f32_16x16x32_bf16 v[60:63], v[144:147], v[168:171], v[60:63]
	v_mfma_f32_16x16x32_bf16 v[56:59], v[160:163], v[168:171], v[56:59]
	v_mfma_f32_16x16x32_bf16 v[44:47], v[144:147], v[182:185], v[44:47]
	v_mfma_f32_16x16x32_bf16 v[40:43], v[160:163], v[182:185], v[40:43]
	v_mfma_f32_16x16x32_bf16 v[28:31], v[144:147], v[194:197], v[28:31]
	v_mfma_f32_16x16x32_bf16 v[24:27], v[160:163], v[194:197], v[24:27]
	v_mfma_f32_16x16x32_bf16 v[12:15], v[144:147], v[202:205], v[12:15]
	v_mfma_f32_16x16x32_bf16 v[8:11], v[160:163], v[202:205], v[8:11]
	v_mfma_f32_16x16x32_bf16 v[60:63], v[156:159], v[172:175], v[60:63]
	v_mfma_f32_16x16x32_bf16 v[56:59], v[164:167], v[172:175], v[56:59]
	v_mfma_f32_16x16x32_bf16 v[44:47], v[156:159], v[190:193], v[44:47]
	v_mfma_f32_16x16x32_bf16 v[40:43], v[164:167], v[190:193], v[40:43]
	v_mfma_f32_16x16x32_bf16 v[28:31], v[156:159], v[198:201], v[28:31]
	v_mfma_f32_16x16x32_bf16 v[24:27], v[164:167], v[198:201], v[24:27]
	v_mfma_f32_16x16x32_bf16 v[12:15], v[156:159], v[206:209], v[12:15]
	v_mfma_f32_16x16x32_bf16 v[8:11], v[164:167], v[206:209], v[8:11]
	v_mfma_f32_16x16x32_bf16 v[52:55], v[210:213], v[168:171], v[52:55]
	v_mfma_f32_16x16x32_bf16 v[48:51], v[218:221], v[168:171], v[48:51]
	v_mfma_f32_16x16x32_bf16 v[36:39], v[210:213], v[182:185], v[36:39]
	v_mfma_f32_16x16x32_bf16 v[32:35], v[218:221], v[182:185], v[32:35]
	v_mfma_f32_16x16x32_bf16 v[20:23], v[210:213], v[194:197], v[20:23]
	v_mfma_f32_16x16x32_bf16 v[16:19], v[218:221], v[194:197], v[16:19]
	v_mfma_f32_16x16x32_bf16 v[4:7], v[210:213], v[202:205], v[4:7]
	v_mfma_f32_16x16x32_bf16 v[0:3], v[218:221], v[202:205], v[0:3]
	v_mfma_f32_16x16x32_bf16 v[52:55], v[214:217], v[172:175], v[52:55]
	v_mfma_f32_16x16x32_bf16 v[48:51], v[222:225], v[172:175], v[48:51]
	v_mfma_f32_16x16x32_bf16 v[36:39], v[214:217], v[190:193], v[36:39]
	v_mfma_f32_16x16x32_bf16 v[32:35], v[222:225], v[190:193], v[32:35]
	v_mfma_f32_16x16x32_bf16 v[20:23], v[214:217], v[198:201], v[20:23]
	v_mfma_f32_16x16x32_bf16 v[16:19], v[222:225], v[198:201], v[16:19]
	v_mfma_f32_16x16x32_bf16 v[4:7], v[214:217], v[206:209], v[4:7]
	v_mfma_f32_16x16x32_bf16 v[0:3], v[222:225], v[206:209], v[0:3]
	s_barrier
	s_add_i32 s48, 0, 0x18000
	v_add_u32_e32 v164, s48, v151
	ds_read_b128 v[144:147], v164
	ds_read_b128 v[156:159], v164 offset:1024
	ds_read_b128 v[160:163], v164 offset:2048
	ds_read_b128 v[164:167], v164 offset:3072
	s_add_u32 s22, s22, 0x40000
	s_addc_u32 s23, s23, 0
	s_mov_b32 m0, s31
	v_lshl_add_u64 v[210:211], s[22:23], 0, v[128:129]
	ds_read_b128 v[168:171], v154 offset:32768
	ds_read_b128 v[172:175], v154 offset:33792
	ds_read_b128 v[182:185], v154 offset:34816
	ds_read_b128 v[190:193], v154 offset:35840
	ds_read_b128 v[194:197], v154 offset:36864
	ds_read_b128 v[198:201], v154 offset:37888
	ds_read_b128 v[202:205], v154 offset:38912
	ds_read_b128 v[206:209], v154 offset:39936
	global_load_lds_dwordx4 v[210:211], off
	v_lshl_add_u64 v[210:211], s[22:23], 0, v[132:133]
	s_mov_b32 m0, s34
	s_nop 0
	global_load_lds_dwordx4 v[210:211], off
	s_add_i32 s22, 0, 0x1c000
	v_add_u32_e32 v179, s22, v151
	s_waitcnt lgkmcnt(8)
	ds_read_b128 v[210:213], v179
	ds_read_b128 v[214:217], v179 offset:1024
	ds_read_b128 v[218:221], v179 offset:2048
	ds_read_b128 v[222:225], v179 offset:3072
	s_waitcnt vmcnt(8) lgkmcnt(0)
	s_barrier
	v_mfma_f32_16x16x32_bf16 v[124:127], v[144:147], v[168:171], v[124:127]
	v_mfma_f32_16x16x32_bf16 v[120:123], v[160:163], v[168:171], v[120:123]
	v_mfma_f32_16x16x32_bf16 v[108:111], v[144:147], v[182:185], v[108:111]
	v_mfma_f32_16x16x32_bf16 v[104:107], v[160:163], v[182:185], v[104:107]
	v_mfma_f32_16x16x32_bf16 v[92:95], v[144:147], v[194:197], v[92:95]
	v_mfma_f32_16x16x32_bf16 v[88:91], v[160:163], v[194:197], v[88:91]
	v_mfma_f32_16x16x32_bf16 v[76:79], v[144:147], v[202:205], v[76:79]
	v_mfma_f32_16x16x32_bf16 v[72:75], v[160:163], v[202:205], v[72:75]
	v_mfma_f32_16x16x32_bf16 v[124:127], v[156:159], v[172:175], v[124:127]
	v_mfma_f32_16x16x32_bf16 v[120:123], v[164:167], v[172:175], v[120:123]
	v_mfma_f32_16x16x32_bf16 v[108:111], v[156:159], v[190:193], v[108:111]
	v_mfma_f32_16x16x32_bf16 v[104:107], v[164:167], v[190:193], v[104:107]
	v_mfma_f32_16x16x32_bf16 v[92:95], v[156:159], v[198:201], v[92:95]
	v_mfma_f32_16x16x32_bf16 v[88:91], v[164:167], v[198:201], v[88:91]
	v_mfma_f32_16x16x32_bf16 v[76:79], v[156:159], v[206:209], v[76:79]
	v_mfma_f32_16x16x32_bf16 v[72:75], v[164:167], v[206:209], v[72:75]
	v_mfma_f32_16x16x32_bf16 v[116:119], v[210:213], v[168:171], v[116:119]
	v_mfma_f32_16x16x32_bf16 v[112:115], v[218:221], v[168:171], v[112:115]
	v_mfma_f32_16x16x32_bf16 v[100:103], v[210:213], v[182:185], v[100:103]
	v_mfma_f32_16x16x32_bf16 v[96:99], v[218:221], v[182:185], v[96:99]
	v_mfma_f32_16x16x32_bf16 v[84:87], v[210:213], v[194:197], v[84:87]
	v_mfma_f32_16x16x32_bf16 v[80:83], v[218:221], v[194:197], v[80:83]
	v_mfma_f32_16x16x32_bf16 v[68:71], v[210:213], v[202:205], v[68:71]
	v_mfma_f32_16x16x32_bf16 v[64:67], v[218:221], v[202:205], v[64:67]
	v_mfma_f32_16x16x32_bf16 v[116:119], v[214:217], v[172:175], v[116:119]
	v_mfma_f32_16x16x32_bf16 v[112:115], v[222:225], v[172:175], v[112:115]
	v_mfma_f32_16x16x32_bf16 v[100:103], v[214:217], v[190:193], v[100:103]
	v_mfma_f32_16x16x32_bf16 v[96:99], v[222:225], v[190:193], v[96:99]
	v_mfma_f32_16x16x32_bf16 v[84:87], v[214:217], v[198:201], v[84:87]
	v_mfma_f32_16x16x32_bf16 v[80:83], v[222:225], v[198:201], v[80:83]
	v_mfma_f32_16x16x32_bf16 v[68:71], v[214:217], v[206:209], v[68:71]
	v_mfma_f32_16x16x32_bf16 v[64:67], v[222:225], v[206:209], v[64:67]
	s_barrier
; __device__ __forceinline__ unsigned cvt_pk_bf16(float lo, float hi) { unsigned r; asm volatile("v_cvt_pk_bf16_f32 %0, %1, %2" : "=v"(r) : "v"(lo), "v"(hi)); return r; }
; __device__ __forceinline__ float bf_lo(unsigned u) { return __uint_as_float(u << 16); }
; __device__ __forceinline__ float bf_hi(unsigned u) { return __uint_as_float(u & 0xffff0000u); }
; #define PG8_STAGE(bufoff, gbase, voff) do { _Pragma("unroll") for (int _i = 0; _i < 2; ++_i) \
;         __builtin_amdgcn_global_load_lds((const unsigned*)((const char*)(gbase) + (voff)[_i]), (PG8_LAS unsigned*)(lds + (bufoff) + ldsw + _i * 8192), 16, 0, 0); } while (0)
; #define PG8_BAR __builtin_amdgcn_s_barrier()
;     __device__ __forceinline__ void operator()(const f32x4 (&acc)[2][2][4][2], const Unit& u, int wr, int wc, int fr, int fq) const {
;     ...
;             for (int m = 0; m < 4; ++m) { const size_t r = (size_t)(row0 + ai * HALF + m * 16); bf16_t* rowp = O + r * ldc + col0; const bf16_t* gp = G + r * ldg + col0;
; #pragma unroll
;                 for (int bj = 0; bj < 2; ++bj) { const u32x4 gw = *(const u32x4*)(gp + bj * HALF);
;                     f32x4 v0 = acc[ai][bj][m][0], v1 = acc[ai][bj][m][1];
;                     v0[0] *= bf_lo(gw.x); v0[1] *= bf_hi(gw.x); v0[2] *= bf_lo(gw.y); v0[3] *= bf_hi(gw.y);
;                     v1[0] *= bf_lo(gw.z); v1[1] *= bf_hi(gw.z); v1[2] *= bf_lo(gw.w); v1[3] *= bf_hi(gw.w);
;                     if (ACCUM) { const u32x4 pw = *(const u32x4*)(rowp + bj * HALF);
;                         v0[0] += bf_lo(pw.x); v0[1] += bf_hi(pw.x); v0[2] += bf_lo(pw.y); v0[3] += bf_hi(pw.y);
;                         v1[0] += bf_lo(pw.z); v1[1] += bf_hi(pw.z); v1[2] += bf_lo(pw.w); v1[3] += bf_hi(pw.w); }
;                     u32x4 w; w.x = cvt_pk_bf16(v0[0], v0[1]); w.y = cvt_pk_bf16(v0[2], v0[3]); w.z = cvt_pk_bf16(v1[0], v1[1]); w.w = cvt_pk_bf16(v1[2], v1[3]);
;                     *(u32x4*)(rowp + bj * HALF) = w; } }
; template <class Epi, class Sched>
; __device__ __forceinline__ void gemm_phase(PG8_LAS unsigned char* lds, const Gemm g, const Sched& S, const Epi& E) {
;     ...
;             PG8_LDA(At, 1, 1); PG8_STAGE(PG8_SA(1, 0), a3, voffA);
;             PG8_BAR; PG8_WAIT_L(0); PG8_MMA(1, 0, At, B0); PG8_BAR; PG8_SCHED;
;             PG8_STAGE(PG8_SB(1, 1), b3 + hstep, voffB);
;             PG8_WAIT_V(6); PG8_BAR; PG8_MMA(1, 1, At, B1); PG8_BAR;
	ds_read_b128 v[168:171], v154 offset:49152
	ds_read_b128 v[172:175], v154 offset:50176
	ds_read_b128 v[182:185], v154 offset:51200
	ds_read_b128 v[190:193], v154 offset:52224
	ds_read_b128 v[194:197], v154 offset:53248
	ds_read_b128 v[198:201], v154 offset:54272
	ds_read_b128 v[202:205], v154 offset:55296
	ds_read_b128 v[206:209], v154 offset:56320
	s_add_i32 s23, s48, s29
	v_lshl_add_u64 v[148:149], v[148:149], 0, s[6:7]
	s_mov_b32 m0, s23
	s_nop 0
	global_load_lds_dwordx4 v[148:149], off
	v_lshl_add_u64 v[148:149], v[186:187], 0, s[6:7]
	s_add_i32 m0, s23, 0x2000
	s_nop 0
	global_load_lds_dwordx4 v[148:149], off
	s_nop 1
	s_mov_b32 m0, s36
	v_lshl_add_u64 v[148:149], v[226:227], 0, s[6:7]
	global_load_lds_dwordx4 v[148:149], off
	v_lshl_add_u64 v[148:149], v[228:229], 0, s[6:7]
	s_mov_b32 m0, s37
	s_nop 0
	global_load_lds_dwordx4 v[148:149], off
	s_add_u32 s20, s20, 0x40080
	s_addc_u32 s21, s21, 0
	s_add_i32 s22, s22, s29
	v_lshl_add_u64 v[246:247], s[20:21], 0, v[130:131]
	s_mov_b32 m0, s22
	s_nop 0
	global_load_lds_dwordx4 v[246:247], off
	v_lshl_add_u64 v[246:247], s[20:21], 0, v[134:135]
	s_add_i32 m0, s22, 0x2000
	s_nop 0
	global_load_lds_dwordx4 v[246:247], off
	s_waitcnt vmcnt(8) lgkmcnt(0)
	s_barrier
	v_mfma_f32_16x16x32_bf16 v[60:63], v[144:147], v[168:171], v[60:63]
	v_mfma_f32_16x16x32_bf16 v[56:59], v[160:163], v[168:171], v[56:59]
	v_mfma_f32_16x16x32_bf16 v[44:47], v[144:147], v[182:185], v[44:47]
	v_mfma_f32_16x16x32_bf16 v[40:43], v[160:163], v[182:185], v[40:43]
	v_mfma_f32_16x16x32_bf16 v[28:31], v[144:147], v[194:197], v[28:31]
	v_mfma_f32_16x16x32_bf16 v[24:27], v[160:163], v[194:197], v[24:27]
	v_mfma_f32_16x16x32_bf16 v[12:15], v[144:147], v[202:205], v[12:15]
	v_mfma_f32_16x16x32_bf16 v[8:11], v[160:163], v[202:205], v[8:11]
	v_mfma_f32_16x16x32_bf16 v[60:63], v[156:159], v[172:175], v[60:63]
	v_mfma_f32_16x16x32_bf16 v[56:59], v[164:167], v[172:175], v[56:59]
	v_mfma_f32_16x16x32_bf16 v[44:47], v[156:159], v[190:193], v[44:47]
	v_mfma_f32_16x16x32_bf16 v[40:43], v[164:167], v[190:193], v[40:43]
	v_mfma_f32_16x16x32_bf16 v[28:31], v[156:159], v[198:201], v[28:31]
	v_mfma_f32_16x16x32_bf16 v[24:27], v[164:167], v[198:201], v[24:27]
	v_mfma_f32_16x16x32_bf16 v[12:15], v[156:159], v[206:209], v[12:15]
	v_mfma_f32_16x16x32_bf16 v[8:11], v[164:167], v[206:209], v[8:11]
	v_mfma_f32_16x16x32_bf16 v[52:55], v[210:213], v[168:171], v[52:55]
	v_mfma_f32_16x16x32_bf16 v[48:51], v[218:221], v[168:171], v[48:51]
	v_mfma_f32_16x16x32_bf16 v[36:39], v[210:213], v[182:185], v[36:39]
	v_mfma_f32_16x16x32_bf16 v[32:35], v[218:221], v[182:185], v[32:35]
	v_mfma_f32_16x16x32_bf16 v[20:23], v[210:213], v[194:197], v[20:23]
	v_mfma_f32_16x16x32_bf16 v[16:19], v[218:221], v[194:197], v[16:19]
	v_mfma_f32_16x16x32_bf16 v[4:7], v[210:213], v[202:205], v[4:7]
	v_mfma_f32_16x16x32_bf16 v[0:3], v[218:221], v[202:205], v[0:3]
	v_mfma_f32_16x16x32_bf16 v[52:55], v[214:217], v[172:175], v[52:55]
	v_mfma_f32_16x16x32_bf16 v[48:51], v[222:225], v[172:175], v[48:51]
	v_mfma_f32_16x16x32_bf16 v[36:39], v[214:217], v[190:193], v[36:39]
	v_mfma_f32_16x16x32_bf16 v[32:35], v[222:225], v[190:193], v[32:35]
	v_mfma_f32_16x16x32_bf16 v[20:23], v[214:217], v[198:201], v[20:23]
	v_mfma_f32_16x16x32_bf16 v[16:19], v[222:225], v[198:201], v[16:19]
	v_mfma_f32_16x16x32_bf16 v[4:7], v[214:217], v[206:209], v[4:7]
	v_mfma_f32_16x16x32_bf16 v[0:3], v[222:225], v[206:209], v[0:3]
	s_barrier
	s_add_i32 s47, s47, 2
	s_add_u32 s18, s18, 0x100
	s_addc_u32 s19, s19, 0
	s_add_u32 s45, s45, 0x100
	s_addc_u32 s46, s46, 0
	s_cmp_gt_u32 s47, 13
	s_cbranch_scc0 .LBB0_1011
	v_lshl_add_u32 v146, s16, 8, v150
	v_lshl_or_b32 v144, s42, 8, v152
	v_ashrrev_i32_e32 v147, 31, v146
	v_ashrrev_i32_e32 v145, 31, v144
	v_mov_b64_e32 v[148:149], s[4:5]
	v_lshlrev_b64 v[160:161], 11, v[146:147]
	v_lshlrev_b64 v[144:145], 1, v[144:145]
	v_mad_i64_i32 v[156:157], s[18:19], v146, s41, v[148:149]
	v_lshl_add_u64 v[160:161], s[0:1], 0, v[160:161]
	v_lshl_add_u64 v[164:165], v[156:157], 0, v[144:145]
	v_lshl_add_u64 v[166:167], v[160:161], 0, v[144:145]
	global_load_dwordx4 v[156:159], v[164:165], off
	global_load_dwordx4 v[160:163], v[166:167], off
	s_and_b64 vcc, exec, s[2:3]
	s_mov_b32 s42, s8
	s_mov_b32 s16, s10
	s_mov_b64 s[20:21], s[14:15]
	s_waitcnt vmcnt(0)
	v_lshlrev_b32_e32 v147, 16, v156
	v_and_b32_e32 v156, 0xffff0000, v156
	v_lshlrev_b32_e32 v168, 16, v157
	v_and_b32_e32 v157, 0xffff0000, v157
	v_lshlrev_b32_e32 v169, 16, v158
	v_and_b32_e32 v158, 0xffff0000, v158
	v_lshlrev_b32_e32 v170, 16, v159
	v_and_b32_e32 v159, 0xffff0000, v159
	v_lshlrev_b32_e32 v171, 16, v160
	v_and_b32_e32 v160, 0xffff0000, v160
	v_lshlrev_b32_e32 v172, 16, v161
	v_and_b32_e32 v161, 0xffff0000, v161
	v_lshlrev_b32_e32 v173, 16, v162
	v_and_b32_e32 v162, 0xffff0000, v162
	v_lshlrev_b32_e32 v174, 16, v163
	v_and_b32_e32 v163, 0xffff0000, v163
	v_fmac_f32_e32 v171, v124, v147
	v_fmac_f32_e32 v160, v125, v156
	v_fmac_f32_e32 v172, v126, v168
	v_fmac_f32_e32 v161, v127, v157
	v_fmac_f32_e32 v173, v120, v169
	v_fmac_f32_e32 v162, v121, v158
	v_fmac_f32_e32 v174, v122, v170
	v_fmac_f32_e32 v163, v123, v159
	v_cvt_pk_bf16_f32 v120, v171, v160
	v_cvt_pk_bf16_f32 v121, v172, v161
	v_cvt_pk_bf16_f32 v122, v173, v162
	v_cvt_pk_bf16_f32 v123, v174, v163
	global_load_dwordx4 v[124:127], v[164:165], off offset:256
	global_load_dwordx4 v[156:159], v[166:167], off offset:256
	v_or_b32_e32 v160, 16, v146
	global_store_dwordx4 v[166:167], v[120:123], off
	v_mad_i64_i32 v[162:163], s[18:19], v160, s41, v[148:149]
	v_lshl_add_u64 v[162:163], v[162:163], 0, v[144:145]
	s_waitcnt vmcnt(0)
; __device__ __forceinline__ unsigned cvt_pk_bf16(float lo, float hi) { unsigned r; asm volatile("v_cvt_pk_bf16_f32 %0, %1, %2" : "=v"(r) : "v"(lo), "v"(hi)); return r; }
; __device__ __forceinline__ float bf_lo(unsigned u) { return __uint_as_float(u << 16); }
; __device__ __forceinline__ float bf_hi(unsigned u) { return __uint_as_float(u & 0xffff0000u); }
;     __device__ __forceinline__ void operator()(const f32x4 (&acc)[2][2][4][2], const Unit& u, int wr, int wc, int fr, int fq) const {
;     ...
;             for (int m = 0; m < 4; ++m) { const size_t r = (size_t)(row0 + ai * HALF + m * 16); bf16_t* rowp = O + r * ldc + col0; const bf16_t* gp = G + r * ldg + col0;
; #pragma unroll
;                 for (int bj = 0; bj < 2; ++bj) { const u32x4 gw = *(const u32x4*)(gp + bj * HALF);
;                     f32x4 v0 = acc[ai][bj][m][0], v1 = acc[ai][bj][m][1];
;                     v0[0] *= bf_lo(gw.x); v0[1] *= bf_hi(gw.x); v0[2] *= bf_lo(gw.y); v0[3] *= bf_hi(gw.y);
;                     v1[0] *= bf_lo(gw.z); v1[1] *= bf_hi(gw.z); v1[2] *= bf_lo(gw.w); v1[3] *= bf_hi(gw.w);
;                     if (ACCUM) { const u32x4 pw = *(const u32x4*)(rowp + bj * HALF);
;                         v0[0] += bf_lo(pw.x); v0[1] += bf_hi(pw.x); v0[2] += bf_lo(pw.y); v0[3] += bf_hi(pw.y);
;                         v1[0] += bf_lo(pw.z); v1[1] += bf_hi(pw.z); v1[2] += bf_lo(pw.w); v1[3] += bf_hi(pw.w); }
;                     u32x4 w; w.x = cvt_pk_bf16(v0[0], v0[1]); w.y = cvt_pk_bf16(v0[2], v0[3]); w.z = cvt_pk_bf16(v1[0], v1[1]); w.w = cvt_pk_bf16(v1[2], v1[3]);
;                     *(u32x4*)(rowp + bj * HALF) = w; } }
	v_lshlrev_b32_e32 v122, 16, v125
	v_lshlrev_b32_e32 v161, 16, v157
	v_lshlrev_b32_e32 v120, 16, v124
	v_and_b32_e32 v121, 0xffff0000, v124
	v_and_b32_e32 v123, 0xffff0000, v125
	v_lshlrev_b32_e32 v124, 16, v126
	v_and_b32_e32 v125, 0xffff0000, v126
	v_lshlrev_b32_e32 v147, 16, v156
	v_and_b32_e32 v156, 0xffff0000, v156
	v_and_b32_e32 v157, 0xffff0000, v157
	v_lshlrev_b32_e32 v164, 16, v158
	v_and_b32_e32 v158, 0xffff0000, v158
	v_fmac_f32_e32 v161, v118, v122
	v_fmac_f32_e32 v147, v116, v120
	v_fmac_f32_e32 v156, v117, v121
	v_fmac_f32_e32 v157, v119, v123
	v_fmac_f32_e32 v164, v112, v124
	v_fmac_f32_e32 v158, v113, v125
	v_cvt_pk_bf16_f32 v112, v147, v156
	v_cvt_pk_bf16_f32 v113, v161, v157
	v_ashrrev_i32_e32 v161, 31, v160
	v_lshlrev_b64 v[120:121], 11, v[160:161]
	v_lshl_add_u64 v[120:121], s[0:1], 0, v[120:121]
	v_lshlrev_b32_e32 v126, 16, v127
	v_and_b32_e32 v127, 0xffff0000, v127
	v_lshlrev_b32_e32 v165, 16, v159
	v_and_b32_e32 v159, 0xffff0000, v159
	v_lshl_add_u64 v[124:125], v[120:121], 0, v[144:145]
	v_fmac_f32_e32 v165, v114, v126
	v_fmac_f32_e32 v159, v115, v127
	v_cvt_pk_bf16_f32 v114, v164, v158
	v_cvt_pk_bf16_f32 v115, v165, v159
	global_load_dwordx4 v[116:119], v[162:163], off
	global_load_dwordx4 v[120:123], v[124:125], off
	s_waitcnt vmcnt(0)
	v_lshlrev_b32_e32 v126, 16, v120
	global_store_dwordx4 v[166:167], v[112:115], off offset:256
	v_and_b32_e32 v120, 0xffff0000, v120
	v_lshlrev_b32_e32 v127, 16, v121
	v_lshlrev_b32_e32 v112, 16, v116
	v_and_b32_e32 v113, 0xffff0000, v116
	v_lshlrev_b32_e32 v114, 16, v117
	v_and_b32_e32 v115, 0xffff0000, v117
	v_lshlrev_b32_e32 v116, 16, v118
	v_and_b32_e32 v117, 0xffff0000, v118
	v_lshlrev_b32_e32 v118, 16, v119
	v_and_b32_e32 v119, 0xffff0000, v119
	v_and_b32_e32 v121, 0xffff0000, v121
	v_lshlrev_b32_e32 v147, 16, v122
	v_and_b32_e32 v122, 0xffff0000, v122
	v_lshlrev_b32_e32 v156, 16, v123
	v_and_b32_e32 v123, 0xffff0000, v123
	v_fmac_f32_e32 v126, v108, v112
	v_fmac_f32_e32 v120, v109, v113
	v_fmac_f32_e32 v127, v110, v114
	v_fmac_f32_e32 v121, v111, v115
	v_fmac_f32_e32 v147, v104, v116
	v_fmac_f32_e32 v122, v105, v117
	v_fmac_f32_e32 v156, v106, v118
	v_fmac_f32_e32 v123, v107, v119
	v_cvt_pk_bf16_f32 v104, v126, v120
	v_cvt_pk_bf16_f32 v105, v127, v121
	v_cvt_pk_bf16_f32 v106, v147, v122
	v_cvt_pk_bf16_f32 v107, v156, v123
	global_load_dwordx4 v[108:111], v[162:163], off offset:256
	global_load_dwordx4 v[112:115], v[124:125], off offset:256
	v_or_b32_e32 v116, 32, v146
	global_store_dwordx4 v[124:125], v[104:107], off
	v_mad_i64_i32 v[118:119], s[18:19], v116, s41, v[148:149]
	v_lshl_add_u64 v[118:119], v[118:119], 0, v[144:145]
	s_waitcnt vmcnt(0)
	v_lshlrev_b32_e32 v104, 16, v108
	v_lshlrev_b32_e32 v117, 16, v112
	v_and_b32_e32 v105, 0xffff0000, v108
	v_lshlrev_b32_e32 v108, 16, v110
	v_and_b32_e32 v112, 0xffff0000, v112
	v_lshlrev_b32_e32 v121, 16, v114
	v_fmac_f32_e32 v117, v100, v104
	v_fmac_f32_e32 v112, v101, v105
	v_fmac_f32_e32 v121, v96, v108
	v_cvt_pk_bf16_f32 v96, v117, v112
	v_ashrrev_i32_e32 v117, 31, v116
	v_lshlrev_b64 v[104:105], 11, v[116:117]
	v_lshlrev_b32_e32 v106, 16, v109
	v_and_b32_e32 v107, 0xffff0000, v109
	v_and_b32_e32 v109, 0xffff0000, v110
	v_and_b32_e32 v114, 0xffff0000, v114
	v_lshl_add_u64 v[104:105], s[0:1], 0, v[104:105]
	v_lshlrev_b32_e32 v110, 16, v111
	v_and_b32_e32 v111, 0xffff0000, v111
	v_lshlrev_b32_e32 v120, 16, v113
	v_and_b32_e32 v113, 0xffff0000, v113
	v_lshlrev_b32_e32 v122, 16, v115
	v_and_b32_e32 v115, 0xffff0000, v115
	v_fmac_f32_e32 v114, v97, v109
	v_lshl_add_u64 v[108:109], v[104:105], 0, v[144:145]
	v_fmac_f32_e32 v120, v102, v106
	v_fmac_f32_e32 v113, v103, v107
	v_fmac_f32_e32 v122, v98, v110
	v_fmac_f32_e32 v115, v99, v111
	v_cvt_pk_bf16_f32 v97, v120, v113
	v_cvt_pk_bf16_f32 v98, v121, v114
	v_cvt_pk_bf16_f32 v99, v122, v115
	global_load_dwordx4 v[100:103], v[118:119], off
	global_load_dwordx4 v[104:107], v[108:109], off
	s_waitcnt vmcnt(0)
	v_lshlrev_b32_e32 v110, 16, v104
	global_store_dwordx4 v[124:125], v[96:99], off offset:256
	v_and_b32_e32 v104, 0xffff0000, v104
	v_lshlrev_b32_e32 v111, 16, v105
	v_lshlrev_b32_e32 v96, 16, v100
	v_and_b32_e32 v97, 0xffff0000, v100
	v_lshlrev_b32_e32 v98, 16, v101
	v_and_b32_e32 v99, 0xffff0000, v101
	v_lshlrev_b32_e32 v100, 16, v102
	v_and_b32_e32 v101, 0xffff0000, v102
	v_lshlrev_b32_e32 v102, 16, v103
	v_and_b32_e32 v103, 0xffff0000, v103
	v_and_b32_e32 v105, 0xffff0000, v105
	v_lshlrev_b32_e32 v112, 16, v106
	v_and_b32_e32 v106, 0xffff0000, v106
	v_lshlrev_b32_e32 v113, 16, v107
	v_and_b32_e32 v107, 0xffff0000, v107
	v_fmac_f32_e32 v110, v92, v96
	v_fmac_f32_e32 v104, v93, v97
	v_fmac_f32_e32 v111, v94, v98
	v_fmac_f32_e32 v105, v95, v99
	v_fmac_f32_e32 v112, v88, v100
	v_fmac_f32_e32 v106, v89, v101
	v_fmac_f32_e32 v113, v90, v102
	v_fmac_f32_e32 v107, v91, v103
	v_cvt_pk_bf16_f32 v88, v110, v104
	v_cvt_pk_bf16_f32 v89, v111, v105
	v_cvt_pk_bf16_f32 v90, v112, v106
	v_cvt_pk_bf16_f32 v91, v113, v107
	global_load_dwordx4 v[92:95], v[118:119], off offset:256
	global_load_dwordx4 v[96:99], v[108:109], off offset:256
	v_or_b32_e32 v100, 48, v146
	global_store_dwordx4 v[108:109], v[88:91], off
	v_mad_i64_i32 v[102:103], s[18:19], v100, s41, v[148:149]
	v_lshl_add_u64 v[102:103], v[102:103], 0, v[144:145]
	s_waitcnt vmcnt(0)
; __device__ __forceinline__ unsigned cvt_pk_bf16(float lo, float hi) { unsigned r; asm volatile("v_cvt_pk_bf16_f32 %0, %1, %2" : "=v"(r) : "v"(lo), "v"(hi)); return r; }
; __device__ __forceinline__ float bf_lo(unsigned u) { return __uint_as_float(u << 16); }
; __device__ __forceinline__ float bf_hi(unsigned u) { return __uint_as_float(u & 0xffff0000u); }
;     __device__ __forceinline__ void operator()(const f32x4 (&acc)[2][2][4][2], const Unit& u, int wr, int wc, int fr, int fq) const {
;     ...
;             for (int m = 0; m < 4; ++m) { const size_t r = (size_t)(row0 + ai * HALF + m * 16); bf16_t* rowp = O + r * ldc + col0; const bf16_t* gp = G + r * ldg + col0;
; #pragma unroll
;                 for (int bj = 0; bj < 2; ++bj) { const u32x4 gw = *(const u32x4*)(gp + bj * HALF);
;                     f32x4 v0 = acc[ai][bj][m][0], v1 = acc[ai][bj][m][1];
;                     v0[0] *= bf_lo(gw.x); v0[1] *= bf_hi(gw.x); v0[2] *= bf_lo(gw.y); v0[3] *= bf_hi(gw.y);
;                     v1[0] *= bf_lo(gw.z); v1[1] *= bf_hi(gw.z); v1[2] *= bf_lo(gw.w); v1[3] *= bf_hi(gw.w);
;                     if (ACCUM) { const u32x4 pw = *(const u32x4*)(rowp + bj * HALF);
;                         v0[0] += bf_lo(pw.x); v0[1] += bf_hi(pw.x); v0[2] += bf_lo(pw.y); v0[3] += bf_hi(pw.y);
;                         v1[0] += bf_lo(pw.z); v1[1] += bf_hi(pw.z); v1[2] += bf_lo(pw.w); v1[3] += bf_hi(pw.w); }
;                     u32x4 w; w.x = cvt_pk_bf16(v0[0], v0[1]); w.y = cvt_pk_bf16(v0[2], v0[3]); w.z = cvt_pk_bf16(v1[0], v1[1]); w.w = cvt_pk_bf16(v1[2], v1[3]);
;                     *(u32x4*)(rowp + bj * HALF) = w; } }
	v_lshlrev_b32_e32 v88, 16, v92
	v_lshlrev_b32_e32 v101, 16, v96
	v_and_b32_e32 v89, 0xffff0000, v92
	v_lshlrev_b32_e32 v92, 16, v94
	v_and_b32_e32 v96, 0xffff0000, v96
	v_lshlrev_b32_e32 v105, 16, v98
	v_fmac_f32_e32 v101, v84, v88
	v_fmac_f32_e32 v96, v85, v89
	v_fmac_f32_e32 v105, v80, v92
	v_cvt_pk_bf16_f32 v80, v101, v96
	v_ashrrev_i32_e32 v101, 31, v100
	v_lshlrev_b64 v[88:89], 11, v[100:101]
	v_lshlrev_b32_e32 v90, 16, v93
	v_and_b32_e32 v91, 0xffff0000, v93
	v_and_b32_e32 v93, 0xffff0000, v94
	v_and_b32_e32 v98, 0xffff0000, v98
	v_lshl_add_u64 v[88:89], s[0:1], 0, v[88:89]
	v_lshlrev_b32_e32 v94, 16, v95
	v_and_b32_e32 v95, 0xffff0000, v95
	v_lshlrev_b32_e32 v104, 16, v97
	v_and_b32_e32 v97, 0xffff0000, v97
	v_lshlrev_b32_e32 v106, 16, v99
	v_and_b32_e32 v99, 0xffff0000, v99
	v_fmac_f32_e32 v98, v81, v93
	v_lshl_add_u64 v[92:93], v[88:89], 0, v[144:145]
	v_fmac_f32_e32 v104, v86, v90
	v_fmac_f32_e32 v97, v87, v91
	v_fmac_f32_e32 v106, v82, v94
	v_fmac_f32_e32 v99, v83, v95
	v_cvt_pk_bf16_f32 v81, v104, v97
	v_cvt_pk_bf16_f32 v82, v105, v98
	v_cvt_pk_bf16_f32 v83, v106, v99
	global_load_dwordx4 v[84:87], v[102:103], off
	global_load_dwordx4 v[88:91], v[92:93], off
	s_waitcnt vmcnt(0)
	v_lshlrev_b32_e32 v94, 16, v88
	global_store_dwordx4 v[108:109], v[80:83], off offset:256
	v_and_b32_e32 v88, 0xffff0000, v88
	v_lshlrev_b32_e32 v95, 16, v89
	v_lshlrev_b32_e32 v80, 16, v84
	v_and_b32_e32 v81, 0xffff0000, v84
	v_lshlrev_b32_e32 v82, 16, v85
	v_and_b32_e32 v83, 0xffff0000, v85
	v_lshlrev_b32_e32 v84, 16, v86
	v_and_b32_e32 v85, 0xffff0000, v86
	v_lshlrev_b32_e32 v86, 16, v87
	v_and_b32_e32 v87, 0xffff0000, v87
	v_and_b32_e32 v89, 0xffff0000, v89
	v_lshlrev_b32_e32 v96, 16, v90
	v_and_b32_e32 v90, 0xffff0000, v90
	v_lshlrev_b32_e32 v97, 16, v91
	v_and_b32_e32 v91, 0xffff0000, v91
	v_fmac_f32_e32 v94, v76, v80
	v_fmac_f32_e32 v88, v77, v81
	v_fmac_f32_e32 v95, v78, v82
	v_fmac_f32_e32 v89, v79, v83
	v_fmac_f32_e32 v96, v72, v84
	v_fmac_f32_e32 v90, v73, v85
	v_fmac_f32_e32 v97, v74, v86
	v_fmac_f32_e32 v91, v75, v87
	v_cvt_pk_bf16_f32 v72, v94, v88
	v_cvt_pk_bf16_f32 v73, v95, v89
	v_cvt_pk_bf16_f32 v74, v96, v90
	v_cvt_pk_bf16_f32 v75, v97, v91
	global_load_dwordx4 v[76:79], v[102:103], off offset:256
	global_load_dwordx4 v[80:83], v[92:93], off offset:256
	v_add_u32_e32 v84, 0x80, v146
	global_store_dwordx4 v[92:93], v[72:75], off
	v_mad_i64_i32 v[86:87], s[18:19], v84, s41, v[148:149]
	v_lshl_add_u64 v[86:87], v[86:87], 0, v[144:145]
	s_waitcnt vmcnt(0)
	v_lshlrev_b32_e32 v72, 16, v76
	v_lshlrev_b32_e32 v85, 16, v80
	v_and_b32_e32 v73, 0xffff0000, v76
	v_lshlrev_b32_e32 v76, 16, v78
	v_and_b32_e32 v80, 0xffff0000, v80
	v_lshlrev_b32_e32 v89, 16, v82
	v_fmac_f32_e32 v85, v68, v72
	v_fmac_f32_e32 v80, v69, v73
	v_fmac_f32_e32 v89, v64, v76
	v_cvt_pk_bf16_f32 v64, v85, v80
	v_ashrrev_i32_e32 v85, 31, v84
	v_lshlrev_b64 v[72:73], 11, v[84:85]
	v_lshlrev_b32_e32 v74, 16, v77
	v_and_b32_e32 v75, 0xffff0000, v77
	v_and_b32_e32 v77, 0xffff0000, v78
	v_and_b32_e32 v82, 0xffff0000, v82
	v_lshl_add_u64 v[72:73], s[0:1], 0, v[72:73]
	v_lshlrev_b32_e32 v78, 16, v79
	v_and_b32_e32 v79, 0xffff0000, v79
	v_lshlrev_b32_e32 v88, 16, v81
	v_and_b32_e32 v81, 0xffff0000, v81
	v_lshlrev_b32_e32 v90, 16, v83
	v_and_b32_e32 v83, 0xffff0000, v83
	v_fmac_f32_e32 v82, v65, v77
	v_lshl_add_u64 v[76:77], v[72:73], 0, v[144:145]
	v_fmac_f32_e32 v88, v70, v74
	v_fmac_f32_e32 v81, v71, v75
	v_fmac_f32_e32 v90, v66, v78
	v_fmac_f32_e32 v83, v67, v79
	v_cvt_pk_bf16_f32 v65, v88, v81
	v_cvt_pk_bf16_f32 v66, v89, v82
	v_cvt_pk_bf16_f32 v67, v90, v83
	global_load_dwordx4 v[68:71], v[86:87], off
	global_load_dwordx4 v[72:75], v[76:77], off
	s_waitcnt vmcnt(0)
	v_lshlrev_b32_e32 v78, 16, v72
	global_store_dwordx4 v[92:93], v[64:67], off offset:256
	v_and_b32_e32 v72, 0xffff0000, v72
	v_lshlrev_b32_e32 v79, 16, v73
	v_lshlrev_b32_e32 v64, 16, v68
	v_and_b32_e32 v65, 0xffff0000, v68
	v_lshlrev_b32_e32 v66, 16, v69
	v_and_b32_e32 v67, 0xffff0000, v69
	v_lshlrev_b32_e32 v68, 16, v70
	v_and_b32_e32 v69, 0xffff0000, v70
	v_lshlrev_b32_e32 v70, 16, v71
	v_and_b32_e32 v71, 0xffff0000, v71
	v_and_b32_e32 v73, 0xffff0000, v73
	v_lshlrev_b32_e32 v80, 16, v74
	v_and_b32_e32 v74, 0xffff0000, v74
	v_lshlrev_b32_e32 v81, 16, v75
	v_and_b32_e32 v75, 0xffff0000, v75
	v_fmac_f32_e32 v78, v60, v64
	v_fmac_f32_e32 v72, v61, v65
	v_fmac_f32_e32 v79, v62, v66
	v_fmac_f32_e32 v73, v63, v67
	v_fmac_f32_e32 v80, v56, v68
	v_fmac_f32_e32 v74, v57, v69
	v_fmac_f32_e32 v81, v58, v70
	v_fmac_f32_e32 v75, v59, v71
	v_cvt_pk_bf16_f32 v56, v78, v72
	v_cvt_pk_bf16_f32 v57, v79, v73
	v_cvt_pk_bf16_f32 v58, v80, v74
	v_cvt_pk_bf16_f32 v59, v81, v75
	global_load_dwordx4 v[60:63], v[86:87], off offset:256
	global_load_dwordx4 v[64:67], v[76:77], off offset:256
	v_add_u32_e32 v68, 0x90, v146
	global_store_dwordx4 v[76:77], v[56:59], off
	v_mad_i64_i32 v[70:71], s[18:19], v68, s41, v[148:149]
	v_lshl_add_u64 v[70:71], v[70:71], 0, v[144:145]
	s_waitcnt vmcnt(0)
	v_lshlrev_b32_e32 v56, 16, v60
	v_lshlrev_b32_e32 v69, 16, v64
	v_and_b32_e32 v57, 0xffff0000, v60
	v_lshlrev_b32_e32 v60, 16, v62
	v_and_b32_e32 v64, 0xffff0000, v64
	v_lshlrev_b32_e32 v73, 16, v66
	v_fmac_f32_e32 v69, v52, v56
	v_fmac_f32_e32 v64, v53, v57
	v_fmac_f32_e32 v73, v48, v60
	v_cvt_pk_bf16_f32 v48, v69, v64
	v_ashrrev_i32_e32 v69, 31, v68
	v_lshlrev_b64 v[56:57], 11, v[68:69]
	v_lshlrev_b32_e32 v58, 16, v61
	v_and_b32_e32 v59, 0xffff0000, v61
	v_and_b32_e32 v61, 0xffff0000, v62
	v_and_b32_e32 v66, 0xffff0000, v66
	v_lshl_add_u64 v[56:57], s[0:1], 0, v[56:57]
	v_lshlrev_b32_e32 v62, 16, v63
	v_and_b32_e32 v63, 0xffff0000, v63
	v_lshlrev_b32_e32 v72, 16, v65
	v_and_b32_e32 v65, 0xffff0000, v65
	v_lshlrev_b32_e32 v74, 16, v67
	v_and_b32_e32 v67, 0xffff0000, v67
	v_fmac_f32_e32 v66, v49, v61
	v_lshl_add_u64 v[60:61], v[56:57], 0, v[144:145]
	v_fmac_f32_e32 v72, v54, v58
	v_fmac_f32_e32 v65, v55, v59
	v_fmac_f32_e32 v74, v50, v62
	v_fmac_f32_e32 v67, v51, v63
	v_cvt_pk_bf16_f32 v49, v72, v65
	v_cvt_pk_bf16_f32 v50, v73, v66
	v_cvt_pk_bf16_f32 v51, v74, v67
	global_load_dwordx4 v[52:55], v[70:71], off
	global_load_dwordx4 v[56:59], v[60:61], off
	s_waitcnt vmcnt(0)
; __device__ __forceinline__ unsigned cvt_pk_bf16(float lo, float hi) { unsigned r; asm volatile("v_cvt_pk_bf16_f32 %0, %1, %2" : "=v"(r) : "v"(lo), "v"(hi)); return r; }
; __device__ __forceinline__ float bf_lo(unsigned u) { return __uint_as_float(u << 16); }
; __device__ __forceinline__ float bf_hi(unsigned u) { return __uint_as_float(u & 0xffff0000u); }
;     __device__ __forceinline__ void operator()(const f32x4 (&acc)[2][2][4][2], const Unit& u, int wr, int wc, int fr, int fq) const {
;     ...
;             for (int m = 0; m < 4; ++m) { const size_t r = (size_t)(row0 + ai * HALF + m * 16); bf16_t* rowp = O + r * ldc + col0; const bf16_t* gp = G + r * ldg + col0;
; #pragma unroll
;                 for (int bj = 0; bj < 2; ++bj) { const u32x4 gw = *(const u32x4*)(gp + bj * HALF);
;                     f32x4 v0 = acc[ai][bj][m][0], v1 = acc[ai][bj][m][1];
;                     v0[0] *= bf_lo(gw.x); v0[1] *= bf_hi(gw.x); v0[2] *= bf_lo(gw.y); v0[3] *= bf_hi(gw.y);
;                     v1[0] *= bf_lo(gw.z); v1[1] *= bf_hi(gw.z); v1[2] *= bf_lo(gw.w); v1[3] *= bf_hi(gw.w);
;                     if (ACCUM) { const u32x4 pw = *(const u32x4*)(rowp + bj * HALF);
;                         v0[0] += bf_lo(pw.x); v0[1] += bf_hi(pw.x); v0[2] += bf_lo(pw.y); v0[3] += bf_hi(pw.y);
;                         v1[0] += bf_lo(pw.z); v1[1] += bf_hi(pw.z); v1[2] += bf_lo(pw.w); v1[3] += bf_hi(pw.w); }
;                     u32x4 w; w.x = cvt_pk_bf16(v0[0], v0[1]); w.y = cvt_pk_bf16(v0[2], v0[3]); w.z = cvt_pk_bf16(v1[0], v1[1]); w.w = cvt_pk_bf16(v1[2], v1[3]);
;                     *(u32x4*)(rowp + bj * HALF) = w; } }
	v_lshlrev_b32_e32 v62, 16, v56
	global_store_dwordx4 v[76:77], v[48:51], off offset:256
	v_and_b32_e32 v56, 0xffff0000, v56
	v_lshlrev_b32_e32 v63, 16, v57
	v_lshlrev_b32_e32 v48, 16, v52
	v_and_b32_e32 v49, 0xffff0000, v52
	v_lshlrev_b32_e32 v50, 16, v53
	v_and_b32_e32 v51, 0xffff0000, v53
	v_lshlrev_b32_e32 v52, 16, v54
	v_and_b32_e32 v53, 0xffff0000, v54
	v_lshlrev_b32_e32 v54, 16, v55
	v_and_b32_e32 v55, 0xffff0000, v55
	v_and_b32_e32 v57, 0xffff0000, v57
	v_lshlrev_b32_e32 v64, 16, v58
	v_and_b32_e32 v58, 0xffff0000, v58
	v_lshlrev_b32_e32 v65, 16, v59
	v_and_b32_e32 v59, 0xffff0000, v59
	v_fmac_f32_e32 v62, v44, v48
	v_fmac_f32_e32 v56, v45, v49
	v_fmac_f32_e32 v63, v46, v50
	v_fmac_f32_e32 v57, v47, v51
	v_fmac_f32_e32 v64, v40, v52
	v_fmac_f32_e32 v58, v41, v53
	v_fmac_f32_e32 v65, v42, v54
	v_fmac_f32_e32 v59, v43, v55
	v_cvt_pk_bf16_f32 v40, v62, v56
	v_cvt_pk_bf16_f32 v41, v63, v57
	v_cvt_pk_bf16_f32 v42, v64, v58
	v_cvt_pk_bf16_f32 v43, v65, v59
	global_load_dwordx4 v[44:47], v[70:71], off offset:256
	global_load_dwordx4 v[48:51], v[60:61], off offset:256
	v_add_u32_e32 v52, 0xa0, v146
	global_store_dwordx4 v[60:61], v[40:43], off
	v_mad_i64_i32 v[54:55], s[18:19], v52, s41, v[148:149]
	v_lshl_add_u64 v[54:55], v[54:55], 0, v[144:145]
	s_waitcnt vmcnt(0)
	v_lshlrev_b32_e32 v40, 16, v44
	v_lshlrev_b32_e32 v53, 16, v48
	v_and_b32_e32 v41, 0xffff0000, v44
	v_lshlrev_b32_e32 v44, 16, v46
	v_and_b32_e32 v48, 0xffff0000, v48
	v_lshlrev_b32_e32 v57, 16, v50
	v_fmac_f32_e32 v53, v36, v40
	v_fmac_f32_e32 v48, v37, v41
	v_fmac_f32_e32 v57, v32, v44
	v_cvt_pk_bf16_f32 v32, v53, v48
	v_ashrrev_i32_e32 v53, 31, v52
	v_lshlrev_b64 v[40:41], 11, v[52:53]
	v_lshlrev_b32_e32 v42, 16, v45
	v_and_b32_e32 v43, 0xffff0000, v45
	v_and_b32_e32 v45, 0xffff0000, v46
	v_and_b32_e32 v50, 0xffff0000, v50
	v_lshl_add_u64 v[40:41], s[0:1], 0, v[40:41]
	v_lshlrev_b32_e32 v46, 16, v47
	v_and_b32_e32 v47, 0xffff0000, v47
	v_lshlrev_b32_e32 v56, 16, v49
	v_and_b32_e32 v49, 0xffff0000, v49
	v_lshlrev_b32_e32 v58, 16, v51
	v_and_b32_e32 v51, 0xffff0000, v51
	v_fmac_f32_e32 v50, v33, v45
	v_lshl_add_u64 v[44:45], v[40:41], 0, v[144:145]
	v_fmac_f32_e32 v56, v38, v42
	v_fmac_f32_e32 v49, v39, v43
	v_fmac_f32_e32 v58, v34, v46
	v_fmac_f32_e32 v51, v35, v47
	v_cvt_pk_bf16_f32 v33, v56, v49
	v_cvt_pk_bf16_f32 v34, v57, v50
	v_cvt_pk_bf16_f32 v35, v58, v51
	global_load_dwordx4 v[36:39], v[54:55], off
	global_load_dwordx4 v[40:43], v[44:45], off
	s_waitcnt vmcnt(0)
	v_lshlrev_b32_e32 v46, 16, v40
	global_store_dwordx4 v[60:61], v[32:35], off offset:256
	v_and_b32_e32 v40, 0xffff0000, v40
	v_lshlrev_b32_e32 v47, 16, v41
	v_lshlrev_b32_e32 v32, 16, v36
	v_and_b32_e32 v33, 0xffff0000, v36
	v_lshlrev_b32_e32 v34, 16, v37
	v_and_b32_e32 v35, 0xffff0000, v37
	v_lshlrev_b32_e32 v36, 16, v38
	v_and_b32_e32 v37, 0xffff0000, v38
	v_lshlrev_b32_e32 v38, 16, v39
	v_and_b32_e32 v39, 0xffff0000, v39
	v_and_b32_e32 v41, 0xffff0000, v41
	v_lshlrev_b32_e32 v48, 16, v42
	v_and_b32_e32 v42, 0xffff0000, v42
	v_lshlrev_b32_e32 v49, 16, v43
	v_and_b32_e32 v43, 0xffff0000, v43
	v_fmac_f32_e32 v46, v28, v32
	v_fmac_f32_e32 v40, v29, v33
	v_fmac_f32_e32 v47, v30, v34
	v_fmac_f32_e32 v41, v31, v35
	v_fmac_f32_e32 v48, v24, v36
	v_fmac_f32_e32 v42, v25, v37
	v_fmac_f32_e32 v49, v26, v38
	v_fmac_f32_e32 v43, v27, v39
	v_cvt_pk_bf16_f32 v24, v46, v40
	v_cvt_pk_bf16_f32 v25, v47, v41
	v_cvt_pk_bf16_f32 v26, v48, v42
	v_cvt_pk_bf16_f32 v27, v49, v43
	global_load_dwordx4 v[28:31], v[54:55], off offset:256
	global_load_dwordx4 v[32:35], v[44:45], off offset:256
	v_add_u32_e32 v36, 0xb0, v146
	global_store_dwordx4 v[44:45], v[24:27], off
	v_mad_i64_i32 v[38:39], s[18:19], v36, s41, v[148:149]
	v_lshl_add_u64 v[38:39], v[38:39], 0, v[144:145]
	s_mov_b64 s[18:19], s[12:13]
	s_waitcnt vmcnt(0)
; __device__ __forceinline__ unsigned cvt_pk_bf16(float lo, float hi) { unsigned r; asm volatile("v_cvt_pk_bf16_f32 %0, %1, %2" : "=v"(r) : "v"(lo), "v"(hi)); return r; }
; __device__ __forceinline__ float bf_lo(unsigned u) { return __uint_as_float(u << 16); }
; __device__ __forceinline__ float bf_hi(unsigned u) { return __uint_as_float(u & 0xffff0000u); }
; #define PG8_WAIT_V(n) asm volatile("s_waitcnt vmcnt(" #n ")" ::: "memory")
; #define PG8_BAR __builtin_amdgcn_s_barrier()
;     __device__ __forceinline__ void operator()(const f32x4 (&acc)[2][2][4][2], const Unit& u, int wr, int wc, int fr, int fq) const {
;     ...
;             for (int m = 0; m < 4; ++m) { const size_t r = (size_t)(row0 + ai * HALF + m * 16); bf16_t* rowp = O + r * ldc + col0; const bf16_t* gp = G + r * ldg + col0;
; #pragma unroll
;                 for (int bj = 0; bj < 2; ++bj) { const u32x4 gw = *(const u32x4*)(gp + bj * HALF);
;                     f32x4 v0 = acc[ai][bj][m][0], v1 = acc[ai][bj][m][1];
;                     v0[0] *= bf_lo(gw.x); v0[1] *= bf_hi(gw.x); v0[2] *= bf_lo(gw.y); v0[3] *= bf_hi(gw.y);
;                     v1[0] *= bf_lo(gw.z); v1[1] *= bf_hi(gw.z); v1[2] *= bf_lo(gw.w); v1[3] *= bf_hi(gw.w);
;                     if (ACCUM) { const u32x4 pw = *(const u32x4*)(rowp + bj * HALF);
;                         v0[0] += bf_lo(pw.x); v0[1] += bf_hi(pw.x); v0[2] += bf_lo(pw.y); v0[3] += bf_hi(pw.y);
;                         v1[0] += bf_lo(pw.z); v1[1] += bf_hi(pw.z); v1[2] += bf_lo(pw.w); v1[3] += bf_hi(pw.w); }
;                     u32x4 w; w.x = cvt_pk_bf16(v0[0], v0[1]); w.y = cvt_pk_bf16(v0[2], v0[3]); w.z = cvt_pk_bf16(v1[0], v1[1]); w.w = cvt_pk_bf16(v1[2], v1[3]);
;                     *(u32x4*)(rowp + bj * HALF) = w; } }
; template <class Epi, class Sched>
; __device__ __forceinline__ void gemm_phase(PG8_LAS unsigned char* lds, const Gemm g, const Sched& S, const Epi& E) {
;     ...
;         if (!has_next) break;
; #pragma unroll
;         for (int a = 0; a < 2; ++a)
; #pragma unroll
;             for (int b = 0; b < 2; ++b)
; #pragma unroll
;                 for (int m = 0; m < 4; ++m)
; #pragma unroll
;                     for (int n = 0; n < 2; ++n) acc[a][b][m][n] = (f32x4){0.f, 0.f, 0.f, 0.f};
;         cur = nxt; cA = nA; cB = nB; ++ui;
;     }
;     PG8_WAIT_V(0);
;     if (wr == 0) PG8_BAR;
;     PG8_BAR;
	v_lshlrev_b32_e32 v24, 16, v28
	v_lshlrev_b32_e32 v37, 16, v32
	v_and_b32_e32 v25, 0xffff0000, v28
	v_lshlrev_b32_e32 v28, 16, v30
	v_and_b32_e32 v32, 0xffff0000, v32
	v_lshlrev_b32_e32 v41, 16, v34
	v_fmac_f32_e32 v37, v20, v24
	v_fmac_f32_e32 v32, v21, v25
	v_fmac_f32_e32 v41, v16, v28
	v_cvt_pk_bf16_f32 v16, v37, v32
	v_ashrrev_i32_e32 v37, 31, v36
	v_lshlrev_b64 v[24:25], 11, v[36:37]
	v_lshlrev_b32_e32 v26, 16, v29
	v_and_b32_e32 v27, 0xffff0000, v29
	v_and_b32_e32 v29, 0xffff0000, v30
	v_and_b32_e32 v34, 0xffff0000, v34
	v_lshl_add_u64 v[24:25], s[0:1], 0, v[24:25]
	v_lshlrev_b32_e32 v30, 16, v31
	v_and_b32_e32 v31, 0xffff0000, v31
	v_lshlrev_b32_e32 v40, 16, v33
	v_and_b32_e32 v33, 0xffff0000, v33
	v_lshlrev_b32_e32 v42, 16, v35
	v_and_b32_e32 v35, 0xffff0000, v35
	v_fmac_f32_e32 v34, v17, v29
	v_lshl_add_u64 v[28:29], v[24:25], 0, v[144:145]
	v_fmac_f32_e32 v40, v22, v26
	v_fmac_f32_e32 v33, v23, v27
	v_fmac_f32_e32 v42, v18, v30
	v_fmac_f32_e32 v35, v19, v31
	v_cvt_pk_bf16_f32 v17, v40, v33
	v_cvt_pk_bf16_f32 v18, v41, v34
	v_cvt_pk_bf16_f32 v19, v42, v35
	global_load_dwordx4 v[20:23], v[38:39], off
	global_load_dwordx4 v[24:27], v[28:29], off
	s_waitcnt vmcnt(0)
	v_lshlrev_b32_e32 v30, 16, v24
	global_store_dwordx4 v[44:45], v[16:19], off offset:256
	v_and_b32_e32 v24, 0xffff0000, v24
	v_lshlrev_b32_e32 v31, 16, v25
	v_lshlrev_b32_e32 v16, 16, v20
	v_and_b32_e32 v17, 0xffff0000, v20
	v_lshlrev_b32_e32 v18, 16, v21
	v_and_b32_e32 v19, 0xffff0000, v21
	v_lshlrev_b32_e32 v20, 16, v22
	v_and_b32_e32 v21, 0xffff0000, v22
	v_lshlrev_b32_e32 v22, 16, v23
	v_and_b32_e32 v23, 0xffff0000, v23
	v_and_b32_e32 v25, 0xffff0000, v25
	v_lshlrev_b32_e32 v32, 16, v26
	v_and_b32_e32 v26, 0xffff0000, v26
	v_lshlrev_b32_e32 v33, 16, v27
	v_and_b32_e32 v27, 0xffff0000, v27
	v_fmac_f32_e32 v30, v12, v16
	v_fmac_f32_e32 v24, v13, v17
	v_fmac_f32_e32 v31, v14, v18
	v_fmac_f32_e32 v25, v15, v19
	v_fmac_f32_e32 v32, v8, v20
	v_fmac_f32_e32 v26, v9, v21
	v_fmac_f32_e32 v33, v10, v22
	v_fmac_f32_e32 v27, v11, v23
	v_cvt_pk_bf16_f32 v8, v30, v24
	v_cvt_pk_bf16_f32 v9, v31, v25
	v_cvt_pk_bf16_f32 v10, v32, v26
	v_cvt_pk_bf16_f32 v11, v33, v27
	global_load_dwordx4 v[12:15], v[38:39], off offset:256
	global_load_dwordx4 v[16:19], v[28:29], off offset:256
	s_waitcnt vmcnt(0)
	v_lshlrev_b32_e32 v20, 16, v16
	global_store_dwordx4 v[28:29], v[8:11], off
	v_and_b32_e32 v16, 0xffff0000, v16
	v_lshlrev_b32_e32 v21, 16, v17
	v_lshlrev_b32_e32 v8, 16, v12
	v_and_b32_e32 v9, 0xffff0000, v12
	v_lshlrev_b32_e32 v10, 16, v13
	v_and_b32_e32 v11, 0xffff0000, v13
	v_lshlrev_b32_e32 v12, 16, v14
	v_and_b32_e32 v13, 0xffff0000, v14
	v_lshlrev_b32_e32 v14, 16, v15
	v_and_b32_e32 v15, 0xffff0000, v15
	v_and_b32_e32 v17, 0xffff0000, v17
	v_lshlrev_b32_e32 v22, 16, v18
	v_and_b32_e32 v18, 0xffff0000, v18
	v_lshlrev_b32_e32 v23, 16, v19
	v_and_b32_e32 v19, 0xffff0000, v19
	v_fmac_f32_e32 v20, v4, v8
	v_fmac_f32_e32 v16, v5, v9
	v_fmac_f32_e32 v21, v6, v10
	v_fmac_f32_e32 v17, v7, v11
	v_fmac_f32_e32 v22, v0, v12
	v_fmac_f32_e32 v18, v1, v13
	v_fmac_f32_e32 v23, v2, v14
	v_fmac_f32_e32 v19, v3, v15
	v_cvt_pk_bf16_f32 v0, v20, v16
	v_cvt_pk_bf16_f32 v1, v21, v17
	v_cvt_pk_bf16_f32 v2, v22, v18
	v_cvt_pk_bf16_f32 v3, v23, v19
	global_store_dwordx4 v[28:29], v[0:3], off offset:256
	s_cbranch_vccz .LBB0_1004
	s_waitcnt vmcnt(0)
	s_cmpk_gt_u32 s25, 0xff
	s_cbranch_scc1 .LBB0_1015
	s_barrier

; #define PG8_STAGE(bufoff, gbase, voff) do { _Pragma("unroll") for (int _i = 0; _i < 2; ++_i) \
;         __builtin_amdgcn_global_load_lds((const unsigned*)((const char*)(gbase) + (voff)[_i]), (PG8_LAS unsigned*)(lds + (bufoff) + ldsw + _i * 8192), 16, 0, 0); } while (0)
; #define PG8_WAIT_V(n) asm volatile("s_waitcnt vmcnt(" #n ")" ::: "memory")
; #define PG8_BAR __builtin_amdgcn_s_barrier()
; template <class Epi, class Sched>
; __device__ __forceinline__ void gemm_phase(PG8_LAS unsigned char* lds, const Gemm g, const Sched& S, const Epi& E) {
;     ...
;     for (int i = 0; i < 2; ++i) { int R, C; stage_rc(tid * 16 + i * 8192, R, C); const int Rb = Epi::PERM ? ((R & ~31) + perm32(R & 31)) : R;
;         voffA[i] = (unsigned)(R * K + C) * 2u; voffB[i] = (unsigned)(Rb * K + C) * 2u; }
;     const size_t kstep = (size_t)(BK * 2);
;     const size_t hstep = (size_t)HALF * K * 2;
;     const size_t tstep = 2 * hstep;
;     const unsigned ldsw = (unsigned)wid * 1024u;
;     const int aoff = lds_byte(wr * 64 + fr, fq * 8), boff = lds_byte(wc * 32 + fr, fq * 8);
;     ...
;     const char* cA = (const char*)g.A + (size_t)cur.pm * tstep; const char* cB = (const char*)g.Bt + (size_t)cur.pn * tstep;
;     S.a_ready(cur);
;     PG8_STAGE(PG8_SB(0, 0), cB, voffB); PG8_STAGE(PG8_SA(0, 0), cA, voffA); PG8_STAGE(PG8_SB(0, 1), cB + hstep, voffB); PG8_STAGE(PG8_SA(0, 1), cA + hstep, voffA);
;     if (wr == 1) PG8_BAR;
;     PG8_WAIT_V(4); PG8_BAR;
;     PG8_STAGE(PG8_SB(1, 0), cB + kstep, voffB); PG8_STAGE(PG8_SA(1, 0), cA + kstep, voffA); PG8_STAGE(PG8_SB(1, 1), cB + hstep + kstep, voffB);
;     PG8_WAIT_V(6); PG8_BAR;
.LBB0_1075:
	s_lshl_b32 s4, s4, 27
	v_readlane_b32 s5, v245, 18
	s_add_u32 s4, s5, s4
	v_readlane_b32 s5, v245, 19
	s_addc_u32 s5, s5, 0
	s_lshl_b32 s3, s3, 5
	s_mov_b64 s[6:7], 0x80
	s_and_b32 s3, s3, 0x60
	s_add_i32 m0, s23, 0x18000
	v_lshl_add_u64 v[6:7], v[6:7], 0, s[6:7]
	s_lshl_b32 s9, s8, 13
	s_lshl_b32 s12, s3, 7
	s_waitcnt vmcnt(0)
	s_barrier
	global_load_lds_dwordx4 v[6:7], off
	v_lshl_add_u64 v[4:5], v[4:5], 0, s[6:7]
	s_add_i32 m0, s23, 0x1a000
	s_add_i32 s42, s23, 0x8000
	s_add_i32 s43, s23, 0xa000
	global_load_lds_dwordx4 v[4:5], off
	v_lshl_add_u64 v[2:3], v[2:3], 0, s[6:7]
	s_mov_b32 m0, s42
	s_add_u32 s10, s26, 0x40080
	global_load_lds_dwordx4 v[2:3], off
	v_lshl_add_u64 v[0:1], v[0:1], 0, s[6:7]
	s_mov_b32 m0, s43
	s_addc_u32 s11, s27, 0
	global_load_lds_dwordx4 v[0:1], off
	s_add_i32 m0, s23, 0x1c000
	v_lshl_add_u64 v[0:1], s[10:11], 0, v[130:131]
	global_load_lds_dwordx4 v[0:1], off
	v_lshl_add_u64 v[0:1], s[10:11], 0, v[134:135]
	s_add_i32 m0, s23, 0x1e000
	s_add_i32 s45, 0, 0x10000
	global_load_lds_dwordx4 v[0:1], off
	v_lshrrev_b32_e32 v1, 1, v8
	v_and_b32_e32 v1, 24, v1
	v_and_b32_e32 v0, 15, v8
	v_lshlrev_b32_e32 v2, 1, v1
	v_lshl_or_b32 v146, s8, 6, v0
	v_lshl_or_b32 v0, v0, 6, v2
	v_lshlrev_b32_e32 v2, 2, v8
	v_and_b32_e32 v2, 32, v2
	v_bitop3_b32 v3, v0, s9, v2 bitop3:0xde
	v_bitop3_b32 v147, v0, s12, v2 bitop3:0xde
	v_lshlrev_b32_e32 v0, 14, v9
	v_and_b32_e32 v0, 0xffff8000, v0
	v_or_b32_e32 v148, s3, v1
	v_lshl_add_u32 v0, v10, 11, v0
	v_and_b32_e32 v1, 1, v9
	v_lshl_or_b32 v0, v1, 6, v0
	v_lshl_add_u32 v136, v11, 1, v0
	v_lshlrev_b32_e32 v0, 14, v12
	v_and_b32_e32 v0, 0xffff8000, v0
	s_waitcnt vmcnt(6)
	v_lshl_add_u32 v0, v13, 11, v0
	v_and_b32_e32 v1, 1, v12
	v_lshl_or_b32 v0, v1, 6, v0
	s_add_i32 s46, 0, 0x14000
	s_sext_i32_i8 s51, s2
	s_ashr_i32 s44, s33, 31
	v_mov_b32_e32 v137, v131
	v_lshl_add_u32 v138, v14, 1, v0
	v_mov_b32_e32 v139, v131
	v_mov_b64_e32 v[140:141], 0x100
	v_mov_b64_e32 v[142:143], 0xff
	v_add_u32_e32 v149, s45, v147
	v_add_u32_e32 v150, 0, v3
	v_add_u32_e32 v151, s46, v147
	s_mov_b32 s47, 0x40000
	s_mov_b64 s[8:9], 0x48000
	s_mov_b32 s48, 0x48000
	s_mov_b64 s[10:11], 0x50000
	s_mov_b32 s49, 0x50000
	s_mov_b64 s[12:13], 0x58000
	s_mov_b32 s50, 0x58000
	s_barrier

; #define PG8_STAGE(bufoff, gbase, voff) do { _Pragma("unroll") for (int _i = 0; _i < 2; ++_i) \
;         __builtin_amdgcn_global_load_lds((const unsigned*)((const char*)(gbase) + (voff)[_i]), (PG8_LAS unsigned*)(lds + (bufoff) + ldsw + _i * 8192), 16, 0, 0); } while (0)
; #define PG8_LDA(dst, b, h) do { _Pragma("unroll") for (int m = 0; m < 4; ++m) _Pragma("unroll") for (int k = 0; k < 2; ++k) dst[m][k] = *(const PG8_LAS bf16x8*)(lds + PG8_SA(b, h) + aoff + m * 2048 + k * 1024); } while (0)
; #define PG8_LDB(dst, b, h) do { _Pragma("unroll") for (int n = 0; n < 2; ++n) _Pragma("unroll") for (int k = 0; k < 2; ++k) dst[n][k] = *(const PG8_LAS bf16x8*)(lds + PG8_SB(b, h) + boff + n * 2048 + k * 1024); } while (0)
; #define PG8_MMA(ai, bj, At, Bt) do { __builtin_amdgcn_s_setprio(1); _Pragma("unroll") for (int m = 0; m < 4; ++m) _Pragma("unroll") for (int n = 0; n < 2; ++n) _Pragma("unroll") for (int k = 0; k < 2; ++k) \
;         acc[ai][bj][m][n] = __builtin_amdgcn_mfma_f32_16x16x32_bf16(Bt[n][k], At[m][k], acc[ai][bj][m][n], 0, 0, 0); __builtin_amdgcn_s_setprio(0); } while (0)
; #define PG8_WAIT_V(n) asm volatile("s_waitcnt vmcnt(" #n ")" ::: "memory")
; #define PG8_WAIT_L(n) asm volatile("s_waitcnt lgkmcnt(" #n ")" ::: "memory")
; #define PG8_BAR __builtin_amdgcn_s_barrier()
; #define PG8_SCHED __builtin_amdgcn_sched_barrier(0)
; template <class Epi, class Sched>
; __device__ __forceinline__ void gemm_phase(PG8_LAS unsigned char* lds, const Gemm g, const Sched& S, const Epi& E) {
;     ...
;             PG8_LDB(B0, 0, 0); PG8_SCHED; PG8_LDA(At, 0, 0); PG8_STAGE(PG8_SA(1, 1), a1 + hstep, voffA);
;             PG8_WAIT_L(8); PG8_BAR; PG8_WAIT_L(0); PG8_MMA(0, 0, At, B0); PG8_BAR; PG8_SCHED;
;             PG8_LDB(B1, 0, 1); PG8_STAGE(PG8_SB(0, 0), b2, voffB);
;             PG8_BAR; PG8_WAIT_L(0); PG8_MMA(0, 1, At, B1); PG8_BAR;
;             PG8_LDA(At, 0, 1); PG8_STAGE(PG8_SA(0, 0), a2, voffA);
;             PG8_BAR; PG8_WAIT_L(0); PG8_MMA(1, 0, At, B0); PG8_BAR; PG8_SCHED;
;             PG8_STAGE(PG8_SB(0, 1), b2 + hstep, voffB);
;             PG8_WAIT_V(6); PG8_BAR; PG8_MMA(1, 1, At, B1); PG8_BAR;
.LBB0_1083:
	ds_read_b128 v[152:155], v149
	ds_read_b128 v[156:159], v149 offset:1024
	ds_read_b128 v[160:163], v149 offset:2048
	ds_read_b128 v[164:167], v149 offset:3072
	s_add_u32 s26, s24, 0xfffc0080
	s_addc_u32 s27, s25, -1
	s_cmp_eq_u32 s56, 12
	s_cselect_b32 s29, s17, s27
	s_cselect_b32 s28, s52, s26
	s_cselect_b32 s27, s15, s55
	s_cselect_b32 s26, s53, s54
	v_lshl_add_u64 v[144:145], s[24:25], 0, v[136:137]
	s_add_i32 m0, s23, 0xc000
	ds_read_b128 v[168:171], v150
	ds_read_b128 v[172:175], v150 offset:1024
	ds_read_b128 v[182:185], v150 offset:2048
	ds_read_b128 v[190:193], v150 offset:3072
	ds_read_b128 v[194:197], v150 offset:4096
	ds_read_b128 v[198:201], v150 offset:5120
	ds_read_b128 v[202:205], v150 offset:6144
	ds_read_b128 v[206:209], v150 offset:7168
	global_load_lds_dwordx4 v[144:145], off
	v_lshl_add_u64 v[144:145], s[24:25], 0, v[138:139]
	s_add_i32 m0, s23, 0xe000
	s_nop 0
	global_load_lds_dwordx4 v[144:145], off
	s_waitcnt lgkmcnt(8)
	ds_read_b128 v[210:213], v151
	ds_read_b128 v[214:217], v151 offset:1024
	ds_read_b128 v[218:221], v151 offset:2048
	ds_read_b128 v[222:225], v151 offset:3072
	s_waitcnt vmcnt(8) lgkmcnt(0)
	s_barrier
	v_mfma_f32_16x16x32_bf16 v[124:127], v[152:155], v[168:171], v[124:127]
	v_mfma_f32_16x16x32_bf16 v[120:123], v[160:163], v[168:171], v[120:123]
	v_mfma_f32_16x16x32_bf16 v[108:111], v[152:155], v[182:185], v[108:111]
	v_mfma_f32_16x16x32_bf16 v[104:107], v[160:163], v[182:185], v[104:107]
	v_mfma_f32_16x16x32_bf16 v[92:95], v[152:155], v[194:197], v[92:95]
	v_mfma_f32_16x16x32_bf16 v[88:91], v[160:163], v[194:197], v[88:91]
	v_mfma_f32_16x16x32_bf16 v[76:79], v[152:155], v[202:205], v[76:79]
	v_mfma_f32_16x16x32_bf16 v[72:75], v[160:163], v[202:205], v[72:75]
	v_mfma_f32_16x16x32_bf16 v[124:127], v[156:159], v[172:175], v[124:127]
	v_mfma_f32_16x16x32_bf16 v[120:123], v[164:167], v[172:175], v[120:123]
	v_mfma_f32_16x16x32_bf16 v[108:111], v[156:159], v[190:193], v[108:111]
	v_mfma_f32_16x16x32_bf16 v[104:107], v[164:167], v[190:193], v[104:107]
	v_mfma_f32_16x16x32_bf16 v[92:95], v[156:159], v[198:201], v[92:95]
	v_mfma_f32_16x16x32_bf16 v[88:91], v[164:167], v[198:201], v[88:91]
	v_mfma_f32_16x16x32_bf16 v[76:79], v[156:159], v[206:209], v[76:79]
	v_mfma_f32_16x16x32_bf16 v[72:75], v[164:167], v[206:209], v[72:75]
	v_mfma_f32_16x16x32_bf16 v[116:119], v[210:213], v[168:171], v[116:119]
	v_mfma_f32_16x16x32_bf16 v[112:115], v[218:221], v[168:171], v[112:115]
	v_mfma_f32_16x16x32_bf16 v[100:103], v[210:213], v[182:185], v[100:103]
	v_mfma_f32_16x16x32_bf16 v[96:99], v[218:221], v[182:185], v[96:99]
	v_mfma_f32_16x16x32_bf16 v[84:87], v[210:213], v[194:197], v[84:87]
	v_mfma_f32_16x16x32_bf16 v[80:83], v[218:221], v[194:197], v[80:83]
	v_mfma_f32_16x16x32_bf16 v[68:71], v[210:213], v[202:205], v[68:71]
	v_mfma_f32_16x16x32_bf16 v[64:67], v[218:221], v[202:205], v[64:67]
	v_mfma_f32_16x16x32_bf16 v[116:119], v[214:217], v[172:175], v[116:119]
	v_mfma_f32_16x16x32_bf16 v[112:115], v[222:225], v[172:175], v[112:115]
	v_mfma_f32_16x16x32_bf16 v[100:103], v[214:217], v[190:193], v[100:103]
	v_mfma_f32_16x16x32_bf16 v[96:99], v[222:225], v[190:193], v[96:99]
	v_mfma_f32_16x16x32_bf16 v[84:87], v[214:217], v[198:201], v[84:87]
	v_mfma_f32_16x16x32_bf16 v[80:83], v[222:225], v[198:201], v[80:83]
	v_mfma_f32_16x16x32_bf16 v[68:71], v[214:217], v[206:209], v[68:71]
	v_mfma_f32_16x16x32_bf16 v[64:67], v[222:225], v[206:209], v[64:67]
	s_barrier
	ds_read_b128 v[168:171], v150 offset:16384
	ds_read_b128 v[172:175], v150 offset:17408
	ds_read_b128 v[182:185], v150 offset:18432
	ds_read_b128 v[190:193], v150 offset:19456
	ds_read_b128 v[194:197], v150 offset:20480
	ds_read_b128 v[198:201], v150 offset:21504
	ds_read_b128 v[202:205], v150 offset:22528
	ds_read_b128 v[206:209], v150 offset:23552
	s_add_i32 s57, s45, s37
	v_lshl_add_u64 v[144:145], s[26:27], 0, v[130:131]
	s_mov_b32 m0, s57
	s_nop 0
	global_load_lds_dwordx4 v[144:145], off
	v_lshl_add_u64 v[186:187], s[26:27], 0, v[134:135]
	s_add_i32 m0, s57, 0x2000
	s_nop 0
	global_load_lds_dwordx4 v[186:187], off
	s_nop 1
	s_mov_b32 m0, s23
	v_lshl_add_u64 v[226:227], s[28:29], 0, v[128:129]
	global_load_lds_dwordx4 v[226:227], off
	v_lshl_add_u64 v[228:229], s[28:29], 0, v[132:133]
	s_mov_b32 m0, s38
	s_nop 0
	global_load_lds_dwordx4 v[228:229], off
	s_add_u32 s58, s26, 0x40000
	s_addc_u32 s59, s27, 0
	s_add_i32 s57, s46, s37
	v_lshl_add_u64 v[246:247], s[58:59], 0, v[130:131]
	s_mov_b32 m0, s57
	s_nop 0
	global_load_lds_dwordx4 v[246:247], off
	v_lshl_add_u64 v[246:247], s[58:59], 0, v[134:135]
	s_add_i32 m0, s57, 0x2000
	s_nop 0
	global_load_lds_dwordx4 v[246:247], off
	s_waitcnt vmcnt(8) lgkmcnt(0)
	s_barrier
; #define PG8_STAGE(bufoff, gbase, voff) do { _Pragma("unroll") for (int _i = 0; _i < 2; ++_i) \
;         __builtin_amdgcn_global_load_lds((const unsigned*)((const char*)(gbase) + (voff)[_i]), (PG8_LAS unsigned*)(lds + (bufoff) + ldsw + _i * 8192), 16, 0, 0); } while (0)
; #define PG8_LDA(dst, b, h) do { _Pragma("unroll") for (int m = 0; m < 4; ++m) _Pragma("unroll") for (int k = 0; k < 2; ++k) dst[m][k] = *(const PG8_LAS bf16x8*)(lds + PG8_SA(b, h) + aoff + m * 2048 + k * 1024); } while (0)
; #define PG8_LDB(dst, b, h) do { _Pragma("unroll") for (int n = 0; n < 2; ++n) _Pragma("unroll") for (int k = 0; k < 2; ++k) dst[n][k] = *(const PG8_LAS bf16x8*)(lds + PG8_SB(b, h) + boff + n * 2048 + k * 1024); } while (0)
; #define PG8_MMA(ai, bj, At, Bt) do { __builtin_amdgcn_s_setprio(1); _Pragma("unroll") for (int m = 0; m < 4; ++m) _Pragma("unroll") for (int n = 0; n < 2; ++n) _Pragma("unroll") for (int k = 0; k < 2; ++k) \
;         acc[ai][bj][m][n] = __builtin_amdgcn_mfma_f32_16x16x32_bf16(Bt[n][k], At[m][k], acc[ai][bj][m][n], 0, 0, 0); __builtin_amdgcn_s_setprio(0); } while (0)
; #define PG8_WAIT_V(n) asm volatile("s_waitcnt vmcnt(" #n ")" ::: "memory")
; #define PG8_WAIT_L(n) asm volatile("s_waitcnt lgkmcnt(" #n ")" ::: "memory")
; #define PG8_BAR __builtin_amdgcn_s_barrier()
; #define PG8_SCHED __builtin_amdgcn_sched_barrier(0)
; template <class Epi, class Sched>
; __device__ __forceinline__ void gemm_phase(PG8_LAS unsigned char* lds, const Gemm g, const Sched& S, const Epi& E) {
;     ...
;             PG8_BAR; PG8_WAIT_L(0); PG8_MMA(1, 0, At, B0); PG8_BAR; PG8_SCHED;
;             PG8_STAGE(PG8_SB(0, 1), b2 + hstep, voffB);
;             PG8_WAIT_V(6); PG8_BAR; PG8_MMA(1, 1, At, B1); PG8_BAR;
;             PG8_LDB(B0, 1, 0); PG8_SCHED; PG8_LDA(At, 1, 0); PG8_STAGE(PG8_SA(0, 1), a2 + hstep, voffA);
;             PG8_WAIT_L(8); PG8_BAR; PG8_WAIT_L(0); PG8_MMA(0, 0, At, B0); PG8_BAR; PG8_SCHED;
;             PG8_LDB(B1, 1, 1); PG8_STAGE(PG8_SB(1, 0), b3, voffB);
;             PG8_BAR; PG8_WAIT_L(0); PG8_MMA(0, 1, At, B1); PG8_BAR;
	v_mfma_f32_16x16x32_bf16 v[60:63], v[152:155], v[168:171], v[60:63]
	v_mfma_f32_16x16x32_bf16 v[56:59], v[160:163], v[168:171], v[56:59]
	v_mfma_f32_16x16x32_bf16 v[48:51], v[152:155], v[182:185], v[48:51]
	v_mfma_f32_16x16x32_bf16 v[40:43], v[160:163], v[182:185], v[40:43]
	v_mfma_f32_16x16x32_bf16 v[32:35], v[152:155], v[194:197], v[32:35]
	v_mfma_f32_16x16x32_bf16 v[24:27], v[160:163], v[194:197], v[24:27]
	v_mfma_f32_16x16x32_bf16 v[16:19], v[152:155], v[202:205], v[16:19]
	v_mfma_f32_16x16x32_bf16 v[8:11], v[160:163], v[202:205], v[8:11]
	v_mfma_f32_16x16x32_bf16 v[60:63], v[156:159], v[172:175], v[60:63]
	v_mfma_f32_16x16x32_bf16 v[56:59], v[164:167], v[172:175], v[56:59]
	v_mfma_f32_16x16x32_bf16 v[48:51], v[156:159], v[190:193], v[48:51]
	v_mfma_f32_16x16x32_bf16 v[40:43], v[164:167], v[190:193], v[40:43]
	v_mfma_f32_16x16x32_bf16 v[32:35], v[156:159], v[198:201], v[32:35]
	v_mfma_f32_16x16x32_bf16 v[24:27], v[164:167], v[198:201], v[24:27]
	v_mfma_f32_16x16x32_bf16 v[16:19], v[156:159], v[206:209], v[16:19]
	v_mfma_f32_16x16x32_bf16 v[8:11], v[164:167], v[206:209], v[8:11]
	v_mfma_f32_16x16x32_bf16 v[52:55], v[210:213], v[168:171], v[52:55]
	v_mfma_f32_16x16x32_bf16 v[44:47], v[218:221], v[168:171], v[44:47]
	v_mfma_f32_16x16x32_bf16 v[36:39], v[210:213], v[182:185], v[36:39]
	v_mfma_f32_16x16x32_bf16 v[28:31], v[218:221], v[182:185], v[28:31]
	v_mfma_f32_16x16x32_bf16 v[20:23], v[210:213], v[194:197], v[20:23]
	v_mfma_f32_16x16x32_bf16 v[12:15], v[218:221], v[194:197], v[12:15]
	v_mfma_f32_16x16x32_bf16 v[4:7], v[210:213], v[202:205], v[4:7]
	v_mfma_f32_16x16x32_bf16 v[0:3], v[218:221], v[202:205], v[0:3]
	v_mfma_f32_16x16x32_bf16 v[52:55], v[214:217], v[172:175], v[52:55]
	v_mfma_f32_16x16x32_bf16 v[44:47], v[222:225], v[172:175], v[44:47]
	v_mfma_f32_16x16x32_bf16 v[36:39], v[214:217], v[190:193], v[36:39]
	v_mfma_f32_16x16x32_bf16 v[28:31], v[222:225], v[190:193], v[28:31]
	v_mfma_f32_16x16x32_bf16 v[20:23], v[214:217], v[198:201], v[20:23]
	v_mfma_f32_16x16x32_bf16 v[12:15], v[222:225], v[198:201], v[12:15]
	v_mfma_f32_16x16x32_bf16 v[4:7], v[214:217], v[206:209], v[4:7]
	v_mfma_f32_16x16x32_bf16 v[0:3], v[222:225], v[206:209], v[0:3]
	s_barrier
	s_add_i32 s57, 0, 0x18000
	v_add_u32_e32 v164, s57, v147
	ds_read_b128 v[152:155], v164
	ds_read_b128 v[156:159], v164 offset:1024
	ds_read_b128 v[160:163], v164 offset:2048
	ds_read_b128 v[164:167], v164 offset:3072
	s_add_u32 s28, s28, 0x40000
	s_addc_u32 s29, s29, 0
	s_mov_b32 m0, s39
	v_lshl_add_u64 v[210:211], s[28:29], 0, v[128:129]
	ds_read_b128 v[168:171], v150 offset:32768
	ds_read_b128 v[172:175], v150 offset:33792
	ds_read_b128 v[182:185], v150 offset:34816
	ds_read_b128 v[190:193], v150 offset:35840
	ds_read_b128 v[194:197], v150 offset:36864
	ds_read_b128 v[198:201], v150 offset:37888
	ds_read_b128 v[202:205], v150 offset:38912
	ds_read_b128 v[206:209], v150 offset:39936
	global_load_lds_dwordx4 v[210:211], off
	v_lshl_add_u64 v[210:211], s[28:29], 0, v[132:133]
	s_mov_b32 m0, s40
	s_nop 0
	global_load_lds_dwordx4 v[210:211], off
	s_add_i32 s28, 0, 0x1c000
	v_add_u32_e32 v179, s28, v147
	s_waitcnt lgkmcnt(8)
	ds_read_b128 v[210:213], v179
	ds_read_b128 v[214:217], v179 offset:1024
	ds_read_b128 v[218:221], v179 offset:2048
	ds_read_b128 v[222:225], v179 offset:3072
	s_waitcnt vmcnt(8) lgkmcnt(0)
	s_barrier
	v_mfma_f32_16x16x32_bf16 v[124:127], v[152:155], v[168:171], v[124:127]
	v_mfma_f32_16x16x32_bf16 v[120:123], v[160:163], v[168:171], v[120:123]
	v_mfma_f32_16x16x32_bf16 v[108:111], v[152:155], v[182:185], v[108:111]
	v_mfma_f32_16x16x32_bf16 v[104:107], v[160:163], v[182:185], v[104:107]
	v_mfma_f32_16x16x32_bf16 v[92:95], v[152:155], v[194:197], v[92:95]
	v_mfma_f32_16x16x32_bf16 v[88:91], v[160:163], v[194:197], v[88:91]
	v_mfma_f32_16x16x32_bf16 v[76:79], v[152:155], v[202:205], v[76:79]
	v_mfma_f32_16x16x32_bf16 v[72:75], v[160:163], v[202:205], v[72:75]
	v_mfma_f32_16x16x32_bf16 v[124:127], v[156:159], v[172:175], v[124:127]
	v_mfma_f32_16x16x32_bf16 v[120:123], v[164:167], v[172:175], v[120:123]
	v_mfma_f32_16x16x32_bf16 v[108:111], v[156:159], v[190:193], v[108:111]
	v_mfma_f32_16x16x32_bf16 v[104:107], v[164:167], v[190:193], v[104:107]
	v_mfma_f32_16x16x32_bf16 v[92:95], v[156:159], v[198:201], v[92:95]
	v_mfma_f32_16x16x32_bf16 v[88:91], v[164:167], v[198:201], v[88:91]
	v_mfma_f32_16x16x32_bf16 v[76:79], v[156:159], v[206:209], v[76:79]
	v_mfma_f32_16x16x32_bf16 v[72:75], v[164:167], v[206:209], v[72:75]
	v_mfma_f32_16x16x32_bf16 v[116:119], v[210:213], v[168:171], v[116:119]
	v_mfma_f32_16x16x32_bf16 v[112:115], v[218:221], v[168:171], v[112:115]
	v_mfma_f32_16x16x32_bf16 v[100:103], v[210:213], v[182:185], v[100:103]
	v_mfma_f32_16x16x32_bf16 v[96:99], v[218:221], v[182:185], v[96:99]
	v_mfma_f32_16x16x32_bf16 v[84:87], v[210:213], v[194:197], v[84:87]
	v_mfma_f32_16x16x32_bf16 v[80:83], v[218:221], v[194:197], v[80:83]
	v_mfma_f32_16x16x32_bf16 v[68:71], v[210:213], v[202:205], v[68:71]
	v_mfma_f32_16x16x32_bf16 v[64:67], v[218:221], v[202:205], v[64:67]
	v_mfma_f32_16x16x32_bf16 v[116:119], v[214:217], v[172:175], v[116:119]
	v_mfma_f32_16x16x32_bf16 v[112:115], v[222:225], v[172:175], v[112:115]
	v_mfma_f32_16x16x32_bf16 v[100:103], v[214:217], v[190:193], v[100:103]
	v_mfma_f32_16x16x32_bf16 v[96:99], v[222:225], v[190:193], v[96:99]
	v_mfma_f32_16x16x32_bf16 v[84:87], v[214:217], v[198:201], v[84:87]
	v_mfma_f32_16x16x32_bf16 v[80:83], v[222:225], v[198:201], v[80:83]
	v_mfma_f32_16x16x32_bf16 v[68:71], v[214:217], v[206:209], v[68:71]
	v_mfma_f32_16x16x32_bf16 v[64:67], v[222:225], v[206:209], v[64:67]
	s_barrier
; __device__ __forceinline__ unsigned cvt_pk_bf16(float lo, float hi) { unsigned r; asm volatile("v_cvt_pk_bf16_f32 %0, %1, %2" : "=v"(r) : "v"(lo), "v"(hi)); return r; }
; __device__ __forceinline__ float flogsig16(float x) { return (fminf(x, 0.f) - __logf(1.0f + __expf(-fabsf(x)))) * 0.0625f; }
; #define PG8_STAGE(bufoff, gbase, voff) do { _Pragma("unroll") for (int _i = 0; _i < 2; ++_i) \
;         __builtin_amdgcn_global_load_lds((const unsigned*)((const char*)(gbase) + (voff)[_i]), (PG8_LAS unsigned*)(lds + (bufoff) + ldsw + _i * 8192), 16, 0, 0); } while (0)
; #define PG8_LDA(dst, b, h) do { _Pragma("unroll") for (int m = 0; m < 4; ++m) _Pragma("unroll") for (int k = 0; k < 2; ++k) dst[m][k] = *(const PG8_LAS bf16x8*)(lds + PG8_SA(b, h) + aoff + m * 2048 + k * 1024); } while (0)
; #define PG8_BAR __builtin_amdgcn_s_barrier()
;     __device__ __forceinline__ void operator()(const f32x4 (&acc)[2][2][4][2], const Unit& u, int wr, int wc, int fr, int fq) const {
;     ...
;             for (int m = 0; m < 4; ++m) { bf16_t* rowp = O + (size_t)(row0 + ai * HALF + m * 16) * ldc + col0;
; #pragma unroll
;                 for (int bj = 0; bj < 2; ++bj) { f32x4 v0 = acc[ai][bj][m][0] + bv[bj][0], v1 = acc[ai][bj][m][1] + bv[bj][1];
;                     if (act == 1) {
; #pragma unroll
;                         for (int j = 0; j < 1; ++j) { v0 = v0 * sigmoid4(v0); v1 = v1 * sigmoid4(v1); } }
;                     else if (act == 2) {
; #pragma unroll
;                         for (int j = 0; j < 1; ++j) { v0 = sigmoid4(v0); v1 = sigmoid4(v1); } }
;                     else if (act == 3) {
; #pragma unroll
;                         for (int j = 0; j < 4; ++j) { v0[j] = flogsig16(v0[j]); v1[j] = flogsig16(v1[j]); } }
;                     u32x4 w; w.x = cvt_pk_bf16(v0[0], v0[1]); w.y = cvt_pk_bf16(v0[2], v0[3]); w.z = cvt_pk_bf16(v1[0], v1[1]); w.w = cvt_pk_bf16(v1[2], v1[3]);
;                     *(u32x4*)(rowp + bj * HALF) = w; } }
; template <class Epi, class Sched>
; __device__ __forceinline__ void gemm_phase(PG8_LAS unsigned char* lds, const Gemm g, const Sched& S, const Epi& E) {
;     ...
;             PG8_LDA(At, 1, 1); PG8_STAGE(PG8_SA(1, 0), a3, voffA);
;             PG8_BAR; PG8_WAIT_L(0); PG8_MMA(1, 0, At, B0); PG8_BAR; PG8_SCHED;
;             PG8_STAGE(PG8_SB(1, 1), b3 + hstep, voffB);
;             PG8_WAIT_V(6); PG8_BAR; PG8_MMA(1, 1, At, B1); PG8_BAR;
	ds_read_b128 v[168:171], v150 offset:49152
	ds_read_b128 v[172:175], v150 offset:50176
	ds_read_b128 v[182:185], v150 offset:51200
	ds_read_b128 v[190:193], v150 offset:52224
	ds_read_b128 v[194:197], v150 offset:53248
	ds_read_b128 v[198:201], v150 offset:54272
	ds_read_b128 v[202:205], v150 offset:55296
	ds_read_b128 v[206:209], v150 offset:56320
	s_add_i32 s29, s57, s37
	v_lshl_add_u64 v[144:145], v[144:145], 0, s[6:7]
	s_mov_b32 m0, s29
	s_nop 0
	global_load_lds_dwordx4 v[144:145], off
	v_lshl_add_u64 v[144:145], v[186:187], 0, s[6:7]
	s_add_i32 m0, s29, 0x2000
	s_nop 0
	global_load_lds_dwordx4 v[144:145], off
	s_nop 1
	s_mov_b32 m0, s42
	v_lshl_add_u64 v[144:145], v[226:227], 0, s[6:7]
	global_load_lds_dwordx4 v[144:145], off
	v_lshl_add_u64 v[144:145], v[228:229], 0, s[6:7]
	s_mov_b32 m0, s43
	s_nop 0
	global_load_lds_dwordx4 v[144:145], off
	s_add_u32 s26, s26, 0x40080
	s_addc_u32 s27, s27, 0
	s_add_i32 s28, s28, s37
	v_lshl_add_u64 v[144:145], s[26:27], 0, v[130:131]
	s_mov_b32 m0, s28
	s_nop 0
	global_load_lds_dwordx4 v[144:145], off
	v_lshl_add_u64 v[144:145], s[26:27], 0, v[134:135]
	s_add_i32 m0, s28, 0x2000
	s_nop 0
	global_load_lds_dwordx4 v[144:145], off
	s_waitcnt vmcnt(8) lgkmcnt(0)
	s_barrier
	v_mfma_f32_16x16x32_bf16 v[60:63], v[152:155], v[168:171], v[60:63]
	v_mfma_f32_16x16x32_bf16 v[56:59], v[160:163], v[168:171], v[56:59]
	v_mfma_f32_16x16x32_bf16 v[48:51], v[152:155], v[182:185], v[48:51]
	v_mfma_f32_16x16x32_bf16 v[40:43], v[160:163], v[182:185], v[40:43]
	v_mfma_f32_16x16x32_bf16 v[32:35], v[152:155], v[194:197], v[32:35]
	v_mfma_f32_16x16x32_bf16 v[24:27], v[160:163], v[194:197], v[24:27]
	v_mfma_f32_16x16x32_bf16 v[16:19], v[152:155], v[202:205], v[16:19]
	v_mfma_f32_16x16x32_bf16 v[8:11], v[160:163], v[202:205], v[8:11]
	v_mfma_f32_16x16x32_bf16 v[60:63], v[156:159], v[172:175], v[60:63]
	v_mfma_f32_16x16x32_bf16 v[56:59], v[164:167], v[172:175], v[56:59]
	v_mfma_f32_16x16x32_bf16 v[48:51], v[156:159], v[190:193], v[48:51]
	v_mfma_f32_16x16x32_bf16 v[40:43], v[164:167], v[190:193], v[40:43]
	v_mfma_f32_16x16x32_bf16 v[32:35], v[156:159], v[198:201], v[32:35]
	v_mfma_f32_16x16x32_bf16 v[24:27], v[164:167], v[198:201], v[24:27]
	v_mfma_f32_16x16x32_bf16 v[16:19], v[156:159], v[206:209], v[16:19]
	v_mfma_f32_16x16x32_bf16 v[8:11], v[164:167], v[206:209], v[8:11]
	v_mfma_f32_16x16x32_bf16 v[52:55], v[210:213], v[168:171], v[52:55]
	v_mfma_f32_16x16x32_bf16 v[44:47], v[218:221], v[168:171], v[44:47]
	v_mfma_f32_16x16x32_bf16 v[36:39], v[210:213], v[182:185], v[36:39]
	v_mfma_f32_16x16x32_bf16 v[28:31], v[218:221], v[182:185], v[28:31]
	v_mfma_f32_16x16x32_bf16 v[20:23], v[210:213], v[194:197], v[20:23]
	v_mfma_f32_16x16x32_bf16 v[12:15], v[218:221], v[194:197], v[12:15]
	v_mfma_f32_16x16x32_bf16 v[4:7], v[210:213], v[202:205], v[4:7]
	v_mfma_f32_16x16x32_bf16 v[0:3], v[218:221], v[202:205], v[0:3]
	v_mfma_f32_16x16x32_bf16 v[52:55], v[214:217], v[172:175], v[52:55]
	v_mfma_f32_16x16x32_bf16 v[44:47], v[222:225], v[172:175], v[44:47]
	v_mfma_f32_16x16x32_bf16 v[36:39], v[214:217], v[190:193], v[36:39]
	v_mfma_f32_16x16x32_bf16 v[28:31], v[222:225], v[190:193], v[28:31]
	v_mfma_f32_16x16x32_bf16 v[20:23], v[214:217], v[198:201], v[20:23]
	v_mfma_f32_16x16x32_bf16 v[12:15], v[222:225], v[198:201], v[12:15]
	v_mfma_f32_16x16x32_bf16 v[4:7], v[214:217], v[206:209], v[4:7]
	v_mfma_f32_16x16x32_bf16 v[0:3], v[222:225], v[206:209], v[0:3]
	s_barrier
	s_add_i32 s56, s56, 2
	s_add_u32 s24, s24, 0x100
	s_addc_u32 s25, s25, 0
	s_add_u32 s54, s54, 0x100
	s_addc_u32 s55, s55, 0
	s_cmp_gt_u32 s56, 13
	s_cbranch_scc0 .LBB0_1083
	v_lshl_add_u32 v152, s22, 8, v146
	v_lshl_or_b32 v144, s51, 8, v148
	v_ashrrev_i32_e32 v153, 31, v152
	v_ashrrev_i32_e32 v145, 31, v144
	v_lshlrev_b64 v[154:155], 11, v[152:153]
	v_lshl_add_u64 v[154:155], s[4:5], 0, v[154:155]
	v_lshlrev_b64 v[156:157], 1, v[144:145]
	v_lshl_add_u64 v[144:145], v[154:155], 0, v[156:157]
	v_pk_add_f32 v[126:127], v[126:127], 0 op_sel_hi:[1,0]
	v_pk_add_f32 v[124:125], v[124:125], 0 op_sel_hi:[1,0]
	v_pk_add_f32 v[154:155], v[122:123], 0 op_sel_hi:[1,0]
	v_pk_add_f32 v[122:123], v[120:121], 0 op_sel_hi:[1,0]
	v_cvt_pk_bf16_f32 v120, v124, v125
	v_cvt_pk_bf16_f32 v121, v126, v127
	v_pk_add_f32 v[116:117], v[116:117], 0 op_sel_hi:[1,0]
	v_cvt_pk_bf16_f32 v122, v122, v123
	v_cvt_pk_bf16_f32 v123, v154, v155
	global_store_dwordx4 v[144:145], v[120:123], off
	v_pk_add_f32 v[118:119], v[118:119], 0 op_sel_hi:[1,0]
	v_pk_add_f32 v[110:111], v[110:111], 0 op_sel_hi:[1,0]
	v_pk_add_f32 v[120:121], v[114:115], 0 op_sel_hi:[1,0]
	v_pk_add_f32 v[114:115], v[112:113], 0 op_sel_hi:[1,0]
	v_cvt_pk_bf16_f32 v112, v116, v117
	v_cvt_pk_bf16_f32 v113, v118, v119
	v_pk_add_f32 v[108:109], v[108:109], 0 op_sel_hi:[1,0]
	v_cvt_pk_bf16_f32 v114, v114, v115
	v_cvt_pk_bf16_f32 v115, v120, v121
	global_store_dwordx4 v[144:145], v[112:115], off offset:256
	v_pk_add_f32 v[100:101], v[100:101], 0 op_sel_hi:[1,0]
	v_pk_add_f32 v[102:103], v[102:103], 0 op_sel_hi:[1,0]
	v_or_b32_e32 v112, 16, v152
	v_ashrrev_i32_e32 v113, 31, v112
	v_lshlrev_b64 v[112:113], 11, v[112:113]
	v_lshl_add_u64 v[112:113], s[4:5], 0, v[112:113]
	v_lshl_add_u64 v[112:113], v[112:113], 0, v[156:157]
	v_pk_add_f32 v[114:115], v[106:107], 0 op_sel_hi:[1,0]
	v_pk_add_f32 v[106:107], v[104:105], 0 op_sel_hi:[1,0]
	v_cvt_pk_bf16_f32 v104, v108, v109
	v_cvt_pk_bf16_f32 v105, v110, v111
	v_pk_add_f32 v[94:95], v[94:95], 0 op_sel_hi:[1,0]
	v_cvt_pk_bf16_f32 v106, v106, v107
	v_cvt_pk_bf16_f32 v107, v114, v115
	global_store_dwordx4 v[112:113], v[104:107], off
	v_pk_add_f32 v[92:93], v[92:93], 0 op_sel_hi:[1,0]
; __device__ __forceinline__ unsigned cvt_pk_bf16(float lo, float hi) { unsigned r; asm volatile("v_cvt_pk_bf16_f32 %0, %1, %2" : "=v"(r) : "v"(lo), "v"(hi)); return r; }
; __device__ __forceinline__ float flogsig16(float x) { return (fminf(x, 0.f) - __logf(1.0f + __expf(-fabsf(x)))) * 0.0625f; }
;     __device__ __forceinline__ void operator()(const f32x4 (&acc)[2][2][4][2], const Unit& u, int wr, int wc, int fr, int fq) const {
;     ...
;             for (int m = 0; m < 4; ++m) { bf16_t* rowp = O + (size_t)(row0 + ai * HALF + m * 16) * ldc + col0;
; #pragma unroll
;                 for (int bj = 0; bj < 2; ++bj) { f32x4 v0 = acc[ai][bj][m][0] + bv[bj][0], v1 = acc[ai][bj][m][1] + bv[bj][1];
;                     if (act == 1) {
; #pragma unroll
;                         for (int j = 0; j < 1; ++j) { v0 = v0 * sigmoid4(v0); v1 = v1 * sigmoid4(v1); } }
;                     else if (act == 2) {
; #pragma unroll
;                         for (int j = 0; j < 1; ++j) { v0 = sigmoid4(v0); v1 = sigmoid4(v1); } }
;                     else if (act == 3) {
; #pragma unroll
;                         for (int j = 0; j < 4; ++j) { v0[j] = flogsig16(v0[j]); v1[j] = flogsig16(v1[j]); } }
;                     u32x4 w; w.x = cvt_pk_bf16(v0[0], v0[1]); w.y = cvt_pk_bf16(v0[2], v0[3]); w.z = cvt_pk_bf16(v1[0], v1[1]); w.w = cvt_pk_bf16(v1[2], v1[3]);
;                     *(u32x4*)(rowp + bj * HALF) = w; } }
; template <class Epi, class Sched>
; __device__ __forceinline__ void gemm_phase(PG8_LAS unsigned char* lds, const Gemm g, const Sched& S, const Epi& E) {
;     ...
;         if (!has_next) break;
; #pragma unroll
;         for (int a = 0; a < 2; ++a)
; #pragma unroll
;             for (int b = 0; b < 2; ++b)
; #pragma unroll
;                 for (int m = 0; m < 4; ++m)
; #pragma unroll
;                     for (int n = 0; n < 2; ++n) acc[a][b][m][n] = (f32x4){0.f, 0.f, 0.f, 0.f};
;         cur = nxt; cA = nA; cB = nB; ++ui;
;     }
	v_pk_add_f32 v[84:85], v[84:85], 0 op_sel_hi:[1,0]
	v_pk_add_f32 v[104:105], v[98:99], 0 op_sel_hi:[1,0]
	v_pk_add_f32 v[98:99], v[96:97], 0 op_sel_hi:[1,0]
	v_cvt_pk_bf16_f32 v96, v100, v101
	v_cvt_pk_bf16_f32 v97, v102, v103
	v_pk_add_f32 v[86:87], v[86:87], 0 op_sel_hi:[1,0]
	v_cvt_pk_bf16_f32 v98, v98, v99
	v_cvt_pk_bf16_f32 v99, v104, v105
	global_store_dwordx4 v[112:113], v[96:99], off offset:256
	v_pk_add_f32 v[78:79], v[78:79], 0 op_sel_hi:[1,0]
	v_pk_add_f32 v[76:77], v[76:77], 0 op_sel_hi:[1,0]
	v_or_b32_e32 v96, 32, v152
	v_ashrrev_i32_e32 v97, 31, v96
	v_lshlrev_b64 v[96:97], 11, v[96:97]
	v_lshl_add_u64 v[96:97], s[4:5], 0, v[96:97]
	v_lshl_add_u64 v[96:97], v[96:97], 0, v[156:157]
	v_pk_add_f32 v[98:99], v[90:91], 0 op_sel_hi:[1,0]
	v_pk_add_f32 v[90:91], v[88:89], 0 op_sel_hi:[1,0]
	v_cvt_pk_bf16_f32 v88, v92, v93
	v_cvt_pk_bf16_f32 v89, v94, v95
	v_pk_add_f32 v[70:71], v[70:71], 0 op_sel_hi:[1,0]
	v_cvt_pk_bf16_f32 v90, v90, v91
	v_cvt_pk_bf16_f32 v91, v98, v99
	global_store_dwordx4 v[96:97], v[88:91], off
	v_pk_add_f32 v[68:69], v[68:69], 0 op_sel_hi:[1,0]
	v_pk_add_f32 v[60:61], v[60:61], 0 op_sel_hi:[1,0]
	v_pk_add_f32 v[88:89], v[82:83], 0 op_sel_hi:[1,0]
	v_pk_add_f32 v[82:83], v[80:81], 0 op_sel_hi:[1,0]
	v_cvt_pk_bf16_f32 v80, v84, v85
	v_cvt_pk_bf16_f32 v81, v86, v87
	v_pk_add_f32 v[62:63], v[62:63], 0 op_sel_hi:[1,0]
	v_cvt_pk_bf16_f32 v82, v82, v83
	v_cvt_pk_bf16_f32 v83, v88, v89
	global_store_dwordx4 v[96:97], v[80:83], off offset:256
	v_pk_add_f32 v[54:55], v[54:55], 0 op_sel_hi:[1,0]
	v_pk_add_f32 v[52:53], v[52:53], 0 op_sel_hi:[1,0]
	v_or_b32_e32 v80, 48, v152
	v_ashrrev_i32_e32 v81, 31, v80
	v_lshlrev_b64 v[80:81], 11, v[80:81]
	v_lshl_add_u64 v[80:81], s[4:5], 0, v[80:81]
	v_lshl_add_u64 v[80:81], v[80:81], 0, v[156:157]
	v_pk_add_f32 v[82:83], v[74:75], 0 op_sel_hi:[1,0]
	v_pk_add_f32 v[74:75], v[72:73], 0 op_sel_hi:[1,0]
	v_cvt_pk_bf16_f32 v72, v76, v77
	v_cvt_pk_bf16_f32 v73, v78, v79
	v_pk_add_f32 v[48:49], v[48:49], 0 op_sel_hi:[1,0]
	v_cvt_pk_bf16_f32 v74, v74, v75
	v_cvt_pk_bf16_f32 v75, v82, v83
	global_store_dwordx4 v[80:81], v[72:75], off
	v_pk_add_f32 v[38:39], v[38:39], 0 op_sel_hi:[1,0]
	v_pk_add_f32 v[36:37], v[36:37], 0 op_sel_hi:[1,0]
	v_pk_add_f32 v[72:73], v[66:67], 0 op_sel_hi:[1,0]
	v_pk_add_f32 v[66:67], v[64:65], 0 op_sel_hi:[1,0]
	v_cvt_pk_bf16_f32 v64, v68, v69
	v_cvt_pk_bf16_f32 v65, v70, v71
	v_pk_add_f32 v[32:33], v[32:33], 0 op_sel_hi:[1,0]
	v_cvt_pk_bf16_f32 v66, v66, v67
	v_cvt_pk_bf16_f32 v67, v72, v73
	global_store_dwordx4 v[80:81], v[64:67], off offset:256
	v_pk_add_f32 v[22:23], v[22:23], 0 op_sel_hi:[1,0]
	v_pk_add_f32 v[20:21], v[20:21], 0 op_sel_hi:[1,0]
	v_pk_add_f32 v[66:67], v[58:59], 0 op_sel_hi:[1,0]
	v_pk_add_f32 v[58:59], v[56:57], 0 op_sel_hi:[1,0]
	v_cvt_pk_bf16_f32 v56, v60, v61
	v_add_co_u32_e32 v60, vcc, s47, v144
	v_cvt_pk_bf16_f32 v57, v62, v63
	v_cvt_pk_bf16_f32 v58, v58, v59
	v_cvt_pk_bf16_f32 v59, v66, v67
	v_lshl_add_u64 v[64:65], v[144:145], 0, s[0:1]
	s_nop 0
	v_addc_co_u32_e32 v61, vcc, 0, v145, vcc
	global_store_dwordx4 v[60:61], v[56:59], off
	v_pk_add_f32 v[16:17], v[16:17], 0 op_sel_hi:[1,0]
	s_mov_b32 s51, s14
	v_pk_add_f32 v[56:57], v[46:47], 0 op_sel_hi:[1,0]
	v_pk_add_f32 v[46:47], v[44:45], 0 op_sel_hi:[1,0]
	v_cvt_pk_bf16_f32 v44, v52, v53
	v_cvt_pk_bf16_f32 v45, v54, v55
	s_mov_b32 s22, s16
	v_cvt_pk_bf16_f32 v46, v46, v47
	v_cvt_pk_bf16_f32 v47, v56, v57
	global_store_dwordx4 v[64:65], v[44:47], off offset:256
	s_mov_b64 s[26:27], s[20:21]
	s_mov_b64 s[24:25], s[18:19]
	v_pk_add_f32 v[46:47], v[50:51], 0 op_sel_hi:[1,0]
	v_pk_add_f32 v[50:51], v[42:43], 0 op_sel_hi:[1,0]
	v_pk_add_f32 v[42:43], v[40:41], 0 op_sel_hi:[1,0]
	v_cvt_pk_bf16_f32 v40, v48, v49
	v_cvt_pk_bf16_f32 v41, v46, v47
	v_add_co_u32_e32 v46, vcc, s48, v144
	v_cvt_pk_bf16_f32 v42, v42, v43
	v_cvt_pk_bf16_f32 v43, v50, v51
	v_lshl_add_u64 v[44:45], v[144:145], 0, s[8:9]
	s_nop 0
	v_addc_co_u32_e32 v47, vcc, 0, v145, vcc
	global_store_dwordx4 v[46:47], v[40:43], off
	v_pk_add_f32 v[6:7], v[6:7], 0 op_sel_hi:[1,0]
	v_pk_add_f32 v[4:5], v[4:5], 0 op_sel_hi:[1,0]
	v_pk_add_f32 v[40:41], v[30:31], 0 op_sel_hi:[1,0]
	v_pk_add_f32 v[30:31], v[28:29], 0 op_sel_hi:[1,0]
	v_cvt_pk_bf16_f32 v28, v36, v37
	v_cvt_pk_bf16_f32 v29, v38, v39
	s_nop 0
	v_cvt_pk_bf16_f32 v30, v30, v31
	v_cvt_pk_bf16_f32 v31, v40, v41
	global_store_dwordx4 v[44:45], v[28:31], off offset:256
	s_nop 1
	v_pk_add_f32 v[30:31], v[34:35], 0 op_sel_hi:[1,0]
	v_pk_add_f32 v[34:35], v[26:27], 0 op_sel_hi:[1,0]
	v_pk_add_f32 v[26:27], v[24:25], 0 op_sel_hi:[1,0]
	v_cvt_pk_bf16_f32 v24, v32, v33
	v_cvt_pk_bf16_f32 v25, v30, v31
	v_add_co_u32_e32 v30, vcc, s49, v144
	v_cvt_pk_bf16_f32 v26, v26, v27
	v_cvt_pk_bf16_f32 v27, v34, v35
	v_lshl_add_u64 v[28:29], v[144:145], 0, s[10:11]
	s_nop 0
	v_addc_co_u32_e32 v31, vcc, 0, v145, vcc
	global_store_dwordx4 v[30:31], v[24:27], off
	s_nop 1
	v_pk_add_f32 v[24:25], v[14:15], 0 op_sel_hi:[1,0]
	v_pk_add_f32 v[14:15], v[12:13], 0 op_sel_hi:[1,0]
	v_cvt_pk_bf16_f32 v12, v20, v21
	v_cvt_pk_bf16_f32 v13, v22, v23
	s_nop 0
	v_cvt_pk_bf16_f32 v14, v14, v15
	v_cvt_pk_bf16_f32 v15, v24, v25
	global_store_dwordx4 v[28:29], v[12:15], off offset:256
	s_nop 1
	v_pk_add_f32 v[14:15], v[18:19], 0 op_sel_hi:[1,0]
	v_pk_add_f32 v[18:19], v[10:11], 0 op_sel_hi:[1,0]
	v_pk_add_f32 v[10:11], v[8:9], 0 op_sel_hi:[1,0]
	v_cvt_pk_bf16_f32 v8, v16, v17
	v_cvt_pk_bf16_f32 v9, v14, v15
	v_add_co_u32_e32 v14, vcc, s50, v144
	v_lshl_add_u64 v[12:13], v[144:145], 0, s[12:13]
	s_nop 0
	v_addc_co_u32_e32 v15, vcc, 0, v145, vcc
	v_cvt_pk_bf16_f32 v10, v10, v11
	v_cvt_pk_bf16_f32 v11, v18, v19
	global_store_dwordx4 v[14:15], v[8:11], off
	s_and_b64 vcc, exec, s[2:3]
	s_nop 0
	v_pk_add_f32 v[8:9], v[2:3], 0 op_sel_hi:[1,0]
	v_pk_add_f32 v[2:3], v[0:1], 0 op_sel_hi:[1,0]
	v_cvt_pk_bf16_f32 v0, v4, v5
	v_cvt_pk_bf16_f32 v1, v6, v7
	s_nop 0
	v_cvt_pk_bf16_f32 v2, v2, v3
	v_cvt_pk_bf16_f32 v3, v8, v9
	global_store_dwordx4 v[12:13], v[0:3], off offset:256
	s_cbranch_vccz .LBB0_1076
	s_waitcnt vmcnt(0)
	s_cmpk_gt_u32 s31, 0xff
	s_cbranch_scc1 .LBB0_1087
	s_barrier

; #define PG8_STAGE(bufoff, gbase, voff) do { _Pragma("unroll") for (int _i = 0; _i < 2; ++_i) \
;         __builtin_amdgcn_global_load_lds((const unsigned*)((const char*)(gbase) + (voff)[_i]), (PG8_LAS unsigned*)(lds + (bufoff) + ldsw + _i * 8192), 16, 0, 0); } while (0)
; #define PG8_WAIT_V(n) asm volatile("s_waitcnt vmcnt(" #n ")" ::: "memory")
; #define PG8_BAR __builtin_amdgcn_s_barrier()
; template <class Epi, class Sched>
; __device__ __forceinline__ void gemm_phase(PG8_LAS unsigned char* lds, const Gemm g, const Sched& S, const Epi& E) {
;     ...
;     for (int i = 0; i < 2; ++i) { int R, C; stage_rc(tid * 16 + i * 8192, R, C); const int Rb = Epi::PERM ? ((R & ~31) + perm32(R & 31)) : R;
;         voffA[i] = (unsigned)(R * K + C) * 2u; voffB[i] = (unsigned)(Rb * K + C) * 2u; }
;     const size_t kstep = (size_t)(BK * 2);
;     const size_t hstep = (size_t)HALF * K * 2;
;     const size_t tstep = 2 * hstep;
;     const unsigned ldsw = (unsigned)wid * 1024u;
;     const int aoff = lds_byte(wr * 64 + fr, fq * 8), boff = lds_byte(wc * 32 + fr, fq * 8);
;     ...
;     const char* cA = (const char*)g.A + (size_t)cur.pm * tstep; const char* cB = (const char*)g.Bt + (size_t)cur.pn * tstep;
;     S.a_ready(cur);
;     PG8_STAGE(PG8_SB(0, 0), cB, voffB); PG8_STAGE(PG8_SA(0, 0), cA, voffA); PG8_STAGE(PG8_SB(0, 1), cB + hstep, voffB); PG8_STAGE(PG8_SA(0, 1), cA + hstep, voffA);
;     if (wr == 1) PG8_BAR;
;     PG8_WAIT_V(4); PG8_BAR;
;     PG8_STAGE(PG8_SB(1, 0), cB + kstep, voffB); PG8_STAGE(PG8_SA(1, 0), cA + kstep, voffA); PG8_STAGE(PG8_SB(1, 1), cB + hstep + kstep, voffB);
;     PG8_WAIT_V(6); PG8_BAR;
.LBB0_1198:
	s_lshl_b32 s0, s0, 27
	v_readlane_b32 s1, v245, 18
	s_add_u32 s0, s1, s0
	v_readlane_b32 s1, v245, 19
	s_addc_u32 s1, s1, 0
	s_lshl_b32 s4, s4, 5
	s_and_b32 s9, s4, 0x60
	s_mov_b64 s[4:5], 0x80
	s_add_i32 m0, s15, 0x18000
	v_lshl_add_u64 v[6:7], v[6:7], 0, s[4:5]
	s_lshl_b32 s8, s3, 13
	s_lshl_b32 s10, s9, 7
	s_waitcnt vmcnt(0)
	s_barrier
	global_load_lds_dwordx4 v[6:7], off
	v_lshl_add_u64 v[4:5], v[4:5], 0, s[4:5]
	s_add_i32 m0, s15, 0x1a000
	s_add_i32 s35, s15, 0x8000
	s_add_i32 s36, s15, 0xa000
	global_load_lds_dwordx4 v[4:5], off
	v_lshl_add_u64 v[2:3], v[2:3], 0, s[4:5]
	s_mov_b32 m0, s35
	s_add_u32 s6, s18, 0x40080
	global_load_lds_dwordx4 v[2:3], off
	v_lshl_add_u64 v[0:1], v[0:1], 0, s[4:5]
	s_mov_b32 m0, s36
	s_addc_u32 s7, s19, 0
	global_load_lds_dwordx4 v[0:1], off
	s_add_i32 m0, s15, 0x1c000
	v_lshl_add_u64 v[0:1], s[6:7], 0, v[132:133]
	global_load_lds_dwordx4 v[0:1], off
	v_lshl_add_u64 v[0:1], s[6:7], 0, v[128:129]
	s_add_i32 m0, s15, 0x1e000
	s_add_i32 s38, 0, 0x10000
	global_load_lds_dwordx4 v[0:1], off
	v_lshrrev_b32_e32 v1, 1, v9
	v_and_b32_e32 v1, 24, v1
	v_and_b32_e32 v0, 15, v9
	v_lshlrev_b32_e32 v2, 1, v1
	v_lshl_or_b32 v148, s3, 6, v0
	v_lshl_or_b32 v0, v0, 6, v2
	v_lshlrev_b32_e32 v2, 2, v9
	v_and_b32_e32 v2, 32, v2
	v_bitop3_b32 v3, v0, s8, v2 bitop3:0xde
	v_bitop3_b32 v149, v0, s10, v2 bitop3:0xde
	v_lshlrev_b32_e32 v0, 14, v13
	v_and_b32_e32 v0, 0xffff8000, v0
	v_or_b32_e32 v150, s9, v1
	v_lshl_add_u32 v0, v12, 11, v0
	v_and_b32_e32 v1, 1, v13
	v_lshl_or_b32 v0, v1, 6, v0
	v_lshl_add_u32 v136, v14, 1, v0
	v_lshlrev_b32_e32 v0, 14, v8
	v_and_b32_e32 v0, 0xffff8000, v0
	s_waitcnt vmcnt(6)
	v_lshl_add_u32 v0, v10, 11, v0
	v_and_b32_e32 v1, 1, v8
	v_lshl_or_b32 v0, v1, 6, v0
	s_add_i32 s39, 0, 0x14000
	s_sext_i32_i16 s41, s2
	s_ashr_i32 s37, s33, 31
	v_mov_b32_e32 v137, v133
	v_lshl_add_u32 v138, v11, 1, v0
	v_mov_b32_e32 v139, v133
	v_mov_b64_e32 v[140:141], 0x580
	v_mov_b64_e32 v[142:143], 0x57f
	v_add_u32_e32 v151, s38, v149
	v_add_u32_e32 v152, 0, v3
	v_add_u32_e32 v153, s39, v149
	s_movk_i32 s40, 0x1600
	s_barrier

; #define PG8_STAGE(bufoff, gbase, voff) do { _Pragma("unroll") for (int _i = 0; _i < 2; ++_i) \
;         __builtin_amdgcn_global_load_lds((const unsigned*)((const char*)(gbase) + (voff)[_i]), (PG8_LAS unsigned*)(lds + (bufoff) + ldsw + _i * 8192), 16, 0, 0); } while (0)
; #define PG8_LDA(dst, b, h) do { _Pragma("unroll") for (int m = 0; m < 4; ++m) _Pragma("unroll") for (int k = 0; k < 2; ++k) dst[m][k] = *(const PG8_LAS bf16x8*)(lds + PG8_SA(b, h) + aoff + m * 2048 + k * 1024); } while (0)
; #define PG8_LDB(dst, b, h) do { _Pragma("unroll") for (int n = 0; n < 2; ++n) _Pragma("unroll") for (int k = 0; k < 2; ++k) dst[n][k] = *(const PG8_LAS bf16x8*)(lds + PG8_SB(b, h) + boff + n * 2048 + k * 1024); } while (0)
; #define PG8_MMA(ai, bj, At, Bt) do { __builtin_amdgcn_s_setprio(1); _Pragma("unroll") for (int m = 0; m < 4; ++m) _Pragma("unroll") for (int n = 0; n < 2; ++n) _Pragma("unroll") for (int k = 0; k < 2; ++k) \
;         acc[ai][bj][m][n] = __builtin_amdgcn_mfma_f32_16x16x32_bf16(Bt[n][k], At[m][k], acc[ai][bj][m][n], 0, 0, 0); __builtin_amdgcn_s_setprio(0); } while (0)
; #define PG8_WAIT_V(n) asm volatile("s_waitcnt vmcnt(" #n ")" ::: "memory")
; #define PG8_WAIT_L(n) asm volatile("s_waitcnt lgkmcnt(" #n ")" ::: "memory")
; #define PG8_BAR __builtin_amdgcn_s_barrier()
; #define PG8_SCHED __builtin_amdgcn_sched_barrier(0)
; template <class Epi, class Sched>
; __device__ __forceinline__ void gemm_phase(PG8_LAS unsigned char* lds, const Gemm g, const Sched& S, const Epi& E) {
;     ...
;             PG8_LDB(B0, 0, 0); PG8_SCHED; PG8_LDA(At, 0, 0); PG8_STAGE(PG8_SA(1, 1), a1 + hstep, voffA);
;             PG8_WAIT_L(8); PG8_BAR; PG8_WAIT_L(0); PG8_MMA(0, 0, At, B0); PG8_BAR; PG8_SCHED;
;             PG8_LDB(B1, 0, 1); PG8_STAGE(PG8_SB(0, 0), b2, voffB);
;             PG8_BAR; PG8_WAIT_L(0); PG8_MMA(0, 1, At, B1); PG8_BAR;
;             PG8_LDA(At, 0, 1); PG8_STAGE(PG8_SA(0, 0), a2, voffA);
;             PG8_BAR; PG8_WAIT_L(0); PG8_MMA(1, 0, At, B0); PG8_BAR; PG8_SCHED;
;             PG8_STAGE(PG8_SB(0, 1), b2 + hstep, voffB);
;             PG8_WAIT_V(6); PG8_BAR; PG8_MMA(1, 1, At, B1); PG8_BAR;
.LBB0_1202:
	ds_read_b128 v[144:147], v151
	ds_read_b128 v[154:157], v151 offset:1024
	ds_read_b128 v[158:161], v151 offset:2048
	ds_read_b128 v[162:165], v151 offset:3072
	s_add_u32 s18, s16, 0xfffc0080
	s_addc_u32 s19, s17, -1
	s_cmp_eq_u32 s46, 12
	s_cselect_b32 s21, s9, s19
	s_cselect_b32 s20, s42, s18
	s_cselect_b32 s19, s7, s45
	s_cselect_b32 s18, s43, s44
	v_lshl_add_u64 v[174:175], s[16:17], 0, v[136:137]
	s_add_i32 m0, s15, 0xc000
	ds_read_b128 v[166:169], v152
	ds_read_b128 v[170:173], v152 offset:1024
	ds_read_b128 v[182:185], v152 offset:2048
	ds_read_b128 v[190:193], v152 offset:3072
	ds_read_b128 v[194:197], v152 offset:4096
	ds_read_b128 v[198:201], v152 offset:5120
	ds_read_b128 v[202:205], v152 offset:6144
	ds_read_b128 v[206:209], v152 offset:7168
	global_load_lds_dwordx4 v[174:175], off
	v_lshl_add_u64 v[174:175], s[16:17], 0, v[138:139]
	s_add_i32 m0, s15, 0xe000
	s_nop 0
	global_load_lds_dwordx4 v[174:175], off
	s_waitcnt lgkmcnt(8)
	ds_read_b128 v[210:213], v153
	ds_read_b128 v[214:217], v153 offset:1024
	ds_read_b128 v[218:221], v153 offset:2048
	ds_read_b128 v[222:225], v153 offset:3072
	s_waitcnt vmcnt(8) lgkmcnt(0)
	s_barrier
	v_mfma_f32_16x16x32_bf16 v[124:127], v[144:147], v[166:169], v[124:127]
	v_mfma_f32_16x16x32_bf16 v[120:123], v[158:161], v[166:169], v[120:123]
	v_mfma_f32_16x16x32_bf16 v[108:111], v[144:147], v[182:185], v[108:111]
	v_mfma_f32_16x16x32_bf16 v[104:107], v[158:161], v[182:185], v[104:107]
	v_mfma_f32_16x16x32_bf16 v[92:95], v[144:147], v[194:197], v[92:95]
	v_mfma_f32_16x16x32_bf16 v[88:91], v[158:161], v[194:197], v[88:91]
	v_mfma_f32_16x16x32_bf16 v[76:79], v[144:147], v[202:205], v[76:79]
	v_mfma_f32_16x16x32_bf16 v[72:75], v[158:161], v[202:205], v[72:75]
	v_mfma_f32_16x16x32_bf16 v[124:127], v[154:157], v[170:173], v[124:127]
	v_mfma_f32_16x16x32_bf16 v[120:123], v[162:165], v[170:173], v[120:123]
	v_mfma_f32_16x16x32_bf16 v[108:111], v[154:157], v[190:193], v[108:111]
	v_mfma_f32_16x16x32_bf16 v[104:107], v[162:165], v[190:193], v[104:107]
	v_mfma_f32_16x16x32_bf16 v[92:95], v[154:157], v[198:201], v[92:95]
	v_mfma_f32_16x16x32_bf16 v[88:91], v[162:165], v[198:201], v[88:91]
	v_mfma_f32_16x16x32_bf16 v[76:79], v[154:157], v[206:209], v[76:79]
	v_mfma_f32_16x16x32_bf16 v[72:75], v[162:165], v[206:209], v[72:75]
	v_mfma_f32_16x16x32_bf16 v[116:119], v[210:213], v[166:169], v[116:119]
	v_mfma_f32_16x16x32_bf16 v[112:115], v[218:221], v[166:169], v[112:115]
	v_mfma_f32_16x16x32_bf16 v[100:103], v[210:213], v[182:185], v[100:103]
	v_mfma_f32_16x16x32_bf16 v[96:99], v[218:221], v[182:185], v[96:99]
	v_mfma_f32_16x16x32_bf16 v[84:87], v[210:213], v[194:197], v[84:87]
	v_mfma_f32_16x16x32_bf16 v[80:83], v[218:221], v[194:197], v[80:83]
	v_mfma_f32_16x16x32_bf16 v[68:71], v[210:213], v[202:205], v[68:71]
	v_mfma_f32_16x16x32_bf16 v[64:67], v[218:221], v[202:205], v[64:67]
	v_mfma_f32_16x16x32_bf16 v[116:119], v[214:217], v[170:173], v[116:119]
	v_mfma_f32_16x16x32_bf16 v[112:115], v[222:225], v[170:173], v[112:115]
	v_mfma_f32_16x16x32_bf16 v[100:103], v[214:217], v[190:193], v[100:103]
	v_mfma_f32_16x16x32_bf16 v[96:99], v[222:225], v[190:193], v[96:99]
	v_mfma_f32_16x16x32_bf16 v[84:87], v[214:217], v[198:201], v[84:87]
	v_mfma_f32_16x16x32_bf16 v[80:83], v[222:225], v[198:201], v[80:83]
	v_mfma_f32_16x16x32_bf16 v[68:71], v[214:217], v[206:209], v[68:71]
	v_mfma_f32_16x16x32_bf16 v[64:67], v[222:225], v[206:209], v[64:67]
	s_barrier
	ds_read_b128 v[166:169], v152 offset:16384
	ds_read_b128 v[170:173], v152 offset:17408
	ds_read_b128 v[182:185], v152 offset:18432
	ds_read_b128 v[190:193], v152 offset:19456
	ds_read_b128 v[194:197], v152 offset:20480
	ds_read_b128 v[198:201], v152 offset:21504
	ds_read_b128 v[202:205], v152 offset:22528
	ds_read_b128 v[206:209], v152 offset:23552
	s_add_i32 s47, s38, s26
	v_lshl_add_u64 v[174:175], s[18:19], 0, v[132:133]
	s_mov_b32 m0, s47
	s_nop 0
	global_load_lds_dwordx4 v[174:175], off
	v_lshl_add_u64 v[186:187], s[18:19], 0, v[128:129]
	s_add_i32 m0, s47, 0x2000
	s_nop 0
	global_load_lds_dwordx4 v[186:187], off
	s_nop 1
	s_mov_b32 m0, s15
	v_lshl_add_u64 v[226:227], s[20:21], 0, v[134:135]
	global_load_lds_dwordx4 v[226:227], off
	v_lshl_add_u64 v[228:229], s[20:21], 0, v[130:131]
	s_mov_b32 m0, s29
	s_nop 0
	global_load_lds_dwordx4 v[228:229], off
	s_add_u32 s48, s18, 0x40000
	s_addc_u32 s49, s19, 0
	s_add_i32 s47, s39, s26
	v_lshl_add_u64 v[246:247], s[48:49], 0, v[132:133]
	s_mov_b32 m0, s47
	s_nop 0
	global_load_lds_dwordx4 v[246:247], off
	v_lshl_add_u64 v[246:247], s[48:49], 0, v[128:129]
	s_add_i32 m0, s47, 0x2000
	s_nop 0
	global_load_lds_dwordx4 v[246:247], off
	s_waitcnt vmcnt(8) lgkmcnt(0)
	s_barrier
; #define PG8_STAGE(bufoff, gbase, voff) do { _Pragma("unroll") for (int _i = 0; _i < 2; ++_i) \
;         __builtin_amdgcn_global_load_lds((const unsigned*)((const char*)(gbase) + (voff)[_i]), (PG8_LAS unsigned*)(lds + (bufoff) + ldsw + _i * 8192), 16, 0, 0); } while (0)
; #define PG8_LDA(dst, b, h) do { _Pragma("unroll") for (int m = 0; m < 4; ++m) _Pragma("unroll") for (int k = 0; k < 2; ++k) dst[m][k] = *(const PG8_LAS bf16x8*)(lds + PG8_SA(b, h) + aoff + m * 2048 + k * 1024); } while (0)
; #define PG8_LDB(dst, b, h) do { _Pragma("unroll") for (int n = 0; n < 2; ++n) _Pragma("unroll") for (int k = 0; k < 2; ++k) dst[n][k] = *(const PG8_LAS bf16x8*)(lds + PG8_SB(b, h) + boff + n * 2048 + k * 1024); } while (0)
; #define PG8_MMA(ai, bj, At, Bt) do { __builtin_amdgcn_s_setprio(1); _Pragma("unroll") for (int m = 0; m < 4; ++m) _Pragma("unroll") for (int n = 0; n < 2; ++n) _Pragma("unroll") for (int k = 0; k < 2; ++k) \
;         acc[ai][bj][m][n] = __builtin_amdgcn_mfma_f32_16x16x32_bf16(Bt[n][k], At[m][k], acc[ai][bj][m][n], 0, 0, 0); __builtin_amdgcn_s_setprio(0); } while (0)
; #define PG8_WAIT_V(n) asm volatile("s_waitcnt vmcnt(" #n ")" ::: "memory")
; #define PG8_WAIT_L(n) asm volatile("s_waitcnt lgkmcnt(" #n ")" ::: "memory")
; #define PG8_BAR __builtin_amdgcn_s_barrier()
; #define PG8_SCHED __builtin_amdgcn_sched_barrier(0)
; template <class Epi, class Sched>
; __device__ __forceinline__ void gemm_phase(PG8_LAS unsigned char* lds, const Gemm g, const Sched& S, const Epi& E) {
;     ...
;             PG8_BAR; PG8_WAIT_L(0); PG8_MMA(1, 0, At, B0); PG8_BAR; PG8_SCHED;
;             PG8_STAGE(PG8_SB(0, 1), b2 + hstep, voffB);
;             PG8_WAIT_V(6); PG8_BAR; PG8_MMA(1, 1, At, B1); PG8_BAR;
;             PG8_LDB(B0, 1, 0); PG8_SCHED; PG8_LDA(At, 1, 0); PG8_STAGE(PG8_SA(0, 1), a2 + hstep, voffA);
;             PG8_WAIT_L(8); PG8_BAR; PG8_WAIT_L(0); PG8_MMA(0, 0, At, B0); PG8_BAR; PG8_SCHED;
;             PG8_LDB(B1, 1, 1); PG8_STAGE(PG8_SB(1, 0), b3, voffB);
;             PG8_BAR; PG8_WAIT_L(0); PG8_MMA(0, 1, At, B1); PG8_BAR;
	v_mfma_f32_16x16x32_bf16 v[60:63], v[144:147], v[166:169], v[60:63]
	v_mfma_f32_16x16x32_bf16 v[56:59], v[158:161], v[166:169], v[56:59]
	v_mfma_f32_16x16x32_bf16 v[44:47], v[144:147], v[182:185], v[44:47]
	v_mfma_f32_16x16x32_bf16 v[40:43], v[158:161], v[182:185], v[40:43]
	v_mfma_f32_16x16x32_bf16 v[28:31], v[144:147], v[194:197], v[28:31]
	v_mfma_f32_16x16x32_bf16 v[24:27], v[158:161], v[194:197], v[24:27]
	v_mfma_f32_16x16x32_bf16 v[12:15], v[144:147], v[202:205], v[12:15]
	v_mfma_f32_16x16x32_bf16 v[8:11], v[158:161], v[202:205], v[8:11]
	v_mfma_f32_16x16x32_bf16 v[60:63], v[154:157], v[170:173], v[60:63]
	v_mfma_f32_16x16x32_bf16 v[56:59], v[162:165], v[170:173], v[56:59]
	v_mfma_f32_16x16x32_bf16 v[44:47], v[154:157], v[190:193], v[44:47]
	v_mfma_f32_16x16x32_bf16 v[40:43], v[162:165], v[190:193], v[40:43]
	v_mfma_f32_16x16x32_bf16 v[28:31], v[154:157], v[198:201], v[28:31]
	v_mfma_f32_16x16x32_bf16 v[24:27], v[162:165], v[198:201], v[24:27]
	v_mfma_f32_16x16x32_bf16 v[12:15], v[154:157], v[206:209], v[12:15]
	v_mfma_f32_16x16x32_bf16 v[8:11], v[162:165], v[206:209], v[8:11]
	v_mfma_f32_16x16x32_bf16 v[52:55], v[210:213], v[166:169], v[52:55]
	v_mfma_f32_16x16x32_bf16 v[48:51], v[218:221], v[166:169], v[48:51]
	v_mfma_f32_16x16x32_bf16 v[36:39], v[210:213], v[182:185], v[36:39]
	v_mfma_f32_16x16x32_bf16 v[32:35], v[218:221], v[182:185], v[32:35]
	v_mfma_f32_16x16x32_bf16 v[20:23], v[210:213], v[194:197], v[20:23]
	v_mfma_f32_16x16x32_bf16 v[16:19], v[218:221], v[194:197], v[16:19]
	v_mfma_f32_16x16x32_bf16 v[4:7], v[210:213], v[202:205], v[4:7]
	v_mfma_f32_16x16x32_bf16 v[0:3], v[218:221], v[202:205], v[0:3]
	v_mfma_f32_16x16x32_bf16 v[52:55], v[214:217], v[170:173], v[52:55]
	v_mfma_f32_16x16x32_bf16 v[48:51], v[222:225], v[170:173], v[48:51]
	v_mfma_f32_16x16x32_bf16 v[36:39], v[214:217], v[190:193], v[36:39]
	v_mfma_f32_16x16x32_bf16 v[32:35], v[222:225], v[190:193], v[32:35]
	v_mfma_f32_16x16x32_bf16 v[20:23], v[214:217], v[198:201], v[20:23]
	v_mfma_f32_16x16x32_bf16 v[16:19], v[222:225], v[198:201], v[16:19]
	v_mfma_f32_16x16x32_bf16 v[4:7], v[214:217], v[206:209], v[4:7]
	v_mfma_f32_16x16x32_bf16 v[0:3], v[222:225], v[206:209], v[0:3]
	s_barrier
	s_add_i32 s47, 0, 0x18000
	v_add_u32_e32 v162, s47, v149
	ds_read_b128 v[144:147], v162
	ds_read_b128 v[154:157], v162 offset:1024
	ds_read_b128 v[158:161], v162 offset:2048
	ds_read_b128 v[162:165], v162 offset:3072
	s_add_u32 s20, s20, 0x40000
	s_addc_u32 s21, s21, 0
	s_mov_b32 m0, s30
	v_lshl_add_u64 v[210:211], s[20:21], 0, v[134:135]
	ds_read_b128 v[166:169], v152 offset:32768
	ds_read_b128 v[170:173], v152 offset:33792
	ds_read_b128 v[182:185], v152 offset:34816
	ds_read_b128 v[190:193], v152 offset:35840
	ds_read_b128 v[194:197], v152 offset:36864
	ds_read_b128 v[198:201], v152 offset:37888
	ds_read_b128 v[202:205], v152 offset:38912
	ds_read_b128 v[206:209], v152 offset:39936
	global_load_lds_dwordx4 v[210:211], off
	v_lshl_add_u64 v[210:211], s[20:21], 0, v[130:131]
	s_mov_b32 m0, s31
	s_nop 0
	global_load_lds_dwordx4 v[210:211], off
	s_add_i32 s20, 0, 0x1c000
	v_add_u32_e32 v179, s20, v149
	s_waitcnt lgkmcnt(8)
	ds_read_b128 v[210:213], v179
	ds_read_b128 v[214:217], v179 offset:1024
	ds_read_b128 v[218:221], v179 offset:2048
	ds_read_b128 v[222:225], v179 offset:3072
	s_waitcnt vmcnt(8) lgkmcnt(0)
	s_barrier
	v_mfma_f32_16x16x32_bf16 v[124:127], v[144:147], v[166:169], v[124:127]
	v_mfma_f32_16x16x32_bf16 v[120:123], v[158:161], v[166:169], v[120:123]
	v_mfma_f32_16x16x32_bf16 v[108:111], v[144:147], v[182:185], v[108:111]
	v_mfma_f32_16x16x32_bf16 v[104:107], v[158:161], v[182:185], v[104:107]
	v_mfma_f32_16x16x32_bf16 v[92:95], v[144:147], v[194:197], v[92:95]
	v_mfma_f32_16x16x32_bf16 v[88:91], v[158:161], v[194:197], v[88:91]
	v_mfma_f32_16x16x32_bf16 v[76:79], v[144:147], v[202:205], v[76:79]
	v_mfma_f32_16x16x32_bf16 v[72:75], v[158:161], v[202:205], v[72:75]
	v_mfma_f32_16x16x32_bf16 v[124:127], v[154:157], v[170:173], v[124:127]
	v_mfma_f32_16x16x32_bf16 v[120:123], v[162:165], v[170:173], v[120:123]
	v_mfma_f32_16x16x32_bf16 v[108:111], v[154:157], v[190:193], v[108:111]
	v_mfma_f32_16x16x32_bf16 v[104:107], v[162:165], v[190:193], v[104:107]
	v_mfma_f32_16x16x32_bf16 v[92:95], v[154:157], v[198:201], v[92:95]
	v_mfma_f32_16x16x32_bf16 v[88:91], v[162:165], v[198:201], v[88:91]
	v_mfma_f32_16x16x32_bf16 v[76:79], v[154:157], v[206:209], v[76:79]
	v_mfma_f32_16x16x32_bf16 v[72:75], v[162:165], v[206:209], v[72:75]
	v_mfma_f32_16x16x32_bf16 v[116:119], v[210:213], v[166:169], v[116:119]
	v_mfma_f32_16x16x32_bf16 v[112:115], v[218:221], v[166:169], v[112:115]
	v_mfma_f32_16x16x32_bf16 v[100:103], v[210:213], v[182:185], v[100:103]
	v_mfma_f32_16x16x32_bf16 v[96:99], v[218:221], v[182:185], v[96:99]
	v_mfma_f32_16x16x32_bf16 v[84:87], v[210:213], v[194:197], v[84:87]
	v_mfma_f32_16x16x32_bf16 v[80:83], v[218:221], v[194:197], v[80:83]
	v_mfma_f32_16x16x32_bf16 v[68:71], v[210:213], v[202:205], v[68:71]
	v_mfma_f32_16x16x32_bf16 v[64:67], v[218:221], v[202:205], v[64:67]
	v_mfma_f32_16x16x32_bf16 v[116:119], v[214:217], v[170:173], v[116:119]
	v_mfma_f32_16x16x32_bf16 v[112:115], v[222:225], v[170:173], v[112:115]
	v_mfma_f32_16x16x32_bf16 v[100:103], v[214:217], v[190:193], v[100:103]
	v_mfma_f32_16x16x32_bf16 v[96:99], v[222:225], v[190:193], v[96:99]
	v_mfma_f32_16x16x32_bf16 v[84:87], v[214:217], v[198:201], v[84:87]
	v_mfma_f32_16x16x32_bf16 v[80:83], v[222:225], v[198:201], v[80:83]
	v_mfma_f32_16x16x32_bf16 v[68:71], v[214:217], v[206:209], v[68:71]
	v_mfma_f32_16x16x32_bf16 v[64:67], v[222:225], v[206:209], v[64:67]
	s_barrier
; __device__ __forceinline__ unsigned cvt_pk_bf16(float lo, float hi) { unsigned r; asm volatile("v_cvt_pk_bf16_f32 %0, %1, %2" : "=v"(r) : "v"(lo), "v"(hi)); return r; }
; #define PG8_STAGE(bufoff, gbase, voff) do { _Pragma("unroll") for (int _i = 0; _i < 2; ++_i) \
;         __builtin_amdgcn_global_load_lds((const unsigned*)((const char*)(gbase) + (voff)[_i]), (PG8_LAS unsigned*)(lds + (bufoff) + ldsw + _i * 8192), 16, 0, 0); } while (0)
; #define PG8_LDA(dst, b, h) do { _Pragma("unroll") for (int m = 0; m < 4; ++m) _Pragma("unroll") for (int k = 0; k < 2; ++k) dst[m][k] = *(const PG8_LAS bf16x8*)(lds + PG8_SA(b, h) + aoff + m * 2048 + k * 1024); } while (0)
; #define PG8_WAIT_V(n) asm volatile("s_waitcnt vmcnt(" #n ")" ::: "memory")
; #define PG8_WAIT_L(n) asm volatile("s_waitcnt lgkmcnt(" #n ")" ::: "memory")
; #define PG8_BAR __builtin_amdgcn_s_barrier()
; __device__ __forceinline__ f32x4 sigmoid4(f32x4 x) {
;     f32x4 d;
; #pragma unroll
;     for (int j = 0; j < 4; ++j) d[j] = 1.0f + __expf(-fmaxf(x[j], -20.0f));
;     const float p01 = d[0] * d[1], p23 = d[2] * d[3], r = __builtin_amdgcn_rcpf(p01 * p23), r01 = r * p23, r23 = r * p01;
;     return (f32x4){r01 * d[1], r01 * d[0], r23 * d[3], r23 * d[2]};
; }
;     __device__ __forceinline__ void operator()(const f32x4 (&acc)[2][2][4][2], const Unit& u, int wr, int wc, int fr, int fq) const {
;     ...
;             for (int m = 0; m < 4; ++m) { bf16_t* rowp = O + (size_t)(row0 + ai * HALF + m * 16) * ldc + col0;
;                 f32x4 v0, v1;
; #pragma unroll
;                 for (int j = 0; j < 1; ++j) { v0 = acc[ai][0][m][0] * sigmoid4(acc[ai][0][m][0]) * acc[ai][1][m][0]; v1 = acc[ai][0][m][1] * sigmoid4(acc[ai][0][m][1]) * acc[ai][1][m][1]; }
;                 u32x4 w; w.x = cvt_pk_bf16(v0[0], v0[1]); w.y = cvt_pk_bf16(v0[2], v0[3]); w.z = cvt_pk_bf16(v1[0], v1[1]); w.w = cvt_pk_bf16(v1[2], v1[3]);
;                 *(u32x4*)rowp = w; }
; template <class Epi, class Sched>
; __device__ __forceinline__ void gemm_phase(PG8_LAS unsigned char* lds, const Gemm g, const Sched& S, const Epi& E) {
;     ...
;             PG8_LDA(At, 1, 1); PG8_STAGE(PG8_SA(1, 0), a3, voffA);
;             PG8_BAR; PG8_WAIT_L(0); PG8_MMA(1, 0, At, B0); PG8_BAR; PG8_SCHED;
;             PG8_STAGE(PG8_SB(1, 1), b3 + hstep, voffB);
;             PG8_WAIT_V(6); PG8_BAR; PG8_MMA(1, 1, At, B1); PG8_BAR;
	ds_read_b128 v[166:169], v152 offset:49152
	ds_read_b128 v[170:173], v152 offset:50176
	ds_read_b128 v[182:185], v152 offset:51200
	ds_read_b128 v[190:193], v152 offset:52224
	ds_read_b128 v[194:197], v152 offset:53248
	ds_read_b128 v[198:201], v152 offset:54272
	ds_read_b128 v[202:205], v152 offset:55296
	ds_read_b128 v[206:209], v152 offset:56320
	s_add_i32 s21, s47, s26
	v_lshl_add_u64 v[174:175], v[174:175], 0, s[4:5]
	s_mov_b32 m0, s21
	s_nop 0
	global_load_lds_dwordx4 v[174:175], off
	v_lshl_add_u64 v[174:175], v[186:187], 0, s[4:5]
	s_add_i32 m0, s21, 0x2000
	s_nop 0
	global_load_lds_dwordx4 v[174:175], off
	s_nop 1
	s_mov_b32 m0, s35
	v_lshl_add_u64 v[174:175], v[226:227], 0, s[4:5]
	global_load_lds_dwordx4 v[174:175], off
	v_lshl_add_u64 v[174:175], v[228:229], 0, s[4:5]
	s_mov_b32 m0, s36
	s_nop 0
	global_load_lds_dwordx4 v[174:175], off
	s_add_u32 s18, s18, 0x40080
	s_addc_u32 s19, s19, 0
	s_add_i32 s20, s20, s26
	v_lshl_add_u64 v[246:247], s[18:19], 0, v[132:133]
	s_mov_b32 m0, s20
	s_nop 0
	global_load_lds_dwordx4 v[246:247], off
	v_lshl_add_u64 v[246:247], s[18:19], 0, v[128:129]
	s_add_i32 m0, s20, 0x2000
	s_nop 0
	global_load_lds_dwordx4 v[246:247], off
	s_waitcnt vmcnt(8) lgkmcnt(0)
	s_barrier
	v_mfma_f32_16x16x32_bf16 v[60:63], v[144:147], v[166:169], v[60:63]
	v_mfma_f32_16x16x32_bf16 v[56:59], v[158:161], v[166:169], v[56:59]
	v_mfma_f32_16x16x32_bf16 v[44:47], v[144:147], v[182:185], v[44:47]
	v_mfma_f32_16x16x32_bf16 v[40:43], v[158:161], v[182:185], v[40:43]
	v_mfma_f32_16x16x32_bf16 v[28:31], v[144:147], v[194:197], v[28:31]
	v_mfma_f32_16x16x32_bf16 v[24:27], v[158:161], v[194:197], v[24:27]
	v_mfma_f32_16x16x32_bf16 v[12:15], v[144:147], v[202:205], v[12:15]
	v_mfma_f32_16x16x32_bf16 v[8:11], v[158:161], v[202:205], v[8:11]
	v_mfma_f32_16x16x32_bf16 v[60:63], v[154:157], v[170:173], v[60:63]
	v_mfma_f32_16x16x32_bf16 v[56:59], v[162:165], v[170:173], v[56:59]
	v_mfma_f32_16x16x32_bf16 v[44:47], v[154:157], v[190:193], v[44:47]
	v_mfma_f32_16x16x32_bf16 v[40:43], v[162:165], v[190:193], v[40:43]
	v_mfma_f32_16x16x32_bf16 v[28:31], v[154:157], v[198:201], v[28:31]
	v_mfma_f32_16x16x32_bf16 v[24:27], v[162:165], v[198:201], v[24:27]
	v_mfma_f32_16x16x32_bf16 v[12:15], v[154:157], v[206:209], v[12:15]
	v_mfma_f32_16x16x32_bf16 v[8:11], v[162:165], v[206:209], v[8:11]
	v_mfma_f32_16x16x32_bf16 v[52:55], v[210:213], v[166:169], v[52:55]
	v_mfma_f32_16x16x32_bf16 v[48:51], v[218:221], v[166:169], v[48:51]
	v_mfma_f32_16x16x32_bf16 v[36:39], v[210:213], v[182:185], v[36:39]
	v_mfma_f32_16x16x32_bf16 v[32:35], v[218:221], v[182:185], v[32:35]
	v_mfma_f32_16x16x32_bf16 v[20:23], v[210:213], v[194:197], v[20:23]
	v_mfma_f32_16x16x32_bf16 v[16:19], v[218:221], v[194:197], v[16:19]
	v_mfma_f32_16x16x32_bf16 v[4:7], v[210:213], v[202:205], v[4:7]
	v_mfma_f32_16x16x32_bf16 v[0:3], v[218:221], v[202:205], v[0:3]
	v_mfma_f32_16x16x32_bf16 v[52:55], v[214:217], v[170:173], v[52:55]
	v_mfma_f32_16x16x32_bf16 v[48:51], v[222:225], v[170:173], v[48:51]
	v_mfma_f32_16x16x32_bf16 v[36:39], v[214:217], v[190:193], v[36:39]
	v_mfma_f32_16x16x32_bf16 v[32:35], v[222:225], v[190:193], v[32:35]
	v_mfma_f32_16x16x32_bf16 v[20:23], v[214:217], v[198:201], v[20:23]
	v_mfma_f32_16x16x32_bf16 v[16:19], v[222:225], v[198:201], v[16:19]
	v_mfma_f32_16x16x32_bf16 v[4:7], v[214:217], v[206:209], v[4:7]
	v_mfma_f32_16x16x32_bf16 v[0:3], v[222:225], v[206:209], v[0:3]
	s_barrier
	s_add_i32 s46, s46, 2
	s_add_u32 s16, s16, 0x100
	s_addc_u32 s17, s17, 0
	s_add_u32 s44, s44, 0x100
	s_addc_u32 s45, s45, 0
	s_cmp_gt_u32 s46, 13
	s_cbranch_scc0 .LBB0_1202
	v_max_f32_e32 v144, v124, v124
	v_max_f32_e32 v144, 0xc1a00000, v144
	v_mul_f32_e32 v144, 0xbfb8aa3b, v144
	v_exp_f32_e32 v157, v144
	v_max_f32_e32 v144, v125, v125
	v_max_f32_e32 v144, 0xc1a00000, v144
	v_mul_f32_e32 v144, 0xbfb8aa3b, v144
	v_exp_f32_e32 v156, v144
	v_max_f32_e32 v144, v126, v126
	v_max_f32_e32 v144, 0xc1a00000, v144
	v_mul_f32_e32 v144, 0xbfb8aa3b, v144
	v_exp_f32_e32 v159, v144
	v_max_f32_e32 v144, v127, v127
	v_max_f32_e32 v144, 0xc1a00000, v144
	v_mul_f32_e32 v144, 0xbfb8aa3b, v144
	v_exp_f32_e32 v158, v144
	v_pk_add_f32 v[156:157], v[156:157], 1.0 op_sel_hi:[1,0]
	v_lshl_or_b32 v146, s41, 7, v150
	v_mov_b32_e32 v160, v157
	v_pk_add_f32 v[158:159], v[158:159], 1.0 op_sel_hi:[1,0]
	v_mov_b32_e32 v162, v156
	v_mov_b32_e32 v161, v159
	v_mov_b32_e32 v163, v158
	v_pk_mul_f32 v[160:161], v[160:161], v[162:163]
	v_lshl_add_u32 v154, s14, 8, v148
	v_mul_f32_e32 v155, v160, v161
	v_rcp_f32_e32 v155, v155
	v_ashrrev_i32_e32 v147, 31, v146
	v_mov_b64_e32 v[144:145], s[0:1]
	v_mad_i64_i32 v[162:163], s[16:17], v154, s40, v[144:145]
	v_mul_f32_e32 v164, v161, v155
	v_mul_f32_e32 v160, v160, v155
	v_max_f32_e32 v155, v120, v120
	v_max_f32_e32 v155, 0xc1a00000, v155
	v_mul_f32_e32 v155, 0xbfb8aa3b, v155
	v_pk_mul_f32 v[158:159], v[158:159], v[160:161] op_sel_hi:[1,0]
	v_exp_f32_e32 v161, v155
	v_max_f32_e32 v155, v121, v121
	v_max_f32_e32 v155, 0xc1a00000, v155
	v_mul_f32_e32 v155, 0xbfb8aa3b, v155
	v_exp_f32_e32 v160, v155
	v_max_f32_e32 v155, v122, v122
	v_max_f32_e32 v155, 0xc1a00000, v155
	v_mul_f32_e32 v155, 0xbfb8aa3b, v155
	v_exp_f32_e32 v167, v155
	v_max_f32_e32 v155, v123, v123
	v_max_f32_e32 v155, 0xc1a00000, v155
	v_mul_f32_e32 v155, 0xbfb8aa3b, v155
	v_exp_f32_e32 v166, v155
	v_pk_mul_f32 v[156:157], v[156:157], v[164:165] op_sel_hi:[1,0]
	v_pk_mul_f32 v[126:127], v[126:127], v[158:159]
	v_pk_mul_f32 v[124:125], v[124:125], v[156:157]
	v_pk_add_f32 v[156:157], v[160:161], 1.0 op_sel_hi:[1,0]
	v_pk_add_f32 v[160:161], v[166:167], 1.0 op_sel_hi:[1,0]
	v_mov_b32_e32 v164, v157
; __device__ __forceinline__ unsigned cvt_pk_bf16(float lo, float hi) { unsigned r; asm volatile("v_cvt_pk_bf16_f32 %0, %1, %2" : "=v"(r) : "v"(lo), "v"(hi)); return r; }
; __device__ __forceinline__ f32x4 sigmoid4(f32x4 x) {
;     f32x4 d;
; #pragma unroll
;     for (int j = 0; j < 4; ++j) d[j] = 1.0f + __expf(-fmaxf(x[j], -20.0f));
;     const float p01 = d[0] * d[1], p23 = d[2] * d[3], r = __builtin_amdgcn_rcpf(p01 * p23), r01 = r * p23, r23 = r * p01;
;     return (f32x4){r01 * d[1], r01 * d[0], r23 * d[3], r23 * d[2]};
; }
;     __device__ __forceinline__ void operator()(const f32x4 (&acc)[2][2][4][2], const Unit& u, int wr, int wc, int fr, int fq) const {
;     ...
;             for (int m = 0; m < 4; ++m) { bf16_t* rowp = O + (size_t)(row0 + ai * HALF + m * 16) * ldc + col0;
;                 f32x4 v0, v1;
; #pragma unroll
;                 for (int j = 0; j < 1; ++j) { v0 = acc[ai][0][m][0] * sigmoid4(acc[ai][0][m][0]) * acc[ai][1][m][0]; v1 = acc[ai][0][m][1] * sigmoid4(acc[ai][0][m][1]) * acc[ai][1][m][1]; }
;                 u32x4 w; w.x = cvt_pk_bf16(v0[0], v0[1]); w.y = cvt_pk_bf16(v0[2], v0[3]); w.z = cvt_pk_bf16(v1[0], v1[1]); w.w = cvt_pk_bf16(v1[2], v1[3]);
;                 *(u32x4*)rowp = w; }
	v_mov_b32_e32 v165, v161
	v_mov_b32_e32 v166, v156
	v_mov_b32_e32 v167, v160
	v_pk_mul_f32 v[164:165], v[164:165], v[166:167]
	v_pk_mul_f32 v[118:119], v[126:127], v[118:119]
	v_mul_f32_e32 v155, v164, v165
	v_rcp_f32_e32 v155, v155
	v_pk_mul_f32 v[116:117], v[124:125], v[116:117]
	v_lshlrev_b64 v[146:147], 1, v[146:147]
	v_lshl_add_u64 v[162:163], v[162:163], 0, v[146:147]
	v_mul_f32_e32 v124, v165, v155
	v_mul_f32_e32 v126, v164, v155
	v_pk_mul_f32 v[126:127], v[160:161], v[126:127] op_sel_hi:[1,0]
	v_pk_mul_f32 v[124:125], v[156:157], v[124:125] op_sel_hi:[1,0]
	v_pk_mul_f32 v[122:123], v[122:123], v[126:127]
	v_pk_mul_f32 v[120:121], v[120:121], v[124:125]
	v_pk_mul_f32 v[122:123], v[122:123], v[114:115]
	v_pk_mul_f32 v[114:115], v[120:121], v[112:113]
	v_cvt_pk_bf16_f32 v112, v116, v117
	v_cvt_pk_bf16_f32 v113, v118, v119
	v_max_f32_e32 v116, v108, v108
	v_max_f32_e32 v118, v110, v110
	v_max_f32_e32 v116, 0xc1a00000, v116
	v_max_f32_e32 v118, 0xc1a00000, v118
	v_mul_f32_e32 v116, 0xbfb8aa3b, v116
	v_mul_f32_e32 v118, 0xbfb8aa3b, v118
	v_exp_f32_e32 v117, v116
	v_max_f32_e32 v116, v109, v109
	v_exp_f32_e32 v119, v118
	v_max_f32_e32 v118, v111, v111
	v_max_f32_e32 v116, 0xc1a00000, v116
	v_max_f32_e32 v118, 0xc1a00000, v118
	v_mul_f32_e32 v116, 0xbfb8aa3b, v116
	v_mul_f32_e32 v118, 0xbfb8aa3b, v118
	v_exp_f32_e32 v116, v116
	v_exp_f32_e32 v118, v118
	v_cvt_pk_bf16_f32 v114, v114, v115
	v_cvt_pk_bf16_f32 v115, v122, v123
	global_store_dwordx4 v[162:163], v[112:115], off
	v_or_b32_e32 v120, 16, v154
	s_and_b64 vcc, exec, s[2:3]
	v_pk_add_f32 v[112:113], v[116:117], 1.0 op_sel_hi:[1,0]
	v_pk_add_f32 v[114:115], v[118:119], 1.0 op_sel_hi:[1,0]
	v_mov_b32_e32 v116, v113
	v_mov_b32_e32 v117, v115
	v_mov_b32_e32 v118, v112
	v_mov_b32_e32 v119, v114
	v_pk_mul_f32 v[116:117], v[116:117], v[118:119]
	s_mov_b32 s41, s6
	v_mul_f32_e32 v118, v116, v117
	v_rcp_f32_e32 v121, v118
	v_mad_i64_i32 v[118:119], s[16:17], v120, s40, v[144:145]
	v_lshl_add_u64 v[118:119], v[118:119], 0, v[146:147]
	v_mul_f32_e32 v116, v116, v121
	v_mul_f32_e32 v120, v117, v121
	v_pk_mul_f32 v[114:115], v[114:115], v[116:117] op_sel_hi:[1,0]
	v_max_f32_e32 v116, v104, v104
	v_max_f32_e32 v121, v106, v106
	v_max_f32_e32 v116, 0xc1a00000, v116
	v_max_f32_e32 v121, 0xc1a00000, v121
	v_mul_f32_e32 v116, 0xbfb8aa3b, v116
	v_mul_f32_e32 v121, 0xbfb8aa3b, v121
	v_exp_f32_e32 v117, v116
	v_max_f32_e32 v116, v105, v105
	v_exp_f32_e32 v123, v121
	v_max_f32_e32 v121, v107, v107
	v_max_f32_e32 v116, 0xc1a00000, v116
	v_max_f32_e32 v121, 0xc1a00000, v121
	v_mul_f32_e32 v116, 0xbfb8aa3b, v116
	v_mul_f32_e32 v121, 0xbfb8aa3b, v121
	v_exp_f32_e32 v116, v116
	v_exp_f32_e32 v122, v121
	v_pk_mul_f32 v[112:113], v[112:113], v[120:121] op_sel_hi:[1,0]
	v_pk_mul_f32 v[110:111], v[110:111], v[114:115]
	v_pk_mul_f32 v[108:109], v[108:109], v[112:113]
	v_pk_add_f32 v[112:113], v[116:117], 1.0 op_sel_hi:[1,0]
	v_pk_add_f32 v[116:117], v[122:123], 1.0 op_sel_hi:[1,0]
	v_mov_b32_e32 v120, v113
	v_mov_b32_e32 v121, v117
	v_mov_b32_e32 v122, v112
	v_mov_b32_e32 v123, v116
	v_pk_mul_f32 v[120:121], v[120:121], v[122:123]
	v_pk_mul_f32 v[102:103], v[110:111], v[102:103]
	v_mul_f32_e32 v122, v120, v121
	v_rcp_f32_e32 v122, v122
	v_pk_mul_f32 v[100:101], v[108:109], v[100:101]
	s_mov_b32 s14, s8
	s_mov_b64 s[18:19], s[12:13]
	v_mul_f32_e32 v108, v121, v122
	v_mul_f32_e32 v110, v120, v122
	v_pk_mul_f32 v[110:111], v[116:117], v[110:111] op_sel_hi:[1,0]
	v_pk_mul_f32 v[108:109], v[112:113], v[108:109] op_sel_hi:[1,0]
	v_pk_mul_f32 v[106:107], v[106:107], v[110:111]
	v_pk_mul_f32 v[104:105], v[104:105], v[108:109]
	v_pk_mul_f32 v[106:107], v[106:107], v[98:99]
	v_pk_mul_f32 v[98:99], v[104:105], v[96:97]
	v_cvt_pk_bf16_f32 v96, v100, v101
	v_cvt_pk_bf16_f32 v97, v102, v103
	v_max_f32_e32 v100, v92, v92
	v_max_f32_e32 v102, v94, v94
	v_max_f32_e32 v100, 0xc1a00000, v100
	v_max_f32_e32 v102, 0xc1a00000, v102
	v_mul_f32_e32 v100, 0xbfb8aa3b, v100
	v_mul_f32_e32 v102, 0xbfb8aa3b, v102
	v_exp_f32_e32 v101, v100
	v_max_f32_e32 v100, v93, v93
	v_exp_f32_e32 v103, v102
	v_max_f32_e32 v102, v95, v95
	v_max_f32_e32 v100, 0xc1a00000, v100
	v_max_f32_e32 v102, 0xc1a00000, v102
	v_mul_f32_e32 v100, 0xbfb8aa3b, v100
	v_mul_f32_e32 v102, 0xbfb8aa3b, v102
	v_exp_f32_e32 v100, v100
	v_exp_f32_e32 v102, v102
	v_cvt_pk_bf16_f32 v98, v98, v99
	v_cvt_pk_bf16_f32 v99, v106, v107
	global_store_dwordx4 v[118:119], v[96:99], off
	v_or_b32_e32 v104, 32, v154
	s_nop 0
	v_pk_add_f32 v[96:97], v[100:101], 1.0 op_sel_hi:[1,0]
	v_pk_add_f32 v[98:99], v[102:103], 1.0 op_sel_hi:[1,0]
	v_mov_b32_e32 v100, v97
	v_mov_b32_e32 v101, v99
	v_mov_b32_e32 v102, v96
	v_mov_b32_e32 v103, v98
	v_pk_mul_f32 v[100:101], v[100:101], v[102:103]
	s_nop 0
	v_mul_f32_e32 v102, v100, v101
	v_rcp_f32_e32 v105, v102
	v_mad_i64_i32 v[102:103], s[16:17], v104, s40, v[144:145]
	v_lshl_add_u64 v[102:103], v[102:103], 0, v[146:147]
	v_mul_f32_e32 v100, v100, v105
	v_mul_f32_e32 v104, v101, v105
	v_pk_mul_f32 v[98:99], v[98:99], v[100:101] op_sel_hi:[1,0]
	v_max_f32_e32 v100, v88, v88
	v_max_f32_e32 v105, v90, v90
	v_max_f32_e32 v100, 0xc1a00000, v100
	v_max_f32_e32 v105, 0xc1a00000, v105
	v_mul_f32_e32 v100, 0xbfb8aa3b, v100
	v_mul_f32_e32 v105, 0xbfb8aa3b, v105
	v_exp_f32_e32 v101, v100
	v_max_f32_e32 v100, v89, v89
	v_exp_f32_e32 v107, v105
	v_max_f32_e32 v105, v91, v91
	v_max_f32_e32 v100, 0xc1a00000, v100
	v_max_f32_e32 v105, 0xc1a00000, v105
	v_mul_f32_e32 v100, 0xbfb8aa3b, v100
	v_mul_f32_e32 v105, 0xbfb8aa3b, v105
	v_exp_f32_e32 v100, v100
	v_exp_f32_e32 v106, v105
	v_pk_mul_f32 v[96:97], v[96:97], v[104:105] op_sel_hi:[1,0]
	v_pk_mul_f32 v[94:95], v[94:95], v[98:99]
; __device__ __forceinline__ unsigned cvt_pk_bf16(float lo, float hi) { unsigned r; asm volatile("v_cvt_pk_bf16_f32 %0, %1, %2" : "=v"(r) : "v"(lo), "v"(hi)); return r; }
; __device__ __forceinline__ f32x4 sigmoid4(f32x4 x) {
;     f32x4 d;
; #pragma unroll
;     for (int j = 0; j < 4; ++j) d[j] = 1.0f + __expf(-fmaxf(x[j], -20.0f));
;     const float p01 = d[0] * d[1], p23 = d[2] * d[3], r = __builtin_amdgcn_rcpf(p01 * p23), r01 = r * p23, r23 = r * p01;
;     return (f32x4){r01 * d[1], r01 * d[0], r23 * d[3], r23 * d[2]};
; }
;     __device__ __forceinline__ void operator()(const f32x4 (&acc)[2][2][4][2], const Unit& u, int wr, int wc, int fr, int fq) const {
;     ...
;             for (int m = 0; m < 4; ++m) { bf16_t* rowp = O + (size_t)(row0 + ai * HALF + m * 16) * ldc + col0;
;                 f32x4 v0, v1;
; #pragma unroll
;                 for (int j = 0; j < 1; ++j) { v0 = acc[ai][0][m][0] * sigmoid4(acc[ai][0][m][0]) * acc[ai][1][m][0]; v1 = acc[ai][0][m][1] * sigmoid4(acc[ai][0][m][1]) * acc[ai][1][m][1]; }
;                 u32x4 w; w.x = cvt_pk_bf16(v0[0], v0[1]); w.y = cvt_pk_bf16(v0[2], v0[3]); w.z = cvt_pk_bf16(v1[0], v1[1]); w.w = cvt_pk_bf16(v1[2], v1[3]);
;                 *(u32x4*)rowp = w; }
	v_pk_mul_f32 v[92:93], v[92:93], v[96:97]
	v_pk_add_f32 v[96:97], v[100:101], 1.0 op_sel_hi:[1,0]
	v_pk_add_f32 v[100:101], v[106:107], 1.0 op_sel_hi:[1,0]
	v_mov_b32_e32 v104, v97
	v_mov_b32_e32 v105, v101
	v_mov_b32_e32 v106, v96
	v_mov_b32_e32 v107, v100
	v_pk_mul_f32 v[104:105], v[104:105], v[106:107]
	v_pk_mul_f32 v[86:87], v[94:95], v[86:87]
	v_mul_f32_e32 v106, v104, v105
	v_rcp_f32_e32 v106, v106
	v_pk_mul_f32 v[84:85], v[92:93], v[84:85]
	v_mul_f32_e32 v92, v105, v106
	v_mul_f32_e32 v94, v104, v106
	v_pk_mul_f32 v[94:95], v[100:101], v[94:95] op_sel_hi:[1,0]
	v_pk_mul_f32 v[92:93], v[96:97], v[92:93] op_sel_hi:[1,0]
	v_pk_mul_f32 v[90:91], v[90:91], v[94:95]
	v_pk_mul_f32 v[88:89], v[88:89], v[92:93]
	v_pk_mul_f32 v[90:91], v[90:91], v[82:83]
	v_pk_mul_f32 v[82:83], v[88:89], v[80:81]
	v_cvt_pk_bf16_f32 v80, v84, v85
	v_cvt_pk_bf16_f32 v81, v86, v87
	v_max_f32_e32 v84, v76, v76
	v_max_f32_e32 v86, v78, v78
	v_max_f32_e32 v84, 0xc1a00000, v84
	v_max_f32_e32 v86, 0xc1a00000, v86
	v_mul_f32_e32 v84, 0xbfb8aa3b, v84
	v_mul_f32_e32 v86, 0xbfb8aa3b, v86
	v_exp_f32_e32 v85, v84
	v_max_f32_e32 v84, v77, v77
	v_exp_f32_e32 v87, v86
	v_max_f32_e32 v86, v79, v79
	v_max_f32_e32 v84, 0xc1a00000, v84
	v_max_f32_e32 v86, 0xc1a00000, v86
	v_mul_f32_e32 v84, 0xbfb8aa3b, v84
	v_mul_f32_e32 v86, 0xbfb8aa3b, v86
	v_exp_f32_e32 v84, v84
	v_exp_f32_e32 v86, v86
	v_cvt_pk_bf16_f32 v82, v82, v83
	v_cvt_pk_bf16_f32 v83, v90, v91
	global_store_dwordx4 v[102:103], v[80:83], off
	v_or_b32_e32 v88, 48, v154
	s_nop 0
	v_pk_add_f32 v[80:81], v[84:85], 1.0 op_sel_hi:[1,0]
	v_pk_add_f32 v[82:83], v[86:87], 1.0 op_sel_hi:[1,0]
	v_mov_b32_e32 v84, v81
	v_mov_b32_e32 v85, v83
	v_mov_b32_e32 v86, v80
	v_mov_b32_e32 v87, v82
	v_pk_mul_f32 v[84:85], v[84:85], v[86:87]
	s_nop 0
	v_mul_f32_e32 v86, v84, v85
	v_rcp_f32_e32 v89, v86
	v_mad_i64_i32 v[86:87], s[16:17], v88, s40, v[144:145]
	v_lshl_add_u64 v[86:87], v[86:87], 0, v[146:147]
	v_mul_f32_e32 v84, v84, v89
	v_mul_f32_e32 v88, v85, v89
	v_pk_mul_f32 v[82:83], v[82:83], v[84:85] op_sel_hi:[1,0]
	v_max_f32_e32 v84, v72, v72
	v_max_f32_e32 v89, v74, v74
	v_max_f32_e32 v84, 0xc1a00000, v84
	v_max_f32_e32 v89, 0xc1a00000, v89
	v_mul_f32_e32 v84, 0xbfb8aa3b, v84
	v_mul_f32_e32 v89, 0xbfb8aa3b, v89
	v_exp_f32_e32 v85, v84
	v_max_f32_e32 v84, v73, v73
	v_exp_f32_e32 v91, v89
	v_max_f32_e32 v89, v75, v75
	v_max_f32_e32 v84, 0xc1a00000, v84
	v_max_f32_e32 v89, 0xc1a00000, v89
	v_mul_f32_e32 v84, 0xbfb8aa3b, v84
	v_mul_f32_e32 v89, 0xbfb8aa3b, v89
	v_exp_f32_e32 v84, v84
	v_exp_f32_e32 v90, v89
	v_pk_mul_f32 v[80:81], v[80:81], v[88:89] op_sel_hi:[1,0]
	v_pk_mul_f32 v[78:79], v[78:79], v[82:83]
	v_pk_mul_f32 v[76:77], v[76:77], v[80:81]
	v_pk_add_f32 v[80:81], v[84:85], 1.0 op_sel_hi:[1,0]
	v_pk_add_f32 v[84:85], v[90:91], 1.0 op_sel_hi:[1,0]
	v_mov_b32_e32 v88, v81
	v_mov_b32_e32 v89, v85
	v_mov_b32_e32 v90, v80
	v_mov_b32_e32 v91, v84
	v_pk_mul_f32 v[88:89], v[88:89], v[90:91]
	v_pk_mul_f32 v[70:71], v[78:79], v[70:71]
	v_mul_f32_e32 v90, v88, v89
	v_rcp_f32_e32 v90, v90
	v_pk_mul_f32 v[68:69], v[76:77], v[68:69]
	v_mul_f32_e32 v76, v89, v90
	v_mul_f32_e32 v78, v88, v90
	v_pk_mul_f32 v[78:79], v[84:85], v[78:79] op_sel_hi:[1,0]
	v_pk_mul_f32 v[76:77], v[80:81], v[76:77] op_sel_hi:[1,0]
	v_pk_mul_f32 v[74:75], v[74:75], v[78:79]
	v_pk_mul_f32 v[72:73], v[72:73], v[76:77]
	v_pk_mul_f32 v[74:75], v[74:75], v[66:67]
	v_pk_mul_f32 v[66:67], v[72:73], v[64:65]
	v_cvt_pk_bf16_f32 v64, v68, v69
	v_cvt_pk_bf16_f32 v65, v70, v71
	v_max_f32_e32 v68, v60, v60
	v_max_f32_e32 v70, v62, v62
	v_max_f32_e32 v68, 0xc1a00000, v68
	v_max_f32_e32 v70, 0xc1a00000, v70
	v_mul_f32_e32 v68, 0xbfb8aa3b, v68
	v_mul_f32_e32 v70, 0xbfb8aa3b, v70
	v_exp_f32_e32 v69, v68
	v_max_f32_e32 v68, v61, v61
	v_exp_f32_e32 v71, v70
	v_max_f32_e32 v70, v63, v63
	v_max_f32_e32 v68, 0xc1a00000, v68
	v_max_f32_e32 v70, 0xc1a00000, v70
	v_mul_f32_e32 v68, 0xbfb8aa3b, v68
	v_mul_f32_e32 v70, 0xbfb8aa3b, v70
	v_exp_f32_e32 v68, v68
	v_exp_f32_e32 v70, v70
	v_cvt_pk_bf16_f32 v66, v66, v67
	v_cvt_pk_bf16_f32 v67, v74, v75
	global_store_dwordx4 v[86:87], v[64:67], off
	v_add_u32_e32 v72, 0x80, v154
	s_nop 0
	v_pk_add_f32 v[64:65], v[68:69], 1.0 op_sel_hi:[1,0]
	v_pk_add_f32 v[66:67], v[70:71], 1.0 op_sel_hi:[1,0]
	v_mov_b32_e32 v68, v65
	v_mov_b32_e32 v69, v67
	v_mov_b32_e32 v70, v64
	v_mov_b32_e32 v71, v66
	v_pk_mul_f32 v[68:69], v[68:69], v[70:71]
	s_nop 0
	v_mul_f32_e32 v70, v68, v69
	v_rcp_f32_e32 v73, v70
	v_mad_i64_i32 v[70:71], s[16:17], v72, s40, v[144:145]
	v_lshl_add_u64 v[70:71], v[70:71], 0, v[146:147]
	v_mul_f32_e32 v68, v68, v73
	v_mul_f32_e32 v72, v69, v73
	v_pk_mul_f32 v[66:67], v[66:67], v[68:69] op_sel_hi:[1,0]
	v_max_f32_e32 v68, v56, v56
	v_max_f32_e32 v73, v58, v58
	v_max_f32_e32 v68, 0xc1a00000, v68
	v_max_f32_e32 v73, 0xc1a00000, v73
	v_mul_f32_e32 v68, 0xbfb8aa3b, v68
	v_mul_f32_e32 v73, 0xbfb8aa3b, v73
	v_exp_f32_e32 v69, v68
	v_max_f32_e32 v68, v57, v57
	v_exp_f32_e32 v75, v73
	v_max_f32_e32 v73, v59, v59
	v_max_f32_e32 v68, 0xc1a00000, v68
	v_max_f32_e32 v73, 0xc1a00000, v73
	v_mul_f32_e32 v68, 0xbfb8aa3b, v68
	v_mul_f32_e32 v73, 0xbfb8aa3b, v73
	v_exp_f32_e32 v68, v68
	v_exp_f32_e32 v74, v73
	v_pk_mul_f32 v[64:65], v[64:65], v[72:73] op_sel_hi:[1,0]
	v_pk_mul_f32 v[62:63], v[62:63], v[66:67]
	v_pk_mul_f32 v[60:61], v[60:61], v[64:65]
	v_pk_add_f32 v[64:65], v[68:69], 1.0 op_sel_hi:[1,0]
	v_pk_add_f32 v[68:69], v[74:75], 1.0 op_sel_hi:[1,0]
	v_mov_b32_e32 v72, v65
	v_mov_b32_e32 v73, v69
	v_mov_b32_e32 v74, v64
	v_mov_b32_e32 v75, v68
	v_pk_mul_f32 v[72:73], v[72:73], v[74:75]
	v_pk_mul_f32 v[54:55], v[62:63], v[54:55]
	v_mul_f32_e32 v74, v72, v73
; __device__ __forceinline__ unsigned cvt_pk_bf16(float lo, float hi) { unsigned r; asm volatile("v_cvt_pk_bf16_f32 %0, %1, %2" : "=v"(r) : "v"(lo), "v"(hi)); return r; }
; __device__ __forceinline__ f32x4 sigmoid4(f32x4 x) {
;     f32x4 d;
; #pragma unroll
;     for (int j = 0; j < 4; ++j) d[j] = 1.0f + __expf(-fmaxf(x[j], -20.0f));
;     const float p01 = d[0] * d[1], p23 = d[2] * d[3], r = __builtin_amdgcn_rcpf(p01 * p23), r01 = r * p23, r23 = r * p01;
;     return (f32x4){r01 * d[1], r01 * d[0], r23 * d[3], r23 * d[2]};
; }
;     __device__ __forceinline__ void operator()(const f32x4 (&acc)[2][2][4][2], const Unit& u, int wr, int wc, int fr, int fq) const {
;     ...
;             for (int m = 0; m < 4; ++m) { bf16_t* rowp = O + (size_t)(row0 + ai * HALF + m * 16) * ldc + col0;
;                 f32x4 v0, v1;
; #pragma unroll
;                 for (int j = 0; j < 1; ++j) { v0 = acc[ai][0][m][0] * sigmoid4(acc[ai][0][m][0]) * acc[ai][1][m][0]; v1 = acc[ai][0][m][1] * sigmoid4(acc[ai][0][m][1]) * acc[ai][1][m][1]; }
;                 u32x4 w; w.x = cvt_pk_bf16(v0[0], v0[1]); w.y = cvt_pk_bf16(v0[2], v0[3]); w.z = cvt_pk_bf16(v1[0], v1[1]); w.w = cvt_pk_bf16(v1[2], v1[3]);
;                 *(u32x4*)rowp = w; }
	v_rcp_f32_e32 v74, v74
	v_pk_mul_f32 v[52:53], v[60:61], v[52:53]
	v_mul_f32_e32 v60, v73, v74
	v_mul_f32_e32 v62, v72, v74
	v_pk_mul_f32 v[62:63], v[68:69], v[62:63] op_sel_hi:[1,0]
	v_pk_mul_f32 v[60:61], v[64:65], v[60:61] op_sel_hi:[1,0]
	v_pk_mul_f32 v[58:59], v[58:59], v[62:63]
	v_pk_mul_f32 v[56:57], v[56:57], v[60:61]
	v_pk_mul_f32 v[58:59], v[58:59], v[50:51]
	v_pk_mul_f32 v[50:51], v[56:57], v[48:49]
	v_cvt_pk_bf16_f32 v48, v52, v53
	v_cvt_pk_bf16_f32 v49, v54, v55
	v_max_f32_e32 v52, v44, v44
	v_max_f32_e32 v54, v46, v46
	v_max_f32_e32 v52, 0xc1a00000, v52
	v_max_f32_e32 v54, 0xc1a00000, v54
	v_mul_f32_e32 v52, 0xbfb8aa3b, v52
	v_mul_f32_e32 v54, 0xbfb8aa3b, v54
	v_exp_f32_e32 v53, v52
	v_max_f32_e32 v52, v45, v45
	v_exp_f32_e32 v55, v54
	v_max_f32_e32 v54, v47, v47
	v_max_f32_e32 v52, 0xc1a00000, v52
	v_max_f32_e32 v54, 0xc1a00000, v54
	v_mul_f32_e32 v52, 0xbfb8aa3b, v52
	v_mul_f32_e32 v54, 0xbfb8aa3b, v54
	v_exp_f32_e32 v52, v52
	v_exp_f32_e32 v54, v54
	v_cvt_pk_bf16_f32 v50, v50, v51
	v_cvt_pk_bf16_f32 v51, v58, v59
	global_store_dwordx4 v[70:71], v[48:51], off
	v_add_u32_e32 v56, 0x90, v154
	s_nop 0
	v_pk_add_f32 v[48:49], v[52:53], 1.0 op_sel_hi:[1,0]
	v_pk_add_f32 v[50:51], v[54:55], 1.0 op_sel_hi:[1,0]
	v_mov_b32_e32 v52, v49
	v_mov_b32_e32 v53, v51
	v_mov_b32_e32 v54, v48
	v_mov_b32_e32 v55, v50
	v_pk_mul_f32 v[52:53], v[52:53], v[54:55]
	s_nop 0
	v_mul_f32_e32 v54, v52, v53
	v_rcp_f32_e32 v57, v54
	v_mad_i64_i32 v[54:55], s[16:17], v56, s40, v[144:145]
	v_lshl_add_u64 v[54:55], v[54:55], 0, v[146:147]
	v_mul_f32_e32 v52, v52, v57
	v_mul_f32_e32 v56, v53, v57
	v_pk_mul_f32 v[50:51], v[50:51], v[52:53] op_sel_hi:[1,0]
	v_max_f32_e32 v52, v40, v40
	v_max_f32_e32 v57, v42, v42
	v_max_f32_e32 v52, 0xc1a00000, v52
	v_max_f32_e32 v57, 0xc1a00000, v57
	v_mul_f32_e32 v52, 0xbfb8aa3b, v52
	v_mul_f32_e32 v57, 0xbfb8aa3b, v57
	v_exp_f32_e32 v53, v52
	v_max_f32_e32 v52, v41, v41
	v_exp_f32_e32 v59, v57
	v_max_f32_e32 v57, v43, v43
	v_max_f32_e32 v52, 0xc1a00000, v52
	v_max_f32_e32 v57, 0xc1a00000, v57
	v_mul_f32_e32 v52, 0xbfb8aa3b, v52
	v_mul_f32_e32 v57, 0xbfb8aa3b, v57
	v_exp_f32_e32 v52, v52
	v_exp_f32_e32 v58, v57
	v_pk_mul_f32 v[48:49], v[48:49], v[56:57] op_sel_hi:[1,0]
	v_pk_mul_f32 v[46:47], v[46:47], v[50:51]
	v_pk_mul_f32 v[44:45], v[44:45], v[48:49]
	v_pk_add_f32 v[48:49], v[52:53], 1.0 op_sel_hi:[1,0]
	v_pk_add_f32 v[52:53], v[58:59], 1.0 op_sel_hi:[1,0]
	v_mov_b32_e32 v56, v49
	v_mov_b32_e32 v57, v53
	v_mov_b32_e32 v58, v48
	v_mov_b32_e32 v59, v52
	v_pk_mul_f32 v[56:57], v[56:57], v[58:59]
	v_pk_mul_f32 v[38:39], v[46:47], v[38:39]
	v_mul_f32_e32 v58, v56, v57
	v_rcp_f32_e32 v58, v58
	v_pk_mul_f32 v[36:37], v[44:45], v[36:37]
	v_mul_f32_e32 v44, v57, v58
	v_mul_f32_e32 v46, v56, v58
	v_pk_mul_f32 v[46:47], v[52:53], v[46:47] op_sel_hi:[1,0]
	v_pk_mul_f32 v[44:45], v[48:49], v[44:45] op_sel_hi:[1,0]
	v_pk_mul_f32 v[42:43], v[42:43], v[46:47]
	v_pk_mul_f32 v[40:41], v[40:41], v[44:45]
	v_pk_mul_f32 v[42:43], v[42:43], v[34:35]
	v_pk_mul_f32 v[34:35], v[40:41], v[32:33]
	v_cvt_pk_bf16_f32 v32, v36, v37
	v_cvt_pk_bf16_f32 v33, v38, v39
	v_max_f32_e32 v36, v28, v28
	v_max_f32_e32 v38, v30, v30
	v_max_f32_e32 v36, 0xc1a00000, v36
	v_max_f32_e32 v38, 0xc1a00000, v38
	v_mul_f32_e32 v36, 0xbfb8aa3b, v36
	v_mul_f32_e32 v38, 0xbfb8aa3b, v38
	v_exp_f32_e32 v37, v36
	v_max_f32_e32 v36, v29, v29
	v_exp_f32_e32 v39, v38
	v_max_f32_e32 v38, v31, v31
	v_max_f32_e32 v36, 0xc1a00000, v36
	v_max_f32_e32 v38, 0xc1a00000, v38
	v_mul_f32_e32 v36, 0xbfb8aa3b, v36
	v_mul_f32_e32 v38, 0xbfb8aa3b, v38
	v_exp_f32_e32 v36, v36
	v_exp_f32_e32 v38, v38
	v_cvt_pk_bf16_f32 v34, v34, v35
	v_cvt_pk_bf16_f32 v35, v42, v43
	global_store_dwordx4 v[54:55], v[32:35], off
	v_add_u32_e32 v40, 0xa0, v154
	s_nop 0
	v_pk_add_f32 v[32:33], v[36:37], 1.0 op_sel_hi:[1,0]
	v_pk_add_f32 v[34:35], v[38:39], 1.0 op_sel_hi:[1,0]
	v_mov_b32_e32 v36, v33
	v_mov_b32_e32 v37, v35
	v_mov_b32_e32 v38, v32
	v_mov_b32_e32 v39, v34
	v_pk_mul_f32 v[36:37], v[36:37], v[38:39]
	s_nop 0
	v_mul_f32_e32 v38, v36, v37
	v_rcp_f32_e32 v41, v38
	v_mad_i64_i32 v[38:39], s[16:17], v40, s40, v[144:145]
	v_lshl_add_u64 v[38:39], v[38:39], 0, v[146:147]
	v_mul_f32_e32 v36, v36, v41
	v_mul_f32_e32 v40, v37, v41
	v_pk_mul_f32 v[34:35], v[34:35], v[36:37] op_sel_hi:[1,0]
; __device__ __forceinline__ unsigned cvt_pk_bf16(float lo, float hi) { unsigned r; asm volatile("v_cvt_pk_bf16_f32 %0, %1, %2" : "=v"(r) : "v"(lo), "v"(hi)); return r; }
; #define PG8_WAIT_V(n) asm volatile("s_waitcnt vmcnt(" #n ")" ::: "memory")
; #define PG8_BAR __builtin_amdgcn_s_barrier()
; __device__ __forceinline__ f32x4 sigmoid4(f32x4 x) {
;     f32x4 d;
; #pragma unroll
;     for (int j = 0; j < 4; ++j) d[j] = 1.0f + __expf(-fmaxf(x[j], -20.0f));
;     const float p01 = d[0] * d[1], p23 = d[2] * d[3], r = __builtin_amdgcn_rcpf(p01 * p23), r01 = r * p23, r23 = r * p01;
;     return (f32x4){r01 * d[1], r01 * d[0], r23 * d[3], r23 * d[2]};
; }
;     __device__ __forceinline__ void operator()(const f32x4 (&acc)[2][2][4][2], const Unit& u, int wr, int wc, int fr, int fq) const {
;     ...
;             for (int m = 0; m < 4; ++m) { bf16_t* rowp = O + (size_t)(row0 + ai * HALF + m * 16) * ldc + col0;
;                 f32x4 v0, v1;
; #pragma unroll
;                 for (int j = 0; j < 1; ++j) { v0 = acc[ai][0][m][0] * sigmoid4(acc[ai][0][m][0]) * acc[ai][1][m][0]; v1 = acc[ai][0][m][1] * sigmoid4(acc[ai][0][m][1]) * acc[ai][1][m][1]; }
;                 u32x4 w; w.x = cvt_pk_bf16(v0[0], v0[1]); w.y = cvt_pk_bf16(v0[2], v0[3]); w.z = cvt_pk_bf16(v1[0], v1[1]); w.w = cvt_pk_bf16(v1[2], v1[3]);
;                 *(u32x4*)rowp = w; }
; template <class Epi, class Sched>
; __device__ __forceinline__ void gemm_phase(PG8_LAS unsigned char* lds, const Gemm g, const Sched& S, const Epi& E) {
;     ...
;         if (!has_next) break;
; #pragma unroll
;         for (int a = 0; a < 2; ++a)
; #pragma unroll
;             for (int b = 0; b < 2; ++b)
; #pragma unroll
;                 for (int m = 0; m < 4; ++m)
; #pragma unroll
;                     for (int n = 0; n < 2; ++n) acc[a][b][m][n] = (f32x4){0.f, 0.f, 0.f, 0.f};
;         cur = nxt; cA = nA; cB = nB; ++ui;
;     }
;     PG8_WAIT_V(0);
;     if (wr == 0) PG8_BAR;
;     PG8_BAR;
	v_max_f32_e32 v36, v24, v24
	v_max_f32_e32 v41, v26, v26
	v_max_f32_e32 v36, 0xc1a00000, v36
	v_max_f32_e32 v41, 0xc1a00000, v41
	v_mul_f32_e32 v36, 0xbfb8aa3b, v36
	v_mul_f32_e32 v41, 0xbfb8aa3b, v41
	v_exp_f32_e32 v37, v36
	v_max_f32_e32 v36, v25, v25
	v_exp_f32_e32 v43, v41
	v_max_f32_e32 v41, v27, v27
	v_max_f32_e32 v36, 0xc1a00000, v36
	v_max_f32_e32 v41, 0xc1a00000, v41
	v_mul_f32_e32 v36, 0xbfb8aa3b, v36
	v_mul_f32_e32 v41, 0xbfb8aa3b, v41
	v_exp_f32_e32 v36, v36
	v_exp_f32_e32 v42, v41
	v_pk_mul_f32 v[32:33], v[32:33], v[40:41] op_sel_hi:[1,0]
	v_pk_mul_f32 v[30:31], v[30:31], v[34:35]
	v_pk_mul_f32 v[28:29], v[28:29], v[32:33]
	v_pk_add_f32 v[32:33], v[36:37], 1.0 op_sel_hi:[1,0]
	v_pk_add_f32 v[36:37], v[42:43], 1.0 op_sel_hi:[1,0]
	v_mov_b32_e32 v40, v33
	v_mov_b32_e32 v41, v37
	v_mov_b32_e32 v42, v32
	v_mov_b32_e32 v43, v36
	v_pk_mul_f32 v[40:41], v[40:41], v[42:43]
	v_pk_mul_f32 v[22:23], v[30:31], v[22:23]
	v_mul_f32_e32 v42, v40, v41
	v_rcp_f32_e32 v42, v42
	v_pk_mul_f32 v[20:21], v[28:29], v[20:21]
	v_mul_f32_e32 v28, v41, v42
	v_mul_f32_e32 v30, v40, v42
	v_pk_mul_f32 v[30:31], v[36:37], v[30:31] op_sel_hi:[1,0]
	v_pk_mul_f32 v[28:29], v[32:33], v[28:29] op_sel_hi:[1,0]
	v_pk_mul_f32 v[26:27], v[26:27], v[30:31]
	v_pk_mul_f32 v[24:25], v[24:25], v[28:29]
	v_pk_mul_f32 v[26:27], v[26:27], v[18:19]
	v_pk_mul_f32 v[18:19], v[24:25], v[16:17]
	v_cvt_pk_bf16_f32 v16, v20, v21
	v_cvt_pk_bf16_f32 v17, v22, v23
	v_max_f32_e32 v20, v12, v12
	v_max_f32_e32 v22, v14, v14
	v_max_f32_e32 v20, 0xc1a00000, v20
	v_max_f32_e32 v22, 0xc1a00000, v22
	v_mul_f32_e32 v20, 0xbfb8aa3b, v20
	v_mul_f32_e32 v22, 0xbfb8aa3b, v22
	v_exp_f32_e32 v21, v20
	v_max_f32_e32 v20, v13, v13
	v_exp_f32_e32 v23, v22
	v_max_f32_e32 v22, v15, v15
	v_max_f32_e32 v20, 0xc1a00000, v20
	v_max_f32_e32 v22, 0xc1a00000, v22
	v_mul_f32_e32 v20, 0xbfb8aa3b, v20
	v_mul_f32_e32 v22, 0xbfb8aa3b, v22
	v_exp_f32_e32 v20, v20
	v_exp_f32_e32 v22, v22
	v_cvt_pk_bf16_f32 v18, v18, v19
	v_cvt_pk_bf16_f32 v19, v26, v27
	global_store_dwordx4 v[38:39], v[16:19], off
	v_add_u32_e32 v24, 0xb0, v154
	s_nop 0
	v_pk_add_f32 v[16:17], v[20:21], 1.0 op_sel_hi:[1,0]
	v_pk_add_f32 v[18:19], v[22:23], 1.0 op_sel_hi:[1,0]
	v_mov_b32_e32 v20, v17
	v_mov_b32_e32 v21, v19
	v_mov_b32_e32 v22, v16
	v_mov_b32_e32 v23, v18
	v_pk_mul_f32 v[20:21], v[20:21], v[22:23]
	s_nop 0
	v_mul_f32_e32 v22, v20, v21
	v_rcp_f32_e32 v25, v22
	v_mad_i64_i32 v[22:23], s[16:17], v24, s40, v[144:145]
	v_lshl_add_u64 v[22:23], v[22:23], 0, v[146:147]
	v_mul_f32_e32 v20, v20, v25
	v_mul_f32_e32 v24, v21, v25
	v_pk_mul_f32 v[18:19], v[18:19], v[20:21] op_sel_hi:[1,0]
	v_max_f32_e32 v20, v8, v8
	v_max_f32_e32 v25, v10, v10
	v_max_f32_e32 v20, 0xc1a00000, v20
	v_max_f32_e32 v25, 0xc1a00000, v25
	v_mul_f32_e32 v20, 0xbfb8aa3b, v20
	v_mul_f32_e32 v25, 0xbfb8aa3b, v25
	v_exp_f32_e32 v21, v20
	v_max_f32_e32 v20, v9, v9
	v_exp_f32_e32 v27, v25
	v_max_f32_e32 v25, v11, v11
	v_max_f32_e32 v20, 0xc1a00000, v20
	v_max_f32_e32 v25, 0xc1a00000, v25
	v_mul_f32_e32 v20, 0xbfb8aa3b, v20
	v_mul_f32_e32 v25, 0xbfb8aa3b, v25
	v_exp_f32_e32 v20, v20
	v_exp_f32_e32 v26, v25
	v_pk_mul_f32 v[16:17], v[16:17], v[24:25] op_sel_hi:[1,0]
	v_pk_mul_f32 v[14:15], v[14:15], v[18:19]
	v_pk_mul_f32 v[12:13], v[12:13], v[16:17]
	v_pk_add_f32 v[16:17], v[20:21], 1.0 op_sel_hi:[1,0]
	v_pk_add_f32 v[20:21], v[26:27], 1.0 op_sel_hi:[1,0]
	v_mov_b32_e32 v24, v17
	v_mov_b32_e32 v25, v21
	v_mov_b32_e32 v26, v16
	v_mov_b32_e32 v27, v20
	v_pk_mul_f32 v[24:25], v[24:25], v[26:27]
	v_pk_mul_f32 v[6:7], v[14:15], v[6:7]
	v_mul_f32_e32 v26, v24, v25
	v_rcp_f32_e32 v26, v26
	v_pk_mul_f32 v[4:5], v[12:13], v[4:5]
	s_mov_b64 s[16:17], s[10:11]
	v_mul_f32_e32 v12, v25, v26
	v_mul_f32_e32 v14, v24, v26
	v_pk_mul_f32 v[14:15], v[20:21], v[14:15] op_sel_hi:[1,0]
	v_pk_mul_f32 v[12:13], v[16:17], v[12:13] op_sel_hi:[1,0]
	v_pk_mul_f32 v[10:11], v[10:11], v[14:15]
	v_pk_mul_f32 v[8:9], v[8:9], v[12:13]
	v_pk_mul_f32 v[10:11], v[10:11], v[2:3]
	v_pk_mul_f32 v[2:3], v[8:9], v[0:1]
	v_cvt_pk_bf16_f32 v0, v4, v5
	v_cvt_pk_bf16_f32 v1, v6, v7
	s_nop 0
	v_cvt_pk_bf16_f32 v2, v2, v3
	v_cvt_pk_bf16_f32 v3, v10, v11
	global_store_dwordx4 v[22:23], v[0:3], off
	s_cbranch_vccz .LBB0_1199
	s_waitcnt vmcnt(0)
	s_cmpk_gt_u32 s23, 0xff
	s_cbranch_scc1 .LBB0_1206
	s_barrier

; #define PG8_STAGE(bufoff, gbase, voff) do { _Pragma("unroll") for (int _i = 0; _i < 2; ++_i) \
;         __builtin_amdgcn_global_load_lds((const unsigned*)((const char*)(gbase) + (voff)[_i]), (PG8_LAS unsigned*)(lds + (bufoff) + ldsw + _i * 8192), 16, 0, 0); } while (0)
; #define PG8_WAIT_V(n) asm volatile("s_waitcnt vmcnt(" #n ")" ::: "memory")
; #define PG8_BAR __builtin_amdgcn_s_barrier()
; template <class Epi, class Sched>
; __device__ __forceinline__ void gemm_phase(PG8_LAS unsigned char* lds, const Gemm g, const Sched& S, const Epi& E) {
;     ...
;     for (int i = 0; i < 2; ++i) { int R, C; stage_rc(tid * 16 + i * 8192, R, C); const int Rb = Epi::PERM ? ((R & ~31) + perm32(R & 31)) : R;
;         voffA[i] = (unsigned)(R * K + C) * 2u; voffB[i] = (unsigned)(Rb * K + C) * 2u; }
;     const size_t kstep = (size_t)(BK * 2);
;     const size_t hstep = (size_t)HALF * K * 2;
;     const size_t tstep = 2 * hstep;
;     const unsigned ldsw = (unsigned)wid * 1024u;
;     const int aoff = lds_byte(wr * 64 + fr, fq * 8), boff = lds_byte(wc * 32 + fr, fq * 8);
;     ...
;     const char* cA = (const char*)g.A + (size_t)cur.pm * tstep; const char* cB = (const char*)g.Bt + (size_t)cur.pn * tstep;
;     S.a_ready(cur);
;     PG8_STAGE(PG8_SB(0, 0), cB, voffB); PG8_STAGE(PG8_SA(0, 0), cA, voffA); PG8_STAGE(PG8_SB(0, 1), cB + hstep, voffB); PG8_STAGE(PG8_SA(0, 1), cA + hstep, voffA);
;     if (wr == 1) PG8_BAR;
;     PG8_WAIT_V(4); PG8_BAR;
;     PG8_STAGE(PG8_SB(1, 0), cB + kstep, voffB); PG8_STAGE(PG8_SA(1, 0), cA + kstep, voffA); PG8_STAGE(PG8_SB(1, 1), cB + hstep + kstep, voffB);
;     PG8_WAIT_V(6); PG8_BAR;
.LBB0_1266:
	s_lshl_b32 s2, s2, 25
	v_readlane_b32 s5, v245, 24
	s_add_u32 s6, s5, s2
	v_readlane_b32 s2, v245, 25
	s_addc_u32 s7, s2, 0
	s_lshl_b32 s1, s1, 5
	s_mov_b64 s[8:9], 0x80
	s_and_b32 s1, s1, 0x60
	s_add_i32 m0, s34, 0x18000
	v_lshl_add_u64 v[6:7], v[6:7], 0, s[8:9]
	s_lshl_b32 s2, s3, 13
	s_lshl_b32 s5, s1, 7
	s_waitcnt vmcnt(0)
	s_barrier
	global_load_lds_dwordx4 v[6:7], off
	v_lshl_add_u64 v[4:5], v[4:5], 0, s[8:9]
	s_add_i32 m0, s34, 0x1a000
	s_add_i32 s39, s34, 0x8000
	s_add_i32 s40, s34, 0xa000
	global_load_lds_dwordx4 v[4:5], off
	v_lshl_add_u64 v[2:3], v[2:3], 0, s[8:9]
	s_mov_b32 m0, s39
	s_add_u32 s10, s20, 0xb0080
	global_load_lds_dwordx4 v[2:3], off
	v_lshl_add_u64 v[0:1], v[0:1], 0, s[8:9]
	s_mov_b32 m0, s40
	s_addc_u32 s11, s21, 0
	global_load_lds_dwordx4 v[0:1], off
	s_add_i32 m0, s34, 0x1c000
	v_lshl_add_u64 v[0:1], s[10:11], 0, v[130:131]
	global_load_lds_dwordx4 v[0:1], off
	v_lshl_add_u64 v[0:1], s[10:11], 0, v[134:135]
	s_add_i32 m0, s34, 0x1e000
	s_sext_i32_i8 s51, s4
	global_load_lds_dwordx4 v[0:1], off
	v_lshrrev_b32_e32 v1, 1, v181
	v_and_b32_e32 v1, 24, v1
	v_and_b32_e32 v0, 15, v181
	v_lshlrev_b32_e32 v2, 1, v1
	v_lshl_or_b32 v146, s3, 6, v0
	v_lshl_or_b32 v0, v0, 6, v2
	v_lshlrev_b32_e32 v2, 2, v181
	v_and_b32_e32 v2, 32, v2
	v_bitop3_b32 v3, v0, s2, v2 bitop3:0xde
	v_bitop3_b32 v147, v0, s5, v2 bitop3:0xde
	v_or_b32_e32 v148, s1, v1
	v_lshrrev_b32_e32 v1, 1, v8
	v_mul_lo_u32 v0, v10, s0
	s_mov_b32 s1, 0xb000
	v_mad_u64_u32 v[0:1], s[4:5], v1, s1, v[0:1]
	v_or_b32_e32 v0, v0, v9
	s_mov_b64 s[2:3], 0xb0080
	v_add_lshl_u32 v0, v0, v11, 1
	v_mov_b32_e32 v1, v131
	v_lshl_add_u64 v[136:137], v[0:1], 0, s[2:3]
	v_lshrrev_b32_e32 v1, 1, v12
	v_mul_lo_u32 v0, v13, s0
	v_mad_u64_u32 v[0:1], s[0:1], v1, s1, v[0:1]
	s_waitcnt vmcnt(6)
	v_or_b32_e32 v0, v0, v14
	v_add_lshl_u32 v0, v0, v15, 1
	v_mov_b32_e32 v1, v131
	s_add_i32 s42, 0, 0x10000
	s_add_i32 s43, 0, 0x14000
	s_ashr_i32 s41, s33, 31
	v_lshl_add_u64 v[138:139], v[0:1], 0, s[2:3]
	v_mov_b64_e32 v[140:141], 0x100
	v_mov_b64_e32 v[142:143], 0xff
	v_add_u32_e32 v149, s42, v147
	v_add_u32_e32 v150, 0, v3
	v_add_u32_e32 v151, s43, v147
	s_mov_b64 s[10:11], 0x40000
	s_mov_b32 s44, 0x40000
	s_mov_b64 s[12:13], 0x48000
	s_mov_b32 s45, 0x48000
	s_mov_b64 s[14:15], 0x50000
	s_mov_b32 s46, 0x50000
	s_mov_b64 s[16:17], 0x58000
	s_mov_b32 s47, 0x58000
	s_barrier

; #define PG8_STAGE(bufoff, gbase, voff) do { _Pragma("unroll") for (int _i = 0; _i < 2; ++_i) \
;         __builtin_amdgcn_global_load_lds((const unsigned*)((const char*)(gbase) + (voff)[_i]), (PG8_LAS unsigned*)(lds + (bufoff) + ldsw + _i * 8192), 16, 0, 0); } while (0)
; #define PG8_LDA(dst, b, h) do { _Pragma("unroll") for (int m = 0; m < 4; ++m) _Pragma("unroll") for (int k = 0; k < 2; ++k) dst[m][k] = *(const PG8_LAS bf16x8*)(lds + PG8_SA(b, h) + aoff + m * 2048 + k * 1024); } while (0)
; #define PG8_LDB(dst, b, h) do { _Pragma("unroll") for (int n = 0; n < 2; ++n) _Pragma("unroll") for (int k = 0; k < 2; ++k) dst[n][k] = *(const PG8_LAS bf16x8*)(lds + PG8_SB(b, h) + boff + n * 2048 + k * 1024); } while (0)
; #define PG8_MMA(ai, bj, At, Bt) do { __builtin_amdgcn_s_setprio(1); _Pragma("unroll") for (int m = 0; m < 4; ++m) _Pragma("unroll") for (int n = 0; n < 2; ++n) _Pragma("unroll") for (int k = 0; k < 2; ++k) \
;         acc[ai][bj][m][n] = __builtin_amdgcn_mfma_f32_16x16x32_bf16(Bt[n][k], At[m][k], acc[ai][bj][m][n], 0, 0, 0); __builtin_amdgcn_s_setprio(0); } while (0)
; #define PG8_WAIT_V(n) asm volatile("s_waitcnt vmcnt(" #n ")" ::: "memory")
; #define PG8_WAIT_L(n) asm volatile("s_waitcnt lgkmcnt(" #n ")" ::: "memory")
; #define PG8_BAR __builtin_amdgcn_s_barrier()
; #define PG8_SCHED __builtin_amdgcn_sched_barrier(0)
; template <class Epi, class Sched>
; __device__ __forceinline__ void gemm_phase(PG8_LAS unsigned char* lds, const Gemm g, const Sched& S, const Epi& E) {
;     ...
;             PG8_LDB(B0, 0, 0); PG8_SCHED; PG8_LDA(At, 0, 0); PG8_STAGE(PG8_SA(1, 1), a1 + hstep, voffA);
;             PG8_WAIT_L(8); PG8_BAR; PG8_WAIT_L(0); PG8_MMA(0, 0, At, B0); PG8_BAR; PG8_SCHED;
;             PG8_LDB(B1, 0, 1); PG8_STAGE(PG8_SB(0, 0), b2, voffB);
;             PG8_BAR; PG8_WAIT_L(0); PG8_MMA(0, 1, At, B1); PG8_BAR;
;             PG8_LDA(At, 0, 1); PG8_STAGE(PG8_SA(0, 0), a2, voffA);
;             PG8_BAR; PG8_WAIT_L(0); PG8_MMA(1, 0, At, B0); PG8_BAR; PG8_SCHED;
;             PG8_STAGE(PG8_SB(0, 1), b2 + hstep, voffB);
;             PG8_WAIT_V(6); PG8_BAR; PG8_MMA(1, 1, At, B1); PG8_BAR;
.LBB0_1278:
	ds_read_b128 v[152:155], v149
	ds_read_b128 v[156:159], v149 offset:1024
	ds_read_b128 v[160:163], v149 offset:2048
	ds_read_b128 v[164:167], v149 offset:3072
	s_add_u32 s20, s18, 0x100
	s_addc_u32 s21, s19, 0
	s_cmp_eq_u32 s54, 40
	s_cselect_b32 s25, s1, s21
	s_cselect_b32 s24, s0, s20
	s_cselect_b32 s23, s5, s53
	s_cselect_b32 s22, s4, s52
	v_lshl_add_u64 v[144:145], s[18:19], 0, v[136:137]
	s_add_i32 m0, s34, 0xc000
	ds_read_b128 v[168:171], v150
	ds_read_b128 v[172:175], v150 offset:1024
	ds_read_b128 v[182:185], v150 offset:2048
	ds_read_b128 v[190:193], v150 offset:3072
	ds_read_b128 v[194:197], v150 offset:4096
	ds_read_b128 v[198:201], v150 offset:5120
	ds_read_b128 v[202:205], v150 offset:6144
	ds_read_b128 v[206:209], v150 offset:7168
	global_load_lds_dwordx4 v[144:145], off
	v_lshl_add_u64 v[144:145], s[18:19], 0, v[138:139]
	s_add_i32 m0, s34, 0xe000
	s_nop 0
	global_load_lds_dwordx4 v[144:145], off
	s_waitcnt lgkmcnt(8)
	ds_read_b128 v[210:213], v151
	ds_read_b128 v[214:217], v151 offset:1024
	ds_read_b128 v[218:221], v151 offset:2048
	ds_read_b128 v[222:225], v151 offset:3072
	s_waitcnt vmcnt(8) lgkmcnt(0)
	s_barrier
	v_mfma_f32_16x16x32_bf16 v[124:127], v[152:155], v[168:171], v[124:127]
	v_mfma_f32_16x16x32_bf16 v[120:123], v[160:163], v[168:171], v[120:123]
	v_mfma_f32_16x16x32_bf16 v[108:111], v[152:155], v[182:185], v[108:111]
	v_mfma_f32_16x16x32_bf16 v[104:107], v[160:163], v[182:185], v[104:107]
	v_mfma_f32_16x16x32_bf16 v[92:95], v[152:155], v[194:197], v[92:95]
	v_mfma_f32_16x16x32_bf16 v[88:91], v[160:163], v[194:197], v[88:91]
	v_mfma_f32_16x16x32_bf16 v[76:79], v[152:155], v[202:205], v[76:79]
	v_mfma_f32_16x16x32_bf16 v[72:75], v[160:163], v[202:205], v[72:75]
	v_mfma_f32_16x16x32_bf16 v[124:127], v[156:159], v[172:175], v[124:127]
	v_mfma_f32_16x16x32_bf16 v[120:123], v[164:167], v[172:175], v[120:123]
	v_mfma_f32_16x16x32_bf16 v[108:111], v[156:159], v[190:193], v[108:111]
	v_mfma_f32_16x16x32_bf16 v[104:107], v[164:167], v[190:193], v[104:107]
	v_mfma_f32_16x16x32_bf16 v[92:95], v[156:159], v[198:201], v[92:95]
	v_mfma_f32_16x16x32_bf16 v[88:91], v[164:167], v[198:201], v[88:91]
	v_mfma_f32_16x16x32_bf16 v[76:79], v[156:159], v[206:209], v[76:79]
	v_mfma_f32_16x16x32_bf16 v[72:75], v[164:167], v[206:209], v[72:75]
	v_mfma_f32_16x16x32_bf16 v[116:119], v[210:213], v[168:171], v[116:119]
	v_mfma_f32_16x16x32_bf16 v[112:115], v[218:221], v[168:171], v[112:115]
	v_mfma_f32_16x16x32_bf16 v[100:103], v[210:213], v[182:185], v[100:103]
	v_mfma_f32_16x16x32_bf16 v[96:99], v[218:221], v[182:185], v[96:99]
	v_mfma_f32_16x16x32_bf16 v[84:87], v[210:213], v[194:197], v[84:87]
	v_mfma_f32_16x16x32_bf16 v[80:83], v[218:221], v[194:197], v[80:83]
	v_mfma_f32_16x16x32_bf16 v[68:71], v[210:213], v[202:205], v[68:71]
	v_mfma_f32_16x16x32_bf16 v[64:67], v[218:221], v[202:205], v[64:67]
	v_mfma_f32_16x16x32_bf16 v[116:119], v[214:217], v[172:175], v[116:119]
	v_mfma_f32_16x16x32_bf16 v[112:115], v[222:225], v[172:175], v[112:115]
	v_mfma_f32_16x16x32_bf16 v[100:103], v[214:217], v[190:193], v[100:103]
	v_mfma_f32_16x16x32_bf16 v[96:99], v[222:225], v[190:193], v[96:99]
	v_mfma_f32_16x16x32_bf16 v[84:87], v[214:217], v[198:201], v[84:87]
	v_mfma_f32_16x16x32_bf16 v[80:83], v[222:225], v[198:201], v[80:83]
	v_mfma_f32_16x16x32_bf16 v[68:71], v[214:217], v[206:209], v[68:71]
	v_mfma_f32_16x16x32_bf16 v[64:67], v[222:225], v[206:209], v[64:67]
	s_barrier
	ds_read_b128 v[168:171], v150 offset:16384
	ds_read_b128 v[172:175], v150 offset:17408
	ds_read_b128 v[182:185], v150 offset:18432
	ds_read_b128 v[190:193], v150 offset:19456
	ds_read_b128 v[194:197], v150 offset:20480
	ds_read_b128 v[198:201], v150 offset:21504
	ds_read_b128 v[202:205], v150 offset:22528
	ds_read_b128 v[206:209], v150 offset:23552
	s_add_i32 s18, s42, s31
	v_lshl_add_u64 v[144:145], s[22:23], 0, v[130:131]
	s_mov_b32 m0, s18
	s_nop 0
	global_load_lds_dwordx4 v[144:145], off
	v_lshl_add_u64 v[186:187], s[22:23], 0, v[134:135]
	s_add_i32 m0, s18, 0x2000
	s_nop 0
	global_load_lds_dwordx4 v[186:187], off
	s_nop 1
	s_mov_b32 m0, s34
	v_lshl_add_u64 v[226:227], s[24:25], 0, v[128:129]
	global_load_lds_dwordx4 v[226:227], off
	v_lshl_add_u64 v[228:229], s[24:25], 0, v[132:133]
	s_mov_b32 m0, s35
	s_nop 0
	global_load_lds_dwordx4 v[228:229], off
	s_add_u32 s18, s22, 0xb0000
	s_addc_u32 s19, s23, 0
	s_add_i32 s55, s43, s31
	v_lshl_add_u64 v[246:247], s[18:19], 0, v[130:131]
	s_mov_b32 m0, s55
	s_nop 0
	global_load_lds_dwordx4 v[246:247], off
	v_lshl_add_u64 v[246:247], s[18:19], 0, v[134:135]
	s_add_i32 m0, s55, 0x2000
	s_nop 0
	global_load_lds_dwordx4 v[246:247], off
	s_waitcnt vmcnt(8) lgkmcnt(0)
	s_barrier
; #define PG8_STAGE(bufoff, gbase, voff) do { _Pragma("unroll") for (int _i = 0; _i < 2; ++_i) \
;         __builtin_amdgcn_global_load_lds((const unsigned*)((const char*)(gbase) + (voff)[_i]), (PG8_LAS unsigned*)(lds + (bufoff) + ldsw + _i * 8192), 16, 0, 0); } while (0)
; #define PG8_LDA(dst, b, h) do { _Pragma("unroll") for (int m = 0; m < 4; ++m) _Pragma("unroll") for (int k = 0; k < 2; ++k) dst[m][k] = *(const PG8_LAS bf16x8*)(lds + PG8_SA(b, h) + aoff + m * 2048 + k * 1024); } while (0)
; #define PG8_LDB(dst, b, h) do { _Pragma("unroll") for (int n = 0; n < 2; ++n) _Pragma("unroll") for (int k = 0; k < 2; ++k) dst[n][k] = *(const PG8_LAS bf16x8*)(lds + PG8_SB(b, h) + boff + n * 2048 + k * 1024); } while (0)
; #define PG8_MMA(ai, bj, At, Bt) do { __builtin_amdgcn_s_setprio(1); _Pragma("unroll") for (int m = 0; m < 4; ++m) _Pragma("unroll") for (int n = 0; n < 2; ++n) _Pragma("unroll") for (int k = 0; k < 2; ++k) \
;         acc[ai][bj][m][n] = __builtin_amdgcn_mfma_f32_16x16x32_bf16(Bt[n][k], At[m][k], acc[ai][bj][m][n], 0, 0, 0); __builtin_amdgcn_s_setprio(0); } while (0)
; #define PG8_WAIT_V(n) asm volatile("s_waitcnt vmcnt(" #n ")" ::: "memory")
; #define PG8_WAIT_L(n) asm volatile("s_waitcnt lgkmcnt(" #n ")" ::: "memory")
; #define PG8_BAR __builtin_amdgcn_s_barrier()
; #define PG8_SCHED __builtin_amdgcn_sched_barrier(0)
; template <class Epi, class Sched>
; __device__ __forceinline__ void gemm_phase(PG8_LAS unsigned char* lds, const Gemm g, const Sched& S, const Epi& E) {
;     ...
;             PG8_BAR; PG8_WAIT_L(0); PG8_MMA(1, 0, At, B0); PG8_BAR; PG8_SCHED;
;             PG8_STAGE(PG8_SB(0, 1), b2 + hstep, voffB);
;             PG8_WAIT_V(6); PG8_BAR; PG8_MMA(1, 1, At, B1); PG8_BAR;
;             PG8_LDB(B0, 1, 0); PG8_SCHED; PG8_LDA(At, 1, 0); PG8_STAGE(PG8_SA(0, 1), a2 + hstep, voffA);
;             PG8_WAIT_L(8); PG8_BAR; PG8_WAIT_L(0); PG8_MMA(0, 0, At, B0); PG8_BAR; PG8_SCHED;
;             PG8_LDB(B1, 1, 1); PG8_STAGE(PG8_SB(1, 0), b3, voffB);
;             PG8_BAR; PG8_WAIT_L(0); PG8_MMA(0, 1, At, B1); PG8_BAR;
	v_mfma_f32_16x16x32_bf16 v[60:63], v[152:155], v[168:171], v[60:63]
	v_mfma_f32_16x16x32_bf16 v[56:59], v[160:163], v[168:171], v[56:59]
	v_mfma_f32_16x16x32_bf16 v[48:51], v[152:155], v[182:185], v[48:51]
	v_mfma_f32_16x16x32_bf16 v[40:43], v[160:163], v[182:185], v[40:43]
	v_mfma_f32_16x16x32_bf16 v[32:35], v[152:155], v[194:197], v[32:35]
	v_mfma_f32_16x16x32_bf16 v[24:27], v[160:163], v[194:197], v[24:27]
	v_mfma_f32_16x16x32_bf16 v[16:19], v[152:155], v[202:205], v[16:19]
	v_mfma_f32_16x16x32_bf16 v[8:11], v[160:163], v[202:205], v[8:11]
	v_mfma_f32_16x16x32_bf16 v[60:63], v[156:159], v[172:175], v[60:63]
	v_mfma_f32_16x16x32_bf16 v[56:59], v[164:167], v[172:175], v[56:59]
	v_mfma_f32_16x16x32_bf16 v[48:51], v[156:159], v[190:193], v[48:51]
	v_mfma_f32_16x16x32_bf16 v[40:43], v[164:167], v[190:193], v[40:43]
	v_mfma_f32_16x16x32_bf16 v[32:35], v[156:159], v[198:201], v[32:35]
	v_mfma_f32_16x16x32_bf16 v[24:27], v[164:167], v[198:201], v[24:27]
	v_mfma_f32_16x16x32_bf16 v[16:19], v[156:159], v[206:209], v[16:19]
	v_mfma_f32_16x16x32_bf16 v[8:11], v[164:167], v[206:209], v[8:11]
	v_mfma_f32_16x16x32_bf16 v[52:55], v[210:213], v[168:171], v[52:55]
	v_mfma_f32_16x16x32_bf16 v[44:47], v[218:221], v[168:171], v[44:47]
	v_mfma_f32_16x16x32_bf16 v[36:39], v[210:213], v[182:185], v[36:39]
	v_mfma_f32_16x16x32_bf16 v[28:31], v[218:221], v[182:185], v[28:31]
	v_mfma_f32_16x16x32_bf16 v[20:23], v[210:213], v[194:197], v[20:23]
	v_mfma_f32_16x16x32_bf16 v[12:15], v[218:221], v[194:197], v[12:15]
	v_mfma_f32_16x16x32_bf16 v[4:7], v[210:213], v[202:205], v[4:7]
	v_mfma_f32_16x16x32_bf16 v[0:3], v[218:221], v[202:205], v[0:3]
	v_mfma_f32_16x16x32_bf16 v[52:55], v[214:217], v[172:175], v[52:55]
	v_mfma_f32_16x16x32_bf16 v[44:47], v[222:225], v[172:175], v[44:47]
	v_mfma_f32_16x16x32_bf16 v[36:39], v[214:217], v[190:193], v[36:39]
	v_mfma_f32_16x16x32_bf16 v[28:31], v[222:225], v[190:193], v[28:31]
	v_mfma_f32_16x16x32_bf16 v[20:23], v[214:217], v[198:201], v[20:23]
	v_mfma_f32_16x16x32_bf16 v[12:15], v[222:225], v[198:201], v[12:15]
	v_mfma_f32_16x16x32_bf16 v[4:7], v[214:217], v[206:209], v[4:7]
	v_mfma_f32_16x16x32_bf16 v[0:3], v[222:225], v[206:209], v[0:3]
	s_barrier
	s_add_i32 s55, 0, 0x18000
	v_add_u32_e32 v164, s55, v147
	ds_read_b128 v[152:155], v164
	ds_read_b128 v[156:159], v164 offset:1024
	ds_read_b128 v[160:163], v164 offset:2048
	ds_read_b128 v[164:167], v164 offset:3072
	s_add_u32 s18, s24, 0xb0000
	s_addc_u32 s19, s25, 0
	s_mov_b32 m0, s36
	v_lshl_add_u64 v[210:211], s[18:19], 0, v[128:129]
	ds_read_b128 v[168:171], v150 offset:32768
	ds_read_b128 v[172:175], v150 offset:33792
	ds_read_b128 v[182:185], v150 offset:34816
	ds_read_b128 v[190:193], v150 offset:35840
	ds_read_b128 v[194:197], v150 offset:36864
	ds_read_b128 v[198:201], v150 offset:37888
	ds_read_b128 v[202:205], v150 offset:38912
	ds_read_b128 v[206:209], v150 offset:39936
	global_load_lds_dwordx4 v[210:211], off
	v_lshl_add_u64 v[210:211], s[18:19], 0, v[132:133]
	s_mov_b32 m0, s37
	s_nop 0
	global_load_lds_dwordx4 v[210:211], off
	s_add_i32 s24, 0, 0x1c000
	v_add_u32_e32 v179, s24, v147
	s_waitcnt lgkmcnt(8)
	ds_read_b128 v[210:213], v179
	ds_read_b128 v[214:217], v179 offset:1024
	ds_read_b128 v[218:221], v179 offset:2048
	ds_read_b128 v[222:225], v179 offset:3072
	s_waitcnt vmcnt(8) lgkmcnt(0)
	s_barrier
	v_mfma_f32_16x16x32_bf16 v[124:127], v[152:155], v[168:171], v[124:127]
	v_mfma_f32_16x16x32_bf16 v[120:123], v[160:163], v[168:171], v[120:123]
	v_mfma_f32_16x16x32_bf16 v[108:111], v[152:155], v[182:185], v[108:111]
	v_mfma_f32_16x16x32_bf16 v[104:107], v[160:163], v[182:185], v[104:107]
	v_mfma_f32_16x16x32_bf16 v[92:95], v[152:155], v[194:197], v[92:95]
	v_mfma_f32_16x16x32_bf16 v[88:91], v[160:163], v[194:197], v[88:91]
	v_mfma_f32_16x16x32_bf16 v[76:79], v[152:155], v[202:205], v[76:79]
	v_mfma_f32_16x16x32_bf16 v[72:75], v[160:163], v[202:205], v[72:75]
	v_mfma_f32_16x16x32_bf16 v[124:127], v[156:159], v[172:175], v[124:127]
	v_mfma_f32_16x16x32_bf16 v[120:123], v[164:167], v[172:175], v[120:123]
	v_mfma_f32_16x16x32_bf16 v[108:111], v[156:159], v[190:193], v[108:111]
	v_mfma_f32_16x16x32_bf16 v[104:107], v[164:167], v[190:193], v[104:107]
	v_mfma_f32_16x16x32_bf16 v[92:95], v[156:159], v[198:201], v[92:95]
	v_mfma_f32_16x16x32_bf16 v[88:91], v[164:167], v[198:201], v[88:91]
	v_mfma_f32_16x16x32_bf16 v[76:79], v[156:159], v[206:209], v[76:79]
	v_mfma_f32_16x16x32_bf16 v[72:75], v[164:167], v[206:209], v[72:75]
	v_mfma_f32_16x16x32_bf16 v[116:119], v[210:213], v[168:171], v[116:119]
	v_mfma_f32_16x16x32_bf16 v[112:115], v[218:221], v[168:171], v[112:115]
	v_mfma_f32_16x16x32_bf16 v[100:103], v[210:213], v[182:185], v[100:103]
	v_mfma_f32_16x16x32_bf16 v[96:99], v[218:221], v[182:185], v[96:99]
	v_mfma_f32_16x16x32_bf16 v[84:87], v[210:213], v[194:197], v[84:87]
	v_mfma_f32_16x16x32_bf16 v[80:83], v[218:221], v[194:197], v[80:83]
	v_mfma_f32_16x16x32_bf16 v[68:71], v[210:213], v[202:205], v[68:71]
	v_mfma_f32_16x16x32_bf16 v[64:67], v[218:221], v[202:205], v[64:67]
	v_mfma_f32_16x16x32_bf16 v[116:119], v[214:217], v[172:175], v[116:119]
	v_mfma_f32_16x16x32_bf16 v[112:115], v[222:225], v[172:175], v[112:115]
	v_mfma_f32_16x16x32_bf16 v[100:103], v[214:217], v[190:193], v[100:103]
	v_mfma_f32_16x16x32_bf16 v[96:99], v[222:225], v[190:193], v[96:99]
	v_mfma_f32_16x16x32_bf16 v[84:87], v[214:217], v[198:201], v[84:87]
	v_mfma_f32_16x16x32_bf16 v[80:83], v[222:225], v[198:201], v[80:83]
	v_mfma_f32_16x16x32_bf16 v[68:71], v[214:217], v[206:209], v[68:71]
	v_mfma_f32_16x16x32_bf16 v[64:67], v[222:225], v[206:209], v[64:67]
	s_barrier
; __device__ __forceinline__ unsigned cvt_pk_bf16(float lo, float hi) { unsigned r; asm volatile("v_cvt_pk_bf16_f32 %0, %1, %2" : "=v"(r) : "v"(lo), "v"(hi)); return r; }
; __device__ __forceinline__ float flogsig16(float x) { return (fminf(x, 0.f) - __logf(1.0f + __expf(-fabsf(x)))) * 0.0625f; }
; #define PG8_STAGE(bufoff, gbase, voff) do { _Pragma("unroll") for (int _i = 0; _i < 2; ++_i) \
;         __builtin_amdgcn_global_load_lds((const unsigned*)((const char*)(gbase) + (voff)[_i]), (PG8_LAS unsigned*)(lds + (bufoff) + ldsw + _i * 8192), 16, 0, 0); } while (0)
; #define PG8_LDA(dst, b, h) do { _Pragma("unroll") for (int m = 0; m < 4; ++m) _Pragma("unroll") for (int k = 0; k < 2; ++k) dst[m][k] = *(const PG8_LAS bf16x8*)(lds + PG8_SA(b, h) + aoff + m * 2048 + k * 1024); } while (0)
; #define PG8_BAR __builtin_amdgcn_s_barrier()
;     __device__ __forceinline__ void operator()(const f32x4 (&acc)[2][2][4][2], const Unit& u, int wr, int wc, int fr, int fq) const {
;     ...
;             for (int m = 0; m < 4; ++m) { bf16_t* rowp = O + (size_t)(row0 + ai * HALF + m * 16) * ldc + col0;
; #pragma unroll
;                 for (int bj = 0; bj < 2; ++bj) { f32x4 v0 = acc[ai][bj][m][0] + bv[bj][0], v1 = acc[ai][bj][m][1] + bv[bj][1];
;                     if (act == 1) {
; #pragma unroll
;                         for (int j = 0; j < 1; ++j) { v0 = v0 * sigmoid4(v0); v1 = v1 * sigmoid4(v1); } }
;                     else if (act == 2) {
; #pragma unroll
;                         for (int j = 0; j < 1; ++j) { v0 = sigmoid4(v0); v1 = sigmoid4(v1); } }
;                     else if (act == 3) {
; #pragma unroll
;                         for (int j = 0; j < 4; ++j) { v0[j] = flogsig16(v0[j]); v1[j] = flogsig16(v1[j]); } }
;                     u32x4 w; w.x = cvt_pk_bf16(v0[0], v0[1]); w.y = cvt_pk_bf16(v0[2], v0[3]); w.z = cvt_pk_bf16(v1[0], v1[1]); w.w = cvt_pk_bf16(v1[2], v1[3]);
;                     *(u32x4*)(rowp + bj * HALF) = w; } }
; template <class Epi, class Sched>
; __device__ __forceinline__ void gemm_phase(PG8_LAS unsigned char* lds, const Gemm g, const Sched& S, const Epi& E) {
;     ...
;             PG8_LDA(At, 1, 1); PG8_STAGE(PG8_SA(1, 0), a3, voffA);
;             PG8_BAR; PG8_WAIT_L(0); PG8_MMA(1, 0, At, B0); PG8_BAR; PG8_SCHED;
;             PG8_STAGE(PG8_SB(1, 1), b3 + hstep, voffB);
;             PG8_WAIT_V(6); PG8_BAR; PG8_MMA(1, 1, At, B1); PG8_BAR;
	ds_read_b128 v[168:171], v150 offset:49152
	ds_read_b128 v[172:175], v150 offset:50176
	ds_read_b128 v[182:185], v150 offset:51200
	ds_read_b128 v[190:193], v150 offset:52224
	ds_read_b128 v[194:197], v150 offset:53248
	ds_read_b128 v[198:201], v150 offset:54272
	ds_read_b128 v[202:205], v150 offset:55296
	ds_read_b128 v[206:209], v150 offset:56320
	s_add_i32 s18, s55, s31
	v_lshl_add_u64 v[144:145], v[144:145], 0, s[8:9]
	s_mov_b32 m0, s18
	s_nop 0
	global_load_lds_dwordx4 v[144:145], off
	v_lshl_add_u64 v[144:145], v[186:187], 0, s[8:9]
	s_add_i32 m0, s18, 0x2000
	s_nop 0
	global_load_lds_dwordx4 v[144:145], off
	s_nop 1
	s_mov_b32 m0, s39
	v_lshl_add_u64 v[144:145], v[226:227], 0, s[8:9]
	global_load_lds_dwordx4 v[144:145], off
	v_lshl_add_u64 v[144:145], v[228:229], 0, s[8:9]
	s_mov_b32 m0, s40
	s_nop 0
	global_load_lds_dwordx4 v[144:145], off
	s_add_u32 s18, s22, 0xb0080
	s_addc_u32 s19, s23, 0
	s_add_i32 s22, s24, s31
	v_lshl_add_u64 v[144:145], s[18:19], 0, v[130:131]
	s_mov_b32 m0, s22
	s_nop 0
	global_load_lds_dwordx4 v[144:145], off
	v_lshl_add_u64 v[144:145], s[18:19], 0, v[134:135]
	s_add_i32 m0, s22, 0x2000
	s_nop 0
	global_load_lds_dwordx4 v[144:145], off
	s_waitcnt vmcnt(8) lgkmcnt(0)
	s_barrier
	v_mfma_f32_16x16x32_bf16 v[60:63], v[152:155], v[168:171], v[60:63]
	v_mfma_f32_16x16x32_bf16 v[56:59], v[160:163], v[168:171], v[56:59]
	v_mfma_f32_16x16x32_bf16 v[48:51], v[152:155], v[182:185], v[48:51]
	v_mfma_f32_16x16x32_bf16 v[40:43], v[160:163], v[182:185], v[40:43]
	v_mfma_f32_16x16x32_bf16 v[32:35], v[152:155], v[194:197], v[32:35]
	v_mfma_f32_16x16x32_bf16 v[24:27], v[160:163], v[194:197], v[24:27]
	v_mfma_f32_16x16x32_bf16 v[16:19], v[152:155], v[202:205], v[16:19]
	v_mfma_f32_16x16x32_bf16 v[8:11], v[160:163], v[202:205], v[8:11]
	v_mfma_f32_16x16x32_bf16 v[60:63], v[156:159], v[172:175], v[60:63]
	v_mfma_f32_16x16x32_bf16 v[56:59], v[164:167], v[172:175], v[56:59]
	v_mfma_f32_16x16x32_bf16 v[48:51], v[156:159], v[190:193], v[48:51]
	v_mfma_f32_16x16x32_bf16 v[40:43], v[164:167], v[190:193], v[40:43]
	v_mfma_f32_16x16x32_bf16 v[32:35], v[156:159], v[198:201], v[32:35]
	v_mfma_f32_16x16x32_bf16 v[24:27], v[164:167], v[198:201], v[24:27]
	v_mfma_f32_16x16x32_bf16 v[16:19], v[156:159], v[206:209], v[16:19]
	v_mfma_f32_16x16x32_bf16 v[8:11], v[164:167], v[206:209], v[8:11]
	v_mfma_f32_16x16x32_bf16 v[52:55], v[210:213], v[168:171], v[52:55]
	v_mfma_f32_16x16x32_bf16 v[44:47], v[218:221], v[168:171], v[44:47]
	v_mfma_f32_16x16x32_bf16 v[36:39], v[210:213], v[182:185], v[36:39]
	v_mfma_f32_16x16x32_bf16 v[28:31], v[218:221], v[182:185], v[28:31]
	v_mfma_f32_16x16x32_bf16 v[20:23], v[210:213], v[194:197], v[20:23]
	v_mfma_f32_16x16x32_bf16 v[12:15], v[218:221], v[194:197], v[12:15]
	v_mfma_f32_16x16x32_bf16 v[4:7], v[210:213], v[202:205], v[4:7]
	v_mfma_f32_16x16x32_bf16 v[0:3], v[218:221], v[202:205], v[0:3]
	v_mfma_f32_16x16x32_bf16 v[52:55], v[214:217], v[172:175], v[52:55]
	v_mfma_f32_16x16x32_bf16 v[44:47], v[222:225], v[172:175], v[44:47]
	v_mfma_f32_16x16x32_bf16 v[36:39], v[214:217], v[190:193], v[36:39]
	v_mfma_f32_16x16x32_bf16 v[28:31], v[222:225], v[190:193], v[28:31]
	v_mfma_f32_16x16x32_bf16 v[20:23], v[214:217], v[198:201], v[20:23]
	v_mfma_f32_16x16x32_bf16 v[12:15], v[222:225], v[198:201], v[12:15]
	v_mfma_f32_16x16x32_bf16 v[4:7], v[214:217], v[206:209], v[4:7]
	v_mfma_f32_16x16x32_bf16 v[0:3], v[222:225], v[206:209], v[0:3]
	s_barrier
	s_add_i32 s54, s54, 2
	s_add_u32 s52, s52, 0x100
	s_addc_u32 s53, s53, 0
	s_cmp_gt_u32 s54, 41
	s_mov_b64 s[18:19], s[20:21]
	s_cbranch_scc0 .LBB0_1278
	v_lshl_add_u32 v152, s50, 8, v146
	v_lshl_or_b32 v144, s51, 8, v148
	v_ashrrev_i32_e32 v153, 31, v152
	v_ashrrev_i32_e32 v145, 31, v144
	v_lshlrev_b64 v[154:155], 11, v[152:153]
	v_lshl_add_u64 v[154:155], s[6:7], 0, v[154:155]
	v_lshlrev_b64 v[156:157], 1, v[144:145]
	v_lshl_add_u64 v[144:145], v[154:155], 0, v[156:157]
	v_pk_add_f32 v[126:127], v[126:127], 0 op_sel_hi:[1,0]
	v_pk_add_f32 v[124:125], v[124:125], 0 op_sel_hi:[1,0]
	v_pk_add_f32 v[154:155], v[122:123], 0 op_sel_hi:[1,0]
	v_pk_add_f32 v[122:123], v[120:121], 0 op_sel_hi:[1,0]
	v_cvt_pk_bf16_f32 v120, v124, v125
	v_cvt_pk_bf16_f32 v121, v126, v127
	v_pk_add_f32 v[116:117], v[116:117], 0 op_sel_hi:[1,0]
	v_cvt_pk_bf16_f32 v122, v122, v123
	v_cvt_pk_bf16_f32 v123, v154, v155
	global_store_dwordx4 v[144:145], v[120:123], off
	v_pk_add_f32 v[118:119], v[118:119], 0 op_sel_hi:[1,0]
	v_pk_add_f32 v[110:111], v[110:111], 0 op_sel_hi:[1,0]
	v_pk_add_f32 v[120:121], v[114:115], 0 op_sel_hi:[1,0]
	v_pk_add_f32 v[114:115], v[112:113], 0 op_sel_hi:[1,0]
	v_cvt_pk_bf16_f32 v112, v116, v117
	v_cvt_pk_bf16_f32 v113, v118, v119
	v_pk_add_f32 v[108:109], v[108:109], 0 op_sel_hi:[1,0]
	v_cvt_pk_bf16_f32 v114, v114, v115
	v_cvt_pk_bf16_f32 v115, v120, v121
	global_store_dwordx4 v[144:145], v[112:115], off offset:256
	v_pk_add_f32 v[100:101], v[100:101], 0 op_sel_hi:[1,0]
	v_pk_add_f32 v[102:103], v[102:103], 0 op_sel_hi:[1,0]
	v_or_b32_e32 v112, 16, v152
	v_ashrrev_i32_e32 v113, 31, v112
	v_lshlrev_b64 v[112:113], 11, v[112:113]
	v_lshl_add_u64 v[112:113], s[6:7], 0, v[112:113]
	v_lshl_add_u64 v[112:113], v[112:113], 0, v[156:157]
	v_pk_add_f32 v[114:115], v[106:107], 0 op_sel_hi:[1,0]
	v_pk_add_f32 v[106:107], v[104:105], 0 op_sel_hi:[1,0]
	v_cvt_pk_bf16_f32 v104, v108, v109
	v_cvt_pk_bf16_f32 v105, v110, v111
	v_pk_add_f32 v[94:95], v[94:95], 0 op_sel_hi:[1,0]
	v_cvt_pk_bf16_f32 v106, v106, v107
	v_cvt_pk_bf16_f32 v107, v114, v115
	global_store_dwordx4 v[112:113], v[104:107], off
	v_pk_add_f32 v[92:93], v[92:93], 0 op_sel_hi:[1,0]
	v_pk_add_f32 v[84:85], v[84:85], 0 op_sel_hi:[1,0]
; __device__ __forceinline__ unsigned cvt_pk_bf16(float lo, float hi) { unsigned r; asm volatile("v_cvt_pk_bf16_f32 %0, %1, %2" : "=v"(r) : "v"(lo), "v"(hi)); return r; }
; __device__ __forceinline__ float flogsig16(float x) { return (fminf(x, 0.f) - __logf(1.0f + __expf(-fabsf(x)))) * 0.0625f; }
;     __device__ __forceinline__ void operator()(const f32x4 (&acc)[2][2][4][2], const Unit& u, int wr, int wc, int fr, int fq) const {
;     ...
;             for (int m = 0; m < 4; ++m) { bf16_t* rowp = O + (size_t)(row0 + ai * HALF + m * 16) * ldc + col0;
; #pragma unroll
;                 for (int bj = 0; bj < 2; ++bj) { f32x4 v0 = acc[ai][bj][m][0] + bv[bj][0], v1 = acc[ai][bj][m][1] + bv[bj][1];
;                     if (act == 1) {
; #pragma unroll
;                         for (int j = 0; j < 1; ++j) { v0 = v0 * sigmoid4(v0); v1 = v1 * sigmoid4(v1); } }
;                     else if (act == 2) {
; #pragma unroll
;                         for (int j = 0; j < 1; ++j) { v0 = sigmoid4(v0); v1 = sigmoid4(v1); } }
;                     else if (act == 3) {
; #pragma unroll
;                         for (int j = 0; j < 4; ++j) { v0[j] = flogsig16(v0[j]); v1[j] = flogsig16(v1[j]); } }
;                     u32x4 w; w.x = cvt_pk_bf16(v0[0], v0[1]); w.y = cvt_pk_bf16(v0[2], v0[3]); w.z = cvt_pk_bf16(v1[0], v1[1]); w.w = cvt_pk_bf16(v1[2], v1[3]);
;                     *(u32x4*)(rowp + bj * HALF) = w; } }
; template <class Epi, class Sched>
; __device__ __forceinline__ void gemm_phase(PG8_LAS unsigned char* lds, const Gemm g, const Sched& S, const Epi& E) {
;     ...
;         if (!has_next) break;
; #pragma unroll
;         for (int a = 0; a < 2; ++a)
; #pragma unroll
;             for (int b = 0; b < 2; ++b)
; #pragma unroll
;                 for (int m = 0; m < 4; ++m)
; #pragma unroll
;                     for (int n = 0; n < 2; ++n) acc[a][b][m][n] = (f32x4){0.f, 0.f, 0.f, 0.f};
;         cur = nxt; cA = nA; cB = nB; ++ui;
;     }
	v_pk_add_f32 v[104:105], v[98:99], 0 op_sel_hi:[1,0]
	v_pk_add_f32 v[98:99], v[96:97], 0 op_sel_hi:[1,0]
	v_cvt_pk_bf16_f32 v96, v100, v101
	v_cvt_pk_bf16_f32 v97, v102, v103
	v_pk_add_f32 v[86:87], v[86:87], 0 op_sel_hi:[1,0]
	v_cvt_pk_bf16_f32 v98, v98, v99
	v_cvt_pk_bf16_f32 v99, v104, v105
	global_store_dwordx4 v[112:113], v[96:99], off offset:256
	v_pk_add_f32 v[78:79], v[78:79], 0 op_sel_hi:[1,0]
	v_pk_add_f32 v[76:77], v[76:77], 0 op_sel_hi:[1,0]
	v_or_b32_e32 v96, 32, v152
	v_ashrrev_i32_e32 v97, 31, v96
	v_lshlrev_b64 v[96:97], 11, v[96:97]
	v_lshl_add_u64 v[96:97], s[6:7], 0, v[96:97]
	v_lshl_add_u64 v[96:97], v[96:97], 0, v[156:157]
	v_pk_add_f32 v[98:99], v[90:91], 0 op_sel_hi:[1,0]
	v_pk_add_f32 v[90:91], v[88:89], 0 op_sel_hi:[1,0]
	v_cvt_pk_bf16_f32 v88, v92, v93
	v_cvt_pk_bf16_f32 v89, v94, v95
	v_pk_add_f32 v[70:71], v[70:71], 0 op_sel_hi:[1,0]
	v_cvt_pk_bf16_f32 v90, v90, v91
	v_cvt_pk_bf16_f32 v91, v98, v99
	global_store_dwordx4 v[96:97], v[88:91], off
	v_pk_add_f32 v[68:69], v[68:69], 0 op_sel_hi:[1,0]
	v_pk_add_f32 v[60:61], v[60:61], 0 op_sel_hi:[1,0]
	v_pk_add_f32 v[88:89], v[82:83], 0 op_sel_hi:[1,0]
	v_pk_add_f32 v[82:83], v[80:81], 0 op_sel_hi:[1,0]
	v_cvt_pk_bf16_f32 v80, v84, v85
	v_cvt_pk_bf16_f32 v81, v86, v87
	v_pk_add_f32 v[62:63], v[62:63], 0 op_sel_hi:[1,0]
	v_cvt_pk_bf16_f32 v82, v82, v83
	v_cvt_pk_bf16_f32 v83, v88, v89
	global_store_dwordx4 v[96:97], v[80:83], off offset:256
	v_pk_add_f32 v[54:55], v[54:55], 0 op_sel_hi:[1,0]
	v_pk_add_f32 v[52:53], v[52:53], 0 op_sel_hi:[1,0]
	v_or_b32_e32 v80, 48, v152
	v_ashrrev_i32_e32 v81, 31, v80
	v_lshlrev_b64 v[80:81], 11, v[80:81]
	v_lshl_add_u64 v[80:81], s[6:7], 0, v[80:81]
	v_lshl_add_u64 v[80:81], v[80:81], 0, v[156:157]
	v_pk_add_f32 v[82:83], v[74:75], 0 op_sel_hi:[1,0]
	v_pk_add_f32 v[74:75], v[72:73], 0 op_sel_hi:[1,0]
	v_cvt_pk_bf16_f32 v72, v76, v77
	v_cvt_pk_bf16_f32 v73, v78, v79
	v_pk_add_f32 v[48:49], v[48:49], 0 op_sel_hi:[1,0]
	v_cvt_pk_bf16_f32 v74, v74, v75
	v_cvt_pk_bf16_f32 v75, v82, v83
	global_store_dwordx4 v[80:81], v[72:75], off
	v_pk_add_f32 v[38:39], v[38:39], 0 op_sel_hi:[1,0]
	v_pk_add_f32 v[36:37], v[36:37], 0 op_sel_hi:[1,0]
	v_pk_add_f32 v[72:73], v[66:67], 0 op_sel_hi:[1,0]
	v_pk_add_f32 v[66:67], v[64:65], 0 op_sel_hi:[1,0]
	v_cvt_pk_bf16_f32 v64, v68, v69
	v_cvt_pk_bf16_f32 v65, v70, v71
	v_pk_add_f32 v[32:33], v[32:33], 0 op_sel_hi:[1,0]
	v_cvt_pk_bf16_f32 v66, v66, v67
	v_cvt_pk_bf16_f32 v67, v72, v73
	global_store_dwordx4 v[80:81], v[64:67], off offset:256
	v_pk_add_f32 v[22:23], v[22:23], 0 op_sel_hi:[1,0]
	v_pk_add_f32 v[20:21], v[20:21], 0 op_sel_hi:[1,0]
	v_pk_add_f32 v[66:67], v[58:59], 0 op_sel_hi:[1,0]
	v_pk_add_f32 v[58:59], v[56:57], 0 op_sel_hi:[1,0]
	v_cvt_pk_bf16_f32 v56, v60, v61
	v_add_co_u32_e32 v60, vcc, s44, v144
	v_cvt_pk_bf16_f32 v57, v62, v63
	v_cvt_pk_bf16_f32 v58, v58, v59
	v_cvt_pk_bf16_f32 v59, v66, v67
	v_lshl_add_u64 v[64:65], v[144:145], 0, s[10:11]
	s_nop 0
	v_addc_co_u32_e32 v61, vcc, 0, v145, vcc
	global_store_dwordx4 v[60:61], v[56:59], off
	v_pk_add_f32 v[16:17], v[16:17], 0 op_sel_hi:[1,0]
	s_mov_b32 s51, s48
	v_pk_add_f32 v[56:57], v[46:47], 0 op_sel_hi:[1,0]
	v_pk_add_f32 v[46:47], v[44:45], 0 op_sel_hi:[1,0]
	v_cvt_pk_bf16_f32 v44, v52, v53
	v_cvt_pk_bf16_f32 v45, v54, v55
	s_mov_b32 s50, s49
	v_cvt_pk_bf16_f32 v46, v46, v47
	v_cvt_pk_bf16_f32 v47, v56, v57
	global_store_dwordx4 v[64:65], v[44:47], off offset:256
	s_mov_b64 s[20:21], s[4:5]
	s_mov_b64 s[18:19], s[0:1]
	v_pk_add_f32 v[46:47], v[50:51], 0 op_sel_hi:[1,0]
	v_pk_add_f32 v[50:51], v[42:43], 0 op_sel_hi:[1,0]
	v_pk_add_f32 v[42:43], v[40:41], 0 op_sel_hi:[1,0]
	v_cvt_pk_bf16_f32 v40, v48, v49
	v_cvt_pk_bf16_f32 v41, v46, v47
	v_add_co_u32_e32 v46, vcc, s45, v144
	v_cvt_pk_bf16_f32 v42, v42, v43
	v_cvt_pk_bf16_f32 v43, v50, v51
	v_lshl_add_u64 v[44:45], v[144:145], 0, s[12:13]
	s_nop 0
	v_addc_co_u32_e32 v47, vcc, 0, v145, vcc
	global_store_dwordx4 v[46:47], v[40:43], off
	v_pk_add_f32 v[6:7], v[6:7], 0 op_sel_hi:[1,0]
	v_pk_add_f32 v[4:5], v[4:5], 0 op_sel_hi:[1,0]
	v_pk_add_f32 v[40:41], v[30:31], 0 op_sel_hi:[1,0]
	v_pk_add_f32 v[30:31], v[28:29], 0 op_sel_hi:[1,0]
	v_cvt_pk_bf16_f32 v28, v36, v37
	v_cvt_pk_bf16_f32 v29, v38, v39
	s_nop 0
	v_cvt_pk_bf16_f32 v30, v30, v31
	v_cvt_pk_bf16_f32 v31, v40, v41
	global_store_dwordx4 v[44:45], v[28:31], off offset:256
	s_nop 1
	v_pk_add_f32 v[30:31], v[34:35], 0 op_sel_hi:[1,0]
	v_pk_add_f32 v[34:35], v[26:27], 0 op_sel_hi:[1,0]
	v_pk_add_f32 v[26:27], v[24:25], 0 op_sel_hi:[1,0]
	v_cvt_pk_bf16_f32 v24, v32, v33
	v_cvt_pk_bf16_f32 v25, v30, v31
	v_add_co_u32_e32 v30, vcc, s46, v144
	v_cvt_pk_bf16_f32 v26, v26, v27
	v_cvt_pk_bf16_f32 v27, v34, v35
	v_lshl_add_u64 v[28:29], v[144:145], 0, s[14:15]
	s_nop 0
	v_addc_co_u32_e32 v31, vcc, 0, v145, vcc
	global_store_dwordx4 v[30:31], v[24:27], off
	s_nop 1
	v_pk_add_f32 v[24:25], v[14:15], 0 op_sel_hi:[1,0]
	v_pk_add_f32 v[14:15], v[12:13], 0 op_sel_hi:[1,0]
	v_cvt_pk_bf16_f32 v12, v20, v21
	v_cvt_pk_bf16_f32 v13, v22, v23
	s_nop 0
	v_cvt_pk_bf16_f32 v14, v14, v15
	v_cvt_pk_bf16_f32 v15, v24, v25
	global_store_dwordx4 v[28:29], v[12:15], off offset:256
	s_nop 1
	v_pk_add_f32 v[14:15], v[18:19], 0 op_sel_hi:[1,0]
	v_pk_add_f32 v[18:19], v[10:11], 0 op_sel_hi:[1,0]
	v_pk_add_f32 v[10:11], v[8:9], 0 op_sel_hi:[1,0]
	v_cvt_pk_bf16_f32 v8, v16, v17
	v_cvt_pk_bf16_f32 v9, v14, v15
	v_add_co_u32_e32 v14, vcc, s47, v144
	v_lshl_add_u64 v[12:13], v[144:145], 0, s[16:17]
	s_nop 0
	v_addc_co_u32_e32 v15, vcc, 0, v145, vcc
	v_cvt_pk_bf16_f32 v10, v10, v11
	v_cvt_pk_bf16_f32 v11, v18, v19
	global_store_dwordx4 v[14:15], v[8:11], off
	s_and_b64 vcc, exec, s[2:3]
	s_nop 0
	v_pk_add_f32 v[8:9], v[2:3], 0 op_sel_hi:[1,0]
	v_pk_add_f32 v[2:3], v[0:1], 0 op_sel_hi:[1,0]
	v_cvt_pk_bf16_f32 v0, v4, v5
	v_cvt_pk_bf16_f32 v1, v6, v7
	s_nop 0
	v_cvt_pk_bf16_f32 v2, v2, v3
	v_cvt_pk_bf16_f32 v3, v8, v9
	global_store_dwordx4 v[12:13], v[0:3], off offset:256
	s_cbranch_vccz .LBB0_1267
	s_waitcnt vmcnt(0)
	s_cmpk_gt_u32 s27, 0xff
	s_cbranch_scc1 .LBB0_1282
	s_barrier

; __global__ void __launch_bounds__(512, 2) mk_fwd(Args a) {
	.amdhsa_kernel _ZN2mk6mk_fwdENS_4ArgsE
		.amdhsa_group_segment_fixed_size 0
		.amdhsa_private_segment_fixed_size 0
		.amdhsa_kernarg_size 456
		.amdhsa_user_sgpr_count 2
		.amdhsa_user_sgpr_dispatch_ptr 0
		.amdhsa_user_sgpr_queue_ptr 0
		.amdhsa_user_sgpr_kernarg_segment_ptr 1
		.amdhsa_user_sgpr_dispatch_id 0
		.amdhsa_user_sgpr_kernarg_preload_length 0
		.amdhsa_user_sgpr_kernarg_preload_offset 0
		.amdhsa_user_sgpr_private_segment_size 0
		.amdhsa_uses_dynamic_stack 0
		.amdhsa_enable_private_segment 0
		.amdhsa_system_sgpr_workgroup_id_x 1
		.amdhsa_system_sgpr_workgroup_id_y 0
		.amdhsa_system_sgpr_workgroup_id_z 0
		.amdhsa_system_sgpr_workgroup_info 0
		.amdhsa_system_vgpr_workitem_id 2
		.amdhsa_next_free_vgpr 248
		.amdhsa_next_free_sgpr 98
		.amdhsa_accum_offset 248
		.amdhsa_reserve_vcc 1
		.amdhsa_float_round_mode_32 0
		.amdhsa_float_round_mode_16_64 0
		.amdhsa_float_denorm_mode_32 3
		.amdhsa_float_denorm_mode_16_64 3
		.amdhsa_dx10_clamp 1
		.amdhsa_ieee_mode 1
		.amdhsa_fp16_overflow 0
		.amdhsa_tg_split 0
		.amdhsa_exception_fp_ieee_invalid_op 0
		.amdhsa_exception_fp_denorm_src 0
		.amdhsa_exception_fp_ieee_div_zero 0
		.amdhsa_exception_fp_ieee_overflow 0
		.amdhsa_exception_fp_ieee_underflow 0
		.amdhsa_exception_fp_ieee_inexact 0
		.amdhsa_exception_int_div_zero 0
	.end_amdhsa_kernel

; __global__ void __launch_bounds__(512, 2) mk_fwd(Args a) {
amdhsa.kernels:
  - .agpr_count:     0
    .args:
      - .offset:         0
        .size:           200
        .value_kind:     by_value
      - .offset:         200
        .size:           4
        .value_kind:     hidden_block_count_x
      - .offset:         204
        .size:           4
        .value_kind:     hidden_block_count_y
      - .offset:         208
        .size:           4
        .value_kind:     hidden_block_count_z
      - .offset:         212
        .size:           2
        .value_kind:     hidden_group_size_x
      - .offset:         214
        .size:           2
        .value_kind:     hidden_group_size_y
      - .offset:         216
        .size:           2
        .value_kind:     hidden_group_size_z
      - .offset:         218
        .size:           2
        .value_kind:     hidden_remainder_x
      - .offset:         220
        .size:           2
        .value_kind:     hidden_remainder_y
      - .offset:         222
        .size:           2
        .value_kind:     hidden_remainder_z
      - .offset:         240
        .size:           8
        .value_kind:     hidden_global_offset_x
      - .offset:         248
        .size:           8
        .value_kind:     hidden_global_offset_y
      - .offset:         256
        .size:           8
        .value_kind:     hidden_global_offset_z
      - .offset:         264
        .size:           2
        .value_kind:     hidden_grid_dims
      - .offset:         288
        .size:           8
        .value_kind:     hidden_multigrid_sync_arg
      - .offset:         320
        .size:           4
        .value_kind:     hidden_dynamic_lds_size
    .group_segment_fixed_size: 0
    .kernarg_segment_align: 8
    .kernarg_segment_size: 456
    .language:       OpenCL C
    .language_version:
      - 2
      - 0
    .max_flat_workgroup_size: 512
    .name:           _ZN2mk6mk_fwdENS_4ArgsE
    .private_segment_fixed_size: 0
    .sgpr_count:     104
    .sgpr_spill_count: 74
    .symbol:         _ZN2mk6mk_fwdENS_4ArgsE.kd
    .uniform_work_group_size: 1
    .uses_dynamic_stack: false
    .vgpr_count:     248
    .vgpr_spill_count: 0
    .wavefront_size: 64
